# all s_setprio 1/0 flips removed from the GEMM main loops (A/B of the priority flips)
# speedup vs baseline: 1.0068x; 1.0068x over previous
; #define PG8_STAGE(bufoff, gbase, voff) do { _Pragma("unroll") for (int _i = 0; _i < 2; ++_i) \
;         __builtin_amdgcn_global_load_lds((const unsigned*)((const char*)(gbase) + (voff)[_i]), (LAS unsigned*)(lds + (bufoff) + ldsw + _i * 8192), 16, 0, 0); } while (0)
; #define PG8_LDA(dst, b, h) do { _Pragma("unroll") for (int m = 0; m < 4; ++m) _Pragma("unroll") for (int k = 0; k < 2; ++k) dst[m][k] = *(const LAS bf16x8*)(lds + PG8_SA(b, h) + aoff + m * 2048 + k * 1024); } while (0)
; #define PG8_LDB(dst, b, h) do { _Pragma("unroll") for (int n = 0; n < 2; ++n) _Pragma("unroll") for (int k = 0; k < 2; ++k) dst[n][k] = *(const LAS bf16x8*)(lds + PG8_SB(b, h) + boff + n * 2048 + k * 1024); } while (0)
; #define PG8_MMA(ai, bj, At, Bt) do { __builtin_amdgcn_s_setprio(1); _Pragma("unroll") for (int m = 0; m < 4; ++m) _Pragma("unroll") for (int n = 0; n < 2; ++n) _Pragma("unroll") for (int k = 0; k < 2; ++k) \
;         acc[ai][bj][m][n] = __builtin_amdgcn_mfma_f32_16x16x32_bf16(Bt[n][k], At[m][k], acc[ai][bj][m][n], 0, 0, 0); __builtin_amdgcn_s_setprio(0); } while (0)
; #define PG8_WAIT_V(n) asm volatile("s_waitcnt vmcnt(" #n ")" ::: "memory")
; #define PG8_WAIT_L(n) asm volatile("s_waitcnt lgkmcnt(" #n ")" ::: "memory")
; #define PG8_BAR __builtin_amdgcn_s_barrier()
; #define PG8_SCHED __builtin_amdgcn_sched_barrier(0)
; template <class Epi>
; __device__ __forceinline__ void gemm_phase(LAS unsigned char* lds, const Gemm g, int G, int c, const Epi& E) {
;     ...
;             PG8_LDB(B0, 0, 0); PG8_LDB(B1, 0, 1); PG8_SCHED; PG8_LDA(At, 0, 0); PG8_STAGE(PG8_SA(1, 1), a1 + hstepA, voffA);
;             PG8_WAIT_V(8); PG8_WAIT_L(0); PG8_BAR; PG8_MMA(0, 0, At, B0); PG8_MMA(0, 1, At, B1); PG8_BAR; PG8_SCHED;
;             PG8_LDA(At, 0, 1); PG8_STAGE(PG8_SB(0, 0), b2, voffB); PG8_STAGE(PG8_SB(0, 1), b2 + hstepB, voffB); PG8_STAGE(PG8_SA(0, 0), a2, voffA);
;             PG8_WAIT_V(8); PG8_WAIT_L(0); PG8_BAR; PG8_MMA(1, 0, At, B0); PG8_MMA(1, 1, At, B1); PG8_BAR; PG8_SCHED;
.LBB0_236:
	ds_read_b128 v[146:149], v152
	ds_read_b128 v[158:161], v152 offset:1024
	ds_read_b128 v[162:165], v152 offset:2048
	ds_read_b128 v[166:169], v152 offset:3072
	ds_read_b128 v[170:173], v153
	ds_read_b128 v[174:177], v153 offset:1024
	ds_read_b128 v[178:181], v153 offset:2048
	ds_read_b128 v[182:185], v153 offset:3072
	s_add_u32 s33, s4, 0xfffc0080
	s_addc_u32 s54, s5, -1
	s_cmp_eq_u32 s85, 12
	s_cselect_b32 s57, s47, s54
	s_cselect_b32 s56, s46, s33
	s_cselect_b32 s55, s7, s84
	s_cselect_b32 s54, s43, s45
	v_lshl_add_u64 v[218:219], s[4:5], 0, v[138:139]
	s_add_i32 m0, s11, 0xc000
	ds_read_b128 v[186:189], v154
	ds_read_b128 v[190:193], v154 offset:1024
	ds_read_b128 v[194:197], v154 offset:2048
	ds_read_b128 v[198:201], v154 offset:3072
	ds_read_b128 v[202:205], v154 offset:4096
	ds_read_b128 v[206:209], v154 offset:5120
	ds_read_b128 v[210:213], v154 offset:6144
	ds_read_b128 v[214:217], v154 offset:7168
	global_load_lds_dwordx4 v[218:219], off
	v_lshl_add_u64 v[218:219], s[4:5], 0, v[140:141]
	s_add_i32 m0, s11, 0xe000
	s_nop 0
	global_load_lds_dwordx4 v[218:219], off
	s_waitcnt vmcnt(8)
	s_waitcnt lgkmcnt(0)
	s_barrier
	s_waitcnt lgkmcnt(0)
	v_mfma_f32_16x16x32_bf16 v[126:129], v[146:149], v[186:189], v[126:129]
	v_mfma_f32_16x16x32_bf16 v[122:125], v[162:165], v[186:189], v[122:125]
	v_mfma_f32_16x16x32_bf16 v[110:113], v[146:149], v[194:197], v[110:113]
	v_mfma_f32_16x16x32_bf16 v[106:109], v[162:165], v[194:197], v[106:109]
	v_mfma_f32_16x16x32_bf16 v[94:97], v[146:149], v[202:205], v[94:97]
	v_mfma_f32_16x16x32_bf16 v[90:93], v[162:165], v[202:205], v[90:93]
	v_mfma_f32_16x16x32_bf16 v[78:81], v[146:149], v[210:213], v[78:81]
	v_mfma_f32_16x16x32_bf16 v[74:77], v[162:165], v[210:213], v[74:77]
	v_mfma_f32_16x16x32_bf16 v[126:129], v[158:161], v[190:193], v[126:129]
	v_mfma_f32_16x16x32_bf16 v[122:125], v[166:169], v[190:193], v[122:125]
	v_mfma_f32_16x16x32_bf16 v[110:113], v[158:161], v[198:201], v[110:113]
	v_mfma_f32_16x16x32_bf16 v[106:109], v[166:169], v[198:201], v[106:109]
	v_mfma_f32_16x16x32_bf16 v[94:97], v[158:161], v[206:209], v[94:97]
	v_mfma_f32_16x16x32_bf16 v[90:93], v[166:169], v[206:209], v[90:93]
	v_mfma_f32_16x16x32_bf16 v[78:81], v[158:161], v[214:217], v[78:81]
	v_mfma_f32_16x16x32_bf16 v[74:77], v[166:169], v[214:217], v[74:77]
	v_mfma_f32_16x16x32_bf16 v[118:121], v[170:173], v[186:189], v[118:121]
	v_mfma_f32_16x16x32_bf16 v[114:117], v[178:181], v[186:189], v[114:117]
	v_mfma_f32_16x16x32_bf16 v[102:105], v[170:173], v[194:197], v[102:105]
	v_mfma_f32_16x16x32_bf16 v[98:101], v[178:181], v[194:197], v[98:101]
	v_mfma_f32_16x16x32_bf16 v[86:89], v[170:173], v[202:205], v[86:89]
	v_mfma_f32_16x16x32_bf16 v[82:85], v[178:181], v[202:205], v[82:85]
	v_mfma_f32_16x16x32_bf16 v[70:73], v[170:173], v[210:213], v[70:73]
	v_mfma_f32_16x16x32_bf16 v[66:69], v[178:181], v[210:213], v[66:69]
	v_mfma_f32_16x16x32_bf16 v[118:121], v[174:177], v[190:193], v[118:121]
	v_mfma_f32_16x16x32_bf16 v[114:117], v[182:185], v[190:193], v[114:117]
	v_mfma_f32_16x16x32_bf16 v[102:105], v[174:177], v[198:201], v[102:105]
	v_mfma_f32_16x16x32_bf16 v[98:101], v[182:185], v[198:201], v[98:101]
	v_mfma_f32_16x16x32_bf16 v[86:89], v[174:177], v[206:209], v[86:89]
	v_mfma_f32_16x16x32_bf16 v[82:85], v[182:185], v[206:209], v[82:85]
	v_mfma_f32_16x16x32_bf16 v[70:73], v[174:177], v[214:217], v[70:73]
	v_mfma_f32_16x16x32_bf16 v[66:69], v[182:185], v[214:217], v[66:69]
	s_barrier
	s_add_i32 s33, s79, s60
	v_lshl_add_u64 v[218:219], s[54:55], 0, v[132:133]
	s_mov_b32 m0, s33
	ds_read_b128 v[186:189], v154 offset:16384
	ds_read_b128 v[190:193], v154 offset:17408
	ds_read_b128 v[194:197], v154 offset:18432
	ds_read_b128 v[198:201], v154 offset:19456
	ds_read_b128 v[202:205], v154 offset:20480
	ds_read_b128 v[206:209], v154 offset:21504
	ds_read_b128 v[210:213], v154 offset:22528
	ds_read_b128 v[214:217], v154 offset:23552
	global_load_lds_dwordx4 v[218:219], off
	s_add_i32 m0, s33, 0x2000
	s_add_u32 s62, s54, 0x40000
	v_lshl_add_u64 v[220:221], s[54:55], 0, v[136:137]
	s_addc_u32 s63, s55, 0
	s_add_i32 s33, s80, s60
	global_load_lds_dwordx4 v[220:221], off
	v_lshl_add_u64 v[222:223], s[62:63], 0, v[132:133]
	s_mov_b32 m0, s33
	v_lshl_add_u64 v[224:225], s[56:57], 0, v[134:135]
	global_load_lds_dwordx4 v[222:223], off
	v_lshl_add_u64 v[222:223], s[62:63], 0, v[136:137]
	s_add_i32 m0, s33, 0x2000
	s_nop 0
	global_load_lds_dwordx4 v[222:223], off
	v_lshl_add_u64 v[222:223], s[56:57], 0, v[130:131]
	s_mov_b32 m0, s11
	s_nop 0
	global_load_lds_dwordx4 v[222:223], off
	s_mov_b32 m0, s61
	s_nop 0
	global_load_lds_dwordx4 v[224:225], off
	s_waitcnt vmcnt(8)
	s_waitcnt lgkmcnt(0)
	s_barrier
; #define PG8_STAGE(bufoff, gbase, voff) do { _Pragma("unroll") for (int _i = 0; _i < 2; ++_i) \
;         __builtin_amdgcn_global_load_lds((const unsigned*)((const char*)(gbase) + (voff)[_i]), (LAS unsigned*)(lds + (bufoff) + ldsw + _i * 8192), 16, 0, 0); } while (0)
; #define PG8_LDA(dst, b, h) do { _Pragma("unroll") for (int m = 0; m < 4; ++m) _Pragma("unroll") for (int k = 0; k < 2; ++k) dst[m][k] = *(const LAS bf16x8*)(lds + PG8_SA(b, h) + aoff + m * 2048 + k * 1024); } while (0)
; #define PG8_LDB(dst, b, h) do { _Pragma("unroll") for (int n = 0; n < 2; ++n) _Pragma("unroll") for (int k = 0; k < 2; ++k) dst[n][k] = *(const LAS bf16x8*)(lds + PG8_SB(b, h) + boff + n * 2048 + k * 1024); } while (0)
; #define PG8_MMA(ai, bj, At, Bt) do { __builtin_amdgcn_s_setprio(1); _Pragma("unroll") for (int m = 0; m < 4; ++m) _Pragma("unroll") for (int n = 0; n < 2; ++n) _Pragma("unroll") for (int k = 0; k < 2; ++k) \
;         acc[ai][bj][m][n] = __builtin_amdgcn_mfma_f32_16x16x32_bf16(Bt[n][k], At[m][k], acc[ai][bj][m][n], 0, 0, 0); __builtin_amdgcn_s_setprio(0); } while (0)
; #define PG8_WAIT_V(n) asm volatile("s_waitcnt vmcnt(" #n ")" ::: "memory")
; #define PG8_WAIT_L(n) asm volatile("s_waitcnt lgkmcnt(" #n ")" ::: "memory")
; #define PG8_BAR __builtin_amdgcn_s_barrier()
; #define PG8_SCHED __builtin_amdgcn_sched_barrier(0)
; template <class Epi>
; __device__ __forceinline__ void gemm_phase(LAS unsigned char* lds, const Gemm g, int G, int c, const Epi& E) {
;     ...
;             PG8_WAIT_V(8); PG8_WAIT_L(0); PG8_BAR; PG8_MMA(1, 0, At, B0); PG8_MMA(1, 1, At, B1); PG8_BAR; PG8_SCHED;
;             PG8_LDB(B0, 1, 0); PG8_LDB(B1, 1, 1); PG8_SCHED; PG8_LDA(At, 1, 0); PG8_STAGE(PG8_SA(0, 1), a2 + hstepA, voffA);
;             PG8_WAIT_V(8); PG8_WAIT_L(0); PG8_BAR; PG8_MMA(0, 0, At, B0); PG8_MMA(0, 1, At, B1); PG8_BAR; PG8_SCHED;
	s_waitcnt lgkmcnt(0)
	v_mfma_f32_16x16x32_bf16 v[62:65], v[146:149], v[186:189], v[62:65]
	v_mfma_f32_16x16x32_bf16 v[58:61], v[162:165], v[186:189], v[58:61]
	v_mfma_f32_16x16x32_bf16 v[46:49], v[146:149], v[194:197], v[46:49]
	v_mfma_f32_16x16x32_bf16 v[42:45], v[162:165], v[194:197], v[42:45]
	v_mfma_f32_16x16x32_bf16 v[30:33], v[146:149], v[202:205], v[30:33]
	v_mfma_f32_16x16x32_bf16 v[26:29], v[162:165], v[202:205], v[26:29]
	v_mfma_f32_16x16x32_bf16 v[14:17], v[146:149], v[210:213], v[14:17]
	v_mfma_f32_16x16x32_bf16 v[10:13], v[162:165], v[210:213], v[10:13]
	v_mfma_f32_16x16x32_bf16 v[62:65], v[158:161], v[190:193], v[62:65]
	v_mfma_f32_16x16x32_bf16 v[58:61], v[166:169], v[190:193], v[58:61]
	v_mfma_f32_16x16x32_bf16 v[46:49], v[158:161], v[198:201], v[46:49]
	v_mfma_f32_16x16x32_bf16 v[42:45], v[166:169], v[198:201], v[42:45]
	v_mfma_f32_16x16x32_bf16 v[30:33], v[158:161], v[206:209], v[30:33]
	v_mfma_f32_16x16x32_bf16 v[26:29], v[166:169], v[206:209], v[26:29]
	v_mfma_f32_16x16x32_bf16 v[14:17], v[158:161], v[214:217], v[14:17]
	v_mfma_f32_16x16x32_bf16 v[10:13], v[166:169], v[214:217], v[10:13]
	v_mfma_f32_16x16x32_bf16 v[54:57], v[170:173], v[186:189], v[54:57]
	v_mfma_f32_16x16x32_bf16 v[50:53], v[178:181], v[186:189], v[50:53]
	v_mfma_f32_16x16x32_bf16 v[38:41], v[170:173], v[194:197], v[38:41]
	v_mfma_f32_16x16x32_bf16 v[34:37], v[178:181], v[194:197], v[34:37]
	v_mfma_f32_16x16x32_bf16 v[22:25], v[170:173], v[202:205], v[22:25]
	v_mfma_f32_16x16x32_bf16 v[18:21], v[178:181], v[202:205], v[18:21]
	v_mfma_f32_16x16x32_bf16 v[6:9], v[170:173], v[210:213], v[6:9]
	v_mfma_f32_16x16x32_bf16 v[2:5], v[178:181], v[210:213], v[2:5]
	v_mfma_f32_16x16x32_bf16 v[54:57], v[174:177], v[190:193], v[54:57]
	v_mfma_f32_16x16x32_bf16 v[50:53], v[182:185], v[190:193], v[50:53]
	v_mfma_f32_16x16x32_bf16 v[38:41], v[174:177], v[198:201], v[38:41]
	v_mfma_f32_16x16x32_bf16 v[34:37], v[182:185], v[198:201], v[34:37]
	v_mfma_f32_16x16x32_bf16 v[22:25], v[174:177], v[206:209], v[22:25]
	v_mfma_f32_16x16x32_bf16 v[18:21], v[182:185], v[206:209], v[18:21]
	v_mfma_f32_16x16x32_bf16 v[6:9], v[174:177], v[214:217], v[6:9]
	v_mfma_f32_16x16x32_bf16 v[2:5], v[182:185], v[214:217], v[2:5]
	s_barrier
	s_add_i32 s33, 0, 0x18000
	v_add_u32_e32 v157, s33, v151
	s_add_i32 s62, 0, 0x1c000
	ds_read_b128 v[146:149], v157
	ds_read_b128 v[158:161], v157 offset:1024
	ds_read_b128 v[162:165], v157 offset:2048
	ds_read_b128 v[166:169], v157 offset:3072
	v_add_u32_e32 v157, s62, v151
	ds_read_b128 v[170:173], v157
	ds_read_b128 v[174:177], v157 offset:1024
	ds_read_b128 v[178:181], v157 offset:2048
	ds_read_b128 v[182:185], v157 offset:3072
	s_add_u32 s56, s56, 0x40000
	s_addc_u32 s57, s57, 0
	s_mov_b32 m0, s66
	v_lshl_add_u64 v[226:227], s[56:57], 0, v[130:131]
	ds_read_b128 v[186:189], v154 offset:32768
	ds_read_b128 v[190:193], v154 offset:33792
	ds_read_b128 v[194:197], v154 offset:34816
	ds_read_b128 v[198:201], v154 offset:35840
	ds_read_b128 v[202:205], v154 offset:36864
	ds_read_b128 v[206:209], v154 offset:37888
	ds_read_b128 v[210:213], v154 offset:38912
	ds_read_b128 v[214:217], v154 offset:39936
	global_load_lds_dwordx4 v[226:227], off
	v_lshl_add_u64 v[226:227], s[56:57], 0, v[134:135]
	s_mov_b32 m0, s67
	s_nop 0
	global_load_lds_dwordx4 v[226:227], off
	s_waitcnt vmcnt(8)
	s_waitcnt lgkmcnt(0)
	s_barrier
	s_waitcnt lgkmcnt(0)
	v_mfma_f32_16x16x32_bf16 v[126:129], v[146:149], v[186:189], v[126:129]
	v_mfma_f32_16x16x32_bf16 v[122:125], v[162:165], v[186:189], v[122:125]
	v_mfma_f32_16x16x32_bf16 v[110:113], v[146:149], v[194:197], v[110:113]
	v_mfma_f32_16x16x32_bf16 v[106:109], v[162:165], v[194:197], v[106:109]
	v_mfma_f32_16x16x32_bf16 v[94:97], v[146:149], v[202:205], v[94:97]
	v_mfma_f32_16x16x32_bf16 v[90:93], v[162:165], v[202:205], v[90:93]
	v_mfma_f32_16x16x32_bf16 v[78:81], v[146:149], v[210:213], v[78:81]
	v_mfma_f32_16x16x32_bf16 v[74:77], v[162:165], v[210:213], v[74:77]
	v_mfma_f32_16x16x32_bf16 v[126:129], v[158:161], v[190:193], v[126:129]
	v_mfma_f32_16x16x32_bf16 v[122:125], v[166:169], v[190:193], v[122:125]
	v_mfma_f32_16x16x32_bf16 v[110:113], v[158:161], v[198:201], v[110:113]
	v_mfma_f32_16x16x32_bf16 v[106:109], v[166:169], v[198:201], v[106:109]
	v_mfma_f32_16x16x32_bf16 v[94:97], v[158:161], v[206:209], v[94:97]
	v_mfma_f32_16x16x32_bf16 v[90:93], v[166:169], v[206:209], v[90:93]
	v_mfma_f32_16x16x32_bf16 v[78:81], v[158:161], v[214:217], v[78:81]
	v_mfma_f32_16x16x32_bf16 v[74:77], v[166:169], v[214:217], v[74:77]
	v_mfma_f32_16x16x32_bf16 v[118:121], v[170:173], v[186:189], v[118:121]
	v_mfma_f32_16x16x32_bf16 v[114:117], v[178:181], v[186:189], v[114:117]
	v_mfma_f32_16x16x32_bf16 v[102:105], v[170:173], v[194:197], v[102:105]
	v_mfma_f32_16x16x32_bf16 v[98:101], v[178:181], v[194:197], v[98:101]
	v_mfma_f32_16x16x32_bf16 v[86:89], v[170:173], v[202:205], v[86:89]
	v_mfma_f32_16x16x32_bf16 v[82:85], v[178:181], v[202:205], v[82:85]
	v_mfma_f32_16x16x32_bf16 v[70:73], v[170:173], v[210:213], v[70:73]
	v_mfma_f32_16x16x32_bf16 v[66:69], v[178:181], v[210:213], v[66:69]
	v_mfma_f32_16x16x32_bf16 v[118:121], v[174:177], v[190:193], v[118:121]
	v_mfma_f32_16x16x32_bf16 v[114:117], v[182:185], v[190:193], v[114:117]
	v_mfma_f32_16x16x32_bf16 v[102:105], v[174:177], v[198:201], v[102:105]
	v_mfma_f32_16x16x32_bf16 v[98:101], v[182:185], v[198:201], v[98:101]
	v_mfma_f32_16x16x32_bf16 v[86:89], v[174:177], v[206:209], v[86:89]
	v_mfma_f32_16x16x32_bf16 v[82:85], v[182:185], v[206:209], v[82:85]
	v_mfma_f32_16x16x32_bf16 v[70:73], v[174:177], v[214:217], v[70:73]
	v_mfma_f32_16x16x32_bf16 v[66:69], v[182:185], v[214:217], v[66:69]
	s_barrier
; #define PG8_STAGE(bufoff, gbase, voff) do { _Pragma("unroll") for (int _i = 0; _i < 2; ++_i) \
;         __builtin_amdgcn_global_load_lds((const unsigned*)((const char*)(gbase) + (voff)[_i]), (LAS unsigned*)(lds + (bufoff) + ldsw + _i * 8192), 16, 0, 0); } while (0)
; #define PG8_LDA(dst, b, h) do { _Pragma("unroll") for (int m = 0; m < 4; ++m) _Pragma("unroll") for (int k = 0; k < 2; ++k) dst[m][k] = *(const LAS bf16x8*)(lds + PG8_SA(b, h) + aoff + m * 2048 + k * 1024); } while (0)
; #define PG8_MMA(ai, bj, At, Bt) do { __builtin_amdgcn_s_setprio(1); _Pragma("unroll") for (int m = 0; m < 4; ++m) _Pragma("unroll") for (int n = 0; n < 2; ++n) _Pragma("unroll") for (int k = 0; k < 2; ++k) \
;         acc[ai][bj][m][n] = __builtin_amdgcn_mfma_f32_16x16x32_bf16(Bt[n][k], At[m][k], acc[ai][bj][m][n], 0, 0, 0); __builtin_amdgcn_s_setprio(0); } while (0)
; #define PG8_WAIT_V(n) asm volatile("s_waitcnt vmcnt(" #n ")" ::: "memory")
; #define PG8_WAIT_L(n) asm volatile("s_waitcnt lgkmcnt(" #n ")" ::: "memory")
; #define PG8_BAR __builtin_amdgcn_s_barrier()
; #define PG8_SCHED __builtin_amdgcn_sched_barrier(0)
; template <class Epi>
; __device__ __forceinline__ void gemm_phase(LAS unsigned char* lds, const Gemm g, int G, int c, const Epi& E) {
;     ...
;             PG8_LDA(At, 1, 1); PG8_STAGE(PG8_SB(1, 0), b3, voffB); PG8_STAGE(PG8_SB(1, 1), b3 + hstepB, voffB); PG8_STAGE(PG8_SA(1, 0), a3, voffA);
;             PG8_WAIT_V(8); PG8_WAIT_L(0); PG8_BAR; PG8_MMA(1, 0, At, B0); PG8_MMA(1, 1, At, B1); PG8_BAR; PG8_SCHED;
;         }
	s_add_i32 s33, s33, s60
	v_lshl_add_u64 v[218:219], v[218:219], 0, s[20:21]
	s_mov_b32 m0, s33
	ds_read_b128 v[186:189], v154 offset:49152
	ds_read_b128 v[190:193], v154 offset:50176
	ds_read_b128 v[194:197], v154 offset:51200
	ds_read_b128 v[198:201], v154 offset:52224
	ds_read_b128 v[202:205], v154 offset:53248
	ds_read_b128 v[206:209], v154 offset:54272
	ds_read_b128 v[210:213], v154 offset:55296
	ds_read_b128 v[214:217], v154 offset:56320
	global_load_lds_dwordx4 v[218:219], off
	s_add_i32 m0, s33, 0x2000
	s_add_u32 s54, s54, 0x40080
	v_lshl_add_u64 v[218:219], v[220:221], 0, s[20:21]
	s_addc_u32 s55, s55, 0
	s_add_i32 s33, s62, s60
	global_load_lds_dwordx4 v[218:219], off
	v_lshl_add_u64 v[218:219], s[54:55], 0, v[132:133]
	s_mov_b32 m0, s33
	s_nop 0
	global_load_lds_dwordx4 v[218:219], off
	v_lshl_add_u64 v[218:219], s[54:55], 0, v[136:137]
	s_add_i32 m0, s33, 0x2000
	s_nop 0
	global_load_lds_dwordx4 v[218:219], off
	v_lshl_add_u64 v[218:219], v[222:223], 0, s[20:21]
	s_mov_b32 m0, s71
	s_nop 0
	global_load_lds_dwordx4 v[218:219], off
	v_lshl_add_u64 v[218:219], v[224:225], 0, s[20:21]
	s_mov_b32 m0, s72
	s_nop 0
	global_load_lds_dwordx4 v[218:219], off
	s_waitcnt vmcnt(8)
	s_waitcnt lgkmcnt(0)
	s_barrier
	s_waitcnt lgkmcnt(0)
	v_mfma_f32_16x16x32_bf16 v[62:65], v[146:149], v[186:189], v[62:65]
	v_mfma_f32_16x16x32_bf16 v[58:61], v[162:165], v[186:189], v[58:61]
	v_mfma_f32_16x16x32_bf16 v[46:49], v[146:149], v[194:197], v[46:49]
	v_mfma_f32_16x16x32_bf16 v[42:45], v[162:165], v[194:197], v[42:45]
	v_mfma_f32_16x16x32_bf16 v[30:33], v[146:149], v[202:205], v[30:33]
	v_mfma_f32_16x16x32_bf16 v[26:29], v[162:165], v[202:205], v[26:29]
	v_mfma_f32_16x16x32_bf16 v[14:17], v[146:149], v[210:213], v[14:17]
	v_mfma_f32_16x16x32_bf16 v[10:13], v[162:165], v[210:213], v[10:13]
	v_mfma_f32_16x16x32_bf16 v[62:65], v[158:161], v[190:193], v[62:65]
	v_mfma_f32_16x16x32_bf16 v[58:61], v[166:169], v[190:193], v[58:61]
	v_mfma_f32_16x16x32_bf16 v[46:49], v[158:161], v[198:201], v[46:49]
	v_mfma_f32_16x16x32_bf16 v[42:45], v[166:169], v[198:201], v[42:45]
	v_mfma_f32_16x16x32_bf16 v[30:33], v[158:161], v[206:209], v[30:33]
	v_mfma_f32_16x16x32_bf16 v[26:29], v[166:169], v[206:209], v[26:29]
	v_mfma_f32_16x16x32_bf16 v[14:17], v[158:161], v[214:217], v[14:17]
	v_mfma_f32_16x16x32_bf16 v[10:13], v[166:169], v[214:217], v[10:13]
	v_mfma_f32_16x16x32_bf16 v[54:57], v[170:173], v[186:189], v[54:57]
	v_mfma_f32_16x16x32_bf16 v[50:53], v[178:181], v[186:189], v[50:53]
	v_mfma_f32_16x16x32_bf16 v[38:41], v[170:173], v[194:197], v[38:41]
	v_mfma_f32_16x16x32_bf16 v[34:37], v[178:181], v[194:197], v[34:37]
	v_mfma_f32_16x16x32_bf16 v[22:25], v[170:173], v[202:205], v[22:25]
	v_mfma_f32_16x16x32_bf16 v[18:21], v[178:181], v[202:205], v[18:21]
	v_mfma_f32_16x16x32_bf16 v[6:9], v[170:173], v[210:213], v[6:9]
	v_mfma_f32_16x16x32_bf16 v[2:5], v[178:181], v[210:213], v[2:5]
	v_mfma_f32_16x16x32_bf16 v[54:57], v[174:177], v[190:193], v[54:57]
	v_mfma_f32_16x16x32_bf16 v[50:53], v[182:185], v[190:193], v[50:53]
	v_mfma_f32_16x16x32_bf16 v[38:41], v[174:177], v[198:201], v[38:41]
	v_mfma_f32_16x16x32_bf16 v[34:37], v[182:185], v[198:201], v[34:37]
	v_mfma_f32_16x16x32_bf16 v[22:25], v[174:177], v[206:209], v[22:25]
	v_mfma_f32_16x16x32_bf16 v[18:21], v[182:185], v[206:209], v[18:21]
	v_mfma_f32_16x16x32_bf16 v[6:9], v[174:177], v[214:217], v[6:9]
	v_mfma_f32_16x16x32_bf16 v[2:5], v[182:185], v[214:217], v[2:5]
	s_barrier
	s_add_i32 s85, s85, 2
	s_add_u32 s4, s4, 0x100
	s_addc_u32 s5, s5, 0
	s_add_u32 s45, s45, 0x100
	s_addc_u32 s84, s84, 0
	s_cmp_gt_u32 s85, 13
	s_cbranch_scc0 .LBB0_236
	s_and_b64 vcc, exec, s[22:23]
	s_cbranch_vccz .LBB0_239
	s_barrier

; #define PG8_STAGE(bufoff, gbase, voff) do { _Pragma("unroll") for (int _i = 0; _i < 2; ++_i) \
;         __builtin_amdgcn_global_load_lds((const unsigned*)((const char*)(gbase) + (voff)[_i]), (LAS unsigned*)(lds + (bufoff) + ldsw + _i * 8192), 16, 0, 0); } while (0)
; #define PG8_LDA(dst, b, h) do { _Pragma("unroll") for (int m = 0; m < 4; ++m) _Pragma("unroll") for (int k = 0; k < 2; ++k) dst[m][k] = *(const LAS bf16x8*)(lds + PG8_SA(b, h) + aoff + m * 2048 + k * 1024); } while (0)
; #define PG8_LDB(dst, b, h) do { _Pragma("unroll") for (int n = 0; n < 2; ++n) _Pragma("unroll") for (int k = 0; k < 2; ++k) dst[n][k] = *(const LAS bf16x8*)(lds + PG8_SB(b, h) + boff + n * 2048 + k * 1024); } while (0)
; #define PG8_MMA(ai, bj, At, Bt) do { __builtin_amdgcn_s_setprio(1); _Pragma("unroll") for (int m = 0; m < 4; ++m) _Pragma("unroll") for (int n = 0; n < 2; ++n) _Pragma("unroll") for (int k = 0; k < 2; ++k) \
;         acc[ai][bj][m][n] = __builtin_amdgcn_mfma_f32_16x16x32_bf16(Bt[n][k], At[m][k], acc[ai][bj][m][n], 0, 0, 0); __builtin_amdgcn_s_setprio(0); } while (0)
; #define PG8_WAIT_V(n) asm volatile("s_waitcnt vmcnt(" #n ")" ::: "memory")
; #define PG8_WAIT_L(n) asm volatile("s_waitcnt lgkmcnt(" #n ")" ::: "memory")
; #define PG8_BAR __builtin_amdgcn_s_barrier()
; #define PG8_SCHED __builtin_amdgcn_sched_barrier(0)
; template <class Epi>
; __device__ __forceinline__ void gemm_phase(LAS unsigned char* lds, const Gemm g, int G, int c, const Epi& E) {
;     ...
;             const bool last = (t == nt - 2);
;             const char* a1 = cA + (size_t)(t + 1) * kstep;
;             const char* a2 = last ? nA : cA + (size_t)(t + 2) * kstep; const char* b2 = last ? nB : cB + (size_t)(t + 2) * kstep;
;             const char* a3 = a2 + kstep; const char* b3 = b2 + kstep;
;             PG8_LDB(B0, 0, 0); PG8_LDB(B1, 0, 1); PG8_SCHED; PG8_LDA(At, 0, 0); PG8_STAGE(PG8_SA(1, 1), a1 + hstepA, voffA);
;             PG8_WAIT_V(8); PG8_WAIT_L(0); PG8_BAR; PG8_MMA(0, 0, At, B0); PG8_MMA(0, 1, At, B1); PG8_BAR; PG8_SCHED;
.LBB0_368:
	s_add_u32 s33, s20, s13
	s_addc_u32 s42, s21, 0
	s_add_u32 s43, s33, 0x100
	s_addc_u32 s44, s42, 0
	s_and_b64 s[38:39], s[24:25], exec
	s_cselect_b32 s45, s5, s44
	s_cselect_b32 s44, s4, s43
	s_add_u32 s13, s18, s13
	s_addc_u32 s38, s19, 0
	s_add_u32 s13, s13, 0x100
	s_addc_u32 s38, s38, 0
	s_and_b64 s[24:25], s[24:25], exec
	s_cselect_b32 s47, s17, s38
	s_cselect_b32 s46, s16, s13
	s_add_u32 s54, s33, 0xb0080
	s_addc_u32 s55, s42, 0
	s_add_i32 s65, s81, s56
	ds_read_b128 v[142:145], v148
	ds_read_b128 v[152:155], v148 offset:1024
	ds_read_b128 v[156:159], v148 offset:2048
	ds_read_b128 v[160:163], v148 offset:3072
	ds_read_b128 v[164:167], v149
	ds_read_b128 v[168:171], v149 offset:1024
	ds_read_b128 v[172:175], v149 offset:2048
	ds_read_b128 v[176:179], v149 offset:3072
	s_add_i32 m0, s57, 0xc000
	s_add_i32 s74, s57, 0xe000
	s_add_i32 s62, s65, 0x2000
	s_add_u32 s52, s46, 0xb0000
	s_addc_u32 s53, s47, 0
	s_add_i32 s64, s82, s56
	s_add_i32 s63, s64, 0x2000
	s_add_i32 s73, 0, 0x18000
	s_add_i32 s33, 0, 0x1c000
	s_add_u32 s42, s44, 0xb0000
	s_addc_u32 s43, s45, 0
	s_add_i32 s88, s73, s56
	s_add_i32 s38, s88, 0x2000
	s_add_u32 s24, s46, 0xb0080
	s_addc_u32 s25, s47, 0
	s_add_i32 s39, s33, s56
	s_add_i32 s13, s39, 0x2000
	v_lshl_add_u64 v[212:213], s[54:55], 0, v[136:137]
	ds_read_b128 v[180:183], v150
	ds_read_b128 v[184:187], v150 offset:1024
	ds_read_b128 v[188:191], v150 offset:2048
	ds_read_b128 v[192:195], v150 offset:3072
	ds_read_b128 v[196:199], v150 offset:4096
	ds_read_b128 v[200:203], v150 offset:5120
	ds_read_b128 v[204:207], v150 offset:6144
	ds_read_b128 v[208:211], v150 offset:7168
	global_load_lds_dwordx4 v[212:213], off
	v_lshl_add_u64 v[212:213], s[54:55], 0, v[132:133]
	s_mov_b32 m0, s74
	s_nop 0
	global_load_lds_dwordx4 v[212:213], off
	s_waitcnt vmcnt(8)
	s_waitcnt lgkmcnt(0)
	s_barrier
	s_waitcnt lgkmcnt(0)
	v_mfma_f32_16x16x32_bf16 v[126:129], v[142:145], v[180:183], v[126:129]
	v_mfma_f32_16x16x32_bf16 v[122:125], v[156:159], v[180:183], v[122:125]
	v_mfma_f32_16x16x32_bf16 v[118:121], v[142:145], v[188:191], v[118:121]
	v_mfma_f32_16x16x32_bf16 v[110:113], v[156:159], v[188:191], v[110:113]
	v_mfma_f32_16x16x32_bf16 v[102:105], v[142:145], v[196:199], v[102:105]
	v_mfma_f32_16x16x32_bf16 v[94:97], v[156:159], v[196:199], v[94:97]
	v_mfma_f32_16x16x32_bf16 v[86:89], v[142:145], v[204:207], v[86:89]
	v_mfma_f32_16x16x32_bf16 v[78:81], v[156:159], v[204:207], v[78:81]
	v_mfma_f32_16x16x32_bf16 v[126:129], v[152:155], v[184:187], v[126:129]
	v_mfma_f32_16x16x32_bf16 v[122:125], v[160:163], v[184:187], v[122:125]
	v_mfma_f32_16x16x32_bf16 v[118:121], v[152:155], v[192:195], v[118:121]
	v_mfma_f32_16x16x32_bf16 v[110:113], v[160:163], v[192:195], v[110:113]
	v_mfma_f32_16x16x32_bf16 v[102:105], v[152:155], v[200:203], v[102:105]
	v_mfma_f32_16x16x32_bf16 v[94:97], v[160:163], v[200:203], v[94:97]
	v_mfma_f32_16x16x32_bf16 v[86:89], v[152:155], v[208:211], v[86:89]
	v_mfma_f32_16x16x32_bf16 v[78:81], v[160:163], v[208:211], v[78:81]
	v_mfma_f32_16x16x32_bf16 v[114:117], v[164:167], v[180:183], v[114:117]
	v_mfma_f32_16x16x32_bf16 v[106:109], v[172:175], v[180:183], v[106:109]
	v_mfma_f32_16x16x32_bf16 v[98:101], v[164:167], v[188:191], v[98:101]
	v_mfma_f32_16x16x32_bf16 v[90:93], v[172:175], v[188:191], v[90:93]
	v_mfma_f32_16x16x32_bf16 v[82:85], v[164:167], v[196:199], v[82:85]
	v_mfma_f32_16x16x32_bf16 v[74:77], v[172:175], v[196:199], v[74:77]
	v_mfma_f32_16x16x32_bf16 v[70:73], v[164:167], v[204:207], v[70:73]
	v_mfma_f32_16x16x32_bf16 v[66:69], v[172:175], v[204:207], v[66:69]
	v_mfma_f32_16x16x32_bf16 v[114:117], v[168:171], v[184:187], v[114:117]
	v_mfma_f32_16x16x32_bf16 v[106:109], v[176:179], v[184:187], v[106:109]
	v_mfma_f32_16x16x32_bf16 v[98:101], v[168:171], v[192:195], v[98:101]
	v_mfma_f32_16x16x32_bf16 v[90:93], v[176:179], v[192:195], v[90:93]
	v_mfma_f32_16x16x32_bf16 v[82:85], v[168:171], v[200:203], v[82:85]
	v_mfma_f32_16x16x32_bf16 v[74:77], v[176:179], v[200:203], v[74:77]
	v_mfma_f32_16x16x32_bf16 v[70:73], v[168:171], v[208:211], v[70:73]
	v_mfma_f32_16x16x32_bf16 v[66:69], v[176:179], v[208:211], v[66:69]
	s_barrier
	s_mov_b32 m0, s65
	v_lshl_add_u64 v[212:213], s[46:47], 0, v[134:135]
	ds_read_b128 v[180:183], v150 offset:16384
	ds_read_b128 v[184:187], v150 offset:17408
	ds_read_b128 v[188:191], v150 offset:18432
	ds_read_b128 v[192:195], v150 offset:19456
	ds_read_b128 v[196:199], v150 offset:20480
	ds_read_b128 v[200:203], v150 offset:21504
	ds_read_b128 v[204:207], v150 offset:22528
	ds_read_b128 v[208:211], v150 offset:23552
	global_load_lds_dwordx4 v[212:213], off
	v_lshl_add_u64 v[214:215], s[46:47], 0, v[130:131]
	s_mov_b32 m0, s62
	v_lshl_add_u64 v[216:217], s[52:53], 0, v[134:135]
	global_load_lds_dwordx4 v[214:215], off
	s_mov_b32 m0, s64
	v_lshl_add_u64 v[218:219], s[44:45], 0, v[132:133]
	global_load_lds_dwordx4 v[216:217], off
	v_lshl_add_u64 v[216:217], s[52:53], 0, v[130:131]
	s_mov_b32 m0, s63
	s_nop 0
	global_load_lds_dwordx4 v[216:217], off
	v_lshl_add_u64 v[216:217], s[44:45], 0, v[136:137]
	s_mov_b32 m0, s57
	s_nop 0
	global_load_lds_dwordx4 v[216:217], off
	s_mov_b32 m0, s58
	s_nop 0
	global_load_lds_dwordx4 v[218:219], off
	s_waitcnt vmcnt(8)
	s_waitcnt lgkmcnt(0)
	s_barrier
; #define PG8_STAGE(bufoff, gbase, voff) do { _Pragma("unroll") for (int _i = 0; _i < 2; ++_i) \
;         __builtin_amdgcn_global_load_lds((const unsigned*)((const char*)(gbase) + (voff)[_i]), (LAS unsigned*)(lds + (bufoff) + ldsw + _i * 8192), 16, 0, 0); } while (0)
; #define PG8_LDA(dst, b, h) do { _Pragma("unroll") for (int m = 0; m < 4; ++m) _Pragma("unroll") for (int k = 0; k < 2; ++k) dst[m][k] = *(const LAS bf16x8*)(lds + PG8_SA(b, h) + aoff + m * 2048 + k * 1024); } while (0)
; #define PG8_LDB(dst, b, h) do { _Pragma("unroll") for (int n = 0; n < 2; ++n) _Pragma("unroll") for (int k = 0; k < 2; ++k) dst[n][k] = *(const LAS bf16x8*)(lds + PG8_SB(b, h) + boff + n * 2048 + k * 1024); } while (0)
; #define PG8_MMA(ai, bj, At, Bt) do { __builtin_amdgcn_s_setprio(1); _Pragma("unroll") for (int m = 0; m < 4; ++m) _Pragma("unroll") for (int n = 0; n < 2; ++n) _Pragma("unroll") for (int k = 0; k < 2; ++k) \
;         acc[ai][bj][m][n] = __builtin_amdgcn_mfma_f32_16x16x32_bf16(Bt[n][k], At[m][k], acc[ai][bj][m][n], 0, 0, 0); __builtin_amdgcn_s_setprio(0); } while (0)
; #define PG8_WAIT_V(n) asm volatile("s_waitcnt vmcnt(" #n ")" ::: "memory")
; #define PG8_WAIT_L(n) asm volatile("s_waitcnt lgkmcnt(" #n ")" ::: "memory")
; #define PG8_BAR __builtin_amdgcn_s_barrier()
; #define PG8_SCHED __builtin_amdgcn_sched_barrier(0)
; template <class Epi>
; __device__ __forceinline__ void gemm_phase(LAS unsigned char* lds, const Gemm g, int G, int c, const Epi& E) {
;     ...
;             PG8_WAIT_V(8); PG8_WAIT_L(0); PG8_BAR; PG8_MMA(1, 0, At, B0); PG8_MMA(1, 1, At, B1); PG8_BAR; PG8_SCHED;
;             PG8_LDB(B0, 1, 0); PG8_LDB(B1, 1, 1); PG8_SCHED; PG8_LDA(At, 1, 0); PG8_STAGE(PG8_SA(0, 1), a2 + hstepA, voffA);
;             PG8_WAIT_V(8); PG8_WAIT_L(0); PG8_BAR; PG8_MMA(0, 0, At, B0); PG8_MMA(0, 1, At, B1); PG8_BAR; PG8_SCHED;
	s_waitcnt lgkmcnt(0)
	v_mfma_f32_16x16x32_bf16 v[62:65], v[142:145], v[180:183], v[62:65]
	v_mfma_f32_16x16x32_bf16 v[58:61], v[156:159], v[180:183], v[58:61]
	v_mfma_f32_16x16x32_bf16 v[54:57], v[142:145], v[188:191], v[54:57]
	v_mfma_f32_16x16x32_bf16 v[46:49], v[156:159], v[188:191], v[46:49]
	v_mfma_f32_16x16x32_bf16 v[38:41], v[142:145], v[196:199], v[38:41]
	v_mfma_f32_16x16x32_bf16 v[30:33], v[156:159], v[196:199], v[30:33]
	v_mfma_f32_16x16x32_bf16 v[22:25], v[142:145], v[204:207], v[22:25]
	v_mfma_f32_16x16x32_bf16 v[14:17], v[156:159], v[204:207], v[14:17]
	v_mfma_f32_16x16x32_bf16 v[62:65], v[152:155], v[184:187], v[62:65]
	v_mfma_f32_16x16x32_bf16 v[58:61], v[160:163], v[184:187], v[58:61]
	v_mfma_f32_16x16x32_bf16 v[54:57], v[152:155], v[192:195], v[54:57]
	v_mfma_f32_16x16x32_bf16 v[46:49], v[160:163], v[192:195], v[46:49]
	v_mfma_f32_16x16x32_bf16 v[38:41], v[152:155], v[200:203], v[38:41]
	v_mfma_f32_16x16x32_bf16 v[30:33], v[160:163], v[200:203], v[30:33]
	v_mfma_f32_16x16x32_bf16 v[22:25], v[152:155], v[208:211], v[22:25]
	v_mfma_f32_16x16x32_bf16 v[14:17], v[160:163], v[208:211], v[14:17]
	v_mfma_f32_16x16x32_bf16 v[50:53], v[164:167], v[180:183], v[50:53]
	v_mfma_f32_16x16x32_bf16 v[42:45], v[172:175], v[180:183], v[42:45]
	v_mfma_f32_16x16x32_bf16 v[34:37], v[164:167], v[188:191], v[34:37]
	v_mfma_f32_16x16x32_bf16 v[26:29], v[172:175], v[188:191], v[26:29]
	v_mfma_f32_16x16x32_bf16 v[18:21], v[164:167], v[196:199], v[18:21]
	v_mfma_f32_16x16x32_bf16 v[10:13], v[172:175], v[196:199], v[10:13]
	v_mfma_f32_16x16x32_bf16 v[6:9], v[164:167], v[204:207], v[6:9]
	v_mfma_f32_16x16x32_bf16 v[2:5], v[172:175], v[204:207], v[2:5]
	v_mfma_f32_16x16x32_bf16 v[50:53], v[168:171], v[184:187], v[50:53]
	v_mfma_f32_16x16x32_bf16 v[42:45], v[176:179], v[184:187], v[42:45]
	v_mfma_f32_16x16x32_bf16 v[34:37], v[168:171], v[192:195], v[34:37]
	v_mfma_f32_16x16x32_bf16 v[26:29], v[176:179], v[192:195], v[26:29]
	v_mfma_f32_16x16x32_bf16 v[18:21], v[168:171], v[200:203], v[18:21]
	v_mfma_f32_16x16x32_bf16 v[10:13], v[176:179], v[200:203], v[10:13]
	v_mfma_f32_16x16x32_bf16 v[6:9], v[168:171], v[208:211], v[6:9]
	v_mfma_f32_16x16x32_bf16 v[2:5], v[176:179], v[208:211], v[2:5]
	s_barrier
	v_add_u32_e32 v151, s73, v147
	ds_read_b128 v[142:145], v151
	ds_read_b128 v[152:155], v151 offset:1024
	ds_read_b128 v[156:159], v151 offset:2048
	ds_read_b128 v[160:163], v151 offset:3072
	v_add_u32_e32 v151, s33, v147
	ds_read_b128 v[164:167], v151
	ds_read_b128 v[168:171], v151 offset:1024
	ds_read_b128 v[172:175], v151 offset:2048
	ds_read_b128 v[176:179], v151 offset:3072
	s_mov_b32 m0, s59
	v_lshl_add_u64 v[220:221], s[42:43], 0, v[136:137]
	ds_read_b128 v[180:183], v150 offset:32768
	ds_read_b128 v[184:187], v150 offset:33792
	ds_read_b128 v[188:191], v150 offset:34816
	ds_read_b128 v[192:195], v150 offset:35840
	ds_read_b128 v[196:199], v150 offset:36864
	ds_read_b128 v[200:203], v150 offset:37888
	ds_read_b128 v[204:207], v150 offset:38912
	ds_read_b128 v[208:211], v150 offset:39936
	global_load_lds_dwordx4 v[220:221], off
	v_lshl_add_u64 v[220:221], s[42:43], 0, v[132:133]
	s_mov_b32 m0, s60
	s_nop 0
	global_load_lds_dwordx4 v[220:221], off
	s_waitcnt vmcnt(8)
	s_waitcnt lgkmcnt(0)
	s_barrier
	s_waitcnt lgkmcnt(0)
	v_mfma_f32_16x16x32_bf16 v[126:129], v[142:145], v[180:183], v[126:129]
	v_mfma_f32_16x16x32_bf16 v[122:125], v[156:159], v[180:183], v[122:125]
	v_mfma_f32_16x16x32_bf16 v[118:121], v[142:145], v[188:191], v[118:121]
	v_mfma_f32_16x16x32_bf16 v[110:113], v[156:159], v[188:191], v[110:113]
	v_mfma_f32_16x16x32_bf16 v[102:105], v[142:145], v[196:199], v[102:105]
	v_mfma_f32_16x16x32_bf16 v[94:97], v[156:159], v[196:199], v[94:97]
	v_mfma_f32_16x16x32_bf16 v[86:89], v[142:145], v[204:207], v[86:89]
	v_mfma_f32_16x16x32_bf16 v[78:81], v[156:159], v[204:207], v[78:81]
	v_mfma_f32_16x16x32_bf16 v[126:129], v[152:155], v[184:187], v[126:129]
	v_mfma_f32_16x16x32_bf16 v[122:125], v[160:163], v[184:187], v[122:125]
	v_mfma_f32_16x16x32_bf16 v[118:121], v[152:155], v[192:195], v[118:121]
	v_mfma_f32_16x16x32_bf16 v[110:113], v[160:163], v[192:195], v[110:113]
	v_mfma_f32_16x16x32_bf16 v[102:105], v[152:155], v[200:203], v[102:105]
	v_mfma_f32_16x16x32_bf16 v[94:97], v[160:163], v[200:203], v[94:97]
	v_mfma_f32_16x16x32_bf16 v[86:89], v[152:155], v[208:211], v[86:89]
	v_mfma_f32_16x16x32_bf16 v[78:81], v[160:163], v[208:211], v[78:81]
	v_mfma_f32_16x16x32_bf16 v[114:117], v[164:167], v[180:183], v[114:117]
	v_mfma_f32_16x16x32_bf16 v[106:109], v[172:175], v[180:183], v[106:109]
	v_mfma_f32_16x16x32_bf16 v[98:101], v[164:167], v[188:191], v[98:101]
	v_mfma_f32_16x16x32_bf16 v[90:93], v[172:175], v[188:191], v[90:93]
	v_mfma_f32_16x16x32_bf16 v[82:85], v[164:167], v[196:199], v[82:85]
	v_mfma_f32_16x16x32_bf16 v[74:77], v[172:175], v[196:199], v[74:77]
	v_mfma_f32_16x16x32_bf16 v[70:73], v[164:167], v[204:207], v[70:73]
	v_mfma_f32_16x16x32_bf16 v[66:69], v[172:175], v[204:207], v[66:69]
	v_mfma_f32_16x16x32_bf16 v[114:117], v[168:171], v[184:187], v[114:117]
	v_mfma_f32_16x16x32_bf16 v[106:109], v[176:179], v[184:187], v[106:109]
	v_mfma_f32_16x16x32_bf16 v[98:101], v[168:171], v[192:195], v[98:101]
	v_mfma_f32_16x16x32_bf16 v[90:93], v[176:179], v[192:195], v[90:93]
	v_mfma_f32_16x16x32_bf16 v[82:85], v[168:171], v[200:203], v[82:85]
	v_mfma_f32_16x16x32_bf16 v[74:77], v[176:179], v[200:203], v[74:77]
	v_mfma_f32_16x16x32_bf16 v[70:73], v[168:171], v[208:211], v[70:73]
	v_mfma_f32_16x16x32_bf16 v[66:69], v[176:179], v[208:211], v[66:69]
	s_barrier
; #define PG8_STAGE(bufoff, gbase, voff) do { _Pragma("unroll") for (int _i = 0; _i < 2; ++_i) \
;         __builtin_amdgcn_global_load_lds((const unsigned*)((const char*)(gbase) + (voff)[_i]), (LAS unsigned*)(lds + (bufoff) + ldsw + _i * 8192), 16, 0, 0); } while (0)
; #define PG8_LDA(dst, b, h) do { _Pragma("unroll") for (int m = 0; m < 4; ++m) _Pragma("unroll") for (int k = 0; k < 2; ++k) dst[m][k] = *(const LAS bf16x8*)(lds + PG8_SA(b, h) + aoff + m * 2048 + k * 1024); } while (0)
; #define PG8_MMA(ai, bj, At, Bt) do { __builtin_amdgcn_s_setprio(1); _Pragma("unroll") for (int m = 0; m < 4; ++m) _Pragma("unroll") for (int n = 0; n < 2; ++n) _Pragma("unroll") for (int k = 0; k < 2; ++k) \
;         acc[ai][bj][m][n] = __builtin_amdgcn_mfma_f32_16x16x32_bf16(Bt[n][k], At[m][k], acc[ai][bj][m][n], 0, 0, 0); __builtin_amdgcn_s_setprio(0); } while (0)
; #define PG8_WAIT_V(n) asm volatile("s_waitcnt vmcnt(" #n ")" ::: "memory")
; #define PG8_WAIT_L(n) asm volatile("s_waitcnt lgkmcnt(" #n ")" ::: "memory")
; #define PG8_BAR __builtin_amdgcn_s_barrier()
; #define PG8_SCHED __builtin_amdgcn_sched_barrier(0)
; template <class Epi>
; __device__ __forceinline__ void gemm_phase(LAS unsigned char* lds, const Gemm g, int G, int c, const Epi& E) {
;     ...
;             PG8_LDA(At, 1, 1); PG8_STAGE(PG8_SB(1, 0), b3, voffB); PG8_STAGE(PG8_SB(1, 1), b3 + hstepB, voffB); PG8_STAGE(PG8_SA(1, 0), a3, voffA);
;             PG8_WAIT_V(8); PG8_WAIT_L(0); PG8_BAR; PG8_MMA(1, 0, At, B0); PG8_MMA(1, 1, At, B1); PG8_BAR; PG8_SCHED;
;         }
	s_mov_b32 m0, s88
	v_lshl_add_u64 v[212:213], v[212:213], 0, s[8:9]
	ds_read_b128 v[180:183], v150 offset:49152
	ds_read_b128 v[184:187], v150 offset:50176
	ds_read_b128 v[188:191], v150 offset:51200
	ds_read_b128 v[192:195], v150 offset:52224
	ds_read_b128 v[196:199], v150 offset:53248
	ds_read_b128 v[200:203], v150 offset:54272
	ds_read_b128 v[204:207], v150 offset:55296
	ds_read_b128 v[208:211], v150 offset:56320
	global_load_lds_dwordx4 v[212:213], off
	v_lshl_add_u64 v[212:213], v[214:215], 0, s[8:9]
	s_mov_b32 m0, s38
	s_nop 0
	global_load_lds_dwordx4 v[212:213], off
	v_lshl_add_u64 v[212:213], s[24:25], 0, v[134:135]
	s_mov_b32 m0, s39
	s_nop 0
	global_load_lds_dwordx4 v[212:213], off
	v_lshl_add_u64 v[212:213], s[24:25], 0, v[130:131]
	s_mov_b32 m0, s13
	s_nop 0
	global_load_lds_dwordx4 v[212:213], off
	v_lshl_add_u64 v[212:213], v[216:217], 0, s[8:9]
	s_mov_b32 m0, s79
	s_nop 0
	global_load_lds_dwordx4 v[212:213], off
	v_lshl_add_u64 v[212:213], v[218:219], 0, s[8:9]
	s_mov_b32 m0, s80
	s_nop 0
	global_load_lds_dwordx4 v[212:213], off
	s_waitcnt vmcnt(8)
	s_waitcnt lgkmcnt(0)
	s_barrier
	s_waitcnt lgkmcnt(0)
	v_mfma_f32_16x16x32_bf16 v[62:65], v[142:145], v[180:183], v[62:65]
	v_mfma_f32_16x16x32_bf16 v[58:61], v[156:159], v[180:183], v[58:61]
	v_mfma_f32_16x16x32_bf16 v[54:57], v[142:145], v[188:191], v[54:57]
	v_mfma_f32_16x16x32_bf16 v[46:49], v[156:159], v[188:191], v[46:49]
	v_mfma_f32_16x16x32_bf16 v[38:41], v[142:145], v[196:199], v[38:41]
	v_mfma_f32_16x16x32_bf16 v[30:33], v[156:159], v[196:199], v[30:33]
	v_mfma_f32_16x16x32_bf16 v[22:25], v[142:145], v[204:207], v[22:25]
	v_mfma_f32_16x16x32_bf16 v[14:17], v[156:159], v[204:207], v[14:17]
	v_mfma_f32_16x16x32_bf16 v[62:65], v[152:155], v[184:187], v[62:65]
	v_mfma_f32_16x16x32_bf16 v[58:61], v[160:163], v[184:187], v[58:61]
	v_mfma_f32_16x16x32_bf16 v[54:57], v[152:155], v[192:195], v[54:57]
	v_mfma_f32_16x16x32_bf16 v[46:49], v[160:163], v[192:195], v[46:49]
	v_mfma_f32_16x16x32_bf16 v[38:41], v[152:155], v[200:203], v[38:41]
	v_mfma_f32_16x16x32_bf16 v[30:33], v[160:163], v[200:203], v[30:33]
	v_mfma_f32_16x16x32_bf16 v[22:25], v[152:155], v[208:211], v[22:25]
	v_mfma_f32_16x16x32_bf16 v[14:17], v[160:163], v[208:211], v[14:17]
	v_mfma_f32_16x16x32_bf16 v[50:53], v[164:167], v[180:183], v[50:53]
	v_mfma_f32_16x16x32_bf16 v[42:45], v[172:175], v[180:183], v[42:45]
	v_mfma_f32_16x16x32_bf16 v[34:37], v[164:167], v[188:191], v[34:37]
	v_mfma_f32_16x16x32_bf16 v[26:29], v[172:175], v[188:191], v[26:29]
	v_mfma_f32_16x16x32_bf16 v[18:21], v[164:167], v[196:199], v[18:21]
	v_mfma_f32_16x16x32_bf16 v[10:13], v[172:175], v[196:199], v[10:13]
	v_mfma_f32_16x16x32_bf16 v[6:9], v[164:167], v[204:207], v[6:9]
	v_mfma_f32_16x16x32_bf16 v[2:5], v[172:175], v[204:207], v[2:5]
	v_mfma_f32_16x16x32_bf16 v[50:53], v[168:171], v[184:187], v[50:53]
	v_mfma_f32_16x16x32_bf16 v[42:45], v[176:179], v[184:187], v[42:45]
	v_mfma_f32_16x16x32_bf16 v[34:37], v[168:171], v[192:195], v[34:37]
	v_mfma_f32_16x16x32_bf16 v[26:29], v[176:179], v[192:195], v[26:29]
	v_mfma_f32_16x16x32_bf16 v[18:21], v[168:171], v[200:203], v[18:21]
	v_mfma_f32_16x16x32_bf16 v[10:13], v[176:179], v[200:203], v[10:13]
	v_mfma_f32_16x16x32_bf16 v[6:9], v[168:171], v[208:211], v[6:9]
	v_mfma_f32_16x16x32_bf16 v[2:5], v[176:179], v[208:211], v[2:5]
	s_barrier
	s_movk_i32 s13, 0x100
	s_andn2_b64 vcc, exec, s[22:23]
	s_mov_b64 s[24:25], -1
	s_mov_b64 s[22:23], 0
	s_cbranch_vccz .LBB0_368
	s_and_b64 vcc, exec, s[10:11]
	s_cbranch_vccz .LBB0_371
	s_barrier

; #define PG8_STAGE(bufoff, gbase, voff) do { _Pragma("unroll") for (int _i = 0; _i < 2; ++_i) \
;         __builtin_amdgcn_global_load_lds((const unsigned*)((const char*)(gbase) + (voff)[_i]), (LAS unsigned*)(lds + (bufoff) + ldsw + _i * 8192), 16, 0, 0); } while (0)
; #define PG8_LDA(dst, b, h) do { _Pragma("unroll") for (int m = 0; m < 4; ++m) _Pragma("unroll") for (int k = 0; k < 2; ++k) dst[m][k] = *(const LAS bf16x8*)(lds + PG8_SA(b, h) + aoff + m * 2048 + k * 1024); } while (0)
; #define PG8_LDB(dst, b, h) do { _Pragma("unroll") for (int n = 0; n < 2; ++n) _Pragma("unroll") for (int k = 0; k < 2; ++k) dst[n][k] = *(const LAS bf16x8*)(lds + PG8_SB(b, h) + boff + n * 2048 + k * 1024); } while (0)
; #define PG8_MMA(ai, bj, At, Bt) do { __builtin_amdgcn_s_setprio(1); _Pragma("unroll") for (int m = 0; m < 4; ++m) _Pragma("unroll") for (int n = 0; n < 2; ++n) _Pragma("unroll") for (int k = 0; k < 2; ++k) \
;         acc[ai][bj][m][n] = __builtin_amdgcn_mfma_f32_16x16x32_bf16(Bt[n][k], At[m][k], acc[ai][bj][m][n], 0, 0, 0); __builtin_amdgcn_s_setprio(0); } while (0)
; #define PG8_WAIT_V(n) asm volatile("s_waitcnt vmcnt(" #n ")" ::: "memory")
; #define PG8_WAIT_L(n) asm volatile("s_waitcnt lgkmcnt(" #n ")" ::: "memory")
; #define PG8_BAR __builtin_amdgcn_s_barrier()
; #define PG8_SCHED __builtin_amdgcn_sched_barrier(0)
; template <class Epi>
; __device__ __forceinline__ void gemm_phase(LAS unsigned char* lds, const Gemm g, int G, int c, const Epi& E) {
;     ...
;             const bool last = (t == nt - 2);
;             const char* a1 = cA + (size_t)(t + 1) * kstep;
;             const char* a2 = last ? nA : cA + (size_t)(t + 2) * kstep; const char* b2 = last ? nB : cB + (size_t)(t + 2) * kstep;
;             const char* a3 = a2 + kstep; const char* b3 = b2 + kstep;
;             PG8_LDB(B0, 0, 0); PG8_LDB(B1, 0, 1); PG8_SCHED; PG8_LDA(At, 0, 0); PG8_STAGE(PG8_SA(1, 1), a1 + hstepA, voffA);
;             PG8_WAIT_V(8); PG8_WAIT_L(0); PG8_BAR; PG8_MMA(0, 0, At, B0); PG8_MMA(0, 1, At, B1); PG8_BAR; PG8_SCHED;
.LBB0_390:
	s_add_u32 s33, s8, s38
	s_addc_u32 s39, s9, 0
	s_add_u32 s56, s33, 0x100
	s_addc_u32 s57, s39, 0
	s_and_b64 s[54:55], s[10:11], exec
	s_cselect_b32 s57, s47, s57
	s_cselect_b32 s56, s46, s56
	s_add_u32 s38, s6, s38
	s_addc_u32 s54, s7, 0
	s_add_u32 s38, s38, 0x100
	s_addc_u32 s54, s54, 0
	s_and_b64 s[10:11], s[10:11], exec
	s_cselect_b32 s59, s53, s54
	s_cselect_b32 s58, s52, s38
	s_add_u32 s66, s33, 0xb0080
	s_addc_u32 s67, s39, 0
	s_add_i32 s65, s87, s14
	ds_read_b128 v[142:145], v160
	ds_read_b128 v[146:149], v160 offset:1024
	ds_read_b128 v[150:153], v160 offset:2048
	ds_read_b128 v[154:157], v160 offset:3072
	ds_read_b128 v[166:169], v161
	ds_read_b128 v[170:173], v161 offset:1024
	ds_read_b128 v[174:177], v161 offset:2048
	ds_read_b128 v[178:181], v161 offset:3072
	s_add_i32 m0, s78, 0xc000
	s_add_i32 s74, s78, 0xe000
	s_add_i32 s62, s65, 0x2000
	s_add_u32 s60, s58, 0xb0000
	s_addc_u32 s61, s59, 0
	s_add_i32 s64, s88, s14
	s_add_i32 s63, s64, 0x2000
	s_add_i32 s73, 0, 0x18000
	s_add_i32 s33, 0, 0x1c000
	s_add_u32 s54, s56, 0xb0000
	s_addc_u32 s55, s57, 0
	s_add_i32 vcc_hi, s73, s14
	s_add_i32 s39, vcc_hi, 0x2000
	s_add_u32 s10, s58, 0xb0080
	s_addc_u32 s11, s59, 0
	s_add_i32 vcc_lo, s33, s14
	s_add_i32 s38, vcc_lo, 0x2000
	v_lshl_add_u64 v[214:215], s[66:67], 0, v[130:131]
	ds_read_b128 v[182:185], v162
	ds_read_b128 v[186:189], v162 offset:1024
	ds_read_b128 v[190:193], v162 offset:2048
	ds_read_b128 v[194:197], v162 offset:3072
	ds_read_b128 v[198:201], v162 offset:4096
	ds_read_b128 v[202:205], v162 offset:5120
	ds_read_b128 v[206:209], v162 offset:6144
	ds_read_b128 v[210:213], v162 offset:7168
	global_load_lds_dwordx4 v[214:215], off
	v_lshl_add_u64 v[214:215], s[66:67], 0, v[134:135]
	s_mov_b32 m0, s74
	s_nop 0
	global_load_lds_dwordx4 v[214:215], off
	s_waitcnt vmcnt(8)
	s_waitcnt lgkmcnt(0)
	s_barrier
	s_waitcnt lgkmcnt(0)
	v_mfma_f32_16x16x32_bf16 v[126:129], v[142:145], v[182:185], v[126:129]
	v_mfma_f32_16x16x32_bf16 v[122:125], v[150:153], v[182:185], v[122:125]
	v_mfma_f32_16x16x32_bf16 v[110:113], v[142:145], v[190:193], v[110:113]
	v_mfma_f32_16x16x32_bf16 v[106:109], v[150:153], v[190:193], v[106:109]
	v_mfma_f32_16x16x32_bf16 v[94:97], v[142:145], v[198:201], v[94:97]
	v_mfma_f32_16x16x32_bf16 v[90:93], v[150:153], v[198:201], v[90:93]
	v_mfma_f32_16x16x32_bf16 v[78:81], v[142:145], v[206:209], v[78:81]
	v_mfma_f32_16x16x32_bf16 v[74:77], v[150:153], v[206:209], v[74:77]
	v_mfma_f32_16x16x32_bf16 v[126:129], v[146:149], v[186:189], v[126:129]
	v_mfma_f32_16x16x32_bf16 v[122:125], v[154:157], v[186:189], v[122:125]
	v_mfma_f32_16x16x32_bf16 v[110:113], v[146:149], v[194:197], v[110:113]
	v_mfma_f32_16x16x32_bf16 v[106:109], v[154:157], v[194:197], v[106:109]
	v_mfma_f32_16x16x32_bf16 v[94:97], v[146:149], v[202:205], v[94:97]
	v_mfma_f32_16x16x32_bf16 v[90:93], v[154:157], v[202:205], v[90:93]
	v_mfma_f32_16x16x32_bf16 v[78:81], v[146:149], v[210:213], v[78:81]
	v_mfma_f32_16x16x32_bf16 v[74:77], v[154:157], v[210:213], v[74:77]
	v_mfma_f32_16x16x32_bf16 v[118:121], v[166:169], v[182:185], v[118:121]
	v_mfma_f32_16x16x32_bf16 v[114:117], v[174:177], v[182:185], v[114:117]
	v_mfma_f32_16x16x32_bf16 v[102:105], v[166:169], v[190:193], v[102:105]
	v_mfma_f32_16x16x32_bf16 v[98:101], v[174:177], v[190:193], v[98:101]
	v_mfma_f32_16x16x32_bf16 v[86:89], v[166:169], v[198:201], v[86:89]
	v_mfma_f32_16x16x32_bf16 v[82:85], v[174:177], v[198:201], v[82:85]
	v_mfma_f32_16x16x32_bf16 v[70:73], v[166:169], v[206:209], v[70:73]
	v_mfma_f32_16x16x32_bf16 v[66:69], v[174:177], v[206:209], v[66:69]
	v_mfma_f32_16x16x32_bf16 v[118:121], v[170:173], v[186:189], v[118:121]
	v_mfma_f32_16x16x32_bf16 v[114:117], v[178:181], v[186:189], v[114:117]
	v_mfma_f32_16x16x32_bf16 v[102:105], v[170:173], v[194:197], v[102:105]
	v_mfma_f32_16x16x32_bf16 v[98:101], v[178:181], v[194:197], v[98:101]
	v_mfma_f32_16x16x32_bf16 v[86:89], v[170:173], v[202:205], v[86:89]
	v_mfma_f32_16x16x32_bf16 v[82:85], v[178:181], v[202:205], v[82:85]
	v_mfma_f32_16x16x32_bf16 v[70:73], v[170:173], v[210:213], v[70:73]
	v_mfma_f32_16x16x32_bf16 v[66:69], v[178:181], v[210:213], v[66:69]
	s_barrier
	s_mov_b32 m0, s65
	v_lshl_add_u64 v[214:215], s[58:59], 0, v[132:133]
	ds_read_b128 v[182:185], v162 offset:16384
	ds_read_b128 v[186:189], v162 offset:17408
	ds_read_b128 v[190:193], v162 offset:18432
	ds_read_b128 v[194:197], v162 offset:19456
	ds_read_b128 v[198:201], v162 offset:20480
	ds_read_b128 v[202:205], v162 offset:21504
	ds_read_b128 v[206:209], v162 offset:22528
	ds_read_b128 v[210:213], v162 offset:23552
	global_load_lds_dwordx4 v[214:215], off
	v_lshl_add_u64 v[216:217], s[58:59], 0, v[136:137]
	s_mov_b32 m0, s62
	v_lshl_add_u64 v[218:219], s[60:61], 0, v[132:133]
	global_load_lds_dwordx4 v[216:217], off
	s_mov_b32 m0, s64
	v_lshl_add_u64 v[220:221], s[56:57], 0, v[134:135]
	global_load_lds_dwordx4 v[218:219], off
	v_lshl_add_u64 v[218:219], s[60:61], 0, v[136:137]
	s_mov_b32 m0, s63
	s_nop 0
	global_load_lds_dwordx4 v[218:219], off
	v_lshl_add_u64 v[218:219], s[56:57], 0, v[130:131]
	s_mov_b32 m0, s78
	s_nop 0
	global_load_lds_dwordx4 v[218:219], off
	s_mov_b32 m0, s79
	s_nop 0
	global_load_lds_dwordx4 v[220:221], off
	s_waitcnt vmcnt(8)
	s_waitcnt lgkmcnt(0)
	s_barrier
; #define PG8_STAGE(bufoff, gbase, voff) do { _Pragma("unroll") for (int _i = 0; _i < 2; ++_i) \
;         __builtin_amdgcn_global_load_lds((const unsigned*)((const char*)(gbase) + (voff)[_i]), (LAS unsigned*)(lds + (bufoff) + ldsw + _i * 8192), 16, 0, 0); } while (0)
; #define PG8_LDA(dst, b, h) do { _Pragma("unroll") for (int m = 0; m < 4; ++m) _Pragma("unroll") for (int k = 0; k < 2; ++k) dst[m][k] = *(const LAS bf16x8*)(lds + PG8_SA(b, h) + aoff + m * 2048 + k * 1024); } while (0)
; #define PG8_LDB(dst, b, h) do { _Pragma("unroll") for (int n = 0; n < 2; ++n) _Pragma("unroll") for (int k = 0; k < 2; ++k) dst[n][k] = *(const LAS bf16x8*)(lds + PG8_SB(b, h) + boff + n * 2048 + k * 1024); } while (0)
; #define PG8_MMA(ai, bj, At, Bt) do { __builtin_amdgcn_s_setprio(1); _Pragma("unroll") for (int m = 0; m < 4; ++m) _Pragma("unroll") for (int n = 0; n < 2; ++n) _Pragma("unroll") for (int k = 0; k < 2; ++k) \
;         acc[ai][bj][m][n] = __builtin_amdgcn_mfma_f32_16x16x32_bf16(Bt[n][k], At[m][k], acc[ai][bj][m][n], 0, 0, 0); __builtin_amdgcn_s_setprio(0); } while (0)
; #define PG8_WAIT_V(n) asm volatile("s_waitcnt vmcnt(" #n ")" ::: "memory")
; #define PG8_WAIT_L(n) asm volatile("s_waitcnt lgkmcnt(" #n ")" ::: "memory")
; #define PG8_BAR __builtin_amdgcn_s_barrier()
; #define PG8_SCHED __builtin_amdgcn_sched_barrier(0)
; template <class Epi>
; __device__ __forceinline__ void gemm_phase(LAS unsigned char* lds, const Gemm g, int G, int c, const Epi& E) {
;     ...
;             PG8_WAIT_V(8); PG8_WAIT_L(0); PG8_BAR; PG8_MMA(1, 0, At, B0); PG8_MMA(1, 1, At, B1); PG8_BAR; PG8_SCHED;
;             PG8_LDB(B0, 1, 0); PG8_LDB(B1, 1, 1); PG8_SCHED; PG8_LDA(At, 1, 0); PG8_STAGE(PG8_SA(0, 1), a2 + hstepA, voffA);
;             PG8_WAIT_V(8); PG8_WAIT_L(0); PG8_BAR; PG8_MMA(0, 0, At, B0); PG8_MMA(0, 1, At, B1); PG8_BAR; PG8_SCHED;
	s_waitcnt lgkmcnt(0)
	v_mfma_f32_16x16x32_bf16 v[62:65], v[142:145], v[182:185], v[62:65]
	v_mfma_f32_16x16x32_bf16 v[58:61], v[150:153], v[182:185], v[58:61]
	v_mfma_f32_16x16x32_bf16 v[46:49], v[142:145], v[190:193], v[46:49]
	v_mfma_f32_16x16x32_bf16 v[42:45], v[150:153], v[190:193], v[42:45]
	v_mfma_f32_16x16x32_bf16 v[30:33], v[142:145], v[198:201], v[30:33]
	v_mfma_f32_16x16x32_bf16 v[26:29], v[150:153], v[198:201], v[26:29]
	v_mfma_f32_16x16x32_bf16 v[14:17], v[142:145], v[206:209], v[14:17]
	v_mfma_f32_16x16x32_bf16 v[10:13], v[150:153], v[206:209], v[10:13]
	v_mfma_f32_16x16x32_bf16 v[62:65], v[146:149], v[186:189], v[62:65]
	v_mfma_f32_16x16x32_bf16 v[58:61], v[154:157], v[186:189], v[58:61]
	v_mfma_f32_16x16x32_bf16 v[46:49], v[146:149], v[194:197], v[46:49]
	v_mfma_f32_16x16x32_bf16 v[42:45], v[154:157], v[194:197], v[42:45]
	v_mfma_f32_16x16x32_bf16 v[30:33], v[146:149], v[202:205], v[30:33]
	v_mfma_f32_16x16x32_bf16 v[26:29], v[154:157], v[202:205], v[26:29]
	v_mfma_f32_16x16x32_bf16 v[14:17], v[146:149], v[210:213], v[14:17]
	v_mfma_f32_16x16x32_bf16 v[10:13], v[154:157], v[210:213], v[10:13]
	v_mfma_f32_16x16x32_bf16 v[54:57], v[166:169], v[182:185], v[54:57]
	v_mfma_f32_16x16x32_bf16 v[50:53], v[174:177], v[182:185], v[50:53]
	v_mfma_f32_16x16x32_bf16 v[38:41], v[166:169], v[190:193], v[38:41]
	v_mfma_f32_16x16x32_bf16 v[34:37], v[174:177], v[190:193], v[34:37]
	v_mfma_f32_16x16x32_bf16 v[22:25], v[166:169], v[198:201], v[22:25]
	v_mfma_f32_16x16x32_bf16 v[18:21], v[174:177], v[198:201], v[18:21]
	v_mfma_f32_16x16x32_bf16 v[6:9], v[166:169], v[206:209], v[6:9]
	v_mfma_f32_16x16x32_bf16 v[2:5], v[174:177], v[206:209], v[2:5]
	v_mfma_f32_16x16x32_bf16 v[54:57], v[170:173], v[186:189], v[54:57]
	v_mfma_f32_16x16x32_bf16 v[50:53], v[178:181], v[186:189], v[50:53]
	v_mfma_f32_16x16x32_bf16 v[38:41], v[170:173], v[194:197], v[38:41]
	v_mfma_f32_16x16x32_bf16 v[34:37], v[178:181], v[194:197], v[34:37]
	v_mfma_f32_16x16x32_bf16 v[22:25], v[170:173], v[202:205], v[22:25]
	v_mfma_f32_16x16x32_bf16 v[18:21], v[178:181], v[202:205], v[18:21]
	v_mfma_f32_16x16x32_bf16 v[6:9], v[170:173], v[210:213], v[6:9]
	v_mfma_f32_16x16x32_bf16 v[2:5], v[178:181], v[210:213], v[2:5]
	s_barrier
	v_add_u32_e32 v154, s73, v159
	v_add_u32_e32 v178, s33, v159
	ds_read_b128 v[142:145], v154
	ds_read_b128 v[146:149], v154 offset:1024
	ds_read_b128 v[150:153], v154 offset:2048
	ds_read_b128 v[154:157], v154 offset:3072
	ds_read_b128 v[166:169], v178
	ds_read_b128 v[170:173], v178 offset:1024
	ds_read_b128 v[174:177], v178 offset:2048
	ds_read_b128 v[178:181], v178 offset:3072
	s_mov_b32 m0, s80
	v_lshl_add_u64 v[222:223], s[54:55], 0, v[130:131]
	ds_read_b128 v[182:185], v162 offset:32768
	ds_read_b128 v[186:189], v162 offset:33792
	ds_read_b128 v[190:193], v162 offset:34816
	ds_read_b128 v[194:197], v162 offset:35840
	ds_read_b128 v[198:201], v162 offset:36864
	ds_read_b128 v[202:205], v162 offset:37888
	ds_read_b128 v[206:209], v162 offset:38912
	ds_read_b128 v[210:213], v162 offset:39936
	global_load_lds_dwordx4 v[222:223], off
	v_lshl_add_u64 v[222:223], s[54:55], 0, v[134:135]
	s_mov_b32 m0, s81
	s_nop 0
	global_load_lds_dwordx4 v[222:223], off
	s_waitcnt vmcnt(8)
	s_waitcnt lgkmcnt(0)
	s_barrier
	s_waitcnt lgkmcnt(0)
	v_mfma_f32_16x16x32_bf16 v[126:129], v[142:145], v[182:185], v[126:129]
	v_mfma_f32_16x16x32_bf16 v[122:125], v[150:153], v[182:185], v[122:125]
	v_mfma_f32_16x16x32_bf16 v[110:113], v[142:145], v[190:193], v[110:113]
	v_mfma_f32_16x16x32_bf16 v[106:109], v[150:153], v[190:193], v[106:109]
	v_mfma_f32_16x16x32_bf16 v[94:97], v[142:145], v[198:201], v[94:97]
	v_mfma_f32_16x16x32_bf16 v[90:93], v[150:153], v[198:201], v[90:93]
	v_mfma_f32_16x16x32_bf16 v[78:81], v[142:145], v[206:209], v[78:81]
	v_mfma_f32_16x16x32_bf16 v[74:77], v[150:153], v[206:209], v[74:77]
	v_mfma_f32_16x16x32_bf16 v[126:129], v[146:149], v[186:189], v[126:129]
	v_mfma_f32_16x16x32_bf16 v[122:125], v[154:157], v[186:189], v[122:125]
	v_mfma_f32_16x16x32_bf16 v[110:113], v[146:149], v[194:197], v[110:113]
	v_mfma_f32_16x16x32_bf16 v[106:109], v[154:157], v[194:197], v[106:109]
	v_mfma_f32_16x16x32_bf16 v[94:97], v[146:149], v[202:205], v[94:97]
	v_mfma_f32_16x16x32_bf16 v[90:93], v[154:157], v[202:205], v[90:93]
	v_mfma_f32_16x16x32_bf16 v[78:81], v[146:149], v[210:213], v[78:81]
	v_mfma_f32_16x16x32_bf16 v[74:77], v[154:157], v[210:213], v[74:77]
	v_mfma_f32_16x16x32_bf16 v[118:121], v[166:169], v[182:185], v[118:121]
	v_mfma_f32_16x16x32_bf16 v[114:117], v[174:177], v[182:185], v[114:117]
	v_mfma_f32_16x16x32_bf16 v[102:105], v[166:169], v[190:193], v[102:105]
	v_mfma_f32_16x16x32_bf16 v[98:101], v[174:177], v[190:193], v[98:101]
	v_mfma_f32_16x16x32_bf16 v[86:89], v[166:169], v[198:201], v[86:89]
	v_mfma_f32_16x16x32_bf16 v[82:85], v[174:177], v[198:201], v[82:85]
	v_mfma_f32_16x16x32_bf16 v[70:73], v[166:169], v[206:209], v[70:73]
	v_mfma_f32_16x16x32_bf16 v[66:69], v[174:177], v[206:209], v[66:69]
	v_mfma_f32_16x16x32_bf16 v[118:121], v[170:173], v[186:189], v[118:121]
	v_mfma_f32_16x16x32_bf16 v[114:117], v[178:181], v[186:189], v[114:117]
	v_mfma_f32_16x16x32_bf16 v[102:105], v[170:173], v[194:197], v[102:105]
	v_mfma_f32_16x16x32_bf16 v[98:101], v[178:181], v[194:197], v[98:101]
	v_mfma_f32_16x16x32_bf16 v[86:89], v[170:173], v[202:205], v[86:89]
	v_mfma_f32_16x16x32_bf16 v[82:85], v[178:181], v[202:205], v[82:85]
	v_mfma_f32_16x16x32_bf16 v[70:73], v[170:173], v[210:213], v[70:73]
	v_mfma_f32_16x16x32_bf16 v[66:69], v[178:181], v[210:213], v[66:69]
	s_barrier
; #define PG8_STAGE(bufoff, gbase, voff) do { _Pragma("unroll") for (int _i = 0; _i < 2; ++_i) \
;         __builtin_amdgcn_global_load_lds((const unsigned*)((const char*)(gbase) + (voff)[_i]), (LAS unsigned*)(lds + (bufoff) + ldsw + _i * 8192), 16, 0, 0); } while (0)
; #define PG8_LDA(dst, b, h) do { _Pragma("unroll") for (int m = 0; m < 4; ++m) _Pragma("unroll") for (int k = 0; k < 2; ++k) dst[m][k] = *(const LAS bf16x8*)(lds + PG8_SA(b, h) + aoff + m * 2048 + k * 1024); } while (0)
; #define PG8_MMA(ai, bj, At, Bt) do { __builtin_amdgcn_s_setprio(1); _Pragma("unroll") for (int m = 0; m < 4; ++m) _Pragma("unroll") for (int n = 0; n < 2; ++n) _Pragma("unroll") for (int k = 0; k < 2; ++k) \
;         acc[ai][bj][m][n] = __builtin_amdgcn_mfma_f32_16x16x32_bf16(Bt[n][k], At[m][k], acc[ai][bj][m][n], 0, 0, 0); __builtin_amdgcn_s_setprio(0); } while (0)
; #define PG8_WAIT_V(n) asm volatile("s_waitcnt vmcnt(" #n ")" ::: "memory")
; #define PG8_WAIT_L(n) asm volatile("s_waitcnt lgkmcnt(" #n ")" ::: "memory")
; #define PG8_BAR __builtin_amdgcn_s_barrier()
; #define PG8_SCHED __builtin_amdgcn_sched_barrier(0)
; template <class Epi>
; __device__ __forceinline__ void gemm_phase(LAS unsigned char* lds, const Gemm g, int G, int c, const Epi& E) {
;     ...
;             PG8_LDA(At, 1, 1); PG8_STAGE(PG8_SB(1, 0), b3, voffB); PG8_STAGE(PG8_SB(1, 1), b3 + hstepB, voffB); PG8_STAGE(PG8_SA(1, 0), a3, voffA);
;             PG8_WAIT_V(8); PG8_WAIT_L(0); PG8_BAR; PG8_MMA(1, 0, At, B0); PG8_MMA(1, 1, At, B1); PG8_BAR; PG8_SCHED;
;         }
	s_mov_b32 m0, vcc_hi
	v_lshl_add_u64 v[214:215], v[214:215], 0, s[24:25]
	ds_read_b128 v[182:185], v162 offset:49152
	ds_read_b128 v[186:189], v162 offset:50176
	ds_read_b128 v[190:193], v162 offset:51200
	ds_read_b128 v[194:197], v162 offset:52224
	ds_read_b128 v[198:201], v162 offset:53248
	ds_read_b128 v[202:205], v162 offset:54272
	ds_read_b128 v[206:209], v162 offset:55296
	ds_read_b128 v[210:213], v162 offset:56320
	global_load_lds_dwordx4 v[214:215], off
	v_lshl_add_u64 v[214:215], v[216:217], 0, s[24:25]
	s_mov_b32 m0, s39
	s_nop 0
	global_load_lds_dwordx4 v[214:215], off
	v_lshl_add_u64 v[214:215], s[10:11], 0, v[132:133]
	s_mov_b32 m0, vcc_lo
	s_nop 0
	global_load_lds_dwordx4 v[214:215], off
	v_lshl_add_u64 v[214:215], s[10:11], 0, v[136:137]
	s_mov_b32 m0, s38
	s_nop 0
	global_load_lds_dwordx4 v[214:215], off
	v_lshl_add_u64 v[214:215], v[218:219], 0, s[24:25]
	s_mov_b32 m0, s85
	s_nop 0
	global_load_lds_dwordx4 v[214:215], off
	v_lshl_add_u64 v[214:215], v[220:221], 0, s[24:25]
	s_mov_b32 m0, s86
	s_nop 0
	global_load_lds_dwordx4 v[214:215], off
	s_waitcnt vmcnt(8)
	s_waitcnt lgkmcnt(0)
	s_barrier
	s_waitcnt lgkmcnt(0)
	v_mfma_f32_16x16x32_bf16 v[62:65], v[142:145], v[182:185], v[62:65]
	v_mfma_f32_16x16x32_bf16 v[58:61], v[150:153], v[182:185], v[58:61]
	v_mfma_f32_16x16x32_bf16 v[46:49], v[142:145], v[190:193], v[46:49]
	v_mfma_f32_16x16x32_bf16 v[42:45], v[150:153], v[190:193], v[42:45]
	v_mfma_f32_16x16x32_bf16 v[30:33], v[142:145], v[198:201], v[30:33]
	v_mfma_f32_16x16x32_bf16 v[26:29], v[150:153], v[198:201], v[26:29]
	v_mfma_f32_16x16x32_bf16 v[14:17], v[142:145], v[206:209], v[14:17]
	v_mfma_f32_16x16x32_bf16 v[10:13], v[150:153], v[206:209], v[10:13]
	v_mfma_f32_16x16x32_bf16 v[62:65], v[146:149], v[186:189], v[62:65]
	v_mfma_f32_16x16x32_bf16 v[58:61], v[154:157], v[186:189], v[58:61]
	v_mfma_f32_16x16x32_bf16 v[46:49], v[146:149], v[194:197], v[46:49]
	v_mfma_f32_16x16x32_bf16 v[42:45], v[154:157], v[194:197], v[42:45]
	v_mfma_f32_16x16x32_bf16 v[30:33], v[146:149], v[202:205], v[30:33]
	v_mfma_f32_16x16x32_bf16 v[26:29], v[154:157], v[202:205], v[26:29]
	v_mfma_f32_16x16x32_bf16 v[14:17], v[146:149], v[210:213], v[14:17]
	v_mfma_f32_16x16x32_bf16 v[10:13], v[154:157], v[210:213], v[10:13]
	v_mfma_f32_16x16x32_bf16 v[54:57], v[166:169], v[182:185], v[54:57]
	v_mfma_f32_16x16x32_bf16 v[50:53], v[174:177], v[182:185], v[50:53]
	v_mfma_f32_16x16x32_bf16 v[38:41], v[166:169], v[190:193], v[38:41]
	v_mfma_f32_16x16x32_bf16 v[34:37], v[174:177], v[190:193], v[34:37]
	v_mfma_f32_16x16x32_bf16 v[22:25], v[166:169], v[198:201], v[22:25]
	v_mfma_f32_16x16x32_bf16 v[18:21], v[174:177], v[198:201], v[18:21]
	v_mfma_f32_16x16x32_bf16 v[6:9], v[166:169], v[206:209], v[6:9]
	v_mfma_f32_16x16x32_bf16 v[2:5], v[174:177], v[206:209], v[2:5]
	v_mfma_f32_16x16x32_bf16 v[54:57], v[170:173], v[186:189], v[54:57]
	v_mfma_f32_16x16x32_bf16 v[50:53], v[178:181], v[186:189], v[50:53]
	v_mfma_f32_16x16x32_bf16 v[38:41], v[170:173], v[194:197], v[38:41]
	v_mfma_f32_16x16x32_bf16 v[34:37], v[178:181], v[194:197], v[34:37]
	v_mfma_f32_16x16x32_bf16 v[22:25], v[170:173], v[202:205], v[22:25]
	v_mfma_f32_16x16x32_bf16 v[18:21], v[178:181], v[202:205], v[18:21]
	v_mfma_f32_16x16x32_bf16 v[6:9], v[170:173], v[210:213], v[6:9]
	v_mfma_f32_16x16x32_bf16 v[2:5], v[178:181], v[210:213], v[2:5]
	s_barrier
	s_movk_i32 s38, 0x100
	s_andn2_b64 vcc, exec, s[4:5]
	s_mov_b64 s[10:11], -1
	s_mov_b64 s[4:5], 0
	s_cbranch_vccz .LBB0_390
	s_and_b64 vcc, exec, s[44:45]
	s_cbranch_vccz .LBB0_393
	s_barrier

; #define PG8_STAGE(bufoff, gbase, voff) do { _Pragma("unroll") for (int _i = 0; _i < 2; ++_i) \
;         __builtin_amdgcn_global_load_lds((const unsigned*)((const char*)(gbase) + (voff)[_i]), (LAS unsigned*)(lds + (bufoff) + ldsw + _i * 8192), 16, 0, 0); } while (0)
; #define PG8_LDA(dst, b, h) do { _Pragma("unroll") for (int m = 0; m < 4; ++m) _Pragma("unroll") for (int k = 0; k < 2; ++k) dst[m][k] = *(const LAS bf16x8*)(lds + PG8_SA(b, h) + aoff + m * 2048 + k * 1024); } while (0)
; #define PG8_LDB(dst, b, h) do { _Pragma("unroll") for (int n = 0; n < 2; ++n) _Pragma("unroll") for (int k = 0; k < 2; ++k) dst[n][k] = *(const LAS bf16x8*)(lds + PG8_SB(b, h) + boff + n * 2048 + k * 1024); } while (0)
; #define PG8_MMA(ai, bj, At, Bt) do { __builtin_amdgcn_s_setprio(1); _Pragma("unroll") for (int m = 0; m < 4; ++m) _Pragma("unroll") for (int n = 0; n < 2; ++n) _Pragma("unroll") for (int k = 0; k < 2; ++k) \
;         acc[ai][bj][m][n] = __builtin_amdgcn_mfma_f32_16x16x32_bf16(Bt[n][k], At[m][k], acc[ai][bj][m][n], 0, 0, 0); __builtin_amdgcn_s_setprio(0); } while (0)
; #define PG8_WAIT_V(n) asm volatile("s_waitcnt vmcnt(" #n ")" ::: "memory")
; #define PG8_WAIT_L(n) asm volatile("s_waitcnt lgkmcnt(" #n ")" ::: "memory")
; #define PG8_BAR __builtin_amdgcn_s_barrier()
; #define PG8_SCHED __builtin_amdgcn_sched_barrier(0)
; template <class Epi>
; __device__ __forceinline__ void gemm_phase(LAS unsigned char* lds, const Gemm g, int G, int c, const Epi& E) {
;     ...
;             const bool last = (t == nt - 2);
;             const char* a1 = cA + (size_t)(t + 1) * kstep;
;             const char* a2 = last ? nA : cA + (size_t)(t + 2) * kstep; const char* b2 = last ? nB : cB + (size_t)(t + 2) * kstep;
;             const char* a3 = a2 + kstep; const char* b3 = b2 + kstep;
;             PG8_LDB(B0, 0, 0); PG8_LDB(B1, 0, 1); PG8_SCHED; PG8_LDA(At, 0, 0); PG8_STAGE(PG8_SA(1, 1), a1 + hstepA, voffA);
;             PG8_WAIT_V(8); PG8_WAIT_L(0); PG8_BAR; PG8_MMA(0, 0, At, B0); PG8_MMA(0, 1, At, B1); PG8_BAR; PG8_SCHED;
.LBB0_476:
	s_add_u32 s33, s8, s38
	s_addc_u32 s39, s9, 0
	s_add_u32 s56, s33, 0x100
	s_addc_u32 s57, s39, 0
	s_and_b64 s[54:55], s[10:11], exec
	s_cselect_b32 s57, s47, s57
	s_cselect_b32 s56, s46, s56
	s_add_u32 s38, s6, s38
	s_addc_u32 s54, s7, 0
	s_add_u32 s38, s38, 0x100
	s_addc_u32 s54, s54, 0
	s_and_b64 s[10:11], s[10:11], exec
	s_cselect_b32 s59, s53, s54
	s_cselect_b32 s58, s52, s38
	s_add_u32 s66, s33, 0xb0080
	ds_read_b128 v[130:133], v166
	ds_read_b128 v[134:137], v166 offset:1024
	ds_read_b128 v[150:153], v166 offset:2048
	ds_read_b128 v[154:157], v166 offset:3072
	ds_read_b128 v[158:161], v167
	ds_read_b128 v[172:175], v167 offset:1024
	ds_read_b128 v[176:179], v167 offset:2048
	ds_read_b128 v[180:183], v167 offset:3072
	s_addc_u32 s67, s39, 0
	s_add_i32 s63, s95, s83
	s_add_i32 m0, s86, 0xc000
	s_add_i32 s64, s86, 0xe000
	s_add_i32 s74, s63, 0x2000
	s_add_u32 s60, s58, 0xb0000
	s_addc_u32 s61, s59, 0
	s_add_i32 s75, s96, s83
	s_add_i32 s62, s75, 0x2000
	s_add_i32 vcc_hi, 0, 0x18000
	s_add_i32 vcc_lo, 0, 0x1c000
	s_add_u32 s54, s56, 0xb0000
	s_addc_u32 s55, s57, 0
	s_add_i32 s39, vcc_hi, s83
	s_add_i32 s73, s39, 0x2000
	s_add_u32 s10, s58, 0xb0080
	s_addc_u32 s11, s59, 0
	s_add_i32 s38, vcc_lo, s83
	s_add_i32 s33, s38, 0x2000
	v_lshl_add_u64 v[162:163], s[66:67], 0, v[138:139]
	ds_read_b128 v[184:187], v168
	ds_read_b128 v[188:191], v168 offset:1024
	ds_read_b128 v[192:195], v168 offset:2048
	ds_read_b128 v[196:199], v168 offset:3072
	ds_read_b128 v[200:203], v168 offset:4096
	ds_read_b128 v[204:207], v168 offset:5120
	ds_read_b128 v[208:211], v168 offset:6144
	ds_read_b128 v[212:215], v168 offset:7168
	global_load_lds_dwordx4 v[162:163], off
	v_lshl_add_u64 v[162:163], s[66:67], 0, v[142:143]
	s_mov_b32 m0, s64
	s_nop 0
	global_load_lds_dwordx4 v[162:163], off
	s_waitcnt vmcnt(8)
	s_waitcnt lgkmcnt(0)
	s_barrier
	s_waitcnt lgkmcnt(0)
	v_mfma_f32_16x16x32_bf16 v[126:129], v[130:133], v[184:187], v[126:129]
	v_mfma_f32_16x16x32_bf16 v[122:125], v[150:153], v[184:187], v[122:125]
	v_mfma_f32_16x16x32_bf16 v[110:113], v[130:133], v[192:195], v[110:113]
	v_mfma_f32_16x16x32_bf16 v[106:109], v[150:153], v[192:195], v[106:109]
	v_mfma_f32_16x16x32_bf16 v[94:97], v[130:133], v[200:203], v[94:97]
	v_mfma_f32_16x16x32_bf16 v[90:93], v[150:153], v[200:203], v[90:93]
	v_mfma_f32_16x16x32_bf16 v[78:81], v[130:133], v[208:211], v[78:81]
	v_mfma_f32_16x16x32_bf16 v[74:77], v[150:153], v[208:211], v[74:77]
	v_mfma_f32_16x16x32_bf16 v[126:129], v[134:137], v[188:191], v[126:129]
	v_mfma_f32_16x16x32_bf16 v[122:125], v[154:157], v[188:191], v[122:125]
	v_mfma_f32_16x16x32_bf16 v[110:113], v[134:137], v[196:199], v[110:113]
	v_mfma_f32_16x16x32_bf16 v[106:109], v[154:157], v[196:199], v[106:109]
	v_mfma_f32_16x16x32_bf16 v[94:97], v[134:137], v[204:207], v[94:97]
	v_mfma_f32_16x16x32_bf16 v[90:93], v[154:157], v[204:207], v[90:93]
	v_mfma_f32_16x16x32_bf16 v[78:81], v[134:137], v[212:215], v[78:81]
	v_mfma_f32_16x16x32_bf16 v[74:77], v[154:157], v[212:215], v[74:77]
	v_mfma_f32_16x16x32_bf16 v[118:121], v[158:161], v[184:187], v[118:121]
	v_mfma_f32_16x16x32_bf16 v[114:117], v[176:179], v[184:187], v[114:117]
	v_mfma_f32_16x16x32_bf16 v[102:105], v[158:161], v[192:195], v[102:105]
	v_mfma_f32_16x16x32_bf16 v[98:101], v[176:179], v[192:195], v[98:101]
	v_mfma_f32_16x16x32_bf16 v[86:89], v[158:161], v[200:203], v[86:89]
	v_mfma_f32_16x16x32_bf16 v[82:85], v[176:179], v[200:203], v[82:85]
	v_mfma_f32_16x16x32_bf16 v[70:73], v[158:161], v[208:211], v[70:73]
	v_mfma_f32_16x16x32_bf16 v[66:69], v[176:179], v[208:211], v[66:69]
	v_mfma_f32_16x16x32_bf16 v[118:121], v[172:175], v[188:191], v[118:121]
	v_mfma_f32_16x16x32_bf16 v[114:117], v[180:183], v[188:191], v[114:117]
	v_mfma_f32_16x16x32_bf16 v[102:105], v[172:175], v[196:199], v[102:105]
	v_mfma_f32_16x16x32_bf16 v[98:101], v[180:183], v[196:199], v[98:101]
	v_mfma_f32_16x16x32_bf16 v[86:89], v[172:175], v[204:207], v[86:89]
	v_mfma_f32_16x16x32_bf16 v[82:85], v[180:183], v[204:207], v[82:85]
	v_mfma_f32_16x16x32_bf16 v[70:73], v[172:175], v[212:215], v[70:73]
	v_mfma_f32_16x16x32_bf16 v[66:69], v[180:183], v[212:215], v[66:69]
	s_barrier
	s_mov_b32 m0, s63
	v_lshl_add_u64 v[162:163], s[58:59], 0, v[140:141]
	ds_read_b128 v[184:187], v168 offset:16384
	ds_read_b128 v[188:191], v168 offset:17408
	ds_read_b128 v[192:195], v168 offset:18432
	ds_read_b128 v[196:199], v168 offset:19456
	ds_read_b128 v[200:203], v168 offset:20480
	ds_read_b128 v[204:207], v168 offset:21504
	ds_read_b128 v[208:211], v168 offset:22528
	ds_read_b128 v[212:215], v168 offset:23552
	global_load_lds_dwordx4 v[162:163], off
	v_lshl_add_u64 v[216:217], s[58:59], 0, v[144:145]
	s_mov_b32 m0, s74
	v_lshl_add_u64 v[218:219], s[60:61], 0, v[140:141]
	global_load_lds_dwordx4 v[216:217], off
	s_mov_b32 m0, s75
	v_lshl_add_u64 v[220:221], s[56:57], 0, v[142:143]
	global_load_lds_dwordx4 v[218:219], off
	v_lshl_add_u64 v[218:219], s[60:61], 0, v[144:145]
	s_mov_b32 m0, s62
	s_nop 0
	global_load_lds_dwordx4 v[218:219], off
	v_lshl_add_u64 v[218:219], s[56:57], 0, v[138:139]
	s_mov_b32 m0, s86
	s_nop 0
	global_load_lds_dwordx4 v[218:219], off
	s_mov_b32 m0, s87
	s_nop 0
	global_load_lds_dwordx4 v[220:221], off
	s_waitcnt vmcnt(8)
	s_waitcnt lgkmcnt(0)
	s_barrier
; #define PG8_STAGE(bufoff, gbase, voff) do { _Pragma("unroll") for (int _i = 0; _i < 2; ++_i) \
;         __builtin_amdgcn_global_load_lds((const unsigned*)((const char*)(gbase) + (voff)[_i]), (LAS unsigned*)(lds + (bufoff) + ldsw + _i * 8192), 16, 0, 0); } while (0)
; #define PG8_LDA(dst, b, h) do { _Pragma("unroll") for (int m = 0; m < 4; ++m) _Pragma("unroll") for (int k = 0; k < 2; ++k) dst[m][k] = *(const LAS bf16x8*)(lds + PG8_SA(b, h) + aoff + m * 2048 + k * 1024); } while (0)
; #define PG8_LDB(dst, b, h) do { _Pragma("unroll") for (int n = 0; n < 2; ++n) _Pragma("unroll") for (int k = 0; k < 2; ++k) dst[n][k] = *(const LAS bf16x8*)(lds + PG8_SB(b, h) + boff + n * 2048 + k * 1024); } while (0)
; #define PG8_MMA(ai, bj, At, Bt) do { __builtin_amdgcn_s_setprio(1); _Pragma("unroll") for (int m = 0; m < 4; ++m) _Pragma("unroll") for (int n = 0; n < 2; ++n) _Pragma("unroll") for (int k = 0; k < 2; ++k) \
;         acc[ai][bj][m][n] = __builtin_amdgcn_mfma_f32_16x16x32_bf16(Bt[n][k], At[m][k], acc[ai][bj][m][n], 0, 0, 0); __builtin_amdgcn_s_setprio(0); } while (0)
; #define PG8_WAIT_V(n) asm volatile("s_waitcnt vmcnt(" #n ")" ::: "memory")
; #define PG8_WAIT_L(n) asm volatile("s_waitcnt lgkmcnt(" #n ")" ::: "memory")
; #define PG8_BAR __builtin_amdgcn_s_barrier()
; #define PG8_SCHED __builtin_amdgcn_sched_barrier(0)
; template <class Epi>
; __device__ __forceinline__ void gemm_phase(LAS unsigned char* lds, const Gemm g, int G, int c, const Epi& E) {
;     ...
;             PG8_WAIT_V(8); PG8_WAIT_L(0); PG8_BAR; PG8_MMA(1, 0, At, B0); PG8_MMA(1, 1, At, B1); PG8_BAR; PG8_SCHED;
;             PG8_LDB(B0, 1, 0); PG8_LDB(B1, 1, 1); PG8_SCHED; PG8_LDA(At, 1, 0); PG8_STAGE(PG8_SA(0, 1), a2 + hstepA, voffA);
;             PG8_WAIT_V(8); PG8_WAIT_L(0); PG8_BAR; PG8_MMA(0, 0, At, B0); PG8_MMA(0, 1, At, B1); PG8_BAR; PG8_SCHED;
	s_waitcnt lgkmcnt(0)
	v_mfma_f32_16x16x32_bf16 v[62:65], v[130:133], v[184:187], v[62:65]
	v_mfma_f32_16x16x32_bf16 v[58:61], v[150:153], v[184:187], v[58:61]
	v_mfma_f32_16x16x32_bf16 v[46:49], v[130:133], v[192:195], v[46:49]
	v_mfma_f32_16x16x32_bf16 v[42:45], v[150:153], v[192:195], v[42:45]
	v_mfma_f32_16x16x32_bf16 v[30:33], v[130:133], v[200:203], v[30:33]
	v_mfma_f32_16x16x32_bf16 v[26:29], v[150:153], v[200:203], v[26:29]
	v_mfma_f32_16x16x32_bf16 v[14:17], v[130:133], v[208:211], v[14:17]
	v_mfma_f32_16x16x32_bf16 v[10:13], v[150:153], v[208:211], v[10:13]
	v_mfma_f32_16x16x32_bf16 v[62:65], v[134:137], v[188:191], v[62:65]
	v_mfma_f32_16x16x32_bf16 v[58:61], v[154:157], v[188:191], v[58:61]
	v_mfma_f32_16x16x32_bf16 v[46:49], v[134:137], v[196:199], v[46:49]
	v_mfma_f32_16x16x32_bf16 v[42:45], v[154:157], v[196:199], v[42:45]
	v_mfma_f32_16x16x32_bf16 v[30:33], v[134:137], v[204:207], v[30:33]
	v_mfma_f32_16x16x32_bf16 v[26:29], v[154:157], v[204:207], v[26:29]
	v_mfma_f32_16x16x32_bf16 v[14:17], v[134:137], v[212:215], v[14:17]
	v_mfma_f32_16x16x32_bf16 v[10:13], v[154:157], v[212:215], v[10:13]
	v_mfma_f32_16x16x32_bf16 v[54:57], v[158:161], v[184:187], v[54:57]
	v_mfma_f32_16x16x32_bf16 v[50:53], v[176:179], v[184:187], v[50:53]
	v_mfma_f32_16x16x32_bf16 v[38:41], v[158:161], v[192:195], v[38:41]
	v_mfma_f32_16x16x32_bf16 v[34:37], v[176:179], v[192:195], v[34:37]
	v_mfma_f32_16x16x32_bf16 v[22:25], v[158:161], v[200:203], v[22:25]
	v_mfma_f32_16x16x32_bf16 v[18:21], v[176:179], v[200:203], v[18:21]
	v_mfma_f32_16x16x32_bf16 v[6:9], v[158:161], v[208:211], v[6:9]
	v_mfma_f32_16x16x32_bf16 v[2:5], v[176:179], v[208:211], v[2:5]
	v_mfma_f32_16x16x32_bf16 v[54:57], v[172:175], v[188:191], v[54:57]
	v_mfma_f32_16x16x32_bf16 v[50:53], v[180:183], v[188:191], v[50:53]
	v_mfma_f32_16x16x32_bf16 v[38:41], v[172:175], v[196:199], v[38:41]
	v_mfma_f32_16x16x32_bf16 v[34:37], v[180:183], v[196:199], v[34:37]
	v_mfma_f32_16x16x32_bf16 v[22:25], v[172:175], v[204:207], v[22:25]
	v_mfma_f32_16x16x32_bf16 v[18:21], v[180:183], v[204:207], v[18:21]
	v_mfma_f32_16x16x32_bf16 v[6:9], v[172:175], v[212:215], v[6:9]
	v_mfma_f32_16x16x32_bf16 v[2:5], v[180:183], v[212:215], v[2:5]
	s_barrier
	v_add_u32_e32 v154, vcc_hi, v165
	v_add_u32_e32 v180, vcc_lo, v165
	ds_read_b128 v[130:133], v154
	ds_read_b128 v[134:137], v154 offset:1024
	ds_read_b128 v[150:153], v154 offset:2048
	ds_read_b128 v[154:157], v154 offset:3072
	ds_read_b128 v[158:161], v180
	ds_read_b128 v[172:175], v180 offset:1024
	ds_read_b128 v[176:179], v180 offset:2048
	ds_read_b128 v[180:183], v180 offset:3072
	s_mov_b32 m0, s88
	v_lshl_add_u64 v[222:223], s[54:55], 0, v[138:139]
	ds_read_b128 v[184:187], v168 offset:32768
	ds_read_b128 v[188:191], v168 offset:33792
	ds_read_b128 v[192:195], v168 offset:34816
	ds_read_b128 v[196:199], v168 offset:35840
	ds_read_b128 v[200:203], v168 offset:36864
	ds_read_b128 v[204:207], v168 offset:37888
	ds_read_b128 v[208:211], v168 offset:38912
	ds_read_b128 v[212:215], v168 offset:39936
	global_load_lds_dwordx4 v[222:223], off
	v_lshl_add_u64 v[222:223], s[54:55], 0, v[142:143]
	s_mov_b32 m0, s89
	s_nop 0
	global_load_lds_dwordx4 v[222:223], off
	s_waitcnt vmcnt(8)
	s_waitcnt lgkmcnt(0)
	s_barrier
	s_waitcnt lgkmcnt(0)
	v_mfma_f32_16x16x32_bf16 v[126:129], v[130:133], v[184:187], v[126:129]
	v_mfma_f32_16x16x32_bf16 v[122:125], v[150:153], v[184:187], v[122:125]
	v_mfma_f32_16x16x32_bf16 v[110:113], v[130:133], v[192:195], v[110:113]
	v_mfma_f32_16x16x32_bf16 v[106:109], v[150:153], v[192:195], v[106:109]
	v_mfma_f32_16x16x32_bf16 v[94:97], v[130:133], v[200:203], v[94:97]
	v_mfma_f32_16x16x32_bf16 v[90:93], v[150:153], v[200:203], v[90:93]
	v_mfma_f32_16x16x32_bf16 v[78:81], v[130:133], v[208:211], v[78:81]
	v_mfma_f32_16x16x32_bf16 v[74:77], v[150:153], v[208:211], v[74:77]
	v_mfma_f32_16x16x32_bf16 v[126:129], v[134:137], v[188:191], v[126:129]
	v_mfma_f32_16x16x32_bf16 v[122:125], v[154:157], v[188:191], v[122:125]
	v_mfma_f32_16x16x32_bf16 v[110:113], v[134:137], v[196:199], v[110:113]
	v_mfma_f32_16x16x32_bf16 v[106:109], v[154:157], v[196:199], v[106:109]
	v_mfma_f32_16x16x32_bf16 v[94:97], v[134:137], v[204:207], v[94:97]
	v_mfma_f32_16x16x32_bf16 v[90:93], v[154:157], v[204:207], v[90:93]
	v_mfma_f32_16x16x32_bf16 v[78:81], v[134:137], v[212:215], v[78:81]
	v_mfma_f32_16x16x32_bf16 v[74:77], v[154:157], v[212:215], v[74:77]
	v_mfma_f32_16x16x32_bf16 v[118:121], v[158:161], v[184:187], v[118:121]
	v_mfma_f32_16x16x32_bf16 v[114:117], v[176:179], v[184:187], v[114:117]
	v_mfma_f32_16x16x32_bf16 v[102:105], v[158:161], v[192:195], v[102:105]
	v_mfma_f32_16x16x32_bf16 v[98:101], v[176:179], v[192:195], v[98:101]
	v_mfma_f32_16x16x32_bf16 v[86:89], v[158:161], v[200:203], v[86:89]
	v_mfma_f32_16x16x32_bf16 v[82:85], v[176:179], v[200:203], v[82:85]
	v_mfma_f32_16x16x32_bf16 v[70:73], v[158:161], v[208:211], v[70:73]
	v_mfma_f32_16x16x32_bf16 v[66:69], v[176:179], v[208:211], v[66:69]
	v_mfma_f32_16x16x32_bf16 v[118:121], v[172:175], v[188:191], v[118:121]
	v_mfma_f32_16x16x32_bf16 v[114:117], v[180:183], v[188:191], v[114:117]
	v_mfma_f32_16x16x32_bf16 v[102:105], v[172:175], v[196:199], v[102:105]
	v_mfma_f32_16x16x32_bf16 v[98:101], v[180:183], v[196:199], v[98:101]
	v_mfma_f32_16x16x32_bf16 v[86:89], v[172:175], v[204:207], v[86:89]
	v_mfma_f32_16x16x32_bf16 v[82:85], v[180:183], v[204:207], v[82:85]
	v_mfma_f32_16x16x32_bf16 v[70:73], v[172:175], v[212:215], v[70:73]
	v_mfma_f32_16x16x32_bf16 v[66:69], v[180:183], v[212:215], v[66:69]
	s_barrier
; #define PG8_STAGE(bufoff, gbase, voff) do { _Pragma("unroll") for (int _i = 0; _i < 2; ++_i) \
;         __builtin_amdgcn_global_load_lds((const unsigned*)((const char*)(gbase) + (voff)[_i]), (LAS unsigned*)(lds + (bufoff) + ldsw + _i * 8192), 16, 0, 0); } while (0)
; #define PG8_LDA(dst, b, h) do { _Pragma("unroll") for (int m = 0; m < 4; ++m) _Pragma("unroll") for (int k = 0; k < 2; ++k) dst[m][k] = *(const LAS bf16x8*)(lds + PG8_SA(b, h) + aoff + m * 2048 + k * 1024); } while (0)
; #define PG8_MMA(ai, bj, At, Bt) do { __builtin_amdgcn_s_setprio(1); _Pragma("unroll") for (int m = 0; m < 4; ++m) _Pragma("unroll") for (int n = 0; n < 2; ++n) _Pragma("unroll") for (int k = 0; k < 2; ++k) \
;         acc[ai][bj][m][n] = __builtin_amdgcn_mfma_f32_16x16x32_bf16(Bt[n][k], At[m][k], acc[ai][bj][m][n], 0, 0, 0); __builtin_amdgcn_s_setprio(0); } while (0)
; #define PG8_WAIT_V(n) asm volatile("s_waitcnt vmcnt(" #n ")" ::: "memory")
; #define PG8_WAIT_L(n) asm volatile("s_waitcnt lgkmcnt(" #n ")" ::: "memory")
; #define PG8_BAR __builtin_amdgcn_s_barrier()
; #define PG8_SCHED __builtin_amdgcn_sched_barrier(0)
; template <class Epi>
; __device__ __forceinline__ void gemm_phase(LAS unsigned char* lds, const Gemm g, int G, int c, const Epi& E) {
;     ...
;             PG8_LDA(At, 1, 1); PG8_STAGE(PG8_SB(1, 0), b3, voffB); PG8_STAGE(PG8_SB(1, 1), b3 + hstepB, voffB); PG8_STAGE(PG8_SA(1, 0), a3, voffA);
;             PG8_WAIT_V(8); PG8_WAIT_L(0); PG8_BAR; PG8_MMA(1, 0, At, B0); PG8_MMA(1, 1, At, B1); PG8_BAR; PG8_SCHED;
;         }
	s_mov_b32 m0, s39
	v_lshl_add_u64 v[162:163], v[162:163], 0, s[24:25]
	ds_read_b128 v[184:187], v168 offset:49152
	ds_read_b128 v[188:191], v168 offset:50176
	ds_read_b128 v[192:195], v168 offset:51200
	ds_read_b128 v[196:199], v168 offset:52224
	ds_read_b128 v[200:203], v168 offset:53248
	ds_read_b128 v[204:207], v168 offset:54272
	ds_read_b128 v[208:211], v168 offset:55296
	ds_read_b128 v[212:215], v168 offset:56320
	global_load_lds_dwordx4 v[162:163], off
	v_lshl_add_u64 v[162:163], v[216:217], 0, s[24:25]
	s_mov_b32 m0, s73
	s_nop 0
	global_load_lds_dwordx4 v[162:163], off
	v_lshl_add_u64 v[162:163], s[10:11], 0, v[140:141]
	s_mov_b32 m0, s38
	s_nop 0
	global_load_lds_dwordx4 v[162:163], off
	v_lshl_add_u64 v[162:163], s[10:11], 0, v[144:145]
	s_mov_b32 m0, s33
	s_nop 0
	global_load_lds_dwordx4 v[162:163], off
	v_lshl_add_u64 v[162:163], v[218:219], 0, s[24:25]
	s_mov_b32 m0, s93
	s_nop 0
	global_load_lds_dwordx4 v[162:163], off
	v_lshl_add_u64 v[162:163], v[220:221], 0, s[24:25]
	s_mov_b32 m0, s94
	s_nop 0
	global_load_lds_dwordx4 v[162:163], off
	s_waitcnt vmcnt(8)
	s_waitcnt lgkmcnt(0)
	s_barrier
	s_waitcnt lgkmcnt(0)
	v_mfma_f32_16x16x32_bf16 v[62:65], v[130:133], v[184:187], v[62:65]
	v_mfma_f32_16x16x32_bf16 v[58:61], v[150:153], v[184:187], v[58:61]
	v_mfma_f32_16x16x32_bf16 v[46:49], v[130:133], v[192:195], v[46:49]
	v_mfma_f32_16x16x32_bf16 v[42:45], v[150:153], v[192:195], v[42:45]
	v_mfma_f32_16x16x32_bf16 v[30:33], v[130:133], v[200:203], v[30:33]
	v_mfma_f32_16x16x32_bf16 v[26:29], v[150:153], v[200:203], v[26:29]
	v_mfma_f32_16x16x32_bf16 v[14:17], v[130:133], v[208:211], v[14:17]
	v_mfma_f32_16x16x32_bf16 v[10:13], v[150:153], v[208:211], v[10:13]
	v_mfma_f32_16x16x32_bf16 v[62:65], v[134:137], v[188:191], v[62:65]
	v_mfma_f32_16x16x32_bf16 v[58:61], v[154:157], v[188:191], v[58:61]
	v_mfma_f32_16x16x32_bf16 v[46:49], v[134:137], v[196:199], v[46:49]
	v_mfma_f32_16x16x32_bf16 v[42:45], v[154:157], v[196:199], v[42:45]
	v_mfma_f32_16x16x32_bf16 v[30:33], v[134:137], v[204:207], v[30:33]
	v_mfma_f32_16x16x32_bf16 v[26:29], v[154:157], v[204:207], v[26:29]
	v_mfma_f32_16x16x32_bf16 v[14:17], v[134:137], v[212:215], v[14:17]
	v_mfma_f32_16x16x32_bf16 v[10:13], v[154:157], v[212:215], v[10:13]
	v_mfma_f32_16x16x32_bf16 v[54:57], v[158:161], v[184:187], v[54:57]
	v_mfma_f32_16x16x32_bf16 v[50:53], v[176:179], v[184:187], v[50:53]
	v_mfma_f32_16x16x32_bf16 v[38:41], v[158:161], v[192:195], v[38:41]
	v_mfma_f32_16x16x32_bf16 v[34:37], v[176:179], v[192:195], v[34:37]
	v_mfma_f32_16x16x32_bf16 v[22:25], v[158:161], v[200:203], v[22:25]
	v_mfma_f32_16x16x32_bf16 v[18:21], v[176:179], v[200:203], v[18:21]
	v_mfma_f32_16x16x32_bf16 v[6:9], v[158:161], v[208:211], v[6:9]
	v_mfma_f32_16x16x32_bf16 v[2:5], v[176:179], v[208:211], v[2:5]
	v_mfma_f32_16x16x32_bf16 v[54:57], v[172:175], v[188:191], v[54:57]
	v_mfma_f32_16x16x32_bf16 v[50:53], v[180:183], v[188:191], v[50:53]
	v_mfma_f32_16x16x32_bf16 v[38:41], v[172:175], v[196:199], v[38:41]
	v_mfma_f32_16x16x32_bf16 v[34:37], v[180:183], v[196:199], v[34:37]
	v_mfma_f32_16x16x32_bf16 v[22:25], v[172:175], v[204:207], v[22:25]
	v_mfma_f32_16x16x32_bf16 v[18:21], v[180:183], v[204:207], v[18:21]
	v_mfma_f32_16x16x32_bf16 v[6:9], v[172:175], v[212:215], v[6:9]
	v_mfma_f32_16x16x32_bf16 v[2:5], v[180:183], v[212:215], v[2:5]
	s_barrier
	s_movk_i32 s38, 0x100
	s_andn2_b64 vcc, exec, s[4:5]
	s_mov_b64 s[10:11], -1
	s_mov_b64 s[4:5], 0
	s_cbranch_vccz .LBB0_476
	s_and_b64 vcc, exec, s[44:45]
	s_cbranch_vccz .LBB0_479
	s_barrier

; #define PG8_STAGE(bufoff, gbase, voff) do { _Pragma("unroll") for (int _i = 0; _i < 2; ++_i) \
;         __builtin_amdgcn_global_load_lds((const unsigned*)((const char*)(gbase) + (voff)[_i]), (LAS unsigned*)(lds + (bufoff) + ldsw + _i * 8192), 16, 0, 0); } while (0)
; #define PG8_LDA(dst, b, h) do { _Pragma("unroll") for (int m = 0; m < 4; ++m) _Pragma("unroll") for (int k = 0; k < 2; ++k) dst[m][k] = *(const LAS bf16x8*)(lds + PG8_SA(b, h) + aoff + m * 2048 + k * 1024); } while (0)
; #define PG8_LDB(dst, b, h) do { _Pragma("unroll") for (int n = 0; n < 2; ++n) _Pragma("unroll") for (int k = 0; k < 2; ++k) dst[n][k] = *(const LAS bf16x8*)(lds + PG8_SB(b, h) + boff + n * 2048 + k * 1024); } while (0)
; #define PG8_MMA(ai, bj, At, Bt) do { __builtin_amdgcn_s_setprio(1); _Pragma("unroll") for (int m = 0; m < 4; ++m) _Pragma("unroll") for (int n = 0; n < 2; ++n) _Pragma("unroll") for (int k = 0; k < 2; ++k) \
;         acc[ai][bj][m][n] = __builtin_amdgcn_mfma_f32_16x16x32_bf16(Bt[n][k], At[m][k], acc[ai][bj][m][n], 0, 0, 0); __builtin_amdgcn_s_setprio(0); } while (0)
; #define PG8_WAIT_V(n) asm volatile("s_waitcnt vmcnt(" #n ")" ::: "memory")
; #define PG8_WAIT_L(n) asm volatile("s_waitcnt lgkmcnt(" #n ")" ::: "memory")
; #define PG8_BAR __builtin_amdgcn_s_barrier()
; #define PG8_SCHED __builtin_amdgcn_sched_barrier(0)
; template <class Epi>
; __device__ __forceinline__ void gemm_phase(LAS unsigned char* lds, const Gemm g, int G, int c, const Epi& E) {
;     ...
;         const bool has_next = S.next(ui + 1, nxt);
;         const char* nA = has_next ? (const char*)(g.A + (size_t)nxt.pb * g.sA) + (size_t)nxt.pm * 2 * hstepA : cA;
;         const char* nB = has_next ? (const char*)(g.Bt + (size_t)nxt.pb * g.sB) + (size_t)nxt.pn * 2 * hstepB : cB;
; #pragma nounroll
;         for (int t = 0; t < nt; t += 2) {
;             const bool last = (t == nt - 2);
;             const char* a1 = cA + (size_t)(t + 1) * kstep;
;             const char* a2 = last ? nA : cA + (size_t)(t + 2) * kstep; const char* b2 = last ? nB : cB + (size_t)(t + 2) * kstep;
;             const char* a3 = a2 + kstep; const char* b3 = b2 + kstep;
;             PG8_LDB(B0, 0, 0); PG8_LDB(B1, 0, 1); PG8_SCHED; PG8_LDA(At, 0, 0); PG8_STAGE(PG8_SA(1, 1), a1 + hstepA, voffA);
;             PG8_WAIT_V(8); PG8_WAIT_L(0); PG8_BAR; PG8_MMA(0, 0, At, B0); PG8_MMA(0, 1, At, B1); PG8_BAR; PG8_SCHED;
.LBB0_594:
	s_add_u32 s33, s8, s38
	s_addc_u32 s62, s9, 0
	s_add_u32 s39, s33, 0x100
	s_addc_u32 s58, s62, 0
	s_and_b64 s[56:57], s[54:55], exec
	s_cselect_b32 s59, s45, s58
	s_cselect_b32 s58, s44, s39
	s_add_u32 s38, s6, s38
	s_addc_u32 s39, s7, 0
	s_add_u32 s56, s38, 0x100
	s_addc_u32 s57, s39, 0
	s_and_b64 s[38:39], s[54:55], exec
	s_cselect_b32 s61, s47, s57
	s_cselect_b32 s60, s46, s56
	s_add_u32 s68, s33, 0xb0080
	s_addc_u32 s69, s62, 0
	s_add_i32 s63, s86, s23
	ds_read_b128 v[142:145], v166
	ds_read_b128 v[146:149], v166 offset:1024
	ds_read_b128 v[150:153], v166 offset:2048
	ds_read_b128 v[154:157], v166 offset:3072
	ds_read_b128 v[158:161], v167
	ds_read_b128 v[170:173], v167 offset:1024
	ds_read_b128 v[174:177], v167 offset:2048
	ds_read_b128 v[178:181], v167 offset:3072
	s_add_i32 m0, s72, 0xc000
	s_add_i32 s64, s72, 0xe000
	s_add_i32 s74, s63, 0x2000
	s_add_u32 s66, s60, 0xb0000
	s_addc_u32 s67, s61, 0
	s_add_i32 s62, s87, s23
	s_add_i32 s75, s62, 0x2000
	s_add_i32 s97, 0, 0x18000
	s_add_i32 s33, 0, 0x1c000
	s_add_u32 s56, s58, 0xb0000
	s_addc_u32 s57, s59, 0
	s_add_i32 s96, s97, s23
	s_add_i32 s39, s96, 0x2000
	s_add_u32 s54, s60, 0xb0080
	s_addc_u32 s55, s61, 0
	s_add_i32 s95, s33, s23
	s_add_i32 s38, s95, 0x2000
	v_lshl_add_u64 v[162:163], s[68:69], 0, v[136:137]
	ds_read_b128 v[182:185], v168
	ds_read_b128 v[186:189], v168 offset:1024
	ds_read_b128 v[190:193], v168 offset:2048
	ds_read_b128 v[194:197], v168 offset:3072
	ds_read_b128 v[198:201], v168 offset:4096
	ds_read_b128 v[202:205], v168 offset:5120
	ds_read_b128 v[206:209], v168 offset:6144
	ds_read_b128 v[210:213], v168 offset:7168
	global_load_lds_dwordx4 v[162:163], off
	v_lshl_add_u64 v[162:163], s[68:69], 0, v[132:133]
	s_mov_b32 m0, s64
	s_nop 0
	global_load_lds_dwordx4 v[162:163], off
	s_waitcnt vmcnt(8)
	s_waitcnt lgkmcnt(0)
	s_barrier
	s_waitcnt lgkmcnt(0)
	v_mfma_f32_16x16x32_bf16 v[126:129], v[142:145], v[182:185], v[126:129]
	v_mfma_f32_16x16x32_bf16 v[122:125], v[150:153], v[182:185], v[122:125]
	v_mfma_f32_16x16x32_bf16 v[110:113], v[142:145], v[190:193], v[110:113]
	v_mfma_f32_16x16x32_bf16 v[106:109], v[150:153], v[190:193], v[106:109]
	v_mfma_f32_16x16x32_bf16 v[94:97], v[142:145], v[198:201], v[94:97]
	v_mfma_f32_16x16x32_bf16 v[90:93], v[150:153], v[198:201], v[90:93]
	v_mfma_f32_16x16x32_bf16 v[78:81], v[142:145], v[206:209], v[78:81]
	v_mfma_f32_16x16x32_bf16 v[74:77], v[150:153], v[206:209], v[74:77]
	v_mfma_f32_16x16x32_bf16 v[126:129], v[146:149], v[186:189], v[126:129]
	v_mfma_f32_16x16x32_bf16 v[122:125], v[154:157], v[186:189], v[122:125]
	v_mfma_f32_16x16x32_bf16 v[110:113], v[146:149], v[194:197], v[110:113]
	v_mfma_f32_16x16x32_bf16 v[106:109], v[154:157], v[194:197], v[106:109]
	v_mfma_f32_16x16x32_bf16 v[94:97], v[146:149], v[202:205], v[94:97]
	v_mfma_f32_16x16x32_bf16 v[90:93], v[154:157], v[202:205], v[90:93]
	v_mfma_f32_16x16x32_bf16 v[78:81], v[146:149], v[210:213], v[78:81]
	v_mfma_f32_16x16x32_bf16 v[74:77], v[154:157], v[210:213], v[74:77]
	v_mfma_f32_16x16x32_bf16 v[118:121], v[158:161], v[182:185], v[118:121]
	v_mfma_f32_16x16x32_bf16 v[114:117], v[174:177], v[182:185], v[114:117]
	v_mfma_f32_16x16x32_bf16 v[102:105], v[158:161], v[190:193], v[102:105]
	v_mfma_f32_16x16x32_bf16 v[98:101], v[174:177], v[190:193], v[98:101]
	v_mfma_f32_16x16x32_bf16 v[86:89], v[158:161], v[198:201], v[86:89]
	v_mfma_f32_16x16x32_bf16 v[82:85], v[174:177], v[198:201], v[82:85]
	v_mfma_f32_16x16x32_bf16 v[70:73], v[158:161], v[206:209], v[70:73]
	v_mfma_f32_16x16x32_bf16 v[66:69], v[174:177], v[206:209], v[66:69]
	v_mfma_f32_16x16x32_bf16 v[118:121], v[170:173], v[186:189], v[118:121]
	v_mfma_f32_16x16x32_bf16 v[114:117], v[178:181], v[186:189], v[114:117]
	v_mfma_f32_16x16x32_bf16 v[102:105], v[170:173], v[194:197], v[102:105]
	v_mfma_f32_16x16x32_bf16 v[98:101], v[178:181], v[194:197], v[98:101]
	v_mfma_f32_16x16x32_bf16 v[86:89], v[170:173], v[202:205], v[86:89]
	v_mfma_f32_16x16x32_bf16 v[82:85], v[178:181], v[202:205], v[82:85]
	v_mfma_f32_16x16x32_bf16 v[70:73], v[170:173], v[210:213], v[70:73]
	v_mfma_f32_16x16x32_bf16 v[66:69], v[178:181], v[210:213], v[66:69]
	s_barrier
	s_mov_b32 m0, s63
	v_lshl_add_u64 v[162:163], s[60:61], 0, v[134:135]
	ds_read_b128 v[182:185], v168 offset:16384
	ds_read_b128 v[186:189], v168 offset:17408
	ds_read_b128 v[190:193], v168 offset:18432
	ds_read_b128 v[194:197], v168 offset:19456
	ds_read_b128 v[198:201], v168 offset:20480
	ds_read_b128 v[202:205], v168 offset:21504
	ds_read_b128 v[206:209], v168 offset:22528
	ds_read_b128 v[210:213], v168 offset:23552
	global_load_lds_dwordx4 v[162:163], off
	v_lshl_add_u64 v[214:215], s[60:61], 0, v[130:131]
	s_mov_b32 m0, s74
	v_lshl_add_u64 v[216:217], s[66:67], 0, v[134:135]
	global_load_lds_dwordx4 v[214:215], off
	s_mov_b32 m0, s62
	v_lshl_add_u64 v[218:219], s[58:59], 0, v[132:133]
	global_load_lds_dwordx4 v[216:217], off
	v_lshl_add_u64 v[216:217], s[66:67], 0, v[130:131]
	s_mov_b32 m0, s75
	s_nop 0
	global_load_lds_dwordx4 v[216:217], off
	v_lshl_add_u64 v[216:217], s[58:59], 0, v[136:137]
	s_mov_b32 m0, s72
	s_nop 0
	global_load_lds_dwordx4 v[216:217], off
	s_mov_b32 m0, s73
	s_nop 0
	global_load_lds_dwordx4 v[218:219], off
	s_waitcnt vmcnt(8)
	s_waitcnt lgkmcnt(0)
	s_barrier
; #define PG8_STAGE(bufoff, gbase, voff) do { _Pragma("unroll") for (int _i = 0; _i < 2; ++_i) \
;         __builtin_amdgcn_global_load_lds((const unsigned*)((const char*)(gbase) + (voff)[_i]), (LAS unsigned*)(lds + (bufoff) + ldsw + _i * 8192), 16, 0, 0); } while (0)
; #define PG8_LDA(dst, b, h) do { _Pragma("unroll") for (int m = 0; m < 4; ++m) _Pragma("unroll") for (int k = 0; k < 2; ++k) dst[m][k] = *(const LAS bf16x8*)(lds + PG8_SA(b, h) + aoff + m * 2048 + k * 1024); } while (0)
; #define PG8_LDB(dst, b, h) do { _Pragma("unroll") for (int n = 0; n < 2; ++n) _Pragma("unroll") for (int k = 0; k < 2; ++k) dst[n][k] = *(const LAS bf16x8*)(lds + PG8_SB(b, h) + boff + n * 2048 + k * 1024); } while (0)
; #define PG8_MMA(ai, bj, At, Bt) do { __builtin_amdgcn_s_setprio(1); _Pragma("unroll") for (int m = 0; m < 4; ++m) _Pragma("unroll") for (int n = 0; n < 2; ++n) _Pragma("unroll") for (int k = 0; k < 2; ++k) \
;         acc[ai][bj][m][n] = __builtin_amdgcn_mfma_f32_16x16x32_bf16(Bt[n][k], At[m][k], acc[ai][bj][m][n], 0, 0, 0); __builtin_amdgcn_s_setprio(0); } while (0)
; #define PG8_WAIT_V(n) asm volatile("s_waitcnt vmcnt(" #n ")" ::: "memory")
; #define PG8_WAIT_L(n) asm volatile("s_waitcnt lgkmcnt(" #n ")" ::: "memory")
; #define PG8_BAR __builtin_amdgcn_s_barrier()
; #define PG8_SCHED __builtin_amdgcn_sched_barrier(0)
; template <class Epi>
; __device__ __forceinline__ void gemm_phase(LAS unsigned char* lds, const Gemm g, int G, int c, const Epi& E) {
;     ...
;             PG8_WAIT_V(8); PG8_WAIT_L(0); PG8_BAR; PG8_MMA(0, 0, At, B0); PG8_MMA(0, 1, At, B1); PG8_BAR; PG8_SCHED;
;             PG8_LDA(At, 0, 1); PG8_STAGE(PG8_SB(0, 0), b2, voffB); PG8_STAGE(PG8_SB(0, 1), b2 + hstepB, voffB); PG8_STAGE(PG8_SA(0, 0), a2, voffA);
;             PG8_WAIT_V(8); PG8_WAIT_L(0); PG8_BAR; PG8_MMA(1, 0, At, B0); PG8_MMA(1, 1, At, B1); PG8_BAR; PG8_SCHED;
;             PG8_LDB(B0, 1, 0); PG8_LDB(B1, 1, 1); PG8_SCHED; PG8_LDA(At, 1, 0); PG8_STAGE(PG8_SA(0, 1), a2 + hstepA, voffA);
;             PG8_WAIT_V(8); PG8_WAIT_L(0); PG8_BAR; PG8_MMA(0, 0, At, B0); PG8_MMA(0, 1, At, B1); PG8_BAR; PG8_SCHED;
;             PG8_LDA(At, 1, 1); PG8_STAGE(PG8_SB(1, 0), b3, voffB); PG8_STAGE(PG8_SB(1, 1), b3 + hstepB, voffB); PG8_STAGE(PG8_SA(1, 0), a3, voffA);
	s_waitcnt lgkmcnt(0)
	v_mfma_f32_16x16x32_bf16 v[62:65], v[142:145], v[182:185], v[62:65]
	v_mfma_f32_16x16x32_bf16 v[58:61], v[150:153], v[182:185], v[58:61]
	v_mfma_f32_16x16x32_bf16 v[46:49], v[142:145], v[190:193], v[46:49]
	v_mfma_f32_16x16x32_bf16 v[42:45], v[150:153], v[190:193], v[42:45]
	v_mfma_f32_16x16x32_bf16 v[30:33], v[142:145], v[198:201], v[30:33]
	v_mfma_f32_16x16x32_bf16 v[26:29], v[150:153], v[198:201], v[26:29]
	v_mfma_f32_16x16x32_bf16 v[14:17], v[142:145], v[206:209], v[14:17]
	v_mfma_f32_16x16x32_bf16 v[10:13], v[150:153], v[206:209], v[10:13]
	v_mfma_f32_16x16x32_bf16 v[62:65], v[146:149], v[186:189], v[62:65]
	v_mfma_f32_16x16x32_bf16 v[58:61], v[154:157], v[186:189], v[58:61]
	v_mfma_f32_16x16x32_bf16 v[46:49], v[146:149], v[194:197], v[46:49]
	v_mfma_f32_16x16x32_bf16 v[42:45], v[154:157], v[194:197], v[42:45]
	v_mfma_f32_16x16x32_bf16 v[30:33], v[146:149], v[202:205], v[30:33]
	v_mfma_f32_16x16x32_bf16 v[26:29], v[154:157], v[202:205], v[26:29]
	v_mfma_f32_16x16x32_bf16 v[14:17], v[146:149], v[210:213], v[14:17]
	v_mfma_f32_16x16x32_bf16 v[10:13], v[154:157], v[210:213], v[10:13]
	v_mfma_f32_16x16x32_bf16 v[54:57], v[158:161], v[182:185], v[54:57]
	v_mfma_f32_16x16x32_bf16 v[50:53], v[174:177], v[182:185], v[50:53]
	v_mfma_f32_16x16x32_bf16 v[38:41], v[158:161], v[190:193], v[38:41]
	v_mfma_f32_16x16x32_bf16 v[34:37], v[174:177], v[190:193], v[34:37]
	v_mfma_f32_16x16x32_bf16 v[22:25], v[158:161], v[198:201], v[22:25]
	v_mfma_f32_16x16x32_bf16 v[18:21], v[174:177], v[198:201], v[18:21]
	v_mfma_f32_16x16x32_bf16 v[6:9], v[158:161], v[206:209], v[6:9]
	v_mfma_f32_16x16x32_bf16 v[2:5], v[174:177], v[206:209], v[2:5]
	v_mfma_f32_16x16x32_bf16 v[54:57], v[170:173], v[186:189], v[54:57]
	v_mfma_f32_16x16x32_bf16 v[50:53], v[178:181], v[186:189], v[50:53]
	v_mfma_f32_16x16x32_bf16 v[38:41], v[170:173], v[194:197], v[38:41]
	v_mfma_f32_16x16x32_bf16 v[34:37], v[178:181], v[194:197], v[34:37]
	v_mfma_f32_16x16x32_bf16 v[22:25], v[170:173], v[202:205], v[22:25]
	v_mfma_f32_16x16x32_bf16 v[18:21], v[178:181], v[202:205], v[18:21]
	v_mfma_f32_16x16x32_bf16 v[6:9], v[170:173], v[210:213], v[6:9]
	v_mfma_f32_16x16x32_bf16 v[2:5], v[178:181], v[210:213], v[2:5]
	s_barrier
	v_add_u32_e32 v154, s97, v165
	v_add_u32_e32 v178, s33, v165
	ds_read_b128 v[142:145], v154
	ds_read_b128 v[146:149], v154 offset:1024
	ds_read_b128 v[150:153], v154 offset:2048
	ds_read_b128 v[154:157], v154 offset:3072
	ds_read_b128 v[158:161], v178
	ds_read_b128 v[170:173], v178 offset:1024
	ds_read_b128 v[174:177], v178 offset:2048
	ds_read_b128 v[178:181], v178 offset:3072
	s_mov_b32 m0, s78
	v_lshl_add_u64 v[220:221], s[56:57], 0, v[136:137]
	ds_read_b128 v[182:185], v168 offset:32768
	ds_read_b128 v[186:189], v168 offset:33792
	ds_read_b128 v[190:193], v168 offset:34816
	ds_read_b128 v[194:197], v168 offset:35840
	ds_read_b128 v[198:201], v168 offset:36864
	ds_read_b128 v[202:205], v168 offset:37888
	ds_read_b128 v[206:209], v168 offset:38912
	ds_read_b128 v[210:213], v168 offset:39936
	global_load_lds_dwordx4 v[220:221], off
	v_lshl_add_u64 v[220:221], s[56:57], 0, v[132:133]
	s_mov_b32 m0, s81
	s_nop 0
	global_load_lds_dwordx4 v[220:221], off
	s_waitcnt vmcnt(8)
	s_waitcnt lgkmcnt(0)
	s_barrier
	s_waitcnt lgkmcnt(0)
	v_mfma_f32_16x16x32_bf16 v[126:129], v[142:145], v[182:185], v[126:129]
	v_mfma_f32_16x16x32_bf16 v[122:125], v[150:153], v[182:185], v[122:125]
	v_mfma_f32_16x16x32_bf16 v[110:113], v[142:145], v[190:193], v[110:113]
	v_mfma_f32_16x16x32_bf16 v[106:109], v[150:153], v[190:193], v[106:109]
	v_mfma_f32_16x16x32_bf16 v[94:97], v[142:145], v[198:201], v[94:97]
	v_mfma_f32_16x16x32_bf16 v[90:93], v[150:153], v[198:201], v[90:93]
	v_mfma_f32_16x16x32_bf16 v[78:81], v[142:145], v[206:209], v[78:81]
	v_mfma_f32_16x16x32_bf16 v[74:77], v[150:153], v[206:209], v[74:77]
	v_mfma_f32_16x16x32_bf16 v[126:129], v[146:149], v[186:189], v[126:129]
	v_mfma_f32_16x16x32_bf16 v[122:125], v[154:157], v[186:189], v[122:125]
	v_mfma_f32_16x16x32_bf16 v[110:113], v[146:149], v[194:197], v[110:113]
	v_mfma_f32_16x16x32_bf16 v[106:109], v[154:157], v[194:197], v[106:109]
	v_mfma_f32_16x16x32_bf16 v[94:97], v[146:149], v[202:205], v[94:97]
	v_mfma_f32_16x16x32_bf16 v[90:93], v[154:157], v[202:205], v[90:93]
	v_mfma_f32_16x16x32_bf16 v[78:81], v[146:149], v[210:213], v[78:81]
	v_mfma_f32_16x16x32_bf16 v[74:77], v[154:157], v[210:213], v[74:77]
	v_mfma_f32_16x16x32_bf16 v[118:121], v[158:161], v[182:185], v[118:121]
	v_mfma_f32_16x16x32_bf16 v[114:117], v[174:177], v[182:185], v[114:117]
	v_mfma_f32_16x16x32_bf16 v[102:105], v[158:161], v[190:193], v[102:105]
	v_mfma_f32_16x16x32_bf16 v[98:101], v[174:177], v[190:193], v[98:101]
	v_mfma_f32_16x16x32_bf16 v[86:89], v[158:161], v[198:201], v[86:89]
	v_mfma_f32_16x16x32_bf16 v[82:85], v[174:177], v[198:201], v[82:85]
	v_mfma_f32_16x16x32_bf16 v[70:73], v[158:161], v[206:209], v[70:73]
	v_mfma_f32_16x16x32_bf16 v[66:69], v[174:177], v[206:209], v[66:69]
	v_mfma_f32_16x16x32_bf16 v[118:121], v[170:173], v[186:189], v[118:121]
	v_mfma_f32_16x16x32_bf16 v[114:117], v[178:181], v[186:189], v[114:117]
	v_mfma_f32_16x16x32_bf16 v[102:105], v[170:173], v[194:197], v[102:105]
	v_mfma_f32_16x16x32_bf16 v[98:101], v[178:181], v[194:197], v[98:101]
	v_mfma_f32_16x16x32_bf16 v[86:89], v[170:173], v[202:205], v[86:89]
	v_mfma_f32_16x16x32_bf16 v[82:85], v[178:181], v[202:205], v[82:85]
	v_mfma_f32_16x16x32_bf16 v[70:73], v[170:173], v[210:213], v[70:73]
	v_mfma_f32_16x16x32_bf16 v[66:69], v[178:181], v[210:213], v[66:69]
	s_barrier
; #define PG8_STAGE(bufoff, gbase, voff) do { _Pragma("unroll") for (int _i = 0; _i < 2; ++_i) \
;         __builtin_amdgcn_global_load_lds((const unsigned*)((const char*)(gbase) + (voff)[_i]), (LAS unsigned*)(lds + (bufoff) + ldsw + _i * 8192), 16, 0, 0); } while (0)
; #define PG8_LDA(dst, b, h) do { _Pragma("unroll") for (int m = 0; m < 4; ++m) _Pragma("unroll") for (int k = 0; k < 2; ++k) dst[m][k] = *(const LAS bf16x8*)(lds + PG8_SA(b, h) + aoff + m * 2048 + k * 1024); } while (0)
; #define PG8_LDB(dst, b, h) do { _Pragma("unroll") for (int n = 0; n < 2; ++n) _Pragma("unroll") for (int k = 0; k < 2; ++k) dst[n][k] = *(const LAS bf16x8*)(lds + PG8_SB(b, h) + boff + n * 2048 + k * 1024); } while (0)
; #define PG8_MMA(ai, bj, At, Bt) do { __builtin_amdgcn_s_setprio(1); _Pragma("unroll") for (int m = 0; m < 4; ++m) _Pragma("unroll") for (int n = 0; n < 2; ++n) _Pragma("unroll") for (int k = 0; k < 2; ++k) \
;         acc[ai][bj][m][n] = __builtin_amdgcn_mfma_f32_16x16x32_bf16(Bt[n][k], At[m][k], acc[ai][bj][m][n], 0, 0, 0); __builtin_amdgcn_s_setprio(0); } while (0)
; #define PG8_WAIT_V(n) asm volatile("s_waitcnt vmcnt(" #n ")" ::: "memory")
; #define PG8_WAIT_L(n) asm volatile("s_waitcnt lgkmcnt(" #n ")" ::: "memory")
; #define PG8_BAR __builtin_amdgcn_s_barrier()
; #define PG8_SCHED __builtin_amdgcn_sched_barrier(0)
; template <class Epi>
; __device__ __forceinline__ void gemm_phase(LAS unsigned char* lds, const Gemm g, int G, int c, const Epi& E) {
;     ...
;             PG8_LDB(B0, 1, 0); PG8_LDB(B1, 1, 1); PG8_SCHED; PG8_LDA(At, 1, 0); PG8_STAGE(PG8_SA(0, 1), a2 + hstepA, voffA);
;             PG8_WAIT_V(8); PG8_WAIT_L(0); PG8_BAR; PG8_MMA(0, 0, At, B0); PG8_MMA(0, 1, At, B1); PG8_BAR; PG8_SCHED;
;             PG8_LDA(At, 1, 1); PG8_STAGE(PG8_SB(1, 0), b3, voffB); PG8_STAGE(PG8_SB(1, 1), b3 + hstepB, voffB); PG8_STAGE(PG8_SA(1, 0), a3, voffA);
;             PG8_WAIT_V(8); PG8_WAIT_L(0); PG8_BAR; PG8_MMA(1, 0, At, B0); PG8_MMA(1, 1, At, B1); PG8_BAR; PG8_SCHED;
;         }
;         if (wr == 0) PG8_BAR;
	s_mov_b32 m0, s96
	v_lshl_add_u64 v[162:163], v[162:163], 0, s[18:19]
	ds_read_b128 v[182:185], v168 offset:49152
	ds_read_b128 v[186:189], v168 offset:50176
	ds_read_b128 v[190:193], v168 offset:51200
	ds_read_b128 v[194:197], v168 offset:52224
	ds_read_b128 v[198:201], v168 offset:53248
	ds_read_b128 v[202:205], v168 offset:54272
	ds_read_b128 v[206:209], v168 offset:55296
	ds_read_b128 v[210:213], v168 offset:56320
	global_load_lds_dwordx4 v[162:163], off
	v_lshl_add_u64 v[162:163], v[214:215], 0, s[18:19]
	s_mov_b32 m0, s39
	s_nop 0
	global_load_lds_dwordx4 v[162:163], off
	v_lshl_add_u64 v[162:163], s[54:55], 0, v[134:135]
	s_mov_b32 m0, s95
	s_nop 0
	global_load_lds_dwordx4 v[162:163], off
	v_lshl_add_u64 v[162:163], s[54:55], 0, v[130:131]
	s_mov_b32 m0, s38
	s_nop 0
	global_load_lds_dwordx4 v[162:163], off
	v_lshl_add_u64 v[162:163], v[216:217], 0, s[18:19]
	s_mov_b32 m0, s84
	s_nop 0
	global_load_lds_dwordx4 v[162:163], off
	v_lshl_add_u64 v[162:163], v[218:219], 0, s[18:19]
	s_mov_b32 m0, s85
	s_nop 0
	global_load_lds_dwordx4 v[162:163], off
	s_waitcnt vmcnt(8)
	s_waitcnt lgkmcnt(0)
	s_barrier
	s_waitcnt lgkmcnt(0)
	v_mfma_f32_16x16x32_bf16 v[62:65], v[142:145], v[182:185], v[62:65]
	v_mfma_f32_16x16x32_bf16 v[58:61], v[150:153], v[182:185], v[58:61]
	v_mfma_f32_16x16x32_bf16 v[46:49], v[142:145], v[190:193], v[46:49]
	v_mfma_f32_16x16x32_bf16 v[42:45], v[150:153], v[190:193], v[42:45]
	v_mfma_f32_16x16x32_bf16 v[30:33], v[142:145], v[198:201], v[30:33]
	v_mfma_f32_16x16x32_bf16 v[26:29], v[150:153], v[198:201], v[26:29]
	v_mfma_f32_16x16x32_bf16 v[14:17], v[142:145], v[206:209], v[14:17]
	v_mfma_f32_16x16x32_bf16 v[10:13], v[150:153], v[206:209], v[10:13]
	v_mfma_f32_16x16x32_bf16 v[62:65], v[146:149], v[186:189], v[62:65]
	v_mfma_f32_16x16x32_bf16 v[58:61], v[154:157], v[186:189], v[58:61]
	v_mfma_f32_16x16x32_bf16 v[46:49], v[146:149], v[194:197], v[46:49]
	v_mfma_f32_16x16x32_bf16 v[42:45], v[154:157], v[194:197], v[42:45]
	v_mfma_f32_16x16x32_bf16 v[30:33], v[146:149], v[202:205], v[30:33]
	v_mfma_f32_16x16x32_bf16 v[26:29], v[154:157], v[202:205], v[26:29]
	v_mfma_f32_16x16x32_bf16 v[14:17], v[146:149], v[210:213], v[14:17]
	v_mfma_f32_16x16x32_bf16 v[10:13], v[154:157], v[210:213], v[10:13]
	v_mfma_f32_16x16x32_bf16 v[54:57], v[158:161], v[182:185], v[54:57]
	v_mfma_f32_16x16x32_bf16 v[50:53], v[174:177], v[182:185], v[50:53]
	v_mfma_f32_16x16x32_bf16 v[38:41], v[158:161], v[190:193], v[38:41]
	v_mfma_f32_16x16x32_bf16 v[34:37], v[174:177], v[190:193], v[34:37]
	v_mfma_f32_16x16x32_bf16 v[22:25], v[158:161], v[198:201], v[22:25]
	v_mfma_f32_16x16x32_bf16 v[18:21], v[174:177], v[198:201], v[18:21]
	v_mfma_f32_16x16x32_bf16 v[6:9], v[158:161], v[206:209], v[6:9]
	v_mfma_f32_16x16x32_bf16 v[2:5], v[174:177], v[206:209], v[2:5]
	v_mfma_f32_16x16x32_bf16 v[54:57], v[170:173], v[186:189], v[54:57]
	v_mfma_f32_16x16x32_bf16 v[50:53], v[178:181], v[186:189], v[50:53]
	v_mfma_f32_16x16x32_bf16 v[38:41], v[170:173], v[194:197], v[38:41]
	v_mfma_f32_16x16x32_bf16 v[34:37], v[178:181], v[194:197], v[34:37]
	v_mfma_f32_16x16x32_bf16 v[22:25], v[170:173], v[202:205], v[22:25]
	v_mfma_f32_16x16x32_bf16 v[18:21], v[178:181], v[202:205], v[18:21]
	v_mfma_f32_16x16x32_bf16 v[6:9], v[170:173], v[210:213], v[6:9]
	v_mfma_f32_16x16x32_bf16 v[2:5], v[178:181], v[210:213], v[2:5]
	s_barrier
	s_movk_i32 s38, 0x100
	s_andn2_b64 vcc, exec, s[4:5]
	s_mov_b64 s[54:55], -1
	s_mov_b64 s[4:5], 0
	s_cbranch_vccz .LBB0_594
	s_and_b64 vcc, exec, s[20:21]
	s_cbranch_vccz .LBB0_597
	s_barrier

; #define PG8_STAGE(bufoff, gbase, voff) do { _Pragma("unroll") for (int _i = 0; _i < 2; ++_i) \
;         __builtin_amdgcn_global_load_lds((const unsigned*)((const char*)(gbase) + (voff)[_i]), (LAS unsigned*)(lds + (bufoff) + ldsw + _i * 8192), 16, 0, 0); } while (0)
; #define PG8_LDA(dst, b, h) do { _Pragma("unroll") for (int m = 0; m < 4; ++m) _Pragma("unroll") for (int k = 0; k < 2; ++k) dst[m][k] = *(const LAS bf16x8*)(lds + PG8_SA(b, h) + aoff + m * 2048 + k * 1024); } while (0)
; #define PG8_LDB(dst, b, h) do { _Pragma("unroll") for (int n = 0; n < 2; ++n) _Pragma("unroll") for (int k = 0; k < 2; ++k) dst[n][k] = *(const LAS bf16x8*)(lds + PG8_SB(b, h) + boff + n * 2048 + k * 1024); } while (0)
; #define PG8_MMA(ai, bj, At, Bt) do { __builtin_amdgcn_s_setprio(1); _Pragma("unroll") for (int m = 0; m < 4; ++m) _Pragma("unroll") for (int n = 0; n < 2; ++n) _Pragma("unroll") for (int k = 0; k < 2; ++k) \
;         acc[ai][bj][m][n] = __builtin_amdgcn_mfma_f32_16x16x32_bf16(Bt[n][k], At[m][k], acc[ai][bj][m][n], 0, 0, 0); __builtin_amdgcn_s_setprio(0); } while (0)
; #define PG8_WAIT_V(n) asm volatile("s_waitcnt vmcnt(" #n ")" ::: "memory")
; #define PG8_WAIT_L(n) asm volatile("s_waitcnt lgkmcnt(" #n ")" ::: "memory")
; #define PG8_BAR __builtin_amdgcn_s_barrier()
; #define PG8_SCHED __builtin_amdgcn_sched_barrier(0)
; template <class Epi>
; __device__ __forceinline__ void gemm_phase(LAS unsigned char* lds, const Gemm g, int G, int c, const Epi& E) {
;     ...
;             const bool last = (t == nt - 2);
;             const char* a1 = cA + (size_t)(t + 1) * kstep;
;             const char* a2 = last ? nA : cA + (size_t)(t + 2) * kstep; const char* b2 = last ? nB : cB + (size_t)(t + 2) * kstep;
;             const char* a3 = a2 + kstep; const char* b3 = b2 + kstep;
;             PG8_LDB(B0, 0, 0); PG8_LDB(B1, 0, 1); PG8_SCHED; PG8_LDA(At, 0, 0); PG8_STAGE(PG8_SA(1, 1), a1 + hstepA, voffA);
;             PG8_WAIT_V(8); PG8_WAIT_L(0); PG8_BAR; PG8_MMA(0, 0, At, B0); PG8_MMA(0, 1, At, B1); PG8_BAR; PG8_SCHED;
.LBB0_765:
	ds_read_b128 v[146:149], v152
	ds_read_b128 v[156:159], v152 offset:1024
	ds_read_b128 v[160:163], v152 offset:2048
	ds_read_b128 v[164:167], v152 offset:3072
	ds_read_b128 v[168:171], v153
	ds_read_b128 v[172:175], v153 offset:1024
	ds_read_b128 v[176:179], v153 offset:2048
	ds_read_b128 v[180:183], v153 offset:3072
	s_add_u32 s33, s44, 0xfff00080
	s_addc_u32 s46, s45, -1
	s_cmp_eq_u32 s83, 60
	s_cselect_b32 s53, s15, s46
	s_cselect_b32 s52, s78, s33
	s_cselect_b32 s47, s11, s82
	s_cselect_b32 s46, s13, s81
	v_lshl_add_u64 v[216:217], s[44:45], 0, v[138:139]
	s_add_i32 m0, s17, 0xc000
	ds_read_b128 v[184:187], v154
	ds_read_b128 v[188:191], v154 offset:1024
	ds_read_b128 v[192:195], v154 offset:2048
	ds_read_b128 v[196:199], v154 offset:3072
	ds_read_b128 v[200:203], v154 offset:4096
	ds_read_b128 v[204:207], v154 offset:5120
	ds_read_b128 v[208:211], v154 offset:6144
	ds_read_b128 v[212:215], v154 offset:7168
	global_load_lds_dwordx4 v[216:217], off
	v_lshl_add_u64 v[216:217], s[44:45], 0, v[140:141]
	s_add_i32 m0, s17, 0xe000
	s_nop 0
	global_load_lds_dwordx4 v[216:217], off
	s_waitcnt vmcnt(8)
	s_waitcnt lgkmcnt(0)
	s_barrier
	s_waitcnt lgkmcnt(0)
	v_mfma_f32_16x16x32_bf16 v[126:129], v[146:149], v[184:187], v[126:129]
	v_mfma_f32_16x16x32_bf16 v[122:125], v[160:163], v[184:187], v[122:125]
	v_mfma_f32_16x16x32_bf16 v[118:121], v[146:149], v[192:195], v[118:121]
	v_mfma_f32_16x16x32_bf16 v[110:113], v[160:163], v[192:195], v[110:113]
	v_mfma_f32_16x16x32_bf16 v[102:105], v[146:149], v[200:203], v[102:105]
	v_mfma_f32_16x16x32_bf16 v[94:97], v[160:163], v[200:203], v[94:97]
	v_mfma_f32_16x16x32_bf16 v[86:89], v[146:149], v[208:211], v[86:89]
	v_mfma_f32_16x16x32_bf16 v[78:81], v[160:163], v[208:211], v[78:81]
	v_mfma_f32_16x16x32_bf16 v[126:129], v[156:159], v[188:191], v[126:129]
	v_mfma_f32_16x16x32_bf16 v[122:125], v[164:167], v[188:191], v[122:125]
	v_mfma_f32_16x16x32_bf16 v[118:121], v[156:159], v[196:199], v[118:121]
	v_mfma_f32_16x16x32_bf16 v[110:113], v[164:167], v[196:199], v[110:113]
	v_mfma_f32_16x16x32_bf16 v[102:105], v[156:159], v[204:207], v[102:105]
	v_mfma_f32_16x16x32_bf16 v[94:97], v[164:167], v[204:207], v[94:97]
	v_mfma_f32_16x16x32_bf16 v[86:89], v[156:159], v[212:215], v[86:89]
	v_mfma_f32_16x16x32_bf16 v[78:81], v[164:167], v[212:215], v[78:81]
	v_mfma_f32_16x16x32_bf16 v[114:117], v[168:171], v[184:187], v[114:117]
	v_mfma_f32_16x16x32_bf16 v[106:109], v[176:179], v[184:187], v[106:109]
	v_mfma_f32_16x16x32_bf16 v[98:101], v[168:171], v[192:195], v[98:101]
	v_mfma_f32_16x16x32_bf16 v[90:93], v[176:179], v[192:195], v[90:93]
	v_mfma_f32_16x16x32_bf16 v[82:85], v[168:171], v[200:203], v[82:85]
	v_mfma_f32_16x16x32_bf16 v[74:77], v[176:179], v[200:203], v[74:77]
	v_mfma_f32_16x16x32_bf16 v[70:73], v[168:171], v[208:211], v[70:73]
	v_mfma_f32_16x16x32_bf16 v[66:69], v[176:179], v[208:211], v[66:69]
	v_mfma_f32_16x16x32_bf16 v[114:117], v[172:175], v[188:191], v[114:117]
	v_mfma_f32_16x16x32_bf16 v[106:109], v[180:183], v[188:191], v[106:109]
	v_mfma_f32_16x16x32_bf16 v[98:101], v[172:175], v[196:199], v[98:101]
	v_mfma_f32_16x16x32_bf16 v[90:93], v[180:183], v[196:199], v[90:93]
	v_mfma_f32_16x16x32_bf16 v[82:85], v[172:175], v[204:207], v[82:85]
	v_mfma_f32_16x16x32_bf16 v[74:77], v[180:183], v[204:207], v[74:77]
	v_mfma_f32_16x16x32_bf16 v[70:73], v[172:175], v[212:215], v[70:73]
	v_mfma_f32_16x16x32_bf16 v[66:69], v[180:183], v[212:215], v[66:69]
	s_barrier
	s_add_i32 s33, s72, s61
	v_lshl_add_u64 v[216:217], s[46:47], 0, v[134:135]
	s_mov_b32 m0, s33
	ds_read_b128 v[184:187], v154 offset:16384
	ds_read_b128 v[188:191], v154 offset:17408
	ds_read_b128 v[192:195], v154 offset:18432
	ds_read_b128 v[196:199], v154 offset:19456
	ds_read_b128 v[200:203], v154 offset:20480
	ds_read_b128 v[204:207], v154 offset:21504
	ds_read_b128 v[208:211], v154 offset:22528
	ds_read_b128 v[212:215], v154 offset:23552
	global_load_lds_dwordx4 v[216:217], off
	s_add_i32 m0, s33, 0x2000
	s_add_u32 s62, s46, 0x100000
	v_lshl_add_u64 v[218:219], s[46:47], 0, v[130:131]
	s_addc_u32 s63, s47, 0
	s_add_i32 s33, s73, s61
	global_load_lds_dwordx4 v[218:219], off
	v_lshl_add_u64 v[220:221], s[62:63], 0, v[134:135]
	s_mov_b32 m0, s33
	v_lshl_add_u64 v[224:225], s[52:53], 0, v[132:133]
	global_load_lds_dwordx4 v[220:221], off
	v_lshl_add_u64 v[220:221], s[62:63], 0, v[130:131]
	s_add_i32 m0, s33, 0x2000
	s_nop 0
	global_load_lds_dwordx4 v[220:221], off
	v_lshl_add_u64 v[220:221], s[52:53], 0, v[136:137]
	s_mov_b32 m0, s17
	s_nop 0
	global_load_lds_dwordx4 v[220:221], off
	s_mov_b32 m0, s39
	s_nop 0
	global_load_lds_dwordx4 v[224:225], off
	s_waitcnt vmcnt(8)
	s_waitcnt lgkmcnt(0)
	s_barrier
; #define PG8_STAGE(bufoff, gbase, voff) do { _Pragma("unroll") for (int _i = 0; _i < 2; ++_i) \
;         __builtin_amdgcn_global_load_lds((const unsigned*)((const char*)(gbase) + (voff)[_i]), (LAS unsigned*)(lds + (bufoff) + ldsw + _i * 8192), 16, 0, 0); } while (0)
; #define PG8_LDA(dst, b, h) do { _Pragma("unroll") for (int m = 0; m < 4; ++m) _Pragma("unroll") for (int k = 0; k < 2; ++k) dst[m][k] = *(const LAS bf16x8*)(lds + PG8_SA(b, h) + aoff + m * 2048 + k * 1024); } while (0)
; #define PG8_LDB(dst, b, h) do { _Pragma("unroll") for (int n = 0; n < 2; ++n) _Pragma("unroll") for (int k = 0; k < 2; ++k) dst[n][k] = *(const LAS bf16x8*)(lds + PG8_SB(b, h) + boff + n * 2048 + k * 1024); } while (0)
; #define PG8_MMA(ai, bj, At, Bt) do { __builtin_amdgcn_s_setprio(1); _Pragma("unroll") for (int m = 0; m < 4; ++m) _Pragma("unroll") for (int n = 0; n < 2; ++n) _Pragma("unroll") for (int k = 0; k < 2; ++k) \
;         acc[ai][bj][m][n] = __builtin_amdgcn_mfma_f32_16x16x32_bf16(Bt[n][k], At[m][k], acc[ai][bj][m][n], 0, 0, 0); __builtin_amdgcn_s_setprio(0); } while (0)
; #define PG8_WAIT_V(n) asm volatile("s_waitcnt vmcnt(" #n ")" ::: "memory")
; #define PG8_WAIT_L(n) asm volatile("s_waitcnt lgkmcnt(" #n ")" ::: "memory")
; #define PG8_BAR __builtin_amdgcn_s_barrier()
; #define PG8_SCHED __builtin_amdgcn_sched_barrier(0)
; template <class Epi>
; __device__ __forceinline__ void gemm_phase(LAS unsigned char* lds, const Gemm g, int G, int c, const Epi& E) {
;     ...
;             PG8_WAIT_V(8); PG8_WAIT_L(0); PG8_BAR; PG8_MMA(0, 0, At, B0); PG8_MMA(0, 1, At, B1); PG8_BAR; PG8_SCHED;
;             PG8_LDA(At, 0, 1); PG8_STAGE(PG8_SB(0, 0), b2, voffB); PG8_STAGE(PG8_SB(0, 1), b2 + hstepB, voffB); PG8_STAGE(PG8_SA(0, 0), a2, voffA);
;             PG8_WAIT_V(8); PG8_WAIT_L(0); PG8_BAR; PG8_MMA(1, 0, At, B0); PG8_MMA(1, 1, At, B1); PG8_BAR; PG8_SCHED;
;             PG8_LDB(B0, 1, 0); PG8_LDB(B1, 1, 1); PG8_SCHED; PG8_LDA(At, 1, 0); PG8_STAGE(PG8_SA(0, 1), a2 + hstepA, voffA);
;             PG8_WAIT_V(8); PG8_WAIT_L(0); PG8_BAR; PG8_MMA(0, 0, At, B0); PG8_MMA(0, 1, At, B1); PG8_BAR; PG8_SCHED;
;             PG8_LDA(At, 1, 1); PG8_STAGE(PG8_SB(1, 0), b3, voffB); PG8_STAGE(PG8_SB(1, 1), b3 + hstepB, voffB); PG8_STAGE(PG8_SA(1, 0), a3, voffA);
	s_waitcnt lgkmcnt(0)
	v_mfma_f32_16x16x32_bf16 v[62:65], v[146:149], v[184:187], v[62:65]
	v_mfma_f32_16x16x32_bf16 v[58:61], v[160:163], v[184:187], v[58:61]
	v_mfma_f32_16x16x32_bf16 v[54:57], v[146:149], v[192:195], v[54:57]
	v_mfma_f32_16x16x32_bf16 v[46:49], v[160:163], v[192:195], v[46:49]
	v_mfma_f32_16x16x32_bf16 v[38:41], v[146:149], v[200:203], v[38:41]
	v_mfma_f32_16x16x32_bf16 v[30:33], v[160:163], v[200:203], v[30:33]
	v_mfma_f32_16x16x32_bf16 v[22:25], v[146:149], v[208:211], v[22:25]
	v_mfma_f32_16x16x32_bf16 v[14:17], v[160:163], v[208:211], v[14:17]
	v_mfma_f32_16x16x32_bf16 v[62:65], v[156:159], v[188:191], v[62:65]
	v_mfma_f32_16x16x32_bf16 v[58:61], v[164:167], v[188:191], v[58:61]
	v_mfma_f32_16x16x32_bf16 v[54:57], v[156:159], v[196:199], v[54:57]
	v_mfma_f32_16x16x32_bf16 v[46:49], v[164:167], v[196:199], v[46:49]
	v_mfma_f32_16x16x32_bf16 v[38:41], v[156:159], v[204:207], v[38:41]
	v_mfma_f32_16x16x32_bf16 v[30:33], v[164:167], v[204:207], v[30:33]
	v_mfma_f32_16x16x32_bf16 v[22:25], v[156:159], v[212:215], v[22:25]
	v_mfma_f32_16x16x32_bf16 v[14:17], v[164:167], v[212:215], v[14:17]
	v_mfma_f32_16x16x32_bf16 v[50:53], v[168:171], v[184:187], v[50:53]
	v_mfma_f32_16x16x32_bf16 v[42:45], v[176:179], v[184:187], v[42:45]
	v_mfma_f32_16x16x32_bf16 v[34:37], v[168:171], v[192:195], v[34:37]
	v_mfma_f32_16x16x32_bf16 v[26:29], v[176:179], v[192:195], v[26:29]
	v_mfma_f32_16x16x32_bf16 v[18:21], v[168:171], v[200:203], v[18:21]
	v_mfma_f32_16x16x32_bf16 v[10:13], v[176:179], v[200:203], v[10:13]
	v_mfma_f32_16x16x32_bf16 v[6:9], v[168:171], v[208:211], v[6:9]
	v_mfma_f32_16x16x32_bf16 v[2:5], v[176:179], v[208:211], v[2:5]
	v_mfma_f32_16x16x32_bf16 v[50:53], v[172:175], v[188:191], v[50:53]
	v_mfma_f32_16x16x32_bf16 v[42:45], v[180:183], v[188:191], v[42:45]
	v_mfma_f32_16x16x32_bf16 v[34:37], v[172:175], v[196:199], v[34:37]
	v_mfma_f32_16x16x32_bf16 v[26:29], v[180:183], v[196:199], v[26:29]
	v_mfma_f32_16x16x32_bf16 v[18:21], v[172:175], v[204:207], v[18:21]
	v_mfma_f32_16x16x32_bf16 v[10:13], v[180:183], v[204:207], v[10:13]
	v_mfma_f32_16x16x32_bf16 v[6:9], v[172:175], v[212:215], v[6:9]
	v_mfma_f32_16x16x32_bf16 v[2:5], v[180:183], v[212:215], v[2:5]
	s_barrier
	s_add_i32 s33, 0, 0x18000
	v_add_u32_e32 v155, s33, v151
	s_add_i32 s62, 0, 0x1c000
	ds_read_b128 v[146:149], v155
	ds_read_b128 v[156:159], v155 offset:1024
	ds_read_b128 v[160:163], v155 offset:2048
	ds_read_b128 v[164:167], v155 offset:3072
	v_add_u32_e32 v155, s62, v151
	ds_read_b128 v[168:171], v155
	ds_read_b128 v[172:175], v155 offset:1024
	ds_read_b128 v[176:179], v155 offset:2048
	ds_read_b128 v[180:183], v155 offset:3072
	s_add_u32 s52, s52, 0x100000
	s_addc_u32 s53, s53, 0
	s_mov_b32 m0, s43
	v_lshl_add_u64 v[226:227], s[52:53], 0, v[136:137]
	ds_read_b128 v[184:187], v154 offset:32768
	ds_read_b128 v[188:191], v154 offset:33792
	ds_read_b128 v[192:195], v154 offset:34816
	ds_read_b128 v[196:199], v154 offset:35840
	ds_read_b128 v[200:203], v154 offset:36864
	ds_read_b128 v[204:207], v154 offset:37888
	ds_read_b128 v[208:211], v154 offset:38912
	ds_read_b128 v[212:215], v154 offset:39936
	global_load_lds_dwordx4 v[226:227], off
	v_lshl_add_u64 v[226:227], s[52:53], 0, v[132:133]
	s_mov_b32 m0, s66
	s_nop 0
	global_load_lds_dwordx4 v[226:227], off
	s_waitcnt vmcnt(8)
	s_waitcnt lgkmcnt(0)
	s_barrier
	s_waitcnt lgkmcnt(0)
	v_mfma_f32_16x16x32_bf16 v[126:129], v[146:149], v[184:187], v[126:129]
	v_mfma_f32_16x16x32_bf16 v[122:125], v[160:163], v[184:187], v[122:125]
	v_mfma_f32_16x16x32_bf16 v[118:121], v[146:149], v[192:195], v[118:121]
	v_mfma_f32_16x16x32_bf16 v[110:113], v[160:163], v[192:195], v[110:113]
	v_mfma_f32_16x16x32_bf16 v[102:105], v[146:149], v[200:203], v[102:105]
	v_mfma_f32_16x16x32_bf16 v[94:97], v[160:163], v[200:203], v[94:97]
	v_mfma_f32_16x16x32_bf16 v[86:89], v[146:149], v[208:211], v[86:89]
	v_mfma_f32_16x16x32_bf16 v[78:81], v[160:163], v[208:211], v[78:81]
	v_mfma_f32_16x16x32_bf16 v[126:129], v[156:159], v[188:191], v[126:129]
	v_mfma_f32_16x16x32_bf16 v[122:125], v[164:167], v[188:191], v[122:125]
	v_mfma_f32_16x16x32_bf16 v[118:121], v[156:159], v[196:199], v[118:121]
	v_mfma_f32_16x16x32_bf16 v[110:113], v[164:167], v[196:199], v[110:113]
	v_mfma_f32_16x16x32_bf16 v[102:105], v[156:159], v[204:207], v[102:105]
	v_mfma_f32_16x16x32_bf16 v[94:97], v[164:167], v[204:207], v[94:97]
	v_mfma_f32_16x16x32_bf16 v[86:89], v[156:159], v[212:215], v[86:89]
	v_mfma_f32_16x16x32_bf16 v[78:81], v[164:167], v[212:215], v[78:81]
	v_mfma_f32_16x16x32_bf16 v[114:117], v[168:171], v[184:187], v[114:117]
	v_mfma_f32_16x16x32_bf16 v[106:109], v[176:179], v[184:187], v[106:109]
	v_mfma_f32_16x16x32_bf16 v[98:101], v[168:171], v[192:195], v[98:101]
	v_mfma_f32_16x16x32_bf16 v[90:93], v[176:179], v[192:195], v[90:93]
	v_mfma_f32_16x16x32_bf16 v[82:85], v[168:171], v[200:203], v[82:85]
	v_mfma_f32_16x16x32_bf16 v[74:77], v[176:179], v[200:203], v[74:77]
	v_mfma_f32_16x16x32_bf16 v[70:73], v[168:171], v[208:211], v[70:73]
	v_mfma_f32_16x16x32_bf16 v[66:69], v[176:179], v[208:211], v[66:69]
	v_mfma_f32_16x16x32_bf16 v[114:117], v[172:175], v[188:191], v[114:117]
	v_mfma_f32_16x16x32_bf16 v[106:109], v[180:183], v[188:191], v[106:109]
	v_mfma_f32_16x16x32_bf16 v[98:101], v[172:175], v[196:199], v[98:101]
	v_mfma_f32_16x16x32_bf16 v[90:93], v[180:183], v[196:199], v[90:93]
	v_mfma_f32_16x16x32_bf16 v[82:85], v[172:175], v[204:207], v[82:85]
	v_mfma_f32_16x16x32_bf16 v[74:77], v[180:183], v[204:207], v[74:77]
	v_mfma_f32_16x16x32_bf16 v[70:73], v[172:175], v[212:215], v[70:73]
	v_mfma_f32_16x16x32_bf16 v[66:69], v[180:183], v[212:215], v[66:69]
	s_barrier
; #define PG8_STAGE(bufoff, gbase, voff) do { _Pragma("unroll") for (int _i = 0; _i < 2; ++_i) \
;         __builtin_amdgcn_global_load_lds((const unsigned*)((const char*)(gbase) + (voff)[_i]), (LAS unsigned*)(lds + (bufoff) + ldsw + _i * 8192), 16, 0, 0); } while (0)
; #define PG8_LDA(dst, b, h) do { _Pragma("unroll") for (int m = 0; m < 4; ++m) _Pragma("unroll") for (int k = 0; k < 2; ++k) dst[m][k] = *(const LAS bf16x8*)(lds + PG8_SA(b, h) + aoff + m * 2048 + k * 1024); } while (0)
; #define PG8_LDB(dst, b, h) do { _Pragma("unroll") for (int n = 0; n < 2; ++n) _Pragma("unroll") for (int k = 0; k < 2; ++k) dst[n][k] = *(const LAS bf16x8*)(lds + PG8_SB(b, h) + boff + n * 2048 + k * 1024); } while (0)
; #define PG8_MMA(ai, bj, At, Bt) do { __builtin_amdgcn_s_setprio(1); _Pragma("unroll") for (int m = 0; m < 4; ++m) _Pragma("unroll") for (int n = 0; n < 2; ++n) _Pragma("unroll") for (int k = 0; k < 2; ++k) \
;         acc[ai][bj][m][n] = __builtin_amdgcn_mfma_f32_16x16x32_bf16(Bt[n][k], At[m][k], acc[ai][bj][m][n], 0, 0, 0); __builtin_amdgcn_s_setprio(0); } while (0)
; #define PG8_WAIT_V(n) asm volatile("s_waitcnt vmcnt(" #n ")" ::: "memory")
; #define PG8_WAIT_L(n) asm volatile("s_waitcnt lgkmcnt(" #n ")" ::: "memory")
; #define PG8_BAR __builtin_amdgcn_s_barrier()
; #define PG8_SCHED __builtin_amdgcn_sched_barrier(0)
; template <class Epi>
; __device__ __forceinline__ void gemm_phase(LAS unsigned char* lds, const Gemm g, int G, int c, const Epi& E) {
;     ...
;             PG8_LDB(B0, 1, 0); PG8_LDB(B1, 1, 1); PG8_SCHED; PG8_LDA(At, 1, 0); PG8_STAGE(PG8_SA(0, 1), a2 + hstepA, voffA);
;             PG8_WAIT_V(8); PG8_WAIT_L(0); PG8_BAR; PG8_MMA(0, 0, At, B0); PG8_MMA(0, 1, At, B1); PG8_BAR; PG8_SCHED;
;             PG8_LDA(At, 1, 1); PG8_STAGE(PG8_SB(1, 0), b3, voffB); PG8_STAGE(PG8_SB(1, 1), b3 + hstepB, voffB); PG8_STAGE(PG8_SA(1, 0), a3, voffA);
;             PG8_WAIT_V(8); PG8_WAIT_L(0); PG8_BAR; PG8_MMA(1, 0, At, B0); PG8_MMA(1, 1, At, B1); PG8_BAR; PG8_SCHED;
;         }
	s_add_i32 s33, s33, s61
	v_lshl_add_u64 v[216:217], v[216:217], 0, s[6:7]
	s_mov_b32 m0, s33
	ds_read_b128 v[184:187], v154 offset:49152
	ds_read_b128 v[188:191], v154 offset:50176
	ds_read_b128 v[192:195], v154 offset:51200
	ds_read_b128 v[196:199], v154 offset:52224
	ds_read_b128 v[200:203], v154 offset:53248
	ds_read_b128 v[204:207], v154 offset:54272
	ds_read_b128 v[208:211], v154 offset:55296
	ds_read_b128 v[212:215], v154 offset:56320
	global_load_lds_dwordx4 v[216:217], off
	s_add_i32 m0, s33, 0x2000
	s_add_u32 s46, s46, 0x100080
	v_lshl_add_u64 v[216:217], v[218:219], 0, s[6:7]
	s_addc_u32 s47, s47, 0
	s_add_i32 s33, s62, s61
	global_load_lds_dwordx4 v[216:217], off
	v_lshl_add_u64 v[216:217], s[46:47], 0, v[134:135]
	s_mov_b32 m0, s33
	s_nop 0
	global_load_lds_dwordx4 v[216:217], off
	v_lshl_add_u64 v[216:217], s[46:47], 0, v[130:131]
	s_add_i32 m0, s33, 0x2000
	s_nop 0
	global_load_lds_dwordx4 v[216:217], off
	v_lshl_add_u64 v[216:217], v[220:221], 0, s[6:7]
	s_mov_b32 m0, s70
	s_nop 0
	global_load_lds_dwordx4 v[216:217], off
	v_lshl_add_u64 v[216:217], v[224:225], 0, s[6:7]
	s_mov_b32 m0, s71
	s_nop 0
	global_load_lds_dwordx4 v[216:217], off
	s_waitcnt vmcnt(8)
	s_waitcnt lgkmcnt(0)
	s_barrier
	s_waitcnt lgkmcnt(0)
	v_mfma_f32_16x16x32_bf16 v[62:65], v[146:149], v[184:187], v[62:65]
	v_mfma_f32_16x16x32_bf16 v[58:61], v[160:163], v[184:187], v[58:61]
	v_mfma_f32_16x16x32_bf16 v[54:57], v[146:149], v[192:195], v[54:57]
	v_mfma_f32_16x16x32_bf16 v[46:49], v[160:163], v[192:195], v[46:49]
	v_mfma_f32_16x16x32_bf16 v[38:41], v[146:149], v[200:203], v[38:41]
	v_mfma_f32_16x16x32_bf16 v[30:33], v[160:163], v[200:203], v[30:33]
	v_mfma_f32_16x16x32_bf16 v[22:25], v[146:149], v[208:211], v[22:25]
	v_mfma_f32_16x16x32_bf16 v[14:17], v[160:163], v[208:211], v[14:17]
	v_mfma_f32_16x16x32_bf16 v[62:65], v[156:159], v[188:191], v[62:65]
	v_mfma_f32_16x16x32_bf16 v[58:61], v[164:167], v[188:191], v[58:61]
	v_mfma_f32_16x16x32_bf16 v[54:57], v[156:159], v[196:199], v[54:57]
	v_mfma_f32_16x16x32_bf16 v[46:49], v[164:167], v[196:199], v[46:49]
	v_mfma_f32_16x16x32_bf16 v[38:41], v[156:159], v[204:207], v[38:41]
	v_mfma_f32_16x16x32_bf16 v[30:33], v[164:167], v[204:207], v[30:33]
	v_mfma_f32_16x16x32_bf16 v[22:25], v[156:159], v[212:215], v[22:25]
	v_mfma_f32_16x16x32_bf16 v[14:17], v[164:167], v[212:215], v[14:17]
	v_mfma_f32_16x16x32_bf16 v[50:53], v[168:171], v[184:187], v[50:53]
	v_mfma_f32_16x16x32_bf16 v[42:45], v[176:179], v[184:187], v[42:45]
	v_mfma_f32_16x16x32_bf16 v[34:37], v[168:171], v[192:195], v[34:37]
	v_mfma_f32_16x16x32_bf16 v[26:29], v[176:179], v[192:195], v[26:29]
	v_mfma_f32_16x16x32_bf16 v[18:21], v[168:171], v[200:203], v[18:21]
	v_mfma_f32_16x16x32_bf16 v[10:13], v[176:179], v[200:203], v[10:13]
	v_mfma_f32_16x16x32_bf16 v[6:9], v[168:171], v[208:211], v[6:9]
	v_mfma_f32_16x16x32_bf16 v[2:5], v[176:179], v[208:211], v[2:5]
	v_mfma_f32_16x16x32_bf16 v[50:53], v[172:175], v[188:191], v[50:53]
	v_mfma_f32_16x16x32_bf16 v[42:45], v[180:183], v[188:191], v[42:45]
	v_mfma_f32_16x16x32_bf16 v[34:37], v[172:175], v[196:199], v[34:37]
	v_mfma_f32_16x16x32_bf16 v[26:29], v[180:183], v[196:199], v[26:29]
	v_mfma_f32_16x16x32_bf16 v[18:21], v[172:175], v[204:207], v[18:21]
	v_mfma_f32_16x16x32_bf16 v[10:13], v[180:183], v[204:207], v[10:13]
	v_mfma_f32_16x16x32_bf16 v[6:9], v[172:175], v[212:215], v[6:9]
	v_mfma_f32_16x16x32_bf16 v[2:5], v[180:183], v[212:215], v[2:5]
	s_barrier
	s_add_i32 s83, s83, 2
	s_add_u32 s44, s44, 0x100
	s_addc_u32 s45, s45, 0
	s_add_u32 s81, s81, 0x100
	s_addc_u32 s82, s82, 0
	s_cmp_gt_u32 s83, 61
	s_cbranch_scc0 .LBB0_765
	s_and_b64 vcc, exec, s[8:9]
	s_cbranch_vccz .LBB0_768
	s_barrier

; #define PG8_STAGE(bufoff, gbase, voff) do { _Pragma("unroll") for (int _i = 0; _i < 2; ++_i) \
;         __builtin_amdgcn_global_load_lds((const unsigned*)((const char*)(gbase) + (voff)[_i]), (LAS unsigned*)(lds + (bufoff) + ldsw + _i * 8192), 16, 0, 0); } while (0)
; #define PG8_LDA(dst, b, h) do { _Pragma("unroll") for (int m = 0; m < 4; ++m) _Pragma("unroll") for (int k = 0; k < 2; ++k) dst[m][k] = *(const LAS bf16x8*)(lds + PG8_SA(b, h) + aoff + m * 2048 + k * 1024); } while (0)
; #define PG8_LDB(dst, b, h) do { _Pragma("unroll") for (int n = 0; n < 2; ++n) _Pragma("unroll") for (int k = 0; k < 2; ++k) dst[n][k] = *(const LAS bf16x8*)(lds + PG8_SB(b, h) + boff + n * 2048 + k * 1024); } while (0)
; #define PG8_MMA(ai, bj, At, Bt) do { __builtin_amdgcn_s_setprio(1); _Pragma("unroll") for (int m = 0; m < 4; ++m) _Pragma("unroll") for (int n = 0; n < 2; ++n) _Pragma("unroll") for (int k = 0; k < 2; ++k) \
;         acc[ai][bj][m][n] = __builtin_amdgcn_mfma_f32_16x16x32_bf16(Bt[n][k], At[m][k], acc[ai][bj][m][n], 0, 0, 0); __builtin_amdgcn_s_setprio(0); } while (0)
; #define PG8_WAIT_V(n) asm volatile("s_waitcnt vmcnt(" #n ")" ::: "memory")
; #define PG8_WAIT_L(n) asm volatile("s_waitcnt lgkmcnt(" #n ")" ::: "memory")
; #define PG8_BAR __builtin_amdgcn_s_barrier()
; #define PG8_SCHED __builtin_amdgcn_sched_barrier(0)
; template <class Epi>
; __device__ __forceinline__ void gemm_phase(LAS unsigned char* lds, const Gemm g, int G, int c, const Epi& E) {
;     ...
;             const bool last = (t == nt - 2);
;             const char* a1 = cA + (size_t)(t + 1) * kstep;
;             const char* a2 = last ? nA : cA + (size_t)(t + 2) * kstep; const char* b2 = last ? nB : cB + (size_t)(t + 2) * kstep;
;             const char* a3 = a2 + kstep; const char* b3 = b2 + kstep;
;             PG8_LDB(B0, 0, 0); PG8_LDB(B1, 0, 1); PG8_SCHED; PG8_LDA(At, 0, 0); PG8_STAGE(PG8_SA(1, 1), a1 + hstepA, voffA);
;             PG8_WAIT_V(8); PG8_WAIT_L(0); PG8_BAR; PG8_MMA(0, 0, At, B0); PG8_MMA(0, 1, At, B1); PG8_BAR; PG8_SCHED;
.LBB0_781:
	ds_read_b128 v[150:153], v146
	ds_read_b128 v[154:157], v146 offset:1024
	ds_read_b128 v[158:161], v146 offset:2048
	ds_read_b128 v[162:165], v146 offset:3072
	ds_read_b128 v[166:169], v147
	ds_read_b128 v[170:173], v147 offset:1024
	ds_read_b128 v[174:177], v147 offset:2048
	ds_read_b128 v[178:181], v147 offset:3072
	s_add_u32 s52, s46, 0x100
	s_addc_u32 s53, s47, 0
	s_add_u32 s33, s90, s46
	s_addc_u32 s55, s91, s47
	s_cmp_eq_u32 s92, 4
	s_cselect_b32 s56, 0, s52
	s_cselect_b32 s57, 0, s53
	s_cselect_b32 s54, s89, s33
	s_cselect_b32 s55, s25, s55
	s_add_u32 s56, s2, s56
	s_addc_u32 s57, s3, s57
	s_mov_b32 m0, s83
	v_lshl_add_u64 v[142:143], v[138:139], 0, s[46:47]
	ds_read_b128 v[182:185], v148
	ds_read_b128 v[186:189], v148 offset:1024
	ds_read_b128 v[190:193], v148 offset:2048
	ds_read_b128 v[194:197], v148 offset:3072
	ds_read_b128 v[198:201], v148 offset:4096
	ds_read_b128 v[202:205], v148 offset:5120
	ds_read_b128 v[206:209], v148 offset:6144
	ds_read_b128 v[210:213], v148 offset:7168
	global_load_lds_dwordx4 v[142:143], off
	v_lshl_add_u64 v[142:143], v[140:141], 0, s[46:47]
	s_mov_b32 m0, s84
	s_nop 0
	global_load_lds_dwordx4 v[142:143], off
	s_waitcnt vmcnt(8)
	s_waitcnt lgkmcnt(0)
	s_barrier
	s_waitcnt lgkmcnt(0)
	v_mfma_f32_16x16x32_bf16 v[126:129], v[150:153], v[182:185], v[126:129]
	v_mfma_f32_16x16x32_bf16 v[122:125], v[158:161], v[182:185], v[122:125]
	v_mfma_f32_16x16x32_bf16 v[118:121], v[150:153], v[190:193], v[118:121]
	v_mfma_f32_16x16x32_bf16 v[110:113], v[158:161], v[190:193], v[110:113]
	v_mfma_f32_16x16x32_bf16 v[102:105], v[150:153], v[198:201], v[102:105]
	v_mfma_f32_16x16x32_bf16 v[94:97], v[158:161], v[198:201], v[94:97]
	v_mfma_f32_16x16x32_bf16 v[86:89], v[150:153], v[206:209], v[86:89]
	v_mfma_f32_16x16x32_bf16 v[78:81], v[158:161], v[206:209], v[78:81]
	v_mfma_f32_16x16x32_bf16 v[126:129], v[154:157], v[186:189], v[126:129]
	v_mfma_f32_16x16x32_bf16 v[122:125], v[162:165], v[186:189], v[122:125]
	v_mfma_f32_16x16x32_bf16 v[118:121], v[154:157], v[194:197], v[118:121]
	v_mfma_f32_16x16x32_bf16 v[110:113], v[162:165], v[194:197], v[110:113]
	v_mfma_f32_16x16x32_bf16 v[102:105], v[154:157], v[202:205], v[102:105]
	v_mfma_f32_16x16x32_bf16 v[94:97], v[162:165], v[202:205], v[94:97]
	v_mfma_f32_16x16x32_bf16 v[86:89], v[154:157], v[210:213], v[86:89]
	v_mfma_f32_16x16x32_bf16 v[78:81], v[162:165], v[210:213], v[78:81]
	v_mfma_f32_16x16x32_bf16 v[114:117], v[166:169], v[182:185], v[114:117]
	v_mfma_f32_16x16x32_bf16 v[106:109], v[174:177], v[182:185], v[106:109]
	v_mfma_f32_16x16x32_bf16 v[98:101], v[166:169], v[190:193], v[98:101]
	v_mfma_f32_16x16x32_bf16 v[90:93], v[174:177], v[190:193], v[90:93]
	v_mfma_f32_16x16x32_bf16 v[82:85], v[166:169], v[198:201], v[82:85]
	v_mfma_f32_16x16x32_bf16 v[74:77], v[174:177], v[198:201], v[74:77]
	v_mfma_f32_16x16x32_bf16 v[70:73], v[166:169], v[206:209], v[70:73]
	v_mfma_f32_16x16x32_bf16 v[66:69], v[174:177], v[206:209], v[66:69]
	v_mfma_f32_16x16x32_bf16 v[114:117], v[170:173], v[186:189], v[114:117]
	v_mfma_f32_16x16x32_bf16 v[106:109], v[178:181], v[186:189], v[106:109]
	v_mfma_f32_16x16x32_bf16 v[98:101], v[170:173], v[194:197], v[98:101]
	v_mfma_f32_16x16x32_bf16 v[90:93], v[178:181], v[194:197], v[90:93]
	v_mfma_f32_16x16x32_bf16 v[82:85], v[170:173], v[202:205], v[82:85]
	v_mfma_f32_16x16x32_bf16 v[74:77], v[178:181], v[202:205], v[74:77]
	v_mfma_f32_16x16x32_bf16 v[70:73], v[170:173], v[210:213], v[70:73]
	v_mfma_f32_16x16x32_bf16 v[66:69], v[178:181], v[210:213], v[66:69]
	s_barrier
	s_mov_b32 m0, s85
	v_lshl_add_u64 v[142:143], s[54:55], 0, v[134:135]
	s_add_u32 s46, s54, 0x20000
	ds_read_b128 v[182:185], v148 offset:16384
	ds_read_b128 v[186:189], v148 offset:17408
	ds_read_b128 v[190:193], v148 offset:18432
	ds_read_b128 v[194:197], v148 offset:19456
	ds_read_b128 v[198:201], v148 offset:20480
	ds_read_b128 v[202:205], v148 offset:21504
	ds_read_b128 v[206:209], v148 offset:22528
	ds_read_b128 v[210:213], v148 offset:23552
	global_load_lds_dwordx4 v[142:143], off
	v_lshl_add_u64 v[214:215], s[54:55], 0, v[130:131]
	s_mov_b32 m0, s86
	s_addc_u32 s47, s55, 0
	global_load_lds_dwordx4 v[214:215], off
	v_lshl_add_u64 v[216:217], s[46:47], 0, v[134:135]
	s_mov_b32 m0, s87
	v_lshl_add_u64 v[218:219], s[56:57], 0, v[132:133]
	global_load_lds_dwordx4 v[216:217], off
	v_lshl_add_u64 v[216:217], s[46:47], 0, v[130:131]
	s_mov_b32 m0, s88
	s_nop 0
	global_load_lds_dwordx4 v[216:217], off
	v_lshl_add_u64 v[216:217], s[56:57], 0, v[136:137]
	s_mov_b32 m0, s45
	s_nop 0
	global_load_lds_dwordx4 v[216:217], off
	s_mov_b32 m0, s61
	s_nop 0
	global_load_lds_dwordx4 v[218:219], off
	s_waitcnt vmcnt(8)
	s_waitcnt lgkmcnt(0)
	s_barrier
; #define PG8_STAGE(bufoff, gbase, voff) do { _Pragma("unroll") for (int _i = 0; _i < 2; ++_i) \
;         __builtin_amdgcn_global_load_lds((const unsigned*)((const char*)(gbase) + (voff)[_i]), (LAS unsigned*)(lds + (bufoff) + ldsw + _i * 8192), 16, 0, 0); } while (0)
; #define PG8_LDA(dst, b, h) do { _Pragma("unroll") for (int m = 0; m < 4; ++m) _Pragma("unroll") for (int k = 0; k < 2; ++k) dst[m][k] = *(const LAS bf16x8*)(lds + PG8_SA(b, h) + aoff + m * 2048 + k * 1024); } while (0)
; #define PG8_LDB(dst, b, h) do { _Pragma("unroll") for (int n = 0; n < 2; ++n) _Pragma("unroll") for (int k = 0; k < 2; ++k) dst[n][k] = *(const LAS bf16x8*)(lds + PG8_SB(b, h) + boff + n * 2048 + k * 1024); } while (0)
; #define PG8_MMA(ai, bj, At, Bt) do { __builtin_amdgcn_s_setprio(1); _Pragma("unroll") for (int m = 0; m < 4; ++m) _Pragma("unroll") for (int n = 0; n < 2; ++n) _Pragma("unroll") for (int k = 0; k < 2; ++k) \
;         acc[ai][bj][m][n] = __builtin_amdgcn_mfma_f32_16x16x32_bf16(Bt[n][k], At[m][k], acc[ai][bj][m][n], 0, 0, 0); __builtin_amdgcn_s_setprio(0); } while (0)
; #define PG8_WAIT_V(n) asm volatile("s_waitcnt vmcnt(" #n ")" ::: "memory")
; #define PG8_WAIT_L(n) asm volatile("s_waitcnt lgkmcnt(" #n ")" ::: "memory")
; #define PG8_BAR __builtin_amdgcn_s_barrier()
; #define PG8_SCHED __builtin_amdgcn_sched_barrier(0)
; template <class Epi>
; __device__ __forceinline__ void gemm_phase(LAS unsigned char* lds, const Gemm g, int G, int c, const Epi& E) {
;     ...
;             PG8_WAIT_V(8); PG8_WAIT_L(0); PG8_BAR; PG8_MMA(0, 0, At, B0); PG8_MMA(0, 1, At, B1); PG8_BAR; PG8_SCHED;
;             PG8_LDA(At, 0, 1); PG8_STAGE(PG8_SB(0, 0), b2, voffB); PG8_STAGE(PG8_SB(0, 1), b2 + hstepB, voffB); PG8_STAGE(PG8_SA(0, 0), a2, voffA);
;             PG8_WAIT_V(8); PG8_WAIT_L(0); PG8_BAR; PG8_MMA(1, 0, At, B0); PG8_MMA(1, 1, At, B1); PG8_BAR; PG8_SCHED;
;             PG8_LDB(B0, 1, 0); PG8_LDB(B1, 1, 1); PG8_SCHED; PG8_LDA(At, 1, 0); PG8_STAGE(PG8_SA(0, 1), a2 + hstepA, voffA);
;             PG8_WAIT_V(8); PG8_WAIT_L(0); PG8_BAR; PG8_MMA(0, 0, At, B0); PG8_MMA(0, 1, At, B1); PG8_BAR; PG8_SCHED;
;             PG8_LDA(At, 1, 1); PG8_STAGE(PG8_SB(1, 0), b3, voffB); PG8_STAGE(PG8_SB(1, 1), b3 + hstepB, voffB); PG8_STAGE(PG8_SA(1, 0), a3, voffA);
	s_waitcnt lgkmcnt(0)
	v_mfma_f32_16x16x32_bf16 v[62:65], v[150:153], v[182:185], v[62:65]
	v_mfma_f32_16x16x32_bf16 v[58:61], v[158:161], v[182:185], v[58:61]
	v_mfma_f32_16x16x32_bf16 v[54:57], v[150:153], v[190:193], v[54:57]
	v_mfma_f32_16x16x32_bf16 v[46:49], v[158:161], v[190:193], v[46:49]
	v_mfma_f32_16x16x32_bf16 v[38:41], v[150:153], v[198:201], v[38:41]
	v_mfma_f32_16x16x32_bf16 v[30:33], v[158:161], v[198:201], v[30:33]
	v_mfma_f32_16x16x32_bf16 v[22:25], v[150:153], v[206:209], v[22:25]
	v_mfma_f32_16x16x32_bf16 v[14:17], v[158:161], v[206:209], v[14:17]
	v_mfma_f32_16x16x32_bf16 v[62:65], v[154:157], v[186:189], v[62:65]
	v_mfma_f32_16x16x32_bf16 v[58:61], v[162:165], v[186:189], v[58:61]
	v_mfma_f32_16x16x32_bf16 v[54:57], v[154:157], v[194:197], v[54:57]
	v_mfma_f32_16x16x32_bf16 v[46:49], v[162:165], v[194:197], v[46:49]
	v_mfma_f32_16x16x32_bf16 v[38:41], v[154:157], v[202:205], v[38:41]
	v_mfma_f32_16x16x32_bf16 v[30:33], v[162:165], v[202:205], v[30:33]
	v_mfma_f32_16x16x32_bf16 v[22:25], v[154:157], v[210:213], v[22:25]
	v_mfma_f32_16x16x32_bf16 v[14:17], v[162:165], v[210:213], v[14:17]
	v_mfma_f32_16x16x32_bf16 v[50:53], v[166:169], v[182:185], v[50:53]
	v_mfma_f32_16x16x32_bf16 v[42:45], v[174:177], v[182:185], v[42:45]
	v_mfma_f32_16x16x32_bf16 v[34:37], v[166:169], v[190:193], v[34:37]
	v_mfma_f32_16x16x32_bf16 v[26:29], v[174:177], v[190:193], v[26:29]
	v_mfma_f32_16x16x32_bf16 v[18:21], v[166:169], v[198:201], v[18:21]
	v_mfma_f32_16x16x32_bf16 v[10:13], v[174:177], v[198:201], v[10:13]
	v_mfma_f32_16x16x32_bf16 v[6:9], v[166:169], v[206:209], v[6:9]
	v_mfma_f32_16x16x32_bf16 v[2:5], v[174:177], v[206:209], v[2:5]
	v_mfma_f32_16x16x32_bf16 v[50:53], v[170:173], v[186:189], v[50:53]
	v_mfma_f32_16x16x32_bf16 v[42:45], v[178:181], v[186:189], v[42:45]
	v_mfma_f32_16x16x32_bf16 v[34:37], v[170:173], v[194:197], v[34:37]
	v_mfma_f32_16x16x32_bf16 v[26:29], v[178:181], v[194:197], v[26:29]
	v_mfma_f32_16x16x32_bf16 v[18:21], v[170:173], v[202:205], v[18:21]
	v_mfma_f32_16x16x32_bf16 v[10:13], v[178:181], v[202:205], v[10:13]
	v_mfma_f32_16x16x32_bf16 v[6:9], v[170:173], v[210:213], v[6:9]
	v_mfma_f32_16x16x32_bf16 v[2:5], v[178:181], v[210:213], v[2:5]
	s_barrier
	s_add_i32 s33, 0, 0x18000
	v_add_u32_e32 v149, s33, v145
	s_add_i32 s62, 0, 0x1c000
	ds_read_b128 v[150:153], v149
	ds_read_b128 v[154:157], v149 offset:1024
	ds_read_b128 v[158:161], v149 offset:2048
	ds_read_b128 v[162:165], v149 offset:3072
	v_add_u32_e32 v149, s62, v145
	ds_read_b128 v[166:169], v149
	ds_read_b128 v[170:173], v149 offset:1024
	ds_read_b128 v[174:177], v149 offset:2048
	ds_read_b128 v[178:181], v149 offset:3072
	s_add_u32 s46, s56, 0x20000
	s_addc_u32 s47, s57, 0
	s_mov_b32 m0, s66
	v_lshl_add_u64 v[220:221], s[46:47], 0, v[136:137]
	ds_read_b128 v[182:185], v148 offset:32768
	ds_read_b128 v[186:189], v148 offset:33792
	ds_read_b128 v[190:193], v148 offset:34816
	ds_read_b128 v[194:197], v148 offset:35840
	ds_read_b128 v[198:201], v148 offset:36864
	ds_read_b128 v[202:205], v148 offset:37888
	ds_read_b128 v[206:209], v148 offset:38912
	ds_read_b128 v[210:213], v148 offset:39936
	global_load_lds_dwordx4 v[220:221], off
	v_lshl_add_u64 v[220:221], s[46:47], 0, v[132:133]
	s_mov_b32 m0, s67
	s_nop 0
	global_load_lds_dwordx4 v[220:221], off
	s_waitcnt vmcnt(8)
	s_waitcnt lgkmcnt(0)
	s_barrier
	s_waitcnt lgkmcnt(0)
	v_mfma_f32_16x16x32_bf16 v[126:129], v[150:153], v[182:185], v[126:129]
	v_mfma_f32_16x16x32_bf16 v[122:125], v[158:161], v[182:185], v[122:125]
	v_mfma_f32_16x16x32_bf16 v[118:121], v[150:153], v[190:193], v[118:121]
	v_mfma_f32_16x16x32_bf16 v[110:113], v[158:161], v[190:193], v[110:113]
	v_mfma_f32_16x16x32_bf16 v[102:105], v[150:153], v[198:201], v[102:105]
	v_mfma_f32_16x16x32_bf16 v[94:97], v[158:161], v[198:201], v[94:97]
	v_mfma_f32_16x16x32_bf16 v[86:89], v[150:153], v[206:209], v[86:89]
	v_mfma_f32_16x16x32_bf16 v[78:81], v[158:161], v[206:209], v[78:81]
	v_mfma_f32_16x16x32_bf16 v[126:129], v[154:157], v[186:189], v[126:129]
	v_mfma_f32_16x16x32_bf16 v[122:125], v[162:165], v[186:189], v[122:125]
	v_mfma_f32_16x16x32_bf16 v[118:121], v[154:157], v[194:197], v[118:121]
	v_mfma_f32_16x16x32_bf16 v[110:113], v[162:165], v[194:197], v[110:113]
	v_mfma_f32_16x16x32_bf16 v[102:105], v[154:157], v[202:205], v[102:105]
	v_mfma_f32_16x16x32_bf16 v[94:97], v[162:165], v[202:205], v[94:97]
	v_mfma_f32_16x16x32_bf16 v[86:89], v[154:157], v[210:213], v[86:89]
	v_mfma_f32_16x16x32_bf16 v[78:81], v[162:165], v[210:213], v[78:81]
	v_mfma_f32_16x16x32_bf16 v[114:117], v[166:169], v[182:185], v[114:117]
	v_mfma_f32_16x16x32_bf16 v[106:109], v[174:177], v[182:185], v[106:109]
	v_mfma_f32_16x16x32_bf16 v[98:101], v[166:169], v[190:193], v[98:101]
	v_mfma_f32_16x16x32_bf16 v[90:93], v[174:177], v[190:193], v[90:93]
	v_mfma_f32_16x16x32_bf16 v[82:85], v[166:169], v[198:201], v[82:85]
	v_mfma_f32_16x16x32_bf16 v[74:77], v[174:177], v[198:201], v[74:77]
	v_mfma_f32_16x16x32_bf16 v[70:73], v[166:169], v[206:209], v[70:73]
	v_mfma_f32_16x16x32_bf16 v[66:69], v[174:177], v[206:209], v[66:69]
	v_mfma_f32_16x16x32_bf16 v[114:117], v[170:173], v[186:189], v[114:117]
	v_mfma_f32_16x16x32_bf16 v[106:109], v[178:181], v[186:189], v[106:109]
	v_mfma_f32_16x16x32_bf16 v[98:101], v[170:173], v[194:197], v[98:101]
	v_mfma_f32_16x16x32_bf16 v[90:93], v[178:181], v[194:197], v[90:93]
	v_mfma_f32_16x16x32_bf16 v[82:85], v[170:173], v[202:205], v[82:85]
	v_mfma_f32_16x16x32_bf16 v[74:77], v[178:181], v[202:205], v[74:77]
	v_mfma_f32_16x16x32_bf16 v[70:73], v[170:173], v[210:213], v[70:73]
	v_mfma_f32_16x16x32_bf16 v[66:69], v[178:181], v[210:213], v[66:69]
	s_barrier
; #define PG8_STAGE(bufoff, gbase, voff) do { _Pragma("unroll") for (int _i = 0; _i < 2; ++_i) \
;         __builtin_amdgcn_global_load_lds((const unsigned*)((const char*)(gbase) + (voff)[_i]), (LAS unsigned*)(lds + (bufoff) + ldsw + _i * 8192), 16, 0, 0); } while (0)
; #define PG8_LDA(dst, b, h) do { _Pragma("unroll") for (int m = 0; m < 4; ++m) _Pragma("unroll") for (int k = 0; k < 2; ++k) dst[m][k] = *(const LAS bf16x8*)(lds + PG8_SA(b, h) + aoff + m * 2048 + k * 1024); } while (0)
; #define PG8_LDB(dst, b, h) do { _Pragma("unroll") for (int n = 0; n < 2; ++n) _Pragma("unroll") for (int k = 0; k < 2; ++k) dst[n][k] = *(const LAS bf16x8*)(lds + PG8_SB(b, h) + boff + n * 2048 + k * 1024); } while (0)
; #define PG8_MMA(ai, bj, At, Bt) do { __builtin_amdgcn_s_setprio(1); _Pragma("unroll") for (int m = 0; m < 4; ++m) _Pragma("unroll") for (int n = 0; n < 2; ++n) _Pragma("unroll") for (int k = 0; k < 2; ++k) \
;         acc[ai][bj][m][n] = __builtin_amdgcn_mfma_f32_16x16x32_bf16(Bt[n][k], At[m][k], acc[ai][bj][m][n], 0, 0, 0); __builtin_amdgcn_s_setprio(0); } while (0)
; #define PG8_WAIT_V(n) asm volatile("s_waitcnt vmcnt(" #n ")" ::: "memory")
; #define PG8_WAIT_L(n) asm volatile("s_waitcnt lgkmcnt(" #n ")" ::: "memory")
; #define PG8_BAR __builtin_amdgcn_s_barrier()
; #define PG8_SCHED __builtin_amdgcn_sched_barrier(0)
; template <class Epi>
; __device__ __forceinline__ void gemm_phase(LAS unsigned char* lds, const Gemm g, int G, int c, const Epi& E) {
;     ...
;             PG8_LDB(B0, 1, 0); PG8_LDB(B1, 1, 1); PG8_SCHED; PG8_LDA(At, 1, 0); PG8_STAGE(PG8_SA(0, 1), a2 + hstepA, voffA);
;             PG8_WAIT_V(8); PG8_WAIT_L(0); PG8_BAR; PG8_MMA(0, 0, At, B0); PG8_MMA(0, 1, At, B1); PG8_BAR; PG8_SCHED;
;             PG8_LDA(At, 1, 1); PG8_STAGE(PG8_SB(1, 0), b3, voffB); PG8_STAGE(PG8_SB(1, 1), b3 + hstepB, voffB); PG8_STAGE(PG8_SA(1, 0), a3, voffA);
;             PG8_WAIT_V(8); PG8_WAIT_L(0); PG8_BAR; PG8_MMA(1, 0, At, B0); PG8_MMA(1, 1, At, B1); PG8_BAR; PG8_SCHED;
;         }
	s_add_i32 s33, s33, s58
	v_lshl_add_u64 v[142:143], v[142:143], 0, s[6:7]
	s_mov_b32 m0, s33
	ds_read_b128 v[182:185], v148 offset:49152
	ds_read_b128 v[186:189], v148 offset:50176
	ds_read_b128 v[190:193], v148 offset:51200
	ds_read_b128 v[194:197], v148 offset:52224
	ds_read_b128 v[198:201], v148 offset:53248
	ds_read_b128 v[202:205], v148 offset:54272
	ds_read_b128 v[206:209], v148 offset:55296
	ds_read_b128 v[210:213], v148 offset:56320
	global_load_lds_dwordx4 v[142:143], off
	s_add_i32 m0, s33, 0x2000
	s_add_u32 s46, s54, 0x20080
	v_lshl_add_u64 v[142:143], v[214:215], 0, s[6:7]
	s_addc_u32 s47, s55, 0
	s_add_i32 s33, s62, s58
	global_load_lds_dwordx4 v[142:143], off
	v_lshl_add_u64 v[142:143], s[46:47], 0, v[134:135]
	s_mov_b32 m0, s33
	s_nop 0
	global_load_lds_dwordx4 v[142:143], off
	v_lshl_add_u64 v[142:143], s[46:47], 0, v[130:131]
	s_add_i32 m0, s33, 0x2000
	s_nop 0
	global_load_lds_dwordx4 v[142:143], off
	v_lshl_add_u64 v[142:143], v[216:217], 0, s[6:7]
	s_mov_b32 m0, s71
	s_nop 0
	global_load_lds_dwordx4 v[142:143], off
	v_lshl_add_u64 v[142:143], v[218:219], 0, s[6:7]
	s_mov_b32 m0, s72
	s_nop 0
	global_load_lds_dwordx4 v[142:143], off
	s_waitcnt vmcnt(8)
	s_waitcnt lgkmcnt(0)
	s_barrier
	s_waitcnt lgkmcnt(0)
	v_mfma_f32_16x16x32_bf16 v[62:65], v[150:153], v[182:185], v[62:65]
	v_mfma_f32_16x16x32_bf16 v[58:61], v[158:161], v[182:185], v[58:61]
	v_mfma_f32_16x16x32_bf16 v[54:57], v[150:153], v[190:193], v[54:57]
	v_mfma_f32_16x16x32_bf16 v[46:49], v[158:161], v[190:193], v[46:49]
	v_mfma_f32_16x16x32_bf16 v[38:41], v[150:153], v[198:201], v[38:41]
	v_mfma_f32_16x16x32_bf16 v[30:33], v[158:161], v[198:201], v[30:33]
	v_mfma_f32_16x16x32_bf16 v[22:25], v[150:153], v[206:209], v[22:25]
	v_mfma_f32_16x16x32_bf16 v[14:17], v[158:161], v[206:209], v[14:17]
	v_mfma_f32_16x16x32_bf16 v[62:65], v[154:157], v[186:189], v[62:65]
	v_mfma_f32_16x16x32_bf16 v[58:61], v[162:165], v[186:189], v[58:61]
	v_mfma_f32_16x16x32_bf16 v[54:57], v[154:157], v[194:197], v[54:57]
	v_mfma_f32_16x16x32_bf16 v[46:49], v[162:165], v[194:197], v[46:49]
	v_mfma_f32_16x16x32_bf16 v[38:41], v[154:157], v[202:205], v[38:41]
	v_mfma_f32_16x16x32_bf16 v[30:33], v[162:165], v[202:205], v[30:33]
	v_mfma_f32_16x16x32_bf16 v[22:25], v[154:157], v[210:213], v[22:25]
	v_mfma_f32_16x16x32_bf16 v[14:17], v[162:165], v[210:213], v[14:17]
	v_mfma_f32_16x16x32_bf16 v[50:53], v[166:169], v[182:185], v[50:53]
	v_mfma_f32_16x16x32_bf16 v[42:45], v[174:177], v[182:185], v[42:45]
	v_mfma_f32_16x16x32_bf16 v[34:37], v[166:169], v[190:193], v[34:37]
	v_mfma_f32_16x16x32_bf16 v[26:29], v[174:177], v[190:193], v[26:29]
	v_mfma_f32_16x16x32_bf16 v[18:21], v[166:169], v[198:201], v[18:21]
	v_mfma_f32_16x16x32_bf16 v[10:13], v[174:177], v[198:201], v[10:13]
	v_mfma_f32_16x16x32_bf16 v[6:9], v[166:169], v[206:209], v[6:9]
	v_mfma_f32_16x16x32_bf16 v[2:5], v[174:177], v[206:209], v[2:5]
	v_mfma_f32_16x16x32_bf16 v[50:53], v[170:173], v[186:189], v[50:53]
	v_mfma_f32_16x16x32_bf16 v[42:45], v[178:181], v[186:189], v[42:45]
	v_mfma_f32_16x16x32_bf16 v[34:37], v[170:173], v[194:197], v[34:37]
	v_mfma_f32_16x16x32_bf16 v[26:29], v[178:181], v[194:197], v[26:29]
	v_mfma_f32_16x16x32_bf16 v[18:21], v[170:173], v[202:205], v[18:21]
	v_mfma_f32_16x16x32_bf16 v[10:13], v[178:181], v[202:205], v[10:13]
	v_mfma_f32_16x16x32_bf16 v[6:9], v[170:173], v[210:213], v[6:9]
	v_mfma_f32_16x16x32_bf16 v[2:5], v[178:181], v[210:213], v[2:5]
	s_barrier
	s_add_i32 s92, s92, 2
	s_cmp_gt_u32 s92, 5
	s_mov_b64 s[46:47], s[52:53]
	s_cbranch_scc0 .LBB0_781
	s_and_b64 vcc, exec, s[8:9]
	s_cbranch_vccz .LBB0_784
	s_barrier

; #define PG8_STAGE(bufoff, gbase, voff) do { _Pragma("unroll") for (int _i = 0; _i < 2; ++_i) \
;         __builtin_amdgcn_global_load_lds((const unsigned*)((const char*)(gbase) + (voff)[_i]), (LAS unsigned*)(lds + (bufoff) + ldsw + _i * 8192), 16, 0, 0); } while (0)
; #define PG8_LDA(dst, b, h) do { _Pragma("unroll") for (int m = 0; m < 4; ++m) _Pragma("unroll") for (int k = 0; k < 2; ++k) dst[m][k] = *(const LAS bf16x8*)(lds + PG8_SA(b, h) + aoff + m * 2048 + k * 1024); } while (0)
; #define PG8_LDB(dst, b, h) do { _Pragma("unroll") for (int n = 0; n < 2; ++n) _Pragma("unroll") for (int k = 0; k < 2; ++k) dst[n][k] = *(const LAS bf16x8*)(lds + PG8_SB(b, h) + boff + n * 2048 + k * 1024); } while (0)
; #define PG8_MMA(ai, bj, At, Bt) do { __builtin_amdgcn_s_setprio(1); _Pragma("unroll") for (int m = 0; m < 4; ++m) _Pragma("unroll") for (int n = 0; n < 2; ++n) _Pragma("unroll") for (int k = 0; k < 2; ++k) \
;         acc[ai][bj][m][n] = __builtin_amdgcn_mfma_f32_16x16x32_bf16(Bt[n][k], At[m][k], acc[ai][bj][m][n], 0, 0, 0); __builtin_amdgcn_s_setprio(0); } while (0)
; #define PG8_WAIT_V(n) asm volatile("s_waitcnt vmcnt(" #n ")" ::: "memory")
; #define PG8_WAIT_L(n) asm volatile("s_waitcnt lgkmcnt(" #n ")" ::: "memory")
; #define PG8_BAR __builtin_amdgcn_s_barrier()
; #define PG8_SCHED __builtin_amdgcn_sched_barrier(0)
; template <class Epi>
; __device__ __forceinline__ void gemm_phase(LAS unsigned char* lds, const Gemm g, int G, int c, const Epi& E) {
;     ...
;             const bool last = (t == nt - 2);
;             const char* a1 = cA + (size_t)(t + 1) * kstep;
;             const char* a2 = last ? nA : cA + (size_t)(t + 2) * kstep; const char* b2 = last ? nB : cB + (size_t)(t + 2) * kstep;
;             const char* a3 = a2 + kstep; const char* b3 = b2 + kstep;
;             PG8_LDB(B0, 0, 0); PG8_LDB(B1, 0, 1); PG8_SCHED; PG8_LDA(At, 0, 0); PG8_STAGE(PG8_SA(1, 1), a1 + hstepA, voffA);
;             PG8_WAIT_V(8); PG8_WAIT_L(0); PG8_BAR; PG8_MMA(0, 0, At, B0); PG8_MMA(0, 1, At, B1); PG8_BAR; PG8_SCHED;
.LBB0_903:
	ds_read_b128 v[130:133], v170
	ds_read_b128 v[134:137], v170 offset:1024
	ds_read_b128 v[138:141], v170 offset:2048
	ds_read_b128 v[142:145], v170 offset:3072
	ds_read_b128 v[162:165], v171
	ds_read_b128 v[174:177], v171 offset:1024
	ds_read_b128 v[178:181], v171 offset:2048
	ds_read_b128 v[182:185], v171 offset:3072
	s_add_u32 s33, s4, 0xfffc0080
	s_addc_u32 s42, s5, -1
	s_cmp_eq_u32 s46, 12
	s_cselect_b32 s45, s19, s42
	s_cselect_b32 s44, s18, s33
	s_cselect_b32 s43, s15, s39
	s_cselect_b32 s42, s17, s23
	v_lshl_add_u64 v[166:167], s[4:5], 0, v[154:155]
	s_add_i32 m0, s25, 0xc000
	ds_read_b128 v[186:189], v172
	ds_read_b128 v[190:193], v172 offset:1024
	ds_read_b128 v[194:197], v172 offset:2048
	ds_read_b128 v[198:201], v172 offset:3072
	ds_read_b128 v[202:205], v172 offset:4096
	ds_read_b128 v[206:209], v172 offset:5120
	ds_read_b128 v[210:213], v172 offset:6144
	ds_read_b128 v[214:217], v172 offset:7168
	global_load_lds_dwordx4 v[166:167], off
	v_lshl_add_u64 v[166:167], s[4:5], 0, v[156:157]
	s_add_i32 m0, s25, 0xe000
	s_nop 0
	global_load_lds_dwordx4 v[166:167], off
	s_waitcnt vmcnt(8)
	s_waitcnt lgkmcnt(0)
	s_barrier
	s_waitcnt lgkmcnt(0)
	v_mfma_f32_16x16x32_bf16 v[126:129], v[130:133], v[186:189], v[126:129]
	v_mfma_f32_16x16x32_bf16 v[122:125], v[138:141], v[186:189], v[122:125]
	v_mfma_f32_16x16x32_bf16 v[110:113], v[130:133], v[194:197], v[110:113]
	v_mfma_f32_16x16x32_bf16 v[106:109], v[138:141], v[194:197], v[106:109]
	v_mfma_f32_16x16x32_bf16 v[94:97], v[130:133], v[202:205], v[94:97]
	v_mfma_f32_16x16x32_bf16 v[90:93], v[138:141], v[202:205], v[90:93]
	v_mfma_f32_16x16x32_bf16 v[78:81], v[130:133], v[210:213], v[78:81]
	v_mfma_f32_16x16x32_bf16 v[74:77], v[138:141], v[210:213], v[74:77]
	v_mfma_f32_16x16x32_bf16 v[126:129], v[134:137], v[190:193], v[126:129]
	v_mfma_f32_16x16x32_bf16 v[122:125], v[142:145], v[190:193], v[122:125]
	v_mfma_f32_16x16x32_bf16 v[110:113], v[134:137], v[198:201], v[110:113]
	v_mfma_f32_16x16x32_bf16 v[106:109], v[142:145], v[198:201], v[106:109]
	v_mfma_f32_16x16x32_bf16 v[94:97], v[134:137], v[206:209], v[94:97]
	v_mfma_f32_16x16x32_bf16 v[90:93], v[142:145], v[206:209], v[90:93]
	v_mfma_f32_16x16x32_bf16 v[78:81], v[134:137], v[214:217], v[78:81]
	v_mfma_f32_16x16x32_bf16 v[74:77], v[142:145], v[214:217], v[74:77]
	v_mfma_f32_16x16x32_bf16 v[118:121], v[162:165], v[186:189], v[118:121]
	v_mfma_f32_16x16x32_bf16 v[114:117], v[178:181], v[186:189], v[114:117]
	v_mfma_f32_16x16x32_bf16 v[102:105], v[162:165], v[194:197], v[102:105]
	v_mfma_f32_16x16x32_bf16 v[98:101], v[178:181], v[194:197], v[98:101]
	v_mfma_f32_16x16x32_bf16 v[86:89], v[162:165], v[202:205], v[86:89]
	v_mfma_f32_16x16x32_bf16 v[82:85], v[178:181], v[202:205], v[82:85]
	v_mfma_f32_16x16x32_bf16 v[70:73], v[162:165], v[210:213], v[70:73]
	v_mfma_f32_16x16x32_bf16 v[66:69], v[178:181], v[210:213], v[66:69]
	v_mfma_f32_16x16x32_bf16 v[118:121], v[174:177], v[190:193], v[118:121]
	v_mfma_f32_16x16x32_bf16 v[114:117], v[182:185], v[190:193], v[114:117]
	v_mfma_f32_16x16x32_bf16 v[102:105], v[174:177], v[198:201], v[102:105]
	v_mfma_f32_16x16x32_bf16 v[98:101], v[182:185], v[198:201], v[98:101]
	v_mfma_f32_16x16x32_bf16 v[86:89], v[174:177], v[206:209], v[86:89]
	v_mfma_f32_16x16x32_bf16 v[82:85], v[182:185], v[206:209], v[82:85]
	v_mfma_f32_16x16x32_bf16 v[70:73], v[174:177], v[214:217], v[70:73]
	v_mfma_f32_16x16x32_bf16 v[66:69], v[182:185], v[214:217], v[66:69]
	s_barrier
	s_add_i32 s33, s72, s54
	v_lshl_add_u64 v[166:167], s[42:43], 0, v[150:151]
	s_mov_b32 m0, s33
	ds_read_b128 v[186:189], v172 offset:16384
	ds_read_b128 v[190:193], v172 offset:17408
	ds_read_b128 v[194:197], v172 offset:18432
	ds_read_b128 v[198:201], v172 offset:19456
	ds_read_b128 v[202:205], v172 offset:20480
	ds_read_b128 v[206:209], v172 offset:21504
	ds_read_b128 v[210:213], v172 offset:22528
	ds_read_b128 v[214:217], v172 offset:23552
	global_load_lds_dwordx4 v[166:167], off
	s_add_i32 m0, s33, 0x2000
	s_add_u32 s62, s42, 0x40000
	v_lshl_add_u64 v[218:219], s[42:43], 0, v[146:147]
	s_addc_u32 s63, s43, 0
	s_add_i32 s33, s73, s54
	global_load_lds_dwordx4 v[218:219], off
	v_lshl_add_u64 v[220:221], s[62:63], 0, v[150:151]
	s_mov_b32 m0, s33
	v_lshl_add_u64 v[222:223], s[44:45], 0, v[148:149]
	global_load_lds_dwordx4 v[220:221], off
	v_lshl_add_u64 v[220:221], s[62:63], 0, v[146:147]
	s_add_i32 m0, s33, 0x2000
	s_nop 0
	global_load_lds_dwordx4 v[220:221], off
	v_lshl_add_u64 v[220:221], s[44:45], 0, v[152:153]
	s_mov_b32 m0, s25
	s_nop 0
	global_load_lds_dwordx4 v[220:221], off
	s_mov_b32 m0, s57
	s_nop 0
	global_load_lds_dwordx4 v[222:223], off
	s_waitcnt vmcnt(8)
	s_waitcnt lgkmcnt(0)
	s_barrier
; #define PG8_STAGE(bufoff, gbase, voff) do { _Pragma("unroll") for (int _i = 0; _i < 2; ++_i) \
;         __builtin_amdgcn_global_load_lds((const unsigned*)((const char*)(gbase) + (voff)[_i]), (LAS unsigned*)(lds + (bufoff) + ldsw + _i * 8192), 16, 0, 0); } while (0)
; #define PG8_LDA(dst, b, h) do { _Pragma("unroll") for (int m = 0; m < 4; ++m) _Pragma("unroll") for (int k = 0; k < 2; ++k) dst[m][k] = *(const LAS bf16x8*)(lds + PG8_SA(b, h) + aoff + m * 2048 + k * 1024); } while (0)
; #define PG8_LDB(dst, b, h) do { _Pragma("unroll") for (int n = 0; n < 2; ++n) _Pragma("unroll") for (int k = 0; k < 2; ++k) dst[n][k] = *(const LAS bf16x8*)(lds + PG8_SB(b, h) + boff + n * 2048 + k * 1024); } while (0)
; #define PG8_MMA(ai, bj, At, Bt) do { __builtin_amdgcn_s_setprio(1); _Pragma("unroll") for (int m = 0; m < 4; ++m) _Pragma("unroll") for (int n = 0; n < 2; ++n) _Pragma("unroll") for (int k = 0; k < 2; ++k) \
;         acc[ai][bj][m][n] = __builtin_amdgcn_mfma_f32_16x16x32_bf16(Bt[n][k], At[m][k], acc[ai][bj][m][n], 0, 0, 0); __builtin_amdgcn_s_setprio(0); } while (0)
; #define PG8_WAIT_V(n) asm volatile("s_waitcnt vmcnt(" #n ")" ::: "memory")
; #define PG8_WAIT_L(n) asm volatile("s_waitcnt lgkmcnt(" #n ")" ::: "memory")
; #define PG8_BAR __builtin_amdgcn_s_barrier()
; #define PG8_SCHED __builtin_amdgcn_sched_barrier(0)
; template <class Epi>
; __device__ __forceinline__ void gemm_phase(LAS unsigned char* lds, const Gemm g, int G, int c, const Epi& E) {
;     ...
;             PG8_WAIT_V(8); PG8_WAIT_L(0); PG8_BAR; PG8_MMA(0, 0, At, B0); PG8_MMA(0, 1, At, B1); PG8_BAR; PG8_SCHED;
;             PG8_LDA(At, 0, 1); PG8_STAGE(PG8_SB(0, 0), b2, voffB); PG8_STAGE(PG8_SB(0, 1), b2 + hstepB, voffB); PG8_STAGE(PG8_SA(0, 0), a2, voffA);
;             PG8_WAIT_V(8); PG8_WAIT_L(0); PG8_BAR; PG8_MMA(1, 0, At, B0); PG8_MMA(1, 1, At, B1); PG8_BAR; PG8_SCHED;
;             PG8_LDB(B0, 1, 0); PG8_LDB(B1, 1, 1); PG8_SCHED; PG8_LDA(At, 1, 0); PG8_STAGE(PG8_SA(0, 1), a2 + hstepA, voffA);
;             PG8_WAIT_V(8); PG8_WAIT_L(0); PG8_BAR; PG8_MMA(0, 0, At, B0); PG8_MMA(0, 1, At, B1); PG8_BAR; PG8_SCHED;
;             PG8_LDA(At, 1, 1); PG8_STAGE(PG8_SB(1, 0), b3, voffB); PG8_STAGE(PG8_SB(1, 1), b3 + hstepB, voffB); PG8_STAGE(PG8_SA(1, 0), a3, voffA);
	s_waitcnt lgkmcnt(0)
	v_mfma_f32_16x16x32_bf16 v[62:65], v[130:133], v[186:189], v[62:65]
	v_mfma_f32_16x16x32_bf16 v[58:61], v[138:141], v[186:189], v[58:61]
	v_mfma_f32_16x16x32_bf16 v[46:49], v[130:133], v[194:197], v[46:49]
	v_mfma_f32_16x16x32_bf16 v[42:45], v[138:141], v[194:197], v[42:45]
	v_mfma_f32_16x16x32_bf16 v[30:33], v[130:133], v[202:205], v[30:33]
	v_mfma_f32_16x16x32_bf16 v[26:29], v[138:141], v[202:205], v[26:29]
	v_mfma_f32_16x16x32_bf16 v[14:17], v[130:133], v[210:213], v[14:17]
	v_mfma_f32_16x16x32_bf16 v[10:13], v[138:141], v[210:213], v[10:13]
	v_mfma_f32_16x16x32_bf16 v[62:65], v[134:137], v[190:193], v[62:65]
	v_mfma_f32_16x16x32_bf16 v[58:61], v[142:145], v[190:193], v[58:61]
	v_mfma_f32_16x16x32_bf16 v[46:49], v[134:137], v[198:201], v[46:49]
	v_mfma_f32_16x16x32_bf16 v[42:45], v[142:145], v[198:201], v[42:45]
	v_mfma_f32_16x16x32_bf16 v[30:33], v[134:137], v[206:209], v[30:33]
	v_mfma_f32_16x16x32_bf16 v[26:29], v[142:145], v[206:209], v[26:29]
	v_mfma_f32_16x16x32_bf16 v[14:17], v[134:137], v[214:217], v[14:17]
	v_mfma_f32_16x16x32_bf16 v[10:13], v[142:145], v[214:217], v[10:13]
	v_mfma_f32_16x16x32_bf16 v[54:57], v[162:165], v[186:189], v[54:57]
	v_mfma_f32_16x16x32_bf16 v[50:53], v[178:181], v[186:189], v[50:53]
	v_mfma_f32_16x16x32_bf16 v[38:41], v[162:165], v[194:197], v[38:41]
	v_mfma_f32_16x16x32_bf16 v[34:37], v[178:181], v[194:197], v[34:37]
	v_mfma_f32_16x16x32_bf16 v[22:25], v[162:165], v[202:205], v[22:25]
	v_mfma_f32_16x16x32_bf16 v[18:21], v[178:181], v[202:205], v[18:21]
	v_mfma_f32_16x16x32_bf16 v[6:9], v[162:165], v[210:213], v[6:9]
	v_mfma_f32_16x16x32_bf16 v[2:5], v[178:181], v[210:213], v[2:5]
	v_mfma_f32_16x16x32_bf16 v[54:57], v[174:177], v[190:193], v[54:57]
	v_mfma_f32_16x16x32_bf16 v[50:53], v[182:185], v[190:193], v[50:53]
	v_mfma_f32_16x16x32_bf16 v[38:41], v[174:177], v[198:201], v[38:41]
	v_mfma_f32_16x16x32_bf16 v[34:37], v[182:185], v[198:201], v[34:37]
	v_mfma_f32_16x16x32_bf16 v[22:25], v[174:177], v[206:209], v[22:25]
	v_mfma_f32_16x16x32_bf16 v[18:21], v[182:185], v[206:209], v[18:21]
	v_mfma_f32_16x16x32_bf16 v[6:9], v[174:177], v[214:217], v[6:9]
	v_mfma_f32_16x16x32_bf16 v[2:5], v[182:185], v[214:217], v[2:5]
	s_barrier
	s_add_i32 s33, 0, 0x18000
	s_add_i32 s47, 0, 0x1c000
	v_add_u32_e32 v142, s33, v169
	v_add_u32_e32 v173, s47, v169
	ds_read_b128 v[130:133], v142
	ds_read_b128 v[134:137], v142 offset:1024
	ds_read_b128 v[138:141], v142 offset:2048
	ds_read_b128 v[142:145], v142 offset:3072
	ds_read_b128 v[162:165], v173
	ds_read_b128 v[174:177], v173 offset:1024
	ds_read_b128 v[178:181], v173 offset:2048
	ds_read_b128 v[182:185], v173 offset:3072
	s_add_u32 s44, s44, 0x40000
	s_addc_u32 s45, s45, 0
	s_mov_b32 m0, s58
	v_lshl_add_u64 v[224:225], s[44:45], 0, v[152:153]
	ds_read_b128 v[186:189], v172 offset:32768
	ds_read_b128 v[190:193], v172 offset:33792
	ds_read_b128 v[194:197], v172 offset:34816
	ds_read_b128 v[198:201], v172 offset:35840
	ds_read_b128 v[202:205], v172 offset:36864
	ds_read_b128 v[206:209], v172 offset:37888
	ds_read_b128 v[210:213], v172 offset:38912
	ds_read_b128 v[214:217], v172 offset:39936
	global_load_lds_dwordx4 v[224:225], off
	v_lshl_add_u64 v[224:225], s[44:45], 0, v[148:149]
	s_mov_b32 m0, s59
	s_nop 0
	global_load_lds_dwordx4 v[224:225], off
	s_waitcnt vmcnt(8)
	s_waitcnt lgkmcnt(0)
	s_barrier
	s_waitcnt lgkmcnt(0)
	v_mfma_f32_16x16x32_bf16 v[126:129], v[130:133], v[186:189], v[126:129]
	v_mfma_f32_16x16x32_bf16 v[122:125], v[138:141], v[186:189], v[122:125]
	v_mfma_f32_16x16x32_bf16 v[110:113], v[130:133], v[194:197], v[110:113]
	v_mfma_f32_16x16x32_bf16 v[106:109], v[138:141], v[194:197], v[106:109]
	v_mfma_f32_16x16x32_bf16 v[94:97], v[130:133], v[202:205], v[94:97]
	v_mfma_f32_16x16x32_bf16 v[90:93], v[138:141], v[202:205], v[90:93]
	v_mfma_f32_16x16x32_bf16 v[78:81], v[130:133], v[210:213], v[78:81]
	v_mfma_f32_16x16x32_bf16 v[74:77], v[138:141], v[210:213], v[74:77]
	v_mfma_f32_16x16x32_bf16 v[126:129], v[134:137], v[190:193], v[126:129]
	v_mfma_f32_16x16x32_bf16 v[122:125], v[142:145], v[190:193], v[122:125]
	v_mfma_f32_16x16x32_bf16 v[110:113], v[134:137], v[198:201], v[110:113]
	v_mfma_f32_16x16x32_bf16 v[106:109], v[142:145], v[198:201], v[106:109]
	v_mfma_f32_16x16x32_bf16 v[94:97], v[134:137], v[206:209], v[94:97]
	v_mfma_f32_16x16x32_bf16 v[90:93], v[142:145], v[206:209], v[90:93]
	v_mfma_f32_16x16x32_bf16 v[78:81], v[134:137], v[214:217], v[78:81]
	v_mfma_f32_16x16x32_bf16 v[74:77], v[142:145], v[214:217], v[74:77]
	v_mfma_f32_16x16x32_bf16 v[118:121], v[162:165], v[186:189], v[118:121]
	v_mfma_f32_16x16x32_bf16 v[114:117], v[178:181], v[186:189], v[114:117]
	v_mfma_f32_16x16x32_bf16 v[102:105], v[162:165], v[194:197], v[102:105]
	v_mfma_f32_16x16x32_bf16 v[98:101], v[178:181], v[194:197], v[98:101]
	v_mfma_f32_16x16x32_bf16 v[86:89], v[162:165], v[202:205], v[86:89]
	v_mfma_f32_16x16x32_bf16 v[82:85], v[178:181], v[202:205], v[82:85]
	v_mfma_f32_16x16x32_bf16 v[70:73], v[162:165], v[210:213], v[70:73]
	v_mfma_f32_16x16x32_bf16 v[66:69], v[178:181], v[210:213], v[66:69]
	v_mfma_f32_16x16x32_bf16 v[118:121], v[174:177], v[190:193], v[118:121]
	v_mfma_f32_16x16x32_bf16 v[114:117], v[182:185], v[190:193], v[114:117]
	v_mfma_f32_16x16x32_bf16 v[102:105], v[174:177], v[198:201], v[102:105]
	v_mfma_f32_16x16x32_bf16 v[98:101], v[182:185], v[198:201], v[98:101]
	v_mfma_f32_16x16x32_bf16 v[86:89], v[174:177], v[206:209], v[86:89]
	v_mfma_f32_16x16x32_bf16 v[82:85], v[182:185], v[206:209], v[82:85]
	v_mfma_f32_16x16x32_bf16 v[70:73], v[174:177], v[214:217], v[70:73]
	v_mfma_f32_16x16x32_bf16 v[66:69], v[182:185], v[214:217], v[66:69]
	s_barrier
; #define PG8_STAGE(bufoff, gbase, voff) do { _Pragma("unroll") for (int _i = 0; _i < 2; ++_i) \
;         __builtin_amdgcn_global_load_lds((const unsigned*)((const char*)(gbase) + (voff)[_i]), (LAS unsigned*)(lds + (bufoff) + ldsw + _i * 8192), 16, 0, 0); } while (0)
; #define PG8_LDA(dst, b, h) do { _Pragma("unroll") for (int m = 0; m < 4; ++m) _Pragma("unroll") for (int k = 0; k < 2; ++k) dst[m][k] = *(const LAS bf16x8*)(lds + PG8_SA(b, h) + aoff + m * 2048 + k * 1024); } while (0)
; #define PG8_LDB(dst, b, h) do { _Pragma("unroll") for (int n = 0; n < 2; ++n) _Pragma("unroll") for (int k = 0; k < 2; ++k) dst[n][k] = *(const LAS bf16x8*)(lds + PG8_SB(b, h) + boff + n * 2048 + k * 1024); } while (0)
; #define PG8_MMA(ai, bj, At, Bt) do { __builtin_amdgcn_s_setprio(1); _Pragma("unroll") for (int m = 0; m < 4; ++m) _Pragma("unroll") for (int n = 0; n < 2; ++n) _Pragma("unroll") for (int k = 0; k < 2; ++k) \
;         acc[ai][bj][m][n] = __builtin_amdgcn_mfma_f32_16x16x32_bf16(Bt[n][k], At[m][k], acc[ai][bj][m][n], 0, 0, 0); __builtin_amdgcn_s_setprio(0); } while (0)
; #define PG8_WAIT_V(n) asm volatile("s_waitcnt vmcnt(" #n ")" ::: "memory")
; #define PG8_WAIT_L(n) asm volatile("s_waitcnt lgkmcnt(" #n ")" ::: "memory")
; #define PG8_BAR __builtin_amdgcn_s_barrier()
; #define PG8_SCHED __builtin_amdgcn_sched_barrier(0)
; template <class Epi>
; __device__ __forceinline__ void gemm_phase(LAS unsigned char* lds, const Gemm g, int G, int c, const Epi& E) {
;     ...
;             PG8_LDB(B0, 1, 0); PG8_LDB(B1, 1, 1); PG8_SCHED; PG8_LDA(At, 1, 0); PG8_STAGE(PG8_SA(0, 1), a2 + hstepA, voffA);
;             PG8_WAIT_V(8); PG8_WAIT_L(0); PG8_BAR; PG8_MMA(0, 0, At, B0); PG8_MMA(0, 1, At, B1); PG8_BAR; PG8_SCHED;
;             PG8_LDA(At, 1, 1); PG8_STAGE(PG8_SB(1, 0), b3, voffB); PG8_STAGE(PG8_SB(1, 1), b3 + hstepB, voffB); PG8_STAGE(PG8_SA(1, 0), a3, voffA);
;             PG8_WAIT_V(8); PG8_WAIT_L(0); PG8_BAR; PG8_MMA(1, 0, At, B0); PG8_MMA(1, 1, At, B1); PG8_BAR; PG8_SCHED;
;         }
	s_add_i32 s33, s33, s54
	v_lshl_add_u64 v[166:167], v[166:167], 0, s[10:11]
	s_mov_b32 m0, s33
	ds_read_b128 v[186:189], v172 offset:49152
	ds_read_b128 v[190:193], v172 offset:50176
	ds_read_b128 v[194:197], v172 offset:51200
	ds_read_b128 v[198:201], v172 offset:52224
	ds_read_b128 v[202:205], v172 offset:53248
	ds_read_b128 v[206:209], v172 offset:54272
	ds_read_b128 v[210:213], v172 offset:55296
	ds_read_b128 v[214:217], v172 offset:56320
	global_load_lds_dwordx4 v[166:167], off
	s_add_i32 m0, s33, 0x2000
	s_add_u32 s42, s42, 0x40080
	v_lshl_add_u64 v[166:167], v[218:219], 0, s[10:11]
	s_addc_u32 s43, s43, 0
	s_add_i32 s33, s47, s54
	global_load_lds_dwordx4 v[166:167], off
	v_lshl_add_u64 v[166:167], s[42:43], 0, v[150:151]
	s_mov_b32 m0, s33
	s_nop 0
	global_load_lds_dwordx4 v[166:167], off
	v_lshl_add_u64 v[166:167], s[42:43], 0, v[146:147]
	s_add_i32 m0, s33, 0x2000
	s_nop 0
	global_load_lds_dwordx4 v[166:167], off
	v_lshl_add_u64 v[166:167], v[220:221], 0, s[10:11]
	s_mov_b32 m0, s69
	s_nop 0
	global_load_lds_dwordx4 v[166:167], off
	v_lshl_add_u64 v[166:167], v[222:223], 0, s[10:11]
	s_mov_b32 m0, s70
	s_nop 0
	global_load_lds_dwordx4 v[166:167], off
	s_waitcnt vmcnt(8)
	s_waitcnt lgkmcnt(0)
	s_barrier
	s_waitcnt lgkmcnt(0)
	v_mfma_f32_16x16x32_bf16 v[62:65], v[130:133], v[186:189], v[62:65]
	v_mfma_f32_16x16x32_bf16 v[58:61], v[138:141], v[186:189], v[58:61]
	v_mfma_f32_16x16x32_bf16 v[46:49], v[130:133], v[194:197], v[46:49]
	v_mfma_f32_16x16x32_bf16 v[42:45], v[138:141], v[194:197], v[42:45]
	v_mfma_f32_16x16x32_bf16 v[30:33], v[130:133], v[202:205], v[30:33]
	v_mfma_f32_16x16x32_bf16 v[26:29], v[138:141], v[202:205], v[26:29]
	v_mfma_f32_16x16x32_bf16 v[14:17], v[130:133], v[210:213], v[14:17]
	v_mfma_f32_16x16x32_bf16 v[10:13], v[138:141], v[210:213], v[10:13]
	v_mfma_f32_16x16x32_bf16 v[62:65], v[134:137], v[190:193], v[62:65]
	v_mfma_f32_16x16x32_bf16 v[58:61], v[142:145], v[190:193], v[58:61]
	v_mfma_f32_16x16x32_bf16 v[46:49], v[134:137], v[198:201], v[46:49]
	v_mfma_f32_16x16x32_bf16 v[42:45], v[142:145], v[198:201], v[42:45]
	v_mfma_f32_16x16x32_bf16 v[30:33], v[134:137], v[206:209], v[30:33]
	v_mfma_f32_16x16x32_bf16 v[26:29], v[142:145], v[206:209], v[26:29]
	v_mfma_f32_16x16x32_bf16 v[14:17], v[134:137], v[214:217], v[14:17]
	v_mfma_f32_16x16x32_bf16 v[10:13], v[142:145], v[214:217], v[10:13]
	v_mfma_f32_16x16x32_bf16 v[54:57], v[162:165], v[186:189], v[54:57]
	v_mfma_f32_16x16x32_bf16 v[50:53], v[178:181], v[186:189], v[50:53]
	v_mfma_f32_16x16x32_bf16 v[38:41], v[162:165], v[194:197], v[38:41]
	v_mfma_f32_16x16x32_bf16 v[34:37], v[178:181], v[194:197], v[34:37]
	v_mfma_f32_16x16x32_bf16 v[22:25], v[162:165], v[202:205], v[22:25]
	v_mfma_f32_16x16x32_bf16 v[18:21], v[178:181], v[202:205], v[18:21]
	v_mfma_f32_16x16x32_bf16 v[6:9], v[162:165], v[210:213], v[6:9]
	v_mfma_f32_16x16x32_bf16 v[2:5], v[178:181], v[210:213], v[2:5]
	v_mfma_f32_16x16x32_bf16 v[54:57], v[174:177], v[190:193], v[54:57]
	v_mfma_f32_16x16x32_bf16 v[50:53], v[182:185], v[190:193], v[50:53]
	v_mfma_f32_16x16x32_bf16 v[38:41], v[174:177], v[198:201], v[38:41]
	v_mfma_f32_16x16x32_bf16 v[34:37], v[182:185], v[198:201], v[34:37]
	v_mfma_f32_16x16x32_bf16 v[22:25], v[174:177], v[206:209], v[22:25]
	v_mfma_f32_16x16x32_bf16 v[18:21], v[182:185], v[206:209], v[18:21]
	v_mfma_f32_16x16x32_bf16 v[6:9], v[174:177], v[214:217], v[6:9]
	v_mfma_f32_16x16x32_bf16 v[2:5], v[182:185], v[214:217], v[2:5]
	s_barrier
	s_add_i32 s46, s46, 2
	s_add_u32 s4, s4, 0x100
	s_addc_u32 s5, s5, 0
	s_add_u32 s23, s23, 0x100
	s_addc_u32 s39, s39, 0
	s_cmp_gt_u32 s46, 13
	s_cbranch_scc0 .LBB0_903
	s_and_b64 vcc, exec, s[12:13]
	s_cbranch_vccz .LBB0_906
	s_barrier

; #define PG8_STAGE(bufoff, gbase, voff) do { _Pragma("unroll") for (int _i = 0; _i < 2; ++_i) \
;         __builtin_amdgcn_global_load_lds((const unsigned*)((const char*)(gbase) + (voff)[_i]), (LAS unsigned*)(lds + (bufoff) + ldsw + _i * 8192), 16, 0, 0); } while (0)
; #define PG8_LDA(dst, b, h) do { _Pragma("unroll") for (int m = 0; m < 4; ++m) _Pragma("unroll") for (int k = 0; k < 2; ++k) dst[m][k] = *(const LAS bf16x8*)(lds + PG8_SA(b, h) + aoff + m * 2048 + k * 1024); } while (0)
; #define PG8_LDB(dst, b, h) do { _Pragma("unroll") for (int n = 0; n < 2; ++n) _Pragma("unroll") for (int k = 0; k < 2; ++k) dst[n][k] = *(const LAS bf16x8*)(lds + PG8_SB(b, h) + boff + n * 2048 + k * 1024); } while (0)
; #define PG8_MMA(ai, bj, At, Bt) do { __builtin_amdgcn_s_setprio(1); _Pragma("unroll") for (int m = 0; m < 4; ++m) _Pragma("unroll") for (int n = 0; n < 2; ++n) _Pragma("unroll") for (int k = 0; k < 2; ++k) \
;         acc[ai][bj][m][n] = __builtin_amdgcn_mfma_f32_16x16x32_bf16(Bt[n][k], At[m][k], acc[ai][bj][m][n], 0, 0, 0); __builtin_amdgcn_s_setprio(0); } while (0)
; #define PG8_WAIT_V(n) asm volatile("s_waitcnt vmcnt(" #n ")" ::: "memory")
; #define PG8_WAIT_L(n) asm volatile("s_waitcnt lgkmcnt(" #n ")" ::: "memory")
; #define PG8_BAR __builtin_amdgcn_s_barrier()
; #define PG8_SCHED __builtin_amdgcn_sched_barrier(0)
; template <class Epi>
; __device__ __forceinline__ void gemm_phase(LAS unsigned char* lds, const Gemm g, int G, int c, const Epi& E) {
;     ...
;             const bool last = (t == nt - 2);
;             const char* a1 = cA + (size_t)(t + 1) * kstep;
;             const char* a2 = last ? nA : cA + (size_t)(t + 2) * kstep; const char* b2 = last ? nB : cB + (size_t)(t + 2) * kstep;
;             const char* a3 = a2 + kstep; const char* b3 = b2 + kstep;
;             PG8_LDB(B0, 0, 0); PG8_LDB(B1, 0, 1); PG8_SCHED; PG8_LDA(At, 0, 0); PG8_STAGE(PG8_SA(1, 1), a1 + hstepA, voffA);
;             PG8_WAIT_V(8); PG8_WAIT_L(0); PG8_BAR; PG8_MMA(0, 0, At, B0); PG8_MMA(0, 1, At, B1); PG8_BAR; PG8_SCHED;
.LBB0_1058:
	ds_read_b128 v[152:155], v148
	ds_read_b128 v[156:159], v148 offset:1024
	ds_read_b128 v[160:163], v148 offset:2048
	ds_read_b128 v[164:167], v148 offset:3072
	ds_read_b128 v[168:171], v149
	ds_read_b128 v[172:175], v149 offset:1024
	ds_read_b128 v[176:179], v149 offset:2048
	ds_read_b128 v[180:183], v149 offset:3072
	s_add_u32 s33, s4, 0xfffc0080
	s_addc_u32 s38, s5, -1
	s_cmp_eq_u32 s80, 12
	s_cselect_b32 s41, s21, s38
	s_cselect_b32 s40, s20, s33
	s_cselect_b32 s39, s17, s79
	s_cselect_b32 s38, s19, s78
	v_lshl_add_u64 v[216:217], s[4:5], 0, v[138:139]
	s_add_i32 m0, s25, 0xc000
	ds_read_b128 v[184:187], v150
	ds_read_b128 v[188:191], v150 offset:1024
	ds_read_b128 v[192:195], v150 offset:2048
	ds_read_b128 v[196:199], v150 offset:3072
	ds_read_b128 v[200:203], v150 offset:4096
	ds_read_b128 v[204:207], v150 offset:5120
	ds_read_b128 v[208:211], v150 offset:6144
	ds_read_b128 v[212:215], v150 offset:7168
	global_load_lds_dwordx4 v[216:217], off
	v_lshl_add_u64 v[216:217], s[4:5], 0, v[140:141]
	s_add_i32 m0, s25, 0xe000
	s_nop 0
	global_load_lds_dwordx4 v[216:217], off
	s_waitcnt vmcnt(8)
	s_waitcnt lgkmcnt(0)
	s_barrier
	s_waitcnt lgkmcnt(0)
	v_mfma_f32_16x16x32_bf16 v[126:129], v[152:155], v[184:187], v[126:129]
	v_mfma_f32_16x16x32_bf16 v[122:125], v[160:163], v[184:187], v[122:125]
	v_mfma_f32_16x16x32_bf16 v[110:113], v[152:155], v[192:195], v[110:113]
	v_mfma_f32_16x16x32_bf16 v[106:109], v[160:163], v[192:195], v[106:109]
	v_mfma_f32_16x16x32_bf16 v[94:97], v[152:155], v[200:203], v[94:97]
	v_mfma_f32_16x16x32_bf16 v[90:93], v[160:163], v[200:203], v[90:93]
	v_mfma_f32_16x16x32_bf16 v[78:81], v[152:155], v[208:211], v[78:81]
	v_mfma_f32_16x16x32_bf16 v[74:77], v[160:163], v[208:211], v[74:77]
	v_mfma_f32_16x16x32_bf16 v[126:129], v[156:159], v[188:191], v[126:129]
	v_mfma_f32_16x16x32_bf16 v[122:125], v[164:167], v[188:191], v[122:125]
	v_mfma_f32_16x16x32_bf16 v[110:113], v[156:159], v[196:199], v[110:113]
	v_mfma_f32_16x16x32_bf16 v[106:109], v[164:167], v[196:199], v[106:109]
	v_mfma_f32_16x16x32_bf16 v[94:97], v[156:159], v[204:207], v[94:97]
	v_mfma_f32_16x16x32_bf16 v[90:93], v[164:167], v[204:207], v[90:93]
	v_mfma_f32_16x16x32_bf16 v[78:81], v[156:159], v[212:215], v[78:81]
	v_mfma_f32_16x16x32_bf16 v[74:77], v[164:167], v[212:215], v[74:77]
	v_mfma_f32_16x16x32_bf16 v[118:121], v[168:171], v[184:187], v[118:121]
	v_mfma_f32_16x16x32_bf16 v[114:117], v[176:179], v[184:187], v[114:117]
	v_mfma_f32_16x16x32_bf16 v[102:105], v[168:171], v[192:195], v[102:105]
	v_mfma_f32_16x16x32_bf16 v[98:101], v[176:179], v[192:195], v[98:101]
	v_mfma_f32_16x16x32_bf16 v[86:89], v[168:171], v[200:203], v[86:89]
	v_mfma_f32_16x16x32_bf16 v[82:85], v[176:179], v[200:203], v[82:85]
	v_mfma_f32_16x16x32_bf16 v[70:73], v[168:171], v[208:211], v[70:73]
	v_mfma_f32_16x16x32_bf16 v[66:69], v[176:179], v[208:211], v[66:69]
	v_mfma_f32_16x16x32_bf16 v[118:121], v[172:175], v[188:191], v[118:121]
	v_mfma_f32_16x16x32_bf16 v[114:117], v[180:183], v[188:191], v[114:117]
	v_mfma_f32_16x16x32_bf16 v[102:105], v[172:175], v[196:199], v[102:105]
	v_mfma_f32_16x16x32_bf16 v[98:101], v[180:183], v[196:199], v[98:101]
	v_mfma_f32_16x16x32_bf16 v[86:89], v[172:175], v[204:207], v[86:89]
	v_mfma_f32_16x16x32_bf16 v[82:85], v[180:183], v[204:207], v[82:85]
	v_mfma_f32_16x16x32_bf16 v[70:73], v[172:175], v[212:215], v[70:73]
	v_mfma_f32_16x16x32_bf16 v[66:69], v[180:183], v[212:215], v[66:69]
	s_barrier
	s_add_i32 s33, s60, s46
	v_lshl_add_u64 v[216:217], s[38:39], 0, v[134:135]
	s_mov_b32 m0, s33
	ds_read_b128 v[184:187], v150 offset:16384
	ds_read_b128 v[188:191], v150 offset:17408
	ds_read_b128 v[192:195], v150 offset:18432
	ds_read_b128 v[196:199], v150 offset:19456
	ds_read_b128 v[200:203], v150 offset:20480
	ds_read_b128 v[204:207], v150 offset:21504
	ds_read_b128 v[208:211], v150 offset:22528
	ds_read_b128 v[212:215], v150 offset:23552
	global_load_lds_dwordx4 v[216:217], off
	s_add_i32 m0, s33, 0x2000
	s_add_u32 s62, s38, 0x40000
	v_lshl_add_u64 v[218:219], s[38:39], 0, v[130:131]
	s_addc_u32 s63, s39, 0
	s_add_i32 s33, s61, s46
	global_load_lds_dwordx4 v[218:219], off
	v_lshl_add_u64 v[220:221], s[62:63], 0, v[134:135]
	s_mov_b32 m0, s33
	v_lshl_add_u64 v[222:223], s[40:41], 0, v[132:133]
	global_load_lds_dwordx4 v[220:221], off
	v_lshl_add_u64 v[220:221], s[62:63], 0, v[130:131]
	s_add_i32 m0, s33, 0x2000
	s_nop 0
	global_load_lds_dwordx4 v[220:221], off
	v_lshl_add_u64 v[220:221], s[40:41], 0, v[136:137]
	s_mov_b32 m0, s25
	s_nop 0
	global_load_lds_dwordx4 v[220:221], off
	s_mov_b32 m0, s37
	s_nop 0
	global_load_lds_dwordx4 v[222:223], off
	s_waitcnt vmcnt(8)
	s_waitcnt lgkmcnt(0)
	s_barrier
; #define PG8_STAGE(bufoff, gbase, voff) do { _Pragma("unroll") for (int _i = 0; _i < 2; ++_i) \
;         __builtin_amdgcn_global_load_lds((const unsigned*)((const char*)(gbase) + (voff)[_i]), (LAS unsigned*)(lds + (bufoff) + ldsw + _i * 8192), 16, 0, 0); } while (0)
; #define PG8_LDA(dst, b, h) do { _Pragma("unroll") for (int m = 0; m < 4; ++m) _Pragma("unroll") for (int k = 0; k < 2; ++k) dst[m][k] = *(const LAS bf16x8*)(lds + PG8_SA(b, h) + aoff + m * 2048 + k * 1024); } while (0)
; #define PG8_LDB(dst, b, h) do { _Pragma("unroll") for (int n = 0; n < 2; ++n) _Pragma("unroll") for (int k = 0; k < 2; ++k) dst[n][k] = *(const LAS bf16x8*)(lds + PG8_SB(b, h) + boff + n * 2048 + k * 1024); } while (0)
; #define PG8_MMA(ai, bj, At, Bt) do { __builtin_amdgcn_s_setprio(1); _Pragma("unroll") for (int m = 0; m < 4; ++m) _Pragma("unroll") for (int n = 0; n < 2; ++n) _Pragma("unroll") for (int k = 0; k < 2; ++k) \
;         acc[ai][bj][m][n] = __builtin_amdgcn_mfma_f32_16x16x32_bf16(Bt[n][k], At[m][k], acc[ai][bj][m][n], 0, 0, 0); __builtin_amdgcn_s_setprio(0); } while (0)
; #define PG8_WAIT_V(n) asm volatile("s_waitcnt vmcnt(" #n ")" ::: "memory")
; #define PG8_WAIT_L(n) asm volatile("s_waitcnt lgkmcnt(" #n ")" ::: "memory")
; #define PG8_BAR __builtin_amdgcn_s_barrier()
; #define PG8_SCHED __builtin_amdgcn_sched_barrier(0)
; template <class Epi>
; __device__ __forceinline__ void gemm_phase(LAS unsigned char* lds, const Gemm g, int G, int c, const Epi& E) {
;     ...
;             PG8_WAIT_V(8); PG8_WAIT_L(0); PG8_BAR; PG8_MMA(0, 0, At, B0); PG8_MMA(0, 1, At, B1); PG8_BAR; PG8_SCHED;
;             PG8_LDA(At, 0, 1); PG8_STAGE(PG8_SB(0, 0), b2, voffB); PG8_STAGE(PG8_SB(0, 1), b2 + hstepB, voffB); PG8_STAGE(PG8_SA(0, 0), a2, voffA);
;             PG8_WAIT_V(8); PG8_WAIT_L(0); PG8_BAR; PG8_MMA(1, 0, At, B0); PG8_MMA(1, 1, At, B1); PG8_BAR; PG8_SCHED;
;             PG8_LDB(B0, 1, 0); PG8_LDB(B1, 1, 1); PG8_SCHED; PG8_LDA(At, 1, 0); PG8_STAGE(PG8_SA(0, 1), a2 + hstepA, voffA);
;             PG8_WAIT_V(8); PG8_WAIT_L(0); PG8_BAR; PG8_MMA(0, 0, At, B0); PG8_MMA(0, 1, At, B1); PG8_BAR; PG8_SCHED;
;             PG8_LDA(At, 1, 1); PG8_STAGE(PG8_SB(1, 0), b3, voffB); PG8_STAGE(PG8_SB(1, 1), b3 + hstepB, voffB); PG8_STAGE(PG8_SA(1, 0), a3, voffA);
	s_waitcnt lgkmcnt(0)
	v_mfma_f32_16x16x32_bf16 v[62:65], v[152:155], v[184:187], v[62:65]
	v_mfma_f32_16x16x32_bf16 v[58:61], v[160:163], v[184:187], v[58:61]
	v_mfma_f32_16x16x32_bf16 v[46:49], v[152:155], v[192:195], v[46:49]
	v_mfma_f32_16x16x32_bf16 v[42:45], v[160:163], v[192:195], v[42:45]
	v_mfma_f32_16x16x32_bf16 v[30:33], v[152:155], v[200:203], v[30:33]
	v_mfma_f32_16x16x32_bf16 v[26:29], v[160:163], v[200:203], v[26:29]
	v_mfma_f32_16x16x32_bf16 v[14:17], v[152:155], v[208:211], v[14:17]
	v_mfma_f32_16x16x32_bf16 v[10:13], v[160:163], v[208:211], v[10:13]
	v_mfma_f32_16x16x32_bf16 v[62:65], v[156:159], v[188:191], v[62:65]
	v_mfma_f32_16x16x32_bf16 v[58:61], v[164:167], v[188:191], v[58:61]
	v_mfma_f32_16x16x32_bf16 v[46:49], v[156:159], v[196:199], v[46:49]
	v_mfma_f32_16x16x32_bf16 v[42:45], v[164:167], v[196:199], v[42:45]
	v_mfma_f32_16x16x32_bf16 v[30:33], v[156:159], v[204:207], v[30:33]
	v_mfma_f32_16x16x32_bf16 v[26:29], v[164:167], v[204:207], v[26:29]
	v_mfma_f32_16x16x32_bf16 v[14:17], v[156:159], v[212:215], v[14:17]
	v_mfma_f32_16x16x32_bf16 v[10:13], v[164:167], v[212:215], v[10:13]
	v_mfma_f32_16x16x32_bf16 v[54:57], v[168:171], v[184:187], v[54:57]
	v_mfma_f32_16x16x32_bf16 v[50:53], v[176:179], v[184:187], v[50:53]
	v_mfma_f32_16x16x32_bf16 v[38:41], v[168:171], v[192:195], v[38:41]
	v_mfma_f32_16x16x32_bf16 v[34:37], v[176:179], v[192:195], v[34:37]
	v_mfma_f32_16x16x32_bf16 v[22:25], v[168:171], v[200:203], v[22:25]
	v_mfma_f32_16x16x32_bf16 v[18:21], v[176:179], v[200:203], v[18:21]
	v_mfma_f32_16x16x32_bf16 v[6:9], v[168:171], v[208:211], v[6:9]
	v_mfma_f32_16x16x32_bf16 v[2:5], v[176:179], v[208:211], v[2:5]
	v_mfma_f32_16x16x32_bf16 v[54:57], v[172:175], v[188:191], v[54:57]
	v_mfma_f32_16x16x32_bf16 v[50:53], v[180:183], v[188:191], v[50:53]
	v_mfma_f32_16x16x32_bf16 v[38:41], v[172:175], v[196:199], v[38:41]
	v_mfma_f32_16x16x32_bf16 v[34:37], v[180:183], v[196:199], v[34:37]
	v_mfma_f32_16x16x32_bf16 v[22:25], v[172:175], v[204:207], v[22:25]
	v_mfma_f32_16x16x32_bf16 v[18:21], v[180:183], v[204:207], v[18:21]
	v_mfma_f32_16x16x32_bf16 v[6:9], v[172:175], v[212:215], v[6:9]
	v_mfma_f32_16x16x32_bf16 v[2:5], v[180:183], v[212:215], v[2:5]
	s_barrier
	s_add_i32 s33, 0, 0x18000
	s_add_i32 s62, 0, 0x1c000
	v_add_u32_e32 v164, s33, v147
	v_add_u32_e32 v180, s62, v147
	ds_read_b128 v[152:155], v164
	ds_read_b128 v[156:159], v164 offset:1024
	ds_read_b128 v[160:163], v164 offset:2048
	ds_read_b128 v[164:167], v164 offset:3072
	ds_read_b128 v[168:171], v180
	ds_read_b128 v[172:175], v180 offset:1024
	ds_read_b128 v[176:179], v180 offset:2048
	ds_read_b128 v[180:183], v180 offset:3072
	s_add_u32 s40, s40, 0x40000
	s_addc_u32 s41, s41, 0
	s_mov_b32 m0, s47
	v_lshl_add_u64 v[224:225], s[40:41], 0, v[136:137]
	ds_read_b128 v[184:187], v150 offset:32768
	ds_read_b128 v[188:191], v150 offset:33792
	ds_read_b128 v[192:195], v150 offset:34816
	ds_read_b128 v[196:199], v150 offset:35840
	ds_read_b128 v[200:203], v150 offset:36864
	ds_read_b128 v[204:207], v150 offset:37888
	ds_read_b128 v[208:211], v150 offset:38912
	ds_read_b128 v[212:215], v150 offset:39936
	global_load_lds_dwordx4 v[224:225], off
	v_lshl_add_u64 v[224:225], s[40:41], 0, v[132:133]
	s_mov_b32 m0, s52
	s_nop 0
	global_load_lds_dwordx4 v[224:225], off
	s_waitcnt vmcnt(8)
	s_waitcnt lgkmcnt(0)
	s_barrier
	s_waitcnt lgkmcnt(0)
	v_mfma_f32_16x16x32_bf16 v[126:129], v[152:155], v[184:187], v[126:129]
	v_mfma_f32_16x16x32_bf16 v[122:125], v[160:163], v[184:187], v[122:125]
	v_mfma_f32_16x16x32_bf16 v[110:113], v[152:155], v[192:195], v[110:113]
	v_mfma_f32_16x16x32_bf16 v[106:109], v[160:163], v[192:195], v[106:109]
	v_mfma_f32_16x16x32_bf16 v[94:97], v[152:155], v[200:203], v[94:97]
	v_mfma_f32_16x16x32_bf16 v[90:93], v[160:163], v[200:203], v[90:93]
	v_mfma_f32_16x16x32_bf16 v[78:81], v[152:155], v[208:211], v[78:81]
	v_mfma_f32_16x16x32_bf16 v[74:77], v[160:163], v[208:211], v[74:77]
	v_mfma_f32_16x16x32_bf16 v[126:129], v[156:159], v[188:191], v[126:129]
	v_mfma_f32_16x16x32_bf16 v[122:125], v[164:167], v[188:191], v[122:125]
	v_mfma_f32_16x16x32_bf16 v[110:113], v[156:159], v[196:199], v[110:113]
	v_mfma_f32_16x16x32_bf16 v[106:109], v[164:167], v[196:199], v[106:109]
	v_mfma_f32_16x16x32_bf16 v[94:97], v[156:159], v[204:207], v[94:97]
	v_mfma_f32_16x16x32_bf16 v[90:93], v[164:167], v[204:207], v[90:93]
	v_mfma_f32_16x16x32_bf16 v[78:81], v[156:159], v[212:215], v[78:81]
	v_mfma_f32_16x16x32_bf16 v[74:77], v[164:167], v[212:215], v[74:77]
	v_mfma_f32_16x16x32_bf16 v[118:121], v[168:171], v[184:187], v[118:121]
	v_mfma_f32_16x16x32_bf16 v[114:117], v[176:179], v[184:187], v[114:117]
	v_mfma_f32_16x16x32_bf16 v[102:105], v[168:171], v[192:195], v[102:105]
	v_mfma_f32_16x16x32_bf16 v[98:101], v[176:179], v[192:195], v[98:101]
	v_mfma_f32_16x16x32_bf16 v[86:89], v[168:171], v[200:203], v[86:89]
	v_mfma_f32_16x16x32_bf16 v[82:85], v[176:179], v[200:203], v[82:85]
	v_mfma_f32_16x16x32_bf16 v[70:73], v[168:171], v[208:211], v[70:73]
	v_mfma_f32_16x16x32_bf16 v[66:69], v[176:179], v[208:211], v[66:69]
	v_mfma_f32_16x16x32_bf16 v[118:121], v[172:175], v[188:191], v[118:121]
	v_mfma_f32_16x16x32_bf16 v[114:117], v[180:183], v[188:191], v[114:117]
	v_mfma_f32_16x16x32_bf16 v[102:105], v[172:175], v[196:199], v[102:105]
	v_mfma_f32_16x16x32_bf16 v[98:101], v[180:183], v[196:199], v[98:101]
	v_mfma_f32_16x16x32_bf16 v[86:89], v[172:175], v[204:207], v[86:89]
	v_mfma_f32_16x16x32_bf16 v[82:85], v[180:183], v[204:207], v[82:85]
	v_mfma_f32_16x16x32_bf16 v[70:73], v[172:175], v[212:215], v[70:73]
	v_mfma_f32_16x16x32_bf16 v[66:69], v[180:183], v[212:215], v[66:69]
	s_barrier
; #define PG8_STAGE(bufoff, gbase, voff) do { _Pragma("unroll") for (int _i = 0; _i < 2; ++_i) \
;         __builtin_amdgcn_global_load_lds((const unsigned*)((const char*)(gbase) + (voff)[_i]), (LAS unsigned*)(lds + (bufoff) + ldsw + _i * 8192), 16, 0, 0); } while (0)
; #define PG8_LDA(dst, b, h) do { _Pragma("unroll") for (int m = 0; m < 4; ++m) _Pragma("unroll") for (int k = 0; k < 2; ++k) dst[m][k] = *(const LAS bf16x8*)(lds + PG8_SA(b, h) + aoff + m * 2048 + k * 1024); } while (0)
; #define PG8_LDB(dst, b, h) do { _Pragma("unroll") for (int n = 0; n < 2; ++n) _Pragma("unroll") for (int k = 0; k < 2; ++k) dst[n][k] = *(const LAS bf16x8*)(lds + PG8_SB(b, h) + boff + n * 2048 + k * 1024); } while (0)
; #define PG8_MMA(ai, bj, At, Bt) do { __builtin_amdgcn_s_setprio(1); _Pragma("unroll") for (int m = 0; m < 4; ++m) _Pragma("unroll") for (int n = 0; n < 2; ++n) _Pragma("unroll") for (int k = 0; k < 2; ++k) \
;         acc[ai][bj][m][n] = __builtin_amdgcn_mfma_f32_16x16x32_bf16(Bt[n][k], At[m][k], acc[ai][bj][m][n], 0, 0, 0); __builtin_amdgcn_s_setprio(0); } while (0)
; #define PG8_WAIT_V(n) asm volatile("s_waitcnt vmcnt(" #n ")" ::: "memory")
; #define PG8_WAIT_L(n) asm volatile("s_waitcnt lgkmcnt(" #n ")" ::: "memory")
; #define PG8_BAR __builtin_amdgcn_s_barrier()
; #define PG8_SCHED __builtin_amdgcn_sched_barrier(0)
; template <class Epi>
; __device__ __forceinline__ void gemm_phase(LAS unsigned char* lds, const Gemm g, int G, int c, const Epi& E) {
;     ...
;             PG8_LDB(B0, 1, 0); PG8_LDB(B1, 1, 1); PG8_SCHED; PG8_LDA(At, 1, 0); PG8_STAGE(PG8_SA(0, 1), a2 + hstepA, voffA);
;             PG8_WAIT_V(8); PG8_WAIT_L(0); PG8_BAR; PG8_MMA(0, 0, At, B0); PG8_MMA(0, 1, At, B1); PG8_BAR; PG8_SCHED;
;             PG8_LDA(At, 1, 1); PG8_STAGE(PG8_SB(1, 0), b3, voffB); PG8_STAGE(PG8_SB(1, 1), b3 + hstepB, voffB); PG8_STAGE(PG8_SA(1, 0), a3, voffA);
;             PG8_WAIT_V(8); PG8_WAIT_L(0); PG8_BAR; PG8_MMA(1, 0, At, B0); PG8_MMA(1, 1, At, B1); PG8_BAR; PG8_SCHED;
;         }
	s_add_i32 s33, s33, s46
	v_lshl_add_u64 v[216:217], v[216:217], 0, s[12:13]
	s_mov_b32 m0, s33
	ds_read_b128 v[184:187], v150 offset:49152
	ds_read_b128 v[188:191], v150 offset:50176
	ds_read_b128 v[192:195], v150 offset:51200
	ds_read_b128 v[196:199], v150 offset:52224
	ds_read_b128 v[200:203], v150 offset:53248
	ds_read_b128 v[204:207], v150 offset:54272
	ds_read_b128 v[208:211], v150 offset:55296
	ds_read_b128 v[212:215], v150 offset:56320
	global_load_lds_dwordx4 v[216:217], off
	s_add_i32 m0, s33, 0x2000
	s_add_u32 s38, s38, 0x40080
	v_lshl_add_u64 v[216:217], v[218:219], 0, s[12:13]
	s_addc_u32 s39, s39, 0
	s_add_i32 s33, s62, s46
	global_load_lds_dwordx4 v[216:217], off
	v_lshl_add_u64 v[216:217], s[38:39], 0, v[134:135]
	s_mov_b32 m0, s33
	s_nop 0
	global_load_lds_dwordx4 v[216:217], off
	v_lshl_add_u64 v[216:217], s[38:39], 0, v[130:131]
	s_add_i32 m0, s33, 0x2000
	s_nop 0
	global_load_lds_dwordx4 v[216:217], off
	v_lshl_add_u64 v[216:217], v[220:221], 0, s[12:13]
	s_mov_b32 m0, s57
	s_nop 0
	global_load_lds_dwordx4 v[216:217], off
	v_lshl_add_u64 v[216:217], v[222:223], 0, s[12:13]
	s_mov_b32 m0, s58
	s_nop 0
	global_load_lds_dwordx4 v[216:217], off
	s_waitcnt vmcnt(8)
	s_waitcnt lgkmcnt(0)
	s_barrier
	s_waitcnt lgkmcnt(0)
	v_mfma_f32_16x16x32_bf16 v[62:65], v[152:155], v[184:187], v[62:65]
	v_mfma_f32_16x16x32_bf16 v[58:61], v[160:163], v[184:187], v[58:61]
	v_mfma_f32_16x16x32_bf16 v[46:49], v[152:155], v[192:195], v[46:49]
	v_mfma_f32_16x16x32_bf16 v[42:45], v[160:163], v[192:195], v[42:45]
	v_mfma_f32_16x16x32_bf16 v[30:33], v[152:155], v[200:203], v[30:33]
	v_mfma_f32_16x16x32_bf16 v[26:29], v[160:163], v[200:203], v[26:29]
	v_mfma_f32_16x16x32_bf16 v[14:17], v[152:155], v[208:211], v[14:17]
	v_mfma_f32_16x16x32_bf16 v[10:13], v[160:163], v[208:211], v[10:13]
	v_mfma_f32_16x16x32_bf16 v[62:65], v[156:159], v[188:191], v[62:65]
	v_mfma_f32_16x16x32_bf16 v[58:61], v[164:167], v[188:191], v[58:61]
	v_mfma_f32_16x16x32_bf16 v[46:49], v[156:159], v[196:199], v[46:49]
	v_mfma_f32_16x16x32_bf16 v[42:45], v[164:167], v[196:199], v[42:45]
	v_mfma_f32_16x16x32_bf16 v[30:33], v[156:159], v[204:207], v[30:33]
	v_mfma_f32_16x16x32_bf16 v[26:29], v[164:167], v[204:207], v[26:29]
	v_mfma_f32_16x16x32_bf16 v[14:17], v[156:159], v[212:215], v[14:17]
	v_mfma_f32_16x16x32_bf16 v[10:13], v[164:167], v[212:215], v[10:13]
	v_mfma_f32_16x16x32_bf16 v[54:57], v[168:171], v[184:187], v[54:57]
	v_mfma_f32_16x16x32_bf16 v[50:53], v[176:179], v[184:187], v[50:53]
	v_mfma_f32_16x16x32_bf16 v[38:41], v[168:171], v[192:195], v[38:41]
	v_mfma_f32_16x16x32_bf16 v[34:37], v[176:179], v[192:195], v[34:37]
	v_mfma_f32_16x16x32_bf16 v[22:25], v[168:171], v[200:203], v[22:25]
	v_mfma_f32_16x16x32_bf16 v[18:21], v[176:179], v[200:203], v[18:21]
	v_mfma_f32_16x16x32_bf16 v[6:9], v[168:171], v[208:211], v[6:9]
	v_mfma_f32_16x16x32_bf16 v[2:5], v[176:179], v[208:211], v[2:5]
	v_mfma_f32_16x16x32_bf16 v[54:57], v[172:175], v[188:191], v[54:57]
	v_mfma_f32_16x16x32_bf16 v[50:53], v[180:183], v[188:191], v[50:53]
	v_mfma_f32_16x16x32_bf16 v[38:41], v[172:175], v[196:199], v[38:41]
	v_mfma_f32_16x16x32_bf16 v[34:37], v[180:183], v[196:199], v[34:37]
	v_mfma_f32_16x16x32_bf16 v[22:25], v[172:175], v[204:207], v[22:25]
	v_mfma_f32_16x16x32_bf16 v[18:21], v[180:183], v[204:207], v[18:21]
	v_mfma_f32_16x16x32_bf16 v[6:9], v[172:175], v[212:215], v[6:9]
	v_mfma_f32_16x16x32_bf16 v[2:5], v[180:183], v[212:215], v[2:5]
	s_barrier
	s_add_i32 s80, s80, 2
	s_add_u32 s4, s4, 0x100
	s_addc_u32 s5, s5, 0
	s_add_u32 s78, s78, 0x100
	s_addc_u32 s79, s79, 0
	s_cmp_gt_u32 s80, 13
	s_cbranch_scc0 .LBB0_1058
	s_and_b64 vcc, exec, s[14:15]
	s_cbranch_vccz .LBB0_1061
	s_barrier

; #define PG8_STAGE(bufoff, gbase, voff) do { _Pragma("unroll") for (int _i = 0; _i < 2; ++_i) \
;         __builtin_amdgcn_global_load_lds((const unsigned*)((const char*)(gbase) + (voff)[_i]), (LAS unsigned*)(lds + (bufoff) + ldsw + _i * 8192), 16, 0, 0); } while (0)
; #define PG8_LDA(dst, b, h) do { _Pragma("unroll") for (int m = 0; m < 4; ++m) _Pragma("unroll") for (int k = 0; k < 2; ++k) dst[m][k] = *(const LAS bf16x8*)(lds + PG8_SA(b, h) + aoff + m * 2048 + k * 1024); } while (0)
; #define PG8_LDB(dst, b, h) do { _Pragma("unroll") for (int n = 0; n < 2; ++n) _Pragma("unroll") for (int k = 0; k < 2; ++k) dst[n][k] = *(const LAS bf16x8*)(lds + PG8_SB(b, h) + boff + n * 2048 + k * 1024); } while (0)
; #define PG8_MMA(ai, bj, At, Bt) do { __builtin_amdgcn_s_setprio(1); _Pragma("unroll") for (int m = 0; m < 4; ++m) _Pragma("unroll") for (int n = 0; n < 2; ++n) _Pragma("unroll") for (int k = 0; k < 2; ++k) \
;         acc[ai][bj][m][n] = __builtin_amdgcn_mfma_f32_16x16x32_bf16(Bt[n][k], At[m][k], acc[ai][bj][m][n], 0, 0, 0); __builtin_amdgcn_s_setprio(0); } while (0)
; #define PG8_WAIT_V(n) asm volatile("s_waitcnt vmcnt(" #n ")" ::: "memory")
; #define PG8_WAIT_L(n) asm volatile("s_waitcnt lgkmcnt(" #n ")" ::: "memory")
; #define PG8_BAR __builtin_amdgcn_s_barrier()
; #define PG8_SCHED __builtin_amdgcn_sched_barrier(0)
; template <class Epi>
; __device__ __forceinline__ void gemm_phase(LAS unsigned char* lds, const Gemm g, int G, int c, const Epi& E) {
;     ...
;             const bool last = (t == nt - 2);
;             const char* a1 = cA + (size_t)(t + 1) * kstep;
;             const char* a2 = last ? nA : cA + (size_t)(t + 2) * kstep; const char* b2 = last ? nB : cB + (size_t)(t + 2) * kstep;
;             const char* a3 = a2 + kstep; const char* b3 = b2 + kstep;
;             PG8_LDB(B0, 0, 0); PG8_LDB(B1, 0, 1); PG8_SCHED; PG8_LDA(At, 0, 0); PG8_STAGE(PG8_SA(1, 1), a1 + hstepA, voffA);
;             PG8_WAIT_V(8); PG8_WAIT_L(0); PG8_BAR; PG8_MMA(0, 0, At, B0); PG8_MMA(0, 1, At, B1); PG8_BAR; PG8_SCHED;
.LBB0_1143:
	ds_read_b128 v[122:125], v168
	ds_read_b128 v[126:129], v168 offset:1024
	ds_read_b128 v[130:133], v168 offset:2048
	ds_read_b128 v[134:137], v168 offset:3072
	ds_read_b128 v[162:165], v169
	ds_read_b128 v[172:175], v169 offset:1024
	ds_read_b128 v[176:179], v169 offset:2048
	ds_read_b128 v[180:183], v169 offset:3072
	s_add_u32 s18, s16, 0x100
	s_addc_u32 s19, s17, 0
	s_cmp_eq_u32 s68, 40
	s_cselect_b32 s23, s5, s19
	s_cselect_b32 s22, s4, s18
	s_cselect_b32 s21, s15, s67
	s_cselect_b32 s20, s14, s66
	v_lshl_add_u64 v[216:217], s[16:17], 0, v[154:155]
	s_add_i32 m0, s38, 0xc000
	ds_read_b128 v[184:187], v170
	ds_read_b128 v[188:191], v170 offset:1024
	ds_read_b128 v[192:195], v170 offset:2048
	ds_read_b128 v[196:199], v170 offset:3072
	ds_read_b128 v[200:203], v170 offset:4096
	ds_read_b128 v[204:207], v170 offset:5120
	ds_read_b128 v[208:211], v170 offset:6144
	ds_read_b128 v[212:215], v170 offset:7168
	global_load_lds_dwordx4 v[216:217], off
	v_lshl_add_u64 v[216:217], s[16:17], 0, v[156:157]
	s_add_i32 m0, s38, 0xe000
	s_nop 0
	global_load_lds_dwordx4 v[216:217], off
	s_waitcnt vmcnt(8)
	s_waitcnt lgkmcnt(0)
	s_barrier
	s_waitcnt lgkmcnt(0)
	v_mfma_f32_16x16x32_bf16 v[142:145], v[122:125], v[184:187], v[142:145]
	v_mfma_f32_16x16x32_bf16 v[138:141], v[130:133], v[184:187], v[138:141]
	v_mfma_f32_16x16x32_bf16 v[118:121], v[122:125], v[192:195], v[118:121]
	v_mfma_f32_16x16x32_bf16 v[106:109], v[130:133], v[192:195], v[106:109]
	v_mfma_f32_16x16x32_bf16 v[102:105], v[122:125], v[200:203], v[102:105]
	v_mfma_f32_16x16x32_bf16 v[90:93], v[130:133], v[200:203], v[90:93]
	v_mfma_f32_16x16x32_bf16 v[86:89], v[122:125], v[208:211], v[86:89]
	v_mfma_f32_16x16x32_bf16 v[74:77], v[130:133], v[208:211], v[74:77]
	v_mfma_f32_16x16x32_bf16 v[142:145], v[126:129], v[188:191], v[142:145]
	v_mfma_f32_16x16x32_bf16 v[138:141], v[134:137], v[188:191], v[138:141]
	v_mfma_f32_16x16x32_bf16 v[118:121], v[126:129], v[196:199], v[118:121]
	v_mfma_f32_16x16x32_bf16 v[106:109], v[134:137], v[196:199], v[106:109]
	v_mfma_f32_16x16x32_bf16 v[102:105], v[126:129], v[204:207], v[102:105]
	v_mfma_f32_16x16x32_bf16 v[90:93], v[134:137], v[204:207], v[90:93]
	v_mfma_f32_16x16x32_bf16 v[86:89], v[126:129], v[212:215], v[86:89]
	v_mfma_f32_16x16x32_bf16 v[74:77], v[134:137], v[212:215], v[74:77]
	v_mfma_f32_16x16x32_bf16 v[114:117], v[162:165], v[184:187], v[114:117]
	v_mfma_f32_16x16x32_bf16 v[110:113], v[176:179], v[184:187], v[110:113]
	v_mfma_f32_16x16x32_bf16 v[98:101], v[162:165], v[192:195], v[98:101]
	v_mfma_f32_16x16x32_bf16 v[94:97], v[176:179], v[192:195], v[94:97]
	v_mfma_f32_16x16x32_bf16 v[82:85], v[162:165], v[200:203], v[82:85]
	v_mfma_f32_16x16x32_bf16 v[78:81], v[176:179], v[200:203], v[78:81]
	v_mfma_f32_16x16x32_bf16 v[70:73], v[162:165], v[208:211], v[70:73]
	v_mfma_f32_16x16x32_bf16 v[66:69], v[176:179], v[208:211], v[66:69]
	v_mfma_f32_16x16x32_bf16 v[114:117], v[172:175], v[188:191], v[114:117]
	v_mfma_f32_16x16x32_bf16 v[110:113], v[180:183], v[188:191], v[110:113]
	v_mfma_f32_16x16x32_bf16 v[98:101], v[172:175], v[196:199], v[98:101]
	v_mfma_f32_16x16x32_bf16 v[94:97], v[180:183], v[196:199], v[94:97]
	v_mfma_f32_16x16x32_bf16 v[82:85], v[172:175], v[204:207], v[82:85]
	v_mfma_f32_16x16x32_bf16 v[78:81], v[180:183], v[204:207], v[78:81]
	v_mfma_f32_16x16x32_bf16 v[70:73], v[172:175], v[212:215], v[70:73]
	v_mfma_f32_16x16x32_bf16 v[66:69], v[180:183], v[212:215], v[66:69]
	s_barrier
	s_add_i32 s16, s54, s36
	v_lshl_add_u64 v[216:217], s[20:21], 0, v[150:151]
	s_mov_b32 m0, s16
	ds_read_b128 v[184:187], v170 offset:16384
	ds_read_b128 v[188:191], v170 offset:17408
	ds_read_b128 v[192:195], v170 offset:18432
	ds_read_b128 v[196:199], v170 offset:19456
	ds_read_b128 v[200:203], v170 offset:20480
	ds_read_b128 v[204:207], v170 offset:21504
	ds_read_b128 v[208:211], v170 offset:22528
	ds_read_b128 v[212:215], v170 offset:23552
	global_load_lds_dwordx4 v[216:217], off
	s_add_i32 m0, s16, 0x2000
	s_add_u32 s16, s20, 0xb0000
	v_lshl_add_u64 v[218:219], s[20:21], 0, v[146:147]
	s_addc_u32 s17, s21, 0
	s_add_i32 s33, s55, s36
	global_load_lds_dwordx4 v[218:219], off
	v_lshl_add_u64 v[220:221], s[16:17], 0, v[150:151]
	s_mov_b32 m0, s33
	v_lshl_add_u64 v[222:223], s[22:23], 0, v[148:149]
	global_load_lds_dwordx4 v[220:221], off
	v_lshl_add_u64 v[220:221], s[16:17], 0, v[146:147]
	s_add_i32 m0, s33, 0x2000
	s_nop 0
	global_load_lds_dwordx4 v[220:221], off
	v_lshl_add_u64 v[220:221], s[22:23], 0, v[152:153]
	s_mov_b32 m0, s38
	s_nop 0
	global_load_lds_dwordx4 v[220:221], off
	s_mov_b32 m0, s39
	s_nop 0
	global_load_lds_dwordx4 v[222:223], off
	s_waitcnt vmcnt(8)
	s_waitcnt lgkmcnt(0)
	s_barrier
; #define PG8_STAGE(bufoff, gbase, voff) do { _Pragma("unroll") for (int _i = 0; _i < 2; ++_i) \
;         __builtin_amdgcn_global_load_lds((const unsigned*)((const char*)(gbase) + (voff)[_i]), (LAS unsigned*)(lds + (bufoff) + ldsw + _i * 8192), 16, 0, 0); } while (0)
; #define PG8_LDA(dst, b, h) do { _Pragma("unroll") for (int m = 0; m < 4; ++m) _Pragma("unroll") for (int k = 0; k < 2; ++k) dst[m][k] = *(const LAS bf16x8*)(lds + PG8_SA(b, h) + aoff + m * 2048 + k * 1024); } while (0)
; #define PG8_LDB(dst, b, h) do { _Pragma("unroll") for (int n = 0; n < 2; ++n) _Pragma("unroll") for (int k = 0; k < 2; ++k) dst[n][k] = *(const LAS bf16x8*)(lds + PG8_SB(b, h) + boff + n * 2048 + k * 1024); } while (0)
; #define PG8_MMA(ai, bj, At, Bt) do { __builtin_amdgcn_s_setprio(1); _Pragma("unroll") for (int m = 0; m < 4; ++m) _Pragma("unroll") for (int n = 0; n < 2; ++n) _Pragma("unroll") for (int k = 0; k < 2; ++k) \
;         acc[ai][bj][m][n] = __builtin_amdgcn_mfma_f32_16x16x32_bf16(Bt[n][k], At[m][k], acc[ai][bj][m][n], 0, 0, 0); __builtin_amdgcn_s_setprio(0); } while (0)
; #define PG8_WAIT_V(n) asm volatile("s_waitcnt vmcnt(" #n ")" ::: "memory")
; #define PG8_WAIT_L(n) asm volatile("s_waitcnt lgkmcnt(" #n ")" ::: "memory")
; #define PG8_BAR __builtin_amdgcn_s_barrier()
; #define PG8_SCHED __builtin_amdgcn_sched_barrier(0)
; template <class Epi>
; __device__ __forceinline__ void gemm_phase(LAS unsigned char* lds, const Gemm g, int G, int c, const Epi& E) {
;     ...
;             PG8_WAIT_V(8); PG8_WAIT_L(0); PG8_BAR; PG8_MMA(0, 0, At, B0); PG8_MMA(0, 1, At, B1); PG8_BAR; PG8_SCHED;
;             PG8_LDA(At, 0, 1); PG8_STAGE(PG8_SB(0, 0), b2, voffB); PG8_STAGE(PG8_SB(0, 1), b2 + hstepB, voffB); PG8_STAGE(PG8_SA(0, 0), a2, voffA);
;             PG8_WAIT_V(8); PG8_WAIT_L(0); PG8_BAR; PG8_MMA(1, 0, At, B0); PG8_MMA(1, 1, At, B1); PG8_BAR; PG8_SCHED;
;             PG8_LDB(B0, 1, 0); PG8_LDB(B1, 1, 1); PG8_SCHED; PG8_LDA(At, 1, 0); PG8_STAGE(PG8_SA(0, 1), a2 + hstepA, voffA);
;             PG8_WAIT_V(8); PG8_WAIT_L(0); PG8_BAR; PG8_MMA(0, 0, At, B0); PG8_MMA(0, 1, At, B1); PG8_BAR; PG8_SCHED;
;             PG8_LDA(At, 1, 1); PG8_STAGE(PG8_SB(1, 0), b3, voffB); PG8_STAGE(PG8_SB(1, 1), b3 + hstepB, voffB); PG8_STAGE(PG8_SA(1, 0), a3, voffA);
	s_waitcnt lgkmcnt(0)
	v_mfma_f32_16x16x32_bf16 v[62:65], v[122:125], v[184:187], v[62:65]
	v_mfma_f32_16x16x32_bf16 v[58:61], v[130:133], v[184:187], v[58:61]
	v_mfma_f32_16x16x32_bf16 v[54:57], v[122:125], v[192:195], v[54:57]
	v_mfma_f32_16x16x32_bf16 v[42:45], v[130:133], v[192:195], v[42:45]
	v_mfma_f32_16x16x32_bf16 v[38:41], v[122:125], v[200:203], v[38:41]
	v_mfma_f32_16x16x32_bf16 v[26:29], v[130:133], v[200:203], v[26:29]
	v_mfma_f32_16x16x32_bf16 v[22:25], v[122:125], v[208:211], v[22:25]
	v_mfma_f32_16x16x32_bf16 v[10:13], v[130:133], v[208:211], v[10:13]
	v_mfma_f32_16x16x32_bf16 v[62:65], v[126:129], v[188:191], v[62:65]
	v_mfma_f32_16x16x32_bf16 v[58:61], v[134:137], v[188:191], v[58:61]
	v_mfma_f32_16x16x32_bf16 v[54:57], v[126:129], v[196:199], v[54:57]
	v_mfma_f32_16x16x32_bf16 v[42:45], v[134:137], v[196:199], v[42:45]
	v_mfma_f32_16x16x32_bf16 v[38:41], v[126:129], v[204:207], v[38:41]
	v_mfma_f32_16x16x32_bf16 v[26:29], v[134:137], v[204:207], v[26:29]
	v_mfma_f32_16x16x32_bf16 v[22:25], v[126:129], v[212:215], v[22:25]
	v_mfma_f32_16x16x32_bf16 v[10:13], v[134:137], v[212:215], v[10:13]
	v_mfma_f32_16x16x32_bf16 v[50:53], v[162:165], v[184:187], v[50:53]
	v_mfma_f32_16x16x32_bf16 v[46:49], v[176:179], v[184:187], v[46:49]
	v_mfma_f32_16x16x32_bf16 v[34:37], v[162:165], v[192:195], v[34:37]
	v_mfma_f32_16x16x32_bf16 v[30:33], v[176:179], v[192:195], v[30:33]
	v_mfma_f32_16x16x32_bf16 v[18:21], v[162:165], v[200:203], v[18:21]
	v_mfma_f32_16x16x32_bf16 v[14:17], v[176:179], v[200:203], v[14:17]
	v_mfma_f32_16x16x32_bf16 v[6:9], v[162:165], v[208:211], v[6:9]
	v_mfma_f32_16x16x32_bf16 v[2:5], v[176:179], v[208:211], v[2:5]
	v_mfma_f32_16x16x32_bf16 v[50:53], v[172:175], v[188:191], v[50:53]
	v_mfma_f32_16x16x32_bf16 v[46:49], v[180:183], v[188:191], v[46:49]
	v_mfma_f32_16x16x32_bf16 v[34:37], v[172:175], v[196:199], v[34:37]
	v_mfma_f32_16x16x32_bf16 v[30:33], v[180:183], v[196:199], v[30:33]
	v_mfma_f32_16x16x32_bf16 v[18:21], v[172:175], v[204:207], v[18:21]
	v_mfma_f32_16x16x32_bf16 v[14:17], v[180:183], v[204:207], v[14:17]
	v_mfma_f32_16x16x32_bf16 v[6:9], v[172:175], v[212:215], v[6:9]
	v_mfma_f32_16x16x32_bf16 v[2:5], v[180:183], v[212:215], v[2:5]
	s_barrier
	s_add_i32 s33, 0, 0x18000
	s_add_i32 s62, 0, 0x1c000
	v_add_u32_e32 v134, s33, v167
	v_add_u32_e32 v171, s62, v167
	ds_read_b128 v[122:125], v134
	ds_read_b128 v[126:129], v134 offset:1024
	ds_read_b128 v[130:133], v134 offset:2048
	ds_read_b128 v[134:137], v134 offset:3072
	ds_read_b128 v[162:165], v171
	ds_read_b128 v[172:175], v171 offset:1024
	ds_read_b128 v[176:179], v171 offset:2048
	ds_read_b128 v[180:183], v171 offset:3072
	s_add_u32 s16, s22, 0xb0000
	s_addc_u32 s17, s23, 0
	s_mov_b32 m0, s40
	v_lshl_add_u64 v[224:225], s[16:17], 0, v[152:153]
	ds_read_b128 v[184:187], v170 offset:32768
	ds_read_b128 v[188:191], v170 offset:33792
	ds_read_b128 v[192:195], v170 offset:34816
	ds_read_b128 v[196:199], v170 offset:35840
	ds_read_b128 v[200:203], v170 offset:36864
	ds_read_b128 v[204:207], v170 offset:37888
	ds_read_b128 v[208:211], v170 offset:38912
	ds_read_b128 v[212:215], v170 offset:39936
	global_load_lds_dwordx4 v[224:225], off
	v_lshl_add_u64 v[224:225], s[16:17], 0, v[148:149]
	s_mov_b32 m0, s41
	s_nop 0
	global_load_lds_dwordx4 v[224:225], off
	s_waitcnt vmcnt(8)
	s_waitcnt lgkmcnt(0)
	s_barrier
	s_waitcnt lgkmcnt(0)
	v_mfma_f32_16x16x32_bf16 v[142:145], v[122:125], v[184:187], v[142:145]
	v_mfma_f32_16x16x32_bf16 v[138:141], v[130:133], v[184:187], v[138:141]
	v_mfma_f32_16x16x32_bf16 v[118:121], v[122:125], v[192:195], v[118:121]
	v_mfma_f32_16x16x32_bf16 v[106:109], v[130:133], v[192:195], v[106:109]
	v_mfma_f32_16x16x32_bf16 v[102:105], v[122:125], v[200:203], v[102:105]
	v_mfma_f32_16x16x32_bf16 v[90:93], v[130:133], v[200:203], v[90:93]
	v_mfma_f32_16x16x32_bf16 v[86:89], v[122:125], v[208:211], v[86:89]
	v_mfma_f32_16x16x32_bf16 v[74:77], v[130:133], v[208:211], v[74:77]
	v_mfma_f32_16x16x32_bf16 v[142:145], v[126:129], v[188:191], v[142:145]
	v_mfma_f32_16x16x32_bf16 v[138:141], v[134:137], v[188:191], v[138:141]
	v_mfma_f32_16x16x32_bf16 v[118:121], v[126:129], v[196:199], v[118:121]
	v_mfma_f32_16x16x32_bf16 v[106:109], v[134:137], v[196:199], v[106:109]
	v_mfma_f32_16x16x32_bf16 v[102:105], v[126:129], v[204:207], v[102:105]
	v_mfma_f32_16x16x32_bf16 v[90:93], v[134:137], v[204:207], v[90:93]
	v_mfma_f32_16x16x32_bf16 v[86:89], v[126:129], v[212:215], v[86:89]
	v_mfma_f32_16x16x32_bf16 v[74:77], v[134:137], v[212:215], v[74:77]
	v_mfma_f32_16x16x32_bf16 v[114:117], v[162:165], v[184:187], v[114:117]
	v_mfma_f32_16x16x32_bf16 v[110:113], v[176:179], v[184:187], v[110:113]
	v_mfma_f32_16x16x32_bf16 v[98:101], v[162:165], v[192:195], v[98:101]
	v_mfma_f32_16x16x32_bf16 v[94:97], v[176:179], v[192:195], v[94:97]
	v_mfma_f32_16x16x32_bf16 v[82:85], v[162:165], v[200:203], v[82:85]
	v_mfma_f32_16x16x32_bf16 v[78:81], v[176:179], v[200:203], v[78:81]
	v_mfma_f32_16x16x32_bf16 v[70:73], v[162:165], v[208:211], v[70:73]
	v_mfma_f32_16x16x32_bf16 v[66:69], v[176:179], v[208:211], v[66:69]
	v_mfma_f32_16x16x32_bf16 v[114:117], v[172:175], v[188:191], v[114:117]
	v_mfma_f32_16x16x32_bf16 v[110:113], v[180:183], v[188:191], v[110:113]
	v_mfma_f32_16x16x32_bf16 v[98:101], v[172:175], v[196:199], v[98:101]
	v_mfma_f32_16x16x32_bf16 v[94:97], v[180:183], v[196:199], v[94:97]
	v_mfma_f32_16x16x32_bf16 v[82:85], v[172:175], v[204:207], v[82:85]
	v_mfma_f32_16x16x32_bf16 v[78:81], v[180:183], v[204:207], v[78:81]
	v_mfma_f32_16x16x32_bf16 v[70:73], v[172:175], v[212:215], v[70:73]
	v_mfma_f32_16x16x32_bf16 v[66:69], v[180:183], v[212:215], v[66:69]
	s_barrier
; #define PG8_STAGE(bufoff, gbase, voff) do { _Pragma("unroll") for (int _i = 0; _i < 2; ++_i) \
;         __builtin_amdgcn_global_load_lds((const unsigned*)((const char*)(gbase) + (voff)[_i]), (LAS unsigned*)(lds + (bufoff) + ldsw + _i * 8192), 16, 0, 0); } while (0)
; #define PG8_LDA(dst, b, h) do { _Pragma("unroll") for (int m = 0; m < 4; ++m) _Pragma("unroll") for (int k = 0; k < 2; ++k) dst[m][k] = *(const LAS bf16x8*)(lds + PG8_SA(b, h) + aoff + m * 2048 + k * 1024); } while (0)
; #define PG8_LDB(dst, b, h) do { _Pragma("unroll") for (int n = 0; n < 2; ++n) _Pragma("unroll") for (int k = 0; k < 2; ++k) dst[n][k] = *(const LAS bf16x8*)(lds + PG8_SB(b, h) + boff + n * 2048 + k * 1024); } while (0)
; #define PG8_MMA(ai, bj, At, Bt) do { __builtin_amdgcn_s_setprio(1); _Pragma("unroll") for (int m = 0; m < 4; ++m) _Pragma("unroll") for (int n = 0; n < 2; ++n) _Pragma("unroll") for (int k = 0; k < 2; ++k) \
;         acc[ai][bj][m][n] = __builtin_amdgcn_mfma_f32_16x16x32_bf16(Bt[n][k], At[m][k], acc[ai][bj][m][n], 0, 0, 0); __builtin_amdgcn_s_setprio(0); } while (0)
; #define PG8_WAIT_V(n) asm volatile("s_waitcnt vmcnt(" #n ")" ::: "memory")
; #define PG8_WAIT_L(n) asm volatile("s_waitcnt lgkmcnt(" #n ")" ::: "memory")
; #define PG8_BAR __builtin_amdgcn_s_barrier()
; #define PG8_SCHED __builtin_amdgcn_sched_barrier(0)
; template <class Epi>
; __device__ __forceinline__ void gemm_phase(LAS unsigned char* lds, const Gemm g, int G, int c, const Epi& E) {
;     ...
;             PG8_LDB(B0, 1, 0); PG8_LDB(B1, 1, 1); PG8_SCHED; PG8_LDA(At, 1, 0); PG8_STAGE(PG8_SA(0, 1), a2 + hstepA, voffA);
;             PG8_WAIT_V(8); PG8_WAIT_L(0); PG8_BAR; PG8_MMA(0, 0, At, B0); PG8_MMA(0, 1, At, B1); PG8_BAR; PG8_SCHED;
;             PG8_LDA(At, 1, 1); PG8_STAGE(PG8_SB(1, 0), b3, voffB); PG8_STAGE(PG8_SB(1, 1), b3 + hstepB, voffB); PG8_STAGE(PG8_SA(1, 0), a3, voffA);
;             PG8_WAIT_V(8); PG8_WAIT_L(0); PG8_BAR; PG8_MMA(1, 0, At, B0); PG8_MMA(1, 1, At, B1); PG8_BAR; PG8_SCHED;
;         }
	s_add_i32 s16, s33, s36
	v_lshl_add_u64 v[216:217], v[216:217], 0, s[10:11]
	s_mov_b32 m0, s16
	ds_read_b128 v[184:187], v170 offset:49152
	ds_read_b128 v[188:191], v170 offset:50176
	ds_read_b128 v[192:195], v170 offset:51200
	ds_read_b128 v[196:199], v170 offset:52224
	ds_read_b128 v[200:203], v170 offset:53248
	ds_read_b128 v[204:207], v170 offset:54272
	ds_read_b128 v[208:211], v170 offset:55296
	ds_read_b128 v[212:215], v170 offset:56320
	global_load_lds_dwordx4 v[216:217], off
	s_add_i32 m0, s16, 0x2000
	s_add_u32 s16, s20, 0xb0080
	v_lshl_add_u64 v[216:217], v[218:219], 0, s[10:11]
	s_addc_u32 s17, s21, 0
	s_add_i32 s20, s62, s36
	global_load_lds_dwordx4 v[216:217], off
	v_lshl_add_u64 v[216:217], s[16:17], 0, v[150:151]
	s_mov_b32 m0, s20
	s_nop 0
	global_load_lds_dwordx4 v[216:217], off
	v_lshl_add_u64 v[216:217], s[16:17], 0, v[146:147]
	s_add_i32 m0, s20, 0x2000
	s_nop 0
	global_load_lds_dwordx4 v[216:217], off
	v_lshl_add_u64 v[216:217], v[220:221], 0, s[10:11]
	s_mov_b32 m0, s47
	s_nop 0
	global_load_lds_dwordx4 v[216:217], off
	v_lshl_add_u64 v[216:217], v[222:223], 0, s[10:11]
	s_mov_b32 m0, s52
	s_nop 0
	global_load_lds_dwordx4 v[216:217], off
	s_waitcnt vmcnt(8)
	s_waitcnt lgkmcnt(0)
	s_barrier
	s_waitcnt lgkmcnt(0)
	v_mfma_f32_16x16x32_bf16 v[62:65], v[122:125], v[184:187], v[62:65]
	v_mfma_f32_16x16x32_bf16 v[58:61], v[130:133], v[184:187], v[58:61]
	v_mfma_f32_16x16x32_bf16 v[54:57], v[122:125], v[192:195], v[54:57]
	v_mfma_f32_16x16x32_bf16 v[42:45], v[130:133], v[192:195], v[42:45]
	v_mfma_f32_16x16x32_bf16 v[38:41], v[122:125], v[200:203], v[38:41]
	v_mfma_f32_16x16x32_bf16 v[26:29], v[130:133], v[200:203], v[26:29]
	v_mfma_f32_16x16x32_bf16 v[22:25], v[122:125], v[208:211], v[22:25]
	v_mfma_f32_16x16x32_bf16 v[10:13], v[130:133], v[208:211], v[10:13]
	v_mfma_f32_16x16x32_bf16 v[62:65], v[126:129], v[188:191], v[62:65]
	v_mfma_f32_16x16x32_bf16 v[58:61], v[134:137], v[188:191], v[58:61]
	v_mfma_f32_16x16x32_bf16 v[54:57], v[126:129], v[196:199], v[54:57]
	v_mfma_f32_16x16x32_bf16 v[42:45], v[134:137], v[196:199], v[42:45]
	v_mfma_f32_16x16x32_bf16 v[38:41], v[126:129], v[204:207], v[38:41]
	v_mfma_f32_16x16x32_bf16 v[26:29], v[134:137], v[204:207], v[26:29]
	v_mfma_f32_16x16x32_bf16 v[22:25], v[126:129], v[212:215], v[22:25]
	v_mfma_f32_16x16x32_bf16 v[10:13], v[134:137], v[212:215], v[10:13]
	v_mfma_f32_16x16x32_bf16 v[50:53], v[162:165], v[184:187], v[50:53]
	v_mfma_f32_16x16x32_bf16 v[46:49], v[176:179], v[184:187], v[46:49]
	v_mfma_f32_16x16x32_bf16 v[34:37], v[162:165], v[192:195], v[34:37]
	v_mfma_f32_16x16x32_bf16 v[30:33], v[176:179], v[192:195], v[30:33]
	v_mfma_f32_16x16x32_bf16 v[18:21], v[162:165], v[200:203], v[18:21]
	v_mfma_f32_16x16x32_bf16 v[14:17], v[176:179], v[200:203], v[14:17]
	v_mfma_f32_16x16x32_bf16 v[6:9], v[162:165], v[208:211], v[6:9]
	v_mfma_f32_16x16x32_bf16 v[2:5], v[176:179], v[208:211], v[2:5]
	v_mfma_f32_16x16x32_bf16 v[50:53], v[172:175], v[188:191], v[50:53]
	v_mfma_f32_16x16x32_bf16 v[46:49], v[180:183], v[188:191], v[46:49]
	v_mfma_f32_16x16x32_bf16 v[34:37], v[172:175], v[196:199], v[34:37]
	v_mfma_f32_16x16x32_bf16 v[30:33], v[180:183], v[196:199], v[30:33]
	v_mfma_f32_16x16x32_bf16 v[18:21], v[172:175], v[204:207], v[18:21]
	v_mfma_f32_16x16x32_bf16 v[14:17], v[180:183], v[204:207], v[14:17]
	v_mfma_f32_16x16x32_bf16 v[6:9], v[172:175], v[212:215], v[6:9]
	v_mfma_f32_16x16x32_bf16 v[2:5], v[180:183], v[212:215], v[2:5]
	s_barrier
	s_add_i32 s68, s68, 2
	s_add_u32 s66, s66, 0x100
	s_addc_u32 s67, s67, 0
	s_cmp_gt_u32 s68, 41
	s_mov_b64 s[16:17], s[18:19]
	s_cbranch_scc0 .LBB0_1143
	s_and_b64 vcc, exec, s[12:13]
	s_cbranch_vccz .LBB0_1146
	s_barrier

; #define PG8_STAGE(bufoff, gbase, voff) do { _Pragma("unroll") for (int _i = 0; _i < 2; ++_i) \
;         __builtin_amdgcn_global_load_lds((const unsigned*)((const char*)(gbase) + (voff)[_i]), (LAS unsigned*)(lds + (bufoff) + ldsw + _i * 8192), 16, 0, 0); } while (0)
; #define PG8_LDA(dst, b, h) do { _Pragma("unroll") for (int m = 0; m < 4; ++m) _Pragma("unroll") for (int k = 0; k < 2; ++k) dst[m][k] = *(const LAS bf16x8*)(lds + PG8_SA(b, h) + aoff + m * 2048 + k * 1024); } while (0)
; #define PG8_LDB(dst, b, h) do { _Pragma("unroll") for (int n = 0; n < 2; ++n) _Pragma("unroll") for (int k = 0; k < 2; ++k) dst[n][k] = *(const LAS bf16x8*)(lds + PG8_SB(b, h) + boff + n * 2048 + k * 1024); } while (0)
; #define PG8_MMA(ai, bj, At, Bt) do { __builtin_amdgcn_s_setprio(1); _Pragma("unroll") for (int m = 0; m < 4; ++m) _Pragma("unroll") for (int n = 0; n < 2; ++n) _Pragma("unroll") for (int k = 0; k < 2; ++k) \
;         acc[ai][bj][m][n] = __builtin_amdgcn_mfma_f32_16x16x32_bf16(Bt[n][k], At[m][k], acc[ai][bj][m][n], 0, 0, 0); __builtin_amdgcn_s_setprio(0); } while (0)
; #define PG8_WAIT_V(n) asm volatile("s_waitcnt vmcnt(" #n ")" ::: "memory")
; #define PG8_WAIT_L(n) asm volatile("s_waitcnt lgkmcnt(" #n ")" ::: "memory")
; #define PG8_BAR __builtin_amdgcn_s_barrier()
; #define PG8_SCHED __builtin_amdgcn_sched_barrier(0)
; template <class Epi>
; __device__ __forceinline__ void gemm_phase(LAS unsigned char* lds, const Gemm g, int G, int c, const Epi& E) {
;     ...
;             const bool last = (t == nt - 2);
;             const char* a1 = cA + (size_t)(t + 1) * kstep;
;             const char* a2 = last ? nA : cA + (size_t)(t + 2) * kstep; const char* b2 = last ? nB : cB + (size_t)(t + 2) * kstep;
;             const char* a3 = a2 + kstep; const char* b3 = b2 + kstep;
;             PG8_LDB(B0, 0, 0); PG8_LDB(B1, 0, 1); PG8_SCHED; PG8_LDA(At, 0, 0); PG8_STAGE(PG8_SA(1, 1), a1 + hstepA, voffA);
;             PG8_WAIT_V(8); PG8_WAIT_L(0); PG8_BAR; PG8_MMA(0, 0, At, B0); PG8_MMA(0, 1, At, B1); PG8_BAR; PG8_SCHED;
.LBB0_1297:
	ds_read_b128 v[146:149], v152
	ds_read_b128 v[158:161], v152 offset:1024
	ds_read_b128 v[162:165], v152 offset:2048
	ds_read_b128 v[166:169], v152 offset:3072
	ds_read_b128 v[170:173], v153
	ds_read_b128 v[174:177], v153 offset:1024
	ds_read_b128 v[178:181], v153 offset:2048
	ds_read_b128 v[182:185], v153 offset:3072
	s_add_u32 s33, s4, 0xfffc0080
	s_addc_u32 s46, s5, -1
	s_cmp_eq_u32 s81, 12
	s_cselect_b32 s49, s43, s46
	s_cselect_b32 s48, s42, s33
	s_cselect_b32 s47, s7, s80
	s_cselect_b32 s46, s39, s41
	v_lshl_add_u64 v[218:219], s[4:5], 0, v[138:139]
	s_add_i32 m0, s11, 0xc000
	ds_read_b128 v[186:189], v154
	ds_read_b128 v[190:193], v154 offset:1024
	ds_read_b128 v[194:197], v154 offset:2048
	ds_read_b128 v[198:201], v154 offset:3072
	ds_read_b128 v[202:205], v154 offset:4096
	ds_read_b128 v[206:209], v154 offset:5120
	ds_read_b128 v[210:213], v154 offset:6144
	ds_read_b128 v[214:217], v154 offset:7168
	global_load_lds_dwordx4 v[218:219], off
	v_lshl_add_u64 v[218:219], s[4:5], 0, v[140:141]
	s_add_i32 m0, s11, 0xe000
	s_nop 0
	global_load_lds_dwordx4 v[218:219], off
	s_waitcnt vmcnt(8)
	s_waitcnt lgkmcnt(0)
	s_barrier
	s_waitcnt lgkmcnt(0)
	v_mfma_f32_16x16x32_bf16 v[126:129], v[146:149], v[186:189], v[126:129]
	v_mfma_f32_16x16x32_bf16 v[122:125], v[162:165], v[186:189], v[122:125]
	v_mfma_f32_16x16x32_bf16 v[110:113], v[146:149], v[194:197], v[110:113]
	v_mfma_f32_16x16x32_bf16 v[106:109], v[162:165], v[194:197], v[106:109]
	v_mfma_f32_16x16x32_bf16 v[94:97], v[146:149], v[202:205], v[94:97]
	v_mfma_f32_16x16x32_bf16 v[90:93], v[162:165], v[202:205], v[90:93]
	v_mfma_f32_16x16x32_bf16 v[78:81], v[146:149], v[210:213], v[78:81]
	v_mfma_f32_16x16x32_bf16 v[74:77], v[162:165], v[210:213], v[74:77]
	v_mfma_f32_16x16x32_bf16 v[126:129], v[158:161], v[190:193], v[126:129]
	v_mfma_f32_16x16x32_bf16 v[122:125], v[166:169], v[190:193], v[122:125]
	v_mfma_f32_16x16x32_bf16 v[110:113], v[158:161], v[198:201], v[110:113]
	v_mfma_f32_16x16x32_bf16 v[106:109], v[166:169], v[198:201], v[106:109]
	v_mfma_f32_16x16x32_bf16 v[94:97], v[158:161], v[206:209], v[94:97]
	v_mfma_f32_16x16x32_bf16 v[90:93], v[166:169], v[206:209], v[90:93]
	v_mfma_f32_16x16x32_bf16 v[78:81], v[158:161], v[214:217], v[78:81]
	v_mfma_f32_16x16x32_bf16 v[74:77], v[166:169], v[214:217], v[74:77]
	v_mfma_f32_16x16x32_bf16 v[118:121], v[170:173], v[186:189], v[118:121]
	v_mfma_f32_16x16x32_bf16 v[114:117], v[178:181], v[186:189], v[114:117]
	v_mfma_f32_16x16x32_bf16 v[102:105], v[170:173], v[194:197], v[102:105]
	v_mfma_f32_16x16x32_bf16 v[98:101], v[178:181], v[194:197], v[98:101]
	v_mfma_f32_16x16x32_bf16 v[86:89], v[170:173], v[202:205], v[86:89]
	v_mfma_f32_16x16x32_bf16 v[82:85], v[178:181], v[202:205], v[82:85]
	v_mfma_f32_16x16x32_bf16 v[70:73], v[170:173], v[210:213], v[70:73]
	v_mfma_f32_16x16x32_bf16 v[66:69], v[178:181], v[210:213], v[66:69]
	v_mfma_f32_16x16x32_bf16 v[118:121], v[174:177], v[190:193], v[118:121]
	v_mfma_f32_16x16x32_bf16 v[114:117], v[182:185], v[190:193], v[114:117]
	v_mfma_f32_16x16x32_bf16 v[102:105], v[174:177], v[198:201], v[102:105]
	v_mfma_f32_16x16x32_bf16 v[98:101], v[182:185], v[198:201], v[98:101]
	v_mfma_f32_16x16x32_bf16 v[86:89], v[174:177], v[206:209], v[86:89]
	v_mfma_f32_16x16x32_bf16 v[82:85], v[182:185], v[206:209], v[82:85]
	v_mfma_f32_16x16x32_bf16 v[70:73], v[174:177], v[214:217], v[70:73]
	v_mfma_f32_16x16x32_bf16 v[66:69], v[182:185], v[214:217], v[66:69]
	s_barrier
	s_add_i32 s33, s71, s56
	v_lshl_add_u64 v[218:219], s[46:47], 0, v[132:133]
	s_mov_b32 m0, s33
	ds_read_b128 v[186:189], v154 offset:16384
	ds_read_b128 v[190:193], v154 offset:17408
	ds_read_b128 v[194:197], v154 offset:18432
	ds_read_b128 v[198:201], v154 offset:19456
	ds_read_b128 v[202:205], v154 offset:20480
	ds_read_b128 v[206:209], v154 offset:21504
	ds_read_b128 v[210:213], v154 offset:22528
	ds_read_b128 v[214:217], v154 offset:23552
	global_load_lds_dwordx4 v[218:219], off
	s_add_i32 m0, s33, 0x2000
	s_add_u32 s62, s46, 0x40000
	v_lshl_add_u64 v[220:221], s[46:47], 0, v[136:137]
	s_addc_u32 s63, s47, 0
	s_add_i32 s33, s72, s56
	global_load_lds_dwordx4 v[220:221], off
	v_lshl_add_u64 v[222:223], s[62:63], 0, v[132:133]
	s_mov_b32 m0, s33
	v_lshl_add_u64 v[224:225], s[48:49], 0, v[134:135]
	global_load_lds_dwordx4 v[222:223], off
	v_lshl_add_u64 v[222:223], s[62:63], 0, v[136:137]
	s_add_i32 m0, s33, 0x2000
	s_nop 0
	global_load_lds_dwordx4 v[222:223], off
	v_lshl_add_u64 v[222:223], s[48:49], 0, v[130:131]
	s_mov_b32 m0, s11
	s_nop 0
	global_load_lds_dwordx4 v[222:223], off
	s_mov_b32 m0, s57
	s_nop 0
	global_load_lds_dwordx4 v[224:225], off
	s_waitcnt vmcnt(8)
	s_waitcnt lgkmcnt(0)
	s_barrier
; #define PG8_STAGE(bufoff, gbase, voff) do { _Pragma("unroll") for (int _i = 0; _i < 2; ++_i) \
;         __builtin_amdgcn_global_load_lds((const unsigned*)((const char*)(gbase) + (voff)[_i]), (LAS unsigned*)(lds + (bufoff) + ldsw + _i * 8192), 16, 0, 0); } while (0)
; #define PG8_LDA(dst, b, h) do { _Pragma("unroll") for (int m = 0; m < 4; ++m) _Pragma("unroll") for (int k = 0; k < 2; ++k) dst[m][k] = *(const LAS bf16x8*)(lds + PG8_SA(b, h) + aoff + m * 2048 + k * 1024); } while (0)
; #define PG8_LDB(dst, b, h) do { _Pragma("unroll") for (int n = 0; n < 2; ++n) _Pragma("unroll") for (int k = 0; k < 2; ++k) dst[n][k] = *(const LAS bf16x8*)(lds + PG8_SB(b, h) + boff + n * 2048 + k * 1024); } while (0)
; #define PG8_MMA(ai, bj, At, Bt) do { __builtin_amdgcn_s_setprio(1); _Pragma("unroll") for (int m = 0; m < 4; ++m) _Pragma("unroll") for (int n = 0; n < 2; ++n) _Pragma("unroll") for (int k = 0; k < 2; ++k) \
;         acc[ai][bj][m][n] = __builtin_amdgcn_mfma_f32_16x16x32_bf16(Bt[n][k], At[m][k], acc[ai][bj][m][n], 0, 0, 0); __builtin_amdgcn_s_setprio(0); } while (0)
; #define PG8_WAIT_V(n) asm volatile("s_waitcnt vmcnt(" #n ")" ::: "memory")
; #define PG8_WAIT_L(n) asm volatile("s_waitcnt lgkmcnt(" #n ")" ::: "memory")
; #define PG8_BAR __builtin_amdgcn_s_barrier()
; #define PG8_SCHED __builtin_amdgcn_sched_barrier(0)
; template <class Epi>
; __device__ __forceinline__ void gemm_phase(LAS unsigned char* lds, const Gemm g, int G, int c, const Epi& E) {
;     ...
;             PG8_WAIT_V(8); PG8_WAIT_L(0); PG8_BAR; PG8_MMA(0, 0, At, B0); PG8_MMA(0, 1, At, B1); PG8_BAR; PG8_SCHED;
;             PG8_LDA(At, 0, 1); PG8_STAGE(PG8_SB(0, 0), b2, voffB); PG8_STAGE(PG8_SB(0, 1), b2 + hstepB, voffB); PG8_STAGE(PG8_SA(0, 0), a2, voffA);
;             PG8_WAIT_V(8); PG8_WAIT_L(0); PG8_BAR; PG8_MMA(1, 0, At, B0); PG8_MMA(1, 1, At, B1); PG8_BAR; PG8_SCHED;
;             PG8_LDB(B0, 1, 0); PG8_LDB(B1, 1, 1); PG8_SCHED; PG8_LDA(At, 1, 0); PG8_STAGE(PG8_SA(0, 1), a2 + hstepA, voffA);
;             PG8_WAIT_V(8); PG8_WAIT_L(0); PG8_BAR; PG8_MMA(0, 0, At, B0); PG8_MMA(0, 1, At, B1); PG8_BAR; PG8_SCHED;
;             PG8_LDA(At, 1, 1); PG8_STAGE(PG8_SB(1, 0), b3, voffB); PG8_STAGE(PG8_SB(1, 1), b3 + hstepB, voffB); PG8_STAGE(PG8_SA(1, 0), a3, voffA);
	s_waitcnt lgkmcnt(0)
	v_mfma_f32_16x16x32_bf16 v[62:65], v[146:149], v[186:189], v[62:65]
	v_mfma_f32_16x16x32_bf16 v[58:61], v[162:165], v[186:189], v[58:61]
	v_mfma_f32_16x16x32_bf16 v[46:49], v[146:149], v[194:197], v[46:49]
	v_mfma_f32_16x16x32_bf16 v[42:45], v[162:165], v[194:197], v[42:45]
	v_mfma_f32_16x16x32_bf16 v[30:33], v[146:149], v[202:205], v[30:33]
	v_mfma_f32_16x16x32_bf16 v[26:29], v[162:165], v[202:205], v[26:29]
	v_mfma_f32_16x16x32_bf16 v[14:17], v[146:149], v[210:213], v[14:17]
	v_mfma_f32_16x16x32_bf16 v[10:13], v[162:165], v[210:213], v[10:13]
	v_mfma_f32_16x16x32_bf16 v[62:65], v[158:161], v[190:193], v[62:65]
	v_mfma_f32_16x16x32_bf16 v[58:61], v[166:169], v[190:193], v[58:61]
	v_mfma_f32_16x16x32_bf16 v[46:49], v[158:161], v[198:201], v[46:49]
	v_mfma_f32_16x16x32_bf16 v[42:45], v[166:169], v[198:201], v[42:45]
	v_mfma_f32_16x16x32_bf16 v[30:33], v[158:161], v[206:209], v[30:33]
	v_mfma_f32_16x16x32_bf16 v[26:29], v[166:169], v[206:209], v[26:29]
	v_mfma_f32_16x16x32_bf16 v[14:17], v[158:161], v[214:217], v[14:17]
	v_mfma_f32_16x16x32_bf16 v[10:13], v[166:169], v[214:217], v[10:13]
	v_mfma_f32_16x16x32_bf16 v[54:57], v[170:173], v[186:189], v[54:57]
	v_mfma_f32_16x16x32_bf16 v[50:53], v[178:181], v[186:189], v[50:53]
	v_mfma_f32_16x16x32_bf16 v[38:41], v[170:173], v[194:197], v[38:41]
	v_mfma_f32_16x16x32_bf16 v[34:37], v[178:181], v[194:197], v[34:37]
	v_mfma_f32_16x16x32_bf16 v[22:25], v[170:173], v[202:205], v[22:25]
	v_mfma_f32_16x16x32_bf16 v[18:21], v[178:181], v[202:205], v[18:21]
	v_mfma_f32_16x16x32_bf16 v[6:9], v[170:173], v[210:213], v[6:9]
	v_mfma_f32_16x16x32_bf16 v[2:5], v[178:181], v[210:213], v[2:5]
	v_mfma_f32_16x16x32_bf16 v[54:57], v[174:177], v[190:193], v[54:57]
	v_mfma_f32_16x16x32_bf16 v[50:53], v[182:185], v[190:193], v[50:53]
	v_mfma_f32_16x16x32_bf16 v[38:41], v[174:177], v[198:201], v[38:41]
	v_mfma_f32_16x16x32_bf16 v[34:37], v[182:185], v[198:201], v[34:37]
	v_mfma_f32_16x16x32_bf16 v[22:25], v[174:177], v[206:209], v[22:25]
	v_mfma_f32_16x16x32_bf16 v[18:21], v[182:185], v[206:209], v[18:21]
	v_mfma_f32_16x16x32_bf16 v[6:9], v[174:177], v[214:217], v[6:9]
	v_mfma_f32_16x16x32_bf16 v[2:5], v[182:185], v[214:217], v[2:5]
	s_barrier
	s_add_i32 s33, 0, 0x18000
	v_add_u32_e32 v157, s33, v151
	s_add_i32 s62, 0, 0x1c000
	ds_read_b128 v[146:149], v157
	ds_read_b128 v[158:161], v157 offset:1024
	ds_read_b128 v[162:165], v157 offset:2048
	ds_read_b128 v[166:169], v157 offset:3072
	v_add_u32_e32 v157, s62, v151
	ds_read_b128 v[170:173], v157
	ds_read_b128 v[174:177], v157 offset:1024
	ds_read_b128 v[178:181], v157 offset:2048
	ds_read_b128 v[182:185], v157 offset:3072
	s_add_u32 s48, s48, 0x40000
	s_addc_u32 s49, s49, 0
	s_mov_b32 m0, s58
	v_lshl_add_u64 v[226:227], s[48:49], 0, v[130:131]
	ds_read_b128 v[186:189], v154 offset:32768
	ds_read_b128 v[190:193], v154 offset:33792
	ds_read_b128 v[194:197], v154 offset:34816
	ds_read_b128 v[198:201], v154 offset:35840
	ds_read_b128 v[202:205], v154 offset:36864
	ds_read_b128 v[206:209], v154 offset:37888
	ds_read_b128 v[210:213], v154 offset:38912
	ds_read_b128 v[214:217], v154 offset:39936
	global_load_lds_dwordx4 v[226:227], off
	v_lshl_add_u64 v[226:227], s[48:49], 0, v[134:135]
	s_mov_b32 m0, s59
	s_nop 0
	global_load_lds_dwordx4 v[226:227], off
	s_waitcnt vmcnt(8)
	s_waitcnt lgkmcnt(0)
	s_barrier
	s_waitcnt lgkmcnt(0)
	v_mfma_f32_16x16x32_bf16 v[126:129], v[146:149], v[186:189], v[126:129]
	v_mfma_f32_16x16x32_bf16 v[122:125], v[162:165], v[186:189], v[122:125]
	v_mfma_f32_16x16x32_bf16 v[110:113], v[146:149], v[194:197], v[110:113]
	v_mfma_f32_16x16x32_bf16 v[106:109], v[162:165], v[194:197], v[106:109]
	v_mfma_f32_16x16x32_bf16 v[94:97], v[146:149], v[202:205], v[94:97]
	v_mfma_f32_16x16x32_bf16 v[90:93], v[162:165], v[202:205], v[90:93]
	v_mfma_f32_16x16x32_bf16 v[78:81], v[146:149], v[210:213], v[78:81]
	v_mfma_f32_16x16x32_bf16 v[74:77], v[162:165], v[210:213], v[74:77]
	v_mfma_f32_16x16x32_bf16 v[126:129], v[158:161], v[190:193], v[126:129]
	v_mfma_f32_16x16x32_bf16 v[122:125], v[166:169], v[190:193], v[122:125]
	v_mfma_f32_16x16x32_bf16 v[110:113], v[158:161], v[198:201], v[110:113]
	v_mfma_f32_16x16x32_bf16 v[106:109], v[166:169], v[198:201], v[106:109]
	v_mfma_f32_16x16x32_bf16 v[94:97], v[158:161], v[206:209], v[94:97]
	v_mfma_f32_16x16x32_bf16 v[90:93], v[166:169], v[206:209], v[90:93]
	v_mfma_f32_16x16x32_bf16 v[78:81], v[158:161], v[214:217], v[78:81]
	v_mfma_f32_16x16x32_bf16 v[74:77], v[166:169], v[214:217], v[74:77]
	v_mfma_f32_16x16x32_bf16 v[118:121], v[170:173], v[186:189], v[118:121]
	v_mfma_f32_16x16x32_bf16 v[114:117], v[178:181], v[186:189], v[114:117]
	v_mfma_f32_16x16x32_bf16 v[102:105], v[170:173], v[194:197], v[102:105]
	v_mfma_f32_16x16x32_bf16 v[98:101], v[178:181], v[194:197], v[98:101]
	v_mfma_f32_16x16x32_bf16 v[86:89], v[170:173], v[202:205], v[86:89]
	v_mfma_f32_16x16x32_bf16 v[82:85], v[178:181], v[202:205], v[82:85]
	v_mfma_f32_16x16x32_bf16 v[70:73], v[170:173], v[210:213], v[70:73]
	v_mfma_f32_16x16x32_bf16 v[66:69], v[178:181], v[210:213], v[66:69]
	v_mfma_f32_16x16x32_bf16 v[118:121], v[174:177], v[190:193], v[118:121]
	v_mfma_f32_16x16x32_bf16 v[114:117], v[182:185], v[190:193], v[114:117]
	v_mfma_f32_16x16x32_bf16 v[102:105], v[174:177], v[198:201], v[102:105]
	v_mfma_f32_16x16x32_bf16 v[98:101], v[182:185], v[198:201], v[98:101]
	v_mfma_f32_16x16x32_bf16 v[86:89], v[174:177], v[206:209], v[86:89]
	v_mfma_f32_16x16x32_bf16 v[82:85], v[182:185], v[206:209], v[82:85]
	v_mfma_f32_16x16x32_bf16 v[70:73], v[174:177], v[214:217], v[70:73]
	v_mfma_f32_16x16x32_bf16 v[66:69], v[182:185], v[214:217], v[66:69]
	s_barrier
; #define PG8_STAGE(bufoff, gbase, voff) do { _Pragma("unroll") for (int _i = 0; _i < 2; ++_i) \
;         __builtin_amdgcn_global_load_lds((const unsigned*)((const char*)(gbase) + (voff)[_i]), (LAS unsigned*)(lds + (bufoff) + ldsw + _i * 8192), 16, 0, 0); } while (0)
; #define PG8_LDA(dst, b, h) do { _Pragma("unroll") for (int m = 0; m < 4; ++m) _Pragma("unroll") for (int k = 0; k < 2; ++k) dst[m][k] = *(const LAS bf16x8*)(lds + PG8_SA(b, h) + aoff + m * 2048 + k * 1024); } while (0)
; #define PG8_LDB(dst, b, h) do { _Pragma("unroll") for (int n = 0; n < 2; ++n) _Pragma("unroll") for (int k = 0; k < 2; ++k) dst[n][k] = *(const LAS bf16x8*)(lds + PG8_SB(b, h) + boff + n * 2048 + k * 1024); } while (0)
; #define PG8_MMA(ai, bj, At, Bt) do { __builtin_amdgcn_s_setprio(1); _Pragma("unroll") for (int m = 0; m < 4; ++m) _Pragma("unroll") for (int n = 0; n < 2; ++n) _Pragma("unroll") for (int k = 0; k < 2; ++k) \
;         acc[ai][bj][m][n] = __builtin_amdgcn_mfma_f32_16x16x32_bf16(Bt[n][k], At[m][k], acc[ai][bj][m][n], 0, 0, 0); __builtin_amdgcn_s_setprio(0); } while (0)
; #define PG8_WAIT_V(n) asm volatile("s_waitcnt vmcnt(" #n ")" ::: "memory")
; #define PG8_WAIT_L(n) asm volatile("s_waitcnt lgkmcnt(" #n ")" ::: "memory")
; #define PG8_BAR __builtin_amdgcn_s_barrier()
; #define PG8_SCHED __builtin_amdgcn_sched_barrier(0)
; template <class Epi>
; __device__ __forceinline__ void gemm_phase(LAS unsigned char* lds, const Gemm g, int G, int c, const Epi& E) {
;     ...
;             PG8_LDB(B0, 1, 0); PG8_LDB(B1, 1, 1); PG8_SCHED; PG8_LDA(At, 1, 0); PG8_STAGE(PG8_SA(0, 1), a2 + hstepA, voffA);
;             PG8_WAIT_V(8); PG8_WAIT_L(0); PG8_BAR; PG8_MMA(0, 0, At, B0); PG8_MMA(0, 1, At, B1); PG8_BAR; PG8_SCHED;
;             PG8_LDA(At, 1, 1); PG8_STAGE(PG8_SB(1, 0), b3, voffB); PG8_STAGE(PG8_SB(1, 1), b3 + hstepB, voffB); PG8_STAGE(PG8_SA(1, 0), a3, voffA);
;             PG8_WAIT_V(8); PG8_WAIT_L(0); PG8_BAR; PG8_MMA(1, 0, At, B0); PG8_MMA(1, 1, At, B1); PG8_BAR; PG8_SCHED;
;         }
	s_add_i32 s33, s33, s56
	v_lshl_add_u64 v[218:219], v[218:219], 0, s[20:21]
	s_mov_b32 m0, s33
	ds_read_b128 v[186:189], v154 offset:49152
	ds_read_b128 v[190:193], v154 offset:50176
	ds_read_b128 v[194:197], v154 offset:51200
	ds_read_b128 v[198:201], v154 offset:52224
	ds_read_b128 v[202:205], v154 offset:53248
	ds_read_b128 v[206:209], v154 offset:54272
	ds_read_b128 v[210:213], v154 offset:55296
	ds_read_b128 v[214:217], v154 offset:56320
	global_load_lds_dwordx4 v[218:219], off
	s_add_i32 m0, s33, 0x2000
	s_add_u32 s46, s46, 0x40080
	v_lshl_add_u64 v[218:219], v[220:221], 0, s[20:21]
	s_addc_u32 s47, s47, 0
	s_add_i32 s33, s62, s56
	global_load_lds_dwordx4 v[218:219], off
	v_lshl_add_u64 v[218:219], s[46:47], 0, v[132:133]
	s_mov_b32 m0, s33
	s_nop 0
	global_load_lds_dwordx4 v[218:219], off
	v_lshl_add_u64 v[218:219], s[46:47], 0, v[136:137]
	s_add_i32 m0, s33, 0x2000
	s_nop 0
	global_load_lds_dwordx4 v[218:219], off
	v_lshl_add_u64 v[218:219], v[222:223], 0, s[20:21]
	s_mov_b32 m0, s67
	s_nop 0
	global_load_lds_dwordx4 v[218:219], off
	v_lshl_add_u64 v[218:219], v[224:225], 0, s[20:21]
	s_mov_b32 m0, s68
	s_nop 0
	global_load_lds_dwordx4 v[218:219], off
	s_waitcnt vmcnt(8)
	s_waitcnt lgkmcnt(0)
	s_barrier
	s_waitcnt lgkmcnt(0)
	v_mfma_f32_16x16x32_bf16 v[62:65], v[146:149], v[186:189], v[62:65]
	v_mfma_f32_16x16x32_bf16 v[58:61], v[162:165], v[186:189], v[58:61]
	v_mfma_f32_16x16x32_bf16 v[46:49], v[146:149], v[194:197], v[46:49]
	v_mfma_f32_16x16x32_bf16 v[42:45], v[162:165], v[194:197], v[42:45]
	v_mfma_f32_16x16x32_bf16 v[30:33], v[146:149], v[202:205], v[30:33]
	v_mfma_f32_16x16x32_bf16 v[26:29], v[162:165], v[202:205], v[26:29]
	v_mfma_f32_16x16x32_bf16 v[14:17], v[146:149], v[210:213], v[14:17]
	v_mfma_f32_16x16x32_bf16 v[10:13], v[162:165], v[210:213], v[10:13]
	v_mfma_f32_16x16x32_bf16 v[62:65], v[158:161], v[190:193], v[62:65]
	v_mfma_f32_16x16x32_bf16 v[58:61], v[166:169], v[190:193], v[58:61]
	v_mfma_f32_16x16x32_bf16 v[46:49], v[158:161], v[198:201], v[46:49]
	v_mfma_f32_16x16x32_bf16 v[42:45], v[166:169], v[198:201], v[42:45]
	v_mfma_f32_16x16x32_bf16 v[30:33], v[158:161], v[206:209], v[30:33]
	v_mfma_f32_16x16x32_bf16 v[26:29], v[166:169], v[206:209], v[26:29]
	v_mfma_f32_16x16x32_bf16 v[14:17], v[158:161], v[214:217], v[14:17]
	v_mfma_f32_16x16x32_bf16 v[10:13], v[166:169], v[214:217], v[10:13]
	v_mfma_f32_16x16x32_bf16 v[54:57], v[170:173], v[186:189], v[54:57]
	v_mfma_f32_16x16x32_bf16 v[50:53], v[178:181], v[186:189], v[50:53]
	v_mfma_f32_16x16x32_bf16 v[38:41], v[170:173], v[194:197], v[38:41]
	v_mfma_f32_16x16x32_bf16 v[34:37], v[178:181], v[194:197], v[34:37]
	v_mfma_f32_16x16x32_bf16 v[22:25], v[170:173], v[202:205], v[22:25]
	v_mfma_f32_16x16x32_bf16 v[18:21], v[178:181], v[202:205], v[18:21]
	v_mfma_f32_16x16x32_bf16 v[6:9], v[170:173], v[210:213], v[6:9]
	v_mfma_f32_16x16x32_bf16 v[2:5], v[178:181], v[210:213], v[2:5]
	v_mfma_f32_16x16x32_bf16 v[54:57], v[174:177], v[190:193], v[54:57]
	v_mfma_f32_16x16x32_bf16 v[50:53], v[182:185], v[190:193], v[50:53]
	v_mfma_f32_16x16x32_bf16 v[38:41], v[174:177], v[198:201], v[38:41]
	v_mfma_f32_16x16x32_bf16 v[34:37], v[182:185], v[198:201], v[34:37]
	v_mfma_f32_16x16x32_bf16 v[22:25], v[174:177], v[206:209], v[22:25]
	v_mfma_f32_16x16x32_bf16 v[18:21], v[182:185], v[206:209], v[18:21]
	v_mfma_f32_16x16x32_bf16 v[6:9], v[174:177], v[214:217], v[6:9]
	v_mfma_f32_16x16x32_bf16 v[2:5], v[182:185], v[214:217], v[2:5]
	s_barrier
	s_add_i32 s81, s81, 2
	s_add_u32 s4, s4, 0x100
	s_addc_u32 s5, s5, 0
	s_add_u32 s41, s41, 0x100
	s_addc_u32 s80, s80, 0
	s_cmp_gt_u32 s81, 13
	s_cbranch_scc0 .LBB0_1297
	s_and_b64 vcc, exec, s[22:23]
	s_cbranch_vccz .LBB0_1300
	s_barrier

; #define PG8_STAGE(bufoff, gbase, voff) do { _Pragma("unroll") for (int _i = 0; _i < 2; ++_i) \
;         __builtin_amdgcn_global_load_lds((const unsigned*)((const char*)(gbase) + (voff)[_i]), (LAS unsigned*)(lds + (bufoff) + ldsw + _i * 8192), 16, 0, 0); } while (0)
; #define PG8_LDA(dst, b, h) do { _Pragma("unroll") for (int m = 0; m < 4; ++m) _Pragma("unroll") for (int k = 0; k < 2; ++k) dst[m][k] = *(const LAS bf16x8*)(lds + PG8_SA(b, h) + aoff + m * 2048 + k * 1024); } while (0)
; #define PG8_LDB(dst, b, h) do { _Pragma("unroll") for (int n = 0; n < 2; ++n) _Pragma("unroll") for (int k = 0; k < 2; ++k) dst[n][k] = *(const LAS bf16x8*)(lds + PG8_SB(b, h) + boff + n * 2048 + k * 1024); } while (0)
; #define PG8_MMA(ai, bj, At, Bt) do { __builtin_amdgcn_s_setprio(1); _Pragma("unroll") for (int m = 0; m < 4; ++m) _Pragma("unroll") for (int n = 0; n < 2; ++n) _Pragma("unroll") for (int k = 0; k < 2; ++k) \
;         acc[ai][bj][m][n] = __builtin_amdgcn_mfma_f32_16x16x32_bf16(Bt[n][k], At[m][k], acc[ai][bj][m][n], 0, 0, 0); __builtin_amdgcn_s_setprio(0); } while (0)
; #define PG8_WAIT_V(n) asm volatile("s_waitcnt vmcnt(" #n ")" ::: "memory")
; #define PG8_WAIT_L(n) asm volatile("s_waitcnt lgkmcnt(" #n ")" ::: "memory")
; #define PG8_BAR __builtin_amdgcn_s_barrier()
; #define PG8_SCHED __builtin_amdgcn_sched_barrier(0)
; template <class Epi>
; __device__ __forceinline__ void gemm_phase(LAS unsigned char* lds, const Gemm g, int G, int c, const Epi& E) {
;     ...
;         const bool has_next = S.next(ui + 1, nxt);
;         const char* nA = has_next ? (const char*)(g.A + (size_t)nxt.pb * g.sA) + (size_t)nxt.pm * 2 * hstepA : cA;
;         const char* nB = has_next ? (const char*)(g.Bt + (size_t)nxt.pb * g.sB) + (size_t)nxt.pn * 2 * hstepB : cB;
; #pragma nounroll
;         for (int t = 0; t < nt; t += 2) {
;             const bool last = (t == nt - 2);
;             const char* a1 = cA + (size_t)(t + 1) * kstep;
;             const char* a2 = last ? nA : cA + (size_t)(t + 2) * kstep; const char* b2 = last ? nB : cB + (size_t)(t + 2) * kstep;
;             const char* a3 = a2 + kstep; const char* b3 = b2 + kstep;
;             PG8_LDB(B0, 0, 0); PG8_LDB(B1, 0, 1); PG8_SCHED; PG8_LDA(At, 0, 0); PG8_STAGE(PG8_SA(1, 1), a1 + hstepA, voffA);
;             PG8_WAIT_V(8); PG8_WAIT_L(0); PG8_BAR; PG8_MMA(0, 0, At, B0); PG8_MMA(0, 1, At, B1); PG8_BAR; PG8_SCHED;
.LBB0_1429:
	s_add_u32 s33, s18, s13
	s_addc_u32 s42, s19, 0
	s_add_u32 s38, s33, 0x100
	s_addc_u32 s39, s42, 0
	s_and_b64 s[24:25], s[22:23], exec
	s_cselect_b32 s39, s5, s39
	s_cselect_b32 s38, s4, s38
	s_add_u32 s13, s16, s13
	s_addc_u32 s24, s17, 0
	s_add_u32 s13, s13, 0x100
	s_addc_u32 s24, s24, 0
	s_and_b64 s[22:23], s[22:23], exec
	s_cselect_b32 s41, s15, s24
	s_cselect_b32 s40, s14, s13
	s_add_u32 s44, s33, 0xb0080
	ds_read_b128 v[142:145], v148
	ds_read_b128 v[152:155], v148 offset:1024
	ds_read_b128 v[156:159], v148 offset:2048
	ds_read_b128 v[160:163], v148 offset:3072
	ds_read_b128 v[164:167], v149
	ds_read_b128 v[168:171], v149 offset:1024
	ds_read_b128 v[172:175], v149 offset:2048
	ds_read_b128 v[176:179], v149 offset:3072
	s_addc_u32 s45, s42, 0
	s_add_i32 s65, s72, s48
	s_add_i32 m0, s49, 0xc000
	s_add_i32 s85, s49, 0xe000
	s_add_i32 s62, s65, 0x2000
	s_add_u32 s42, s40, 0xb0000
	s_addc_u32 s43, s41, 0
	s_add_i32 s64, s73, s48
	s_add_i32 s63, s64, 0x2000
	s_add_i32 s84, 0, 0x18000
	s_add_i32 s33, 0, 0x1c000
	s_add_u32 s24, s38, 0xb0000
	s_addc_u32 s25, s39, 0
	s_add_i32 s83, s84, s48
	s_add_i32 s13, s83, 0x2000
	s_add_u32 s22, s40, 0xb0080
	s_addc_u32 s23, s41, 0
	s_add_i32 s75, s33, s48
	s_add_i32 s74, s75, 0x2000
	v_lshl_add_u64 v[212:213], s[44:45], 0, v[136:137]
	ds_read_b128 v[180:183], v150
	ds_read_b128 v[184:187], v150 offset:1024
	ds_read_b128 v[188:191], v150 offset:2048
	ds_read_b128 v[192:195], v150 offset:3072
	ds_read_b128 v[196:199], v150 offset:4096
	ds_read_b128 v[200:203], v150 offset:5120
	ds_read_b128 v[204:207], v150 offset:6144
	ds_read_b128 v[208:211], v150 offset:7168
	global_load_lds_dwordx4 v[212:213], off
	v_lshl_add_u64 v[212:213], s[44:45], 0, v[132:133]
	s_mov_b32 m0, s85
	s_nop 0
	global_load_lds_dwordx4 v[212:213], off
	s_waitcnt vmcnt(8)
	s_waitcnt lgkmcnt(0)
	s_barrier
	s_waitcnt lgkmcnt(0)
	v_mfma_f32_16x16x32_bf16 v[126:129], v[142:145], v[180:183], v[126:129]
	v_mfma_f32_16x16x32_bf16 v[122:125], v[156:159], v[180:183], v[122:125]
	v_mfma_f32_16x16x32_bf16 v[118:121], v[142:145], v[188:191], v[118:121]
	v_mfma_f32_16x16x32_bf16 v[110:113], v[156:159], v[188:191], v[110:113]
	v_mfma_f32_16x16x32_bf16 v[102:105], v[142:145], v[196:199], v[102:105]
	v_mfma_f32_16x16x32_bf16 v[94:97], v[156:159], v[196:199], v[94:97]
	v_mfma_f32_16x16x32_bf16 v[86:89], v[142:145], v[204:207], v[86:89]
	v_mfma_f32_16x16x32_bf16 v[78:81], v[156:159], v[204:207], v[78:81]
	v_mfma_f32_16x16x32_bf16 v[126:129], v[152:155], v[184:187], v[126:129]
	v_mfma_f32_16x16x32_bf16 v[122:125], v[160:163], v[184:187], v[122:125]
	v_mfma_f32_16x16x32_bf16 v[118:121], v[152:155], v[192:195], v[118:121]
	v_mfma_f32_16x16x32_bf16 v[110:113], v[160:163], v[192:195], v[110:113]
	v_mfma_f32_16x16x32_bf16 v[102:105], v[152:155], v[200:203], v[102:105]
	v_mfma_f32_16x16x32_bf16 v[94:97], v[160:163], v[200:203], v[94:97]
	v_mfma_f32_16x16x32_bf16 v[86:89], v[152:155], v[208:211], v[86:89]
	v_mfma_f32_16x16x32_bf16 v[78:81], v[160:163], v[208:211], v[78:81]
	v_mfma_f32_16x16x32_bf16 v[114:117], v[164:167], v[180:183], v[114:117]
	v_mfma_f32_16x16x32_bf16 v[106:109], v[172:175], v[180:183], v[106:109]
	v_mfma_f32_16x16x32_bf16 v[98:101], v[164:167], v[188:191], v[98:101]
	v_mfma_f32_16x16x32_bf16 v[90:93], v[172:175], v[188:191], v[90:93]
	v_mfma_f32_16x16x32_bf16 v[82:85], v[164:167], v[196:199], v[82:85]
	v_mfma_f32_16x16x32_bf16 v[74:77], v[172:175], v[196:199], v[74:77]
	v_mfma_f32_16x16x32_bf16 v[70:73], v[164:167], v[204:207], v[70:73]
	v_mfma_f32_16x16x32_bf16 v[66:69], v[172:175], v[204:207], v[66:69]
	v_mfma_f32_16x16x32_bf16 v[114:117], v[168:171], v[184:187], v[114:117]
	v_mfma_f32_16x16x32_bf16 v[106:109], v[176:179], v[184:187], v[106:109]
	v_mfma_f32_16x16x32_bf16 v[98:101], v[168:171], v[192:195], v[98:101]
	v_mfma_f32_16x16x32_bf16 v[90:93], v[176:179], v[192:195], v[90:93]
	v_mfma_f32_16x16x32_bf16 v[82:85], v[168:171], v[200:203], v[82:85]
	v_mfma_f32_16x16x32_bf16 v[74:77], v[176:179], v[200:203], v[74:77]
	v_mfma_f32_16x16x32_bf16 v[70:73], v[168:171], v[208:211], v[70:73]
	v_mfma_f32_16x16x32_bf16 v[66:69], v[176:179], v[208:211], v[66:69]
	s_barrier
	s_mov_b32 m0, s65
	v_lshl_add_u64 v[212:213], s[40:41], 0, v[134:135]
	ds_read_b128 v[180:183], v150 offset:16384
	ds_read_b128 v[184:187], v150 offset:17408
	ds_read_b128 v[188:191], v150 offset:18432
	ds_read_b128 v[192:195], v150 offset:19456
	ds_read_b128 v[196:199], v150 offset:20480
	ds_read_b128 v[200:203], v150 offset:21504
	ds_read_b128 v[204:207], v150 offset:22528
	ds_read_b128 v[208:211], v150 offset:23552
	global_load_lds_dwordx4 v[212:213], off
	v_lshl_add_u64 v[214:215], s[40:41], 0, v[130:131]
	s_mov_b32 m0, s62
	v_lshl_add_u64 v[216:217], s[42:43], 0, v[134:135]
	global_load_lds_dwordx4 v[214:215], off
	s_mov_b32 m0, s64
	v_lshl_add_u64 v[218:219], s[38:39], 0, v[132:133]
	global_load_lds_dwordx4 v[216:217], off
	v_lshl_add_u64 v[216:217], s[42:43], 0, v[130:131]
	s_mov_b32 m0, s63
	s_nop 0
	global_load_lds_dwordx4 v[216:217], off
	v_lshl_add_u64 v[216:217], s[38:39], 0, v[136:137]
	s_mov_b32 m0, s49
	s_nop 0
	global_load_lds_dwordx4 v[216:217], off
	s_mov_b32 m0, s52
	s_nop 0
	global_load_lds_dwordx4 v[218:219], off
	s_waitcnt vmcnt(8)
	s_waitcnt lgkmcnt(0)
	s_barrier
; #define PG8_STAGE(bufoff, gbase, voff) do { _Pragma("unroll") for (int _i = 0; _i < 2; ++_i) \
;         __builtin_amdgcn_global_load_lds((const unsigned*)((const char*)(gbase) + (voff)[_i]), (LAS unsigned*)(lds + (bufoff) + ldsw + _i * 8192), 16, 0, 0); } while (0)
; #define PG8_LDA(dst, b, h) do { _Pragma("unroll") for (int m = 0; m < 4; ++m) _Pragma("unroll") for (int k = 0; k < 2; ++k) dst[m][k] = *(const LAS bf16x8*)(lds + PG8_SA(b, h) + aoff + m * 2048 + k * 1024); } while (0)
; #define PG8_LDB(dst, b, h) do { _Pragma("unroll") for (int n = 0; n < 2; ++n) _Pragma("unroll") for (int k = 0; k < 2; ++k) dst[n][k] = *(const LAS bf16x8*)(lds + PG8_SB(b, h) + boff + n * 2048 + k * 1024); } while (0)
; #define PG8_MMA(ai, bj, At, Bt) do { __builtin_amdgcn_s_setprio(1); _Pragma("unroll") for (int m = 0; m < 4; ++m) _Pragma("unroll") for (int n = 0; n < 2; ++n) _Pragma("unroll") for (int k = 0; k < 2; ++k) \
;         acc[ai][bj][m][n] = __builtin_amdgcn_mfma_f32_16x16x32_bf16(Bt[n][k], At[m][k], acc[ai][bj][m][n], 0, 0, 0); __builtin_amdgcn_s_setprio(0); } while (0)
; #define PG8_WAIT_V(n) asm volatile("s_waitcnt vmcnt(" #n ")" ::: "memory")
; #define PG8_WAIT_L(n) asm volatile("s_waitcnt lgkmcnt(" #n ")" ::: "memory")
; #define PG8_BAR __builtin_amdgcn_s_barrier()
; #define PG8_SCHED __builtin_amdgcn_sched_barrier(0)
; template <class Epi>
; __device__ __forceinline__ void gemm_phase(LAS unsigned char* lds, const Gemm g, int G, int c, const Epi& E) {
;     ...
;             PG8_WAIT_V(8); PG8_WAIT_L(0); PG8_BAR; PG8_MMA(0, 0, At, B0); PG8_MMA(0, 1, At, B1); PG8_BAR; PG8_SCHED;
;             PG8_LDA(At, 0, 1); PG8_STAGE(PG8_SB(0, 0), b2, voffB); PG8_STAGE(PG8_SB(0, 1), b2 + hstepB, voffB); PG8_STAGE(PG8_SA(0, 0), a2, voffA);
;             PG8_WAIT_V(8); PG8_WAIT_L(0); PG8_BAR; PG8_MMA(1, 0, At, B0); PG8_MMA(1, 1, At, B1); PG8_BAR; PG8_SCHED;
;             PG8_LDB(B0, 1, 0); PG8_LDB(B1, 1, 1); PG8_SCHED; PG8_LDA(At, 1, 0); PG8_STAGE(PG8_SA(0, 1), a2 + hstepA, voffA);
;             PG8_WAIT_V(8); PG8_WAIT_L(0); PG8_BAR; PG8_MMA(0, 0, At, B0); PG8_MMA(0, 1, At, B1); PG8_BAR; PG8_SCHED;
;             PG8_LDA(At, 1, 1); PG8_STAGE(PG8_SB(1, 0), b3, voffB); PG8_STAGE(PG8_SB(1, 1), b3 + hstepB, voffB); PG8_STAGE(PG8_SA(1, 0), a3, voffA);
	s_waitcnt lgkmcnt(0)
	v_mfma_f32_16x16x32_bf16 v[62:65], v[142:145], v[180:183], v[62:65]
	v_mfma_f32_16x16x32_bf16 v[58:61], v[156:159], v[180:183], v[58:61]
	v_mfma_f32_16x16x32_bf16 v[54:57], v[142:145], v[188:191], v[54:57]
	v_mfma_f32_16x16x32_bf16 v[46:49], v[156:159], v[188:191], v[46:49]
	v_mfma_f32_16x16x32_bf16 v[38:41], v[142:145], v[196:199], v[38:41]
	v_mfma_f32_16x16x32_bf16 v[30:33], v[156:159], v[196:199], v[30:33]
	v_mfma_f32_16x16x32_bf16 v[22:25], v[142:145], v[204:207], v[22:25]
	v_mfma_f32_16x16x32_bf16 v[14:17], v[156:159], v[204:207], v[14:17]
	v_mfma_f32_16x16x32_bf16 v[62:65], v[152:155], v[184:187], v[62:65]
	v_mfma_f32_16x16x32_bf16 v[58:61], v[160:163], v[184:187], v[58:61]
	v_mfma_f32_16x16x32_bf16 v[54:57], v[152:155], v[192:195], v[54:57]
	v_mfma_f32_16x16x32_bf16 v[46:49], v[160:163], v[192:195], v[46:49]
	v_mfma_f32_16x16x32_bf16 v[38:41], v[152:155], v[200:203], v[38:41]
	v_mfma_f32_16x16x32_bf16 v[30:33], v[160:163], v[200:203], v[30:33]
	v_mfma_f32_16x16x32_bf16 v[22:25], v[152:155], v[208:211], v[22:25]
	v_mfma_f32_16x16x32_bf16 v[14:17], v[160:163], v[208:211], v[14:17]
	v_mfma_f32_16x16x32_bf16 v[50:53], v[164:167], v[180:183], v[50:53]
	v_mfma_f32_16x16x32_bf16 v[42:45], v[172:175], v[180:183], v[42:45]
	v_mfma_f32_16x16x32_bf16 v[34:37], v[164:167], v[188:191], v[34:37]
	v_mfma_f32_16x16x32_bf16 v[26:29], v[172:175], v[188:191], v[26:29]
	v_mfma_f32_16x16x32_bf16 v[18:21], v[164:167], v[196:199], v[18:21]
	v_mfma_f32_16x16x32_bf16 v[10:13], v[172:175], v[196:199], v[10:13]
	v_mfma_f32_16x16x32_bf16 v[6:9], v[164:167], v[204:207], v[6:9]
	v_mfma_f32_16x16x32_bf16 v[2:5], v[172:175], v[204:207], v[2:5]
	v_mfma_f32_16x16x32_bf16 v[50:53], v[168:171], v[184:187], v[50:53]
	v_mfma_f32_16x16x32_bf16 v[42:45], v[176:179], v[184:187], v[42:45]
	v_mfma_f32_16x16x32_bf16 v[34:37], v[168:171], v[192:195], v[34:37]
	v_mfma_f32_16x16x32_bf16 v[26:29], v[176:179], v[192:195], v[26:29]
	v_mfma_f32_16x16x32_bf16 v[18:21], v[168:171], v[200:203], v[18:21]
	v_mfma_f32_16x16x32_bf16 v[10:13], v[176:179], v[200:203], v[10:13]
	v_mfma_f32_16x16x32_bf16 v[6:9], v[168:171], v[208:211], v[6:9]
	v_mfma_f32_16x16x32_bf16 v[2:5], v[176:179], v[208:211], v[2:5]
	s_barrier
	v_add_u32_e32 v151, s84, v147
	ds_read_b128 v[142:145], v151
	ds_read_b128 v[152:155], v151 offset:1024
	ds_read_b128 v[156:159], v151 offset:2048
	ds_read_b128 v[160:163], v151 offset:3072
	v_add_u32_e32 v151, s33, v147
	ds_read_b128 v[164:167], v151
	ds_read_b128 v[168:171], v151 offset:1024
	ds_read_b128 v[172:175], v151 offset:2048
	ds_read_b128 v[176:179], v151 offset:3072
	s_mov_b32 m0, s53
	v_lshl_add_u64 v[220:221], s[24:25], 0, v[136:137]
	ds_read_b128 v[180:183], v150 offset:32768
	ds_read_b128 v[184:187], v150 offset:33792
	ds_read_b128 v[188:191], v150 offset:34816
	ds_read_b128 v[192:195], v150 offset:35840
	ds_read_b128 v[196:199], v150 offset:36864
	ds_read_b128 v[200:203], v150 offset:37888
	ds_read_b128 v[204:207], v150 offset:38912
	ds_read_b128 v[208:211], v150 offset:39936
	global_load_lds_dwordx4 v[220:221], off
	v_lshl_add_u64 v[220:221], s[24:25], 0, v[132:133]
	s_mov_b32 m0, s54
	s_nop 0
	global_load_lds_dwordx4 v[220:221], off
	s_waitcnt vmcnt(8)
	s_waitcnt lgkmcnt(0)
	s_barrier
	s_waitcnt lgkmcnt(0)
	v_mfma_f32_16x16x32_bf16 v[126:129], v[142:145], v[180:183], v[126:129]
	v_mfma_f32_16x16x32_bf16 v[122:125], v[156:159], v[180:183], v[122:125]
	v_mfma_f32_16x16x32_bf16 v[118:121], v[142:145], v[188:191], v[118:121]
	v_mfma_f32_16x16x32_bf16 v[110:113], v[156:159], v[188:191], v[110:113]
	v_mfma_f32_16x16x32_bf16 v[102:105], v[142:145], v[196:199], v[102:105]
	v_mfma_f32_16x16x32_bf16 v[94:97], v[156:159], v[196:199], v[94:97]
	v_mfma_f32_16x16x32_bf16 v[86:89], v[142:145], v[204:207], v[86:89]
	v_mfma_f32_16x16x32_bf16 v[78:81], v[156:159], v[204:207], v[78:81]
	v_mfma_f32_16x16x32_bf16 v[126:129], v[152:155], v[184:187], v[126:129]
	v_mfma_f32_16x16x32_bf16 v[122:125], v[160:163], v[184:187], v[122:125]
	v_mfma_f32_16x16x32_bf16 v[118:121], v[152:155], v[192:195], v[118:121]
	v_mfma_f32_16x16x32_bf16 v[110:113], v[160:163], v[192:195], v[110:113]
	v_mfma_f32_16x16x32_bf16 v[102:105], v[152:155], v[200:203], v[102:105]
	v_mfma_f32_16x16x32_bf16 v[94:97], v[160:163], v[200:203], v[94:97]
	v_mfma_f32_16x16x32_bf16 v[86:89], v[152:155], v[208:211], v[86:89]
	v_mfma_f32_16x16x32_bf16 v[78:81], v[160:163], v[208:211], v[78:81]
	v_mfma_f32_16x16x32_bf16 v[114:117], v[164:167], v[180:183], v[114:117]
	v_mfma_f32_16x16x32_bf16 v[106:109], v[172:175], v[180:183], v[106:109]
	v_mfma_f32_16x16x32_bf16 v[98:101], v[164:167], v[188:191], v[98:101]
	v_mfma_f32_16x16x32_bf16 v[90:93], v[172:175], v[188:191], v[90:93]
	v_mfma_f32_16x16x32_bf16 v[82:85], v[164:167], v[196:199], v[82:85]
	v_mfma_f32_16x16x32_bf16 v[74:77], v[172:175], v[196:199], v[74:77]
	v_mfma_f32_16x16x32_bf16 v[70:73], v[164:167], v[204:207], v[70:73]
	v_mfma_f32_16x16x32_bf16 v[66:69], v[172:175], v[204:207], v[66:69]
	v_mfma_f32_16x16x32_bf16 v[114:117], v[168:171], v[184:187], v[114:117]
	v_mfma_f32_16x16x32_bf16 v[106:109], v[176:179], v[184:187], v[106:109]
	v_mfma_f32_16x16x32_bf16 v[98:101], v[168:171], v[192:195], v[98:101]
	v_mfma_f32_16x16x32_bf16 v[90:93], v[176:179], v[192:195], v[90:93]
	v_mfma_f32_16x16x32_bf16 v[82:85], v[168:171], v[200:203], v[82:85]
	v_mfma_f32_16x16x32_bf16 v[74:77], v[176:179], v[200:203], v[74:77]
	v_mfma_f32_16x16x32_bf16 v[70:73], v[168:171], v[208:211], v[70:73]
	v_mfma_f32_16x16x32_bf16 v[66:69], v[176:179], v[208:211], v[66:69]
	s_barrier
; #define PG8_STAGE(bufoff, gbase, voff) do { _Pragma("unroll") for (int _i = 0; _i < 2; ++_i) \
;         __builtin_amdgcn_global_load_lds((const unsigned*)((const char*)(gbase) + (voff)[_i]), (LAS unsigned*)(lds + (bufoff) + ldsw + _i * 8192), 16, 0, 0); } while (0)
; #define PG8_LDA(dst, b, h) do { _Pragma("unroll") for (int m = 0; m < 4; ++m) _Pragma("unroll") for (int k = 0; k < 2; ++k) dst[m][k] = *(const LAS bf16x8*)(lds + PG8_SA(b, h) + aoff + m * 2048 + k * 1024); } while (0)
; #define PG8_LDB(dst, b, h) do { _Pragma("unroll") for (int n = 0; n < 2; ++n) _Pragma("unroll") for (int k = 0; k < 2; ++k) dst[n][k] = *(const LAS bf16x8*)(lds + PG8_SB(b, h) + boff + n * 2048 + k * 1024); } while (0)
; #define PG8_MMA(ai, bj, At, Bt) do { __builtin_amdgcn_s_setprio(1); _Pragma("unroll") for (int m = 0; m < 4; ++m) _Pragma("unroll") for (int n = 0; n < 2; ++n) _Pragma("unroll") for (int k = 0; k < 2; ++k) \
;         acc[ai][bj][m][n] = __builtin_amdgcn_mfma_f32_16x16x32_bf16(Bt[n][k], At[m][k], acc[ai][bj][m][n], 0, 0, 0); __builtin_amdgcn_s_setprio(0); } while (0)
; #define PG8_WAIT_V(n) asm volatile("s_waitcnt vmcnt(" #n ")" ::: "memory")
; #define PG8_WAIT_L(n) asm volatile("s_waitcnt lgkmcnt(" #n ")" ::: "memory")
; #define PG8_BAR __builtin_amdgcn_s_barrier()
; #define PG8_SCHED __builtin_amdgcn_sched_barrier(0)
; template <class Epi>
; __device__ __forceinline__ void gemm_phase(LAS unsigned char* lds, const Gemm g, int G, int c, const Epi& E) {
;     ...
;             PG8_LDB(B0, 1, 0); PG8_LDB(B1, 1, 1); PG8_SCHED; PG8_LDA(At, 1, 0); PG8_STAGE(PG8_SA(0, 1), a2 + hstepA, voffA);
;             PG8_WAIT_V(8); PG8_WAIT_L(0); PG8_BAR; PG8_MMA(0, 0, At, B0); PG8_MMA(0, 1, At, B1); PG8_BAR; PG8_SCHED;
;             PG8_LDA(At, 1, 1); PG8_STAGE(PG8_SB(1, 0), b3, voffB); PG8_STAGE(PG8_SB(1, 1), b3 + hstepB, voffB); PG8_STAGE(PG8_SA(1, 0), a3, voffA);
;             PG8_WAIT_V(8); PG8_WAIT_L(0); PG8_BAR; PG8_MMA(1, 0, At, B0); PG8_MMA(1, 1, At, B1); PG8_BAR; PG8_SCHED;
;         }
;         if (wr == 0) PG8_BAR;
	s_mov_b32 m0, s83
	v_lshl_add_u64 v[212:213], v[212:213], 0, s[8:9]
	ds_read_b128 v[180:183], v150 offset:49152
	ds_read_b128 v[184:187], v150 offset:50176
	ds_read_b128 v[188:191], v150 offset:51200
	ds_read_b128 v[192:195], v150 offset:52224
	ds_read_b128 v[196:199], v150 offset:53248
	ds_read_b128 v[200:203], v150 offset:54272
	ds_read_b128 v[204:207], v150 offset:55296
	ds_read_b128 v[208:211], v150 offset:56320
	global_load_lds_dwordx4 v[212:213], off
	v_lshl_add_u64 v[212:213], v[214:215], 0, s[8:9]
	s_mov_b32 m0, s13
	s_nop 0
	global_load_lds_dwordx4 v[212:213], off
	v_lshl_add_u64 v[212:213], s[22:23], 0, v[134:135]
	s_mov_b32 m0, s75
	s_nop 0
	global_load_lds_dwordx4 v[212:213], off
	v_lshl_add_u64 v[212:213], s[22:23], 0, v[130:131]
	s_mov_b32 m0, s74
	s_nop 0
	global_load_lds_dwordx4 v[212:213], off
	v_lshl_add_u64 v[212:213], v[216:217], 0, s[8:9]
	s_mov_b32 m0, s70
	s_nop 0
	global_load_lds_dwordx4 v[212:213], off
	v_lshl_add_u64 v[212:213], v[218:219], 0, s[8:9]
	s_mov_b32 m0, s71
	s_nop 0
	global_load_lds_dwordx4 v[212:213], off
	s_waitcnt vmcnt(8)
	s_waitcnt lgkmcnt(0)
	s_barrier
	s_waitcnt lgkmcnt(0)
	v_mfma_f32_16x16x32_bf16 v[62:65], v[142:145], v[180:183], v[62:65]
	v_mfma_f32_16x16x32_bf16 v[58:61], v[156:159], v[180:183], v[58:61]
	v_mfma_f32_16x16x32_bf16 v[54:57], v[142:145], v[188:191], v[54:57]
	v_mfma_f32_16x16x32_bf16 v[46:49], v[156:159], v[188:191], v[46:49]
	v_mfma_f32_16x16x32_bf16 v[38:41], v[142:145], v[196:199], v[38:41]
	v_mfma_f32_16x16x32_bf16 v[30:33], v[156:159], v[196:199], v[30:33]
	v_mfma_f32_16x16x32_bf16 v[22:25], v[142:145], v[204:207], v[22:25]
	v_mfma_f32_16x16x32_bf16 v[14:17], v[156:159], v[204:207], v[14:17]
	v_mfma_f32_16x16x32_bf16 v[62:65], v[152:155], v[184:187], v[62:65]
	v_mfma_f32_16x16x32_bf16 v[58:61], v[160:163], v[184:187], v[58:61]
	v_mfma_f32_16x16x32_bf16 v[54:57], v[152:155], v[192:195], v[54:57]
	v_mfma_f32_16x16x32_bf16 v[46:49], v[160:163], v[192:195], v[46:49]
	v_mfma_f32_16x16x32_bf16 v[38:41], v[152:155], v[200:203], v[38:41]
	v_mfma_f32_16x16x32_bf16 v[30:33], v[160:163], v[200:203], v[30:33]
	v_mfma_f32_16x16x32_bf16 v[22:25], v[152:155], v[208:211], v[22:25]
	v_mfma_f32_16x16x32_bf16 v[14:17], v[160:163], v[208:211], v[14:17]
	v_mfma_f32_16x16x32_bf16 v[50:53], v[164:167], v[180:183], v[50:53]
	v_mfma_f32_16x16x32_bf16 v[42:45], v[172:175], v[180:183], v[42:45]
	v_mfma_f32_16x16x32_bf16 v[34:37], v[164:167], v[188:191], v[34:37]
	v_mfma_f32_16x16x32_bf16 v[26:29], v[172:175], v[188:191], v[26:29]
	v_mfma_f32_16x16x32_bf16 v[18:21], v[164:167], v[196:199], v[18:21]
	v_mfma_f32_16x16x32_bf16 v[10:13], v[172:175], v[196:199], v[10:13]
	v_mfma_f32_16x16x32_bf16 v[6:9], v[164:167], v[204:207], v[6:9]
	v_mfma_f32_16x16x32_bf16 v[2:5], v[172:175], v[204:207], v[2:5]
	v_mfma_f32_16x16x32_bf16 v[50:53], v[168:171], v[184:187], v[50:53]
	v_mfma_f32_16x16x32_bf16 v[42:45], v[176:179], v[184:187], v[42:45]
	v_mfma_f32_16x16x32_bf16 v[34:37], v[168:171], v[192:195], v[34:37]
	v_mfma_f32_16x16x32_bf16 v[26:29], v[176:179], v[192:195], v[26:29]
	v_mfma_f32_16x16x32_bf16 v[18:21], v[168:171], v[200:203], v[18:21]
	v_mfma_f32_16x16x32_bf16 v[10:13], v[176:179], v[200:203], v[10:13]
	v_mfma_f32_16x16x32_bf16 v[6:9], v[168:171], v[208:211], v[6:9]
	v_mfma_f32_16x16x32_bf16 v[2:5], v[176:179], v[208:211], v[2:5]
	s_barrier
	s_movk_i32 s13, 0x100
	s_andn2_b64 vcc, exec, s[20:21]
	s_mov_b64 s[22:23], -1
	s_mov_b64 s[20:21], 0
	s_cbranch_vccz .LBB0_1429
	s_and_b64 vcc, exec, s[10:11]
	s_cbranch_vccz .LBB0_1432
	s_barrier

; #define PG8_STAGE(bufoff, gbase, voff) do { _Pragma("unroll") for (int _i = 0; _i < 2; ++_i) \
;         __builtin_amdgcn_global_load_lds((const unsigned*)((const char*)(gbase) + (voff)[_i]), (LAS unsigned*)(lds + (bufoff) + ldsw + _i * 8192), 16, 0, 0); } while (0)
; #define PG8_LDA(dst, b, h) do { _Pragma("unroll") for (int m = 0; m < 4; ++m) _Pragma("unroll") for (int k = 0; k < 2; ++k) dst[m][k] = *(const LAS bf16x8*)(lds + PG8_SA(b, h) + aoff + m * 2048 + k * 1024); } while (0)
; #define PG8_LDB(dst, b, h) do { _Pragma("unroll") for (int n = 0; n < 2; ++n) _Pragma("unroll") for (int k = 0; k < 2; ++k) dst[n][k] = *(const LAS bf16x8*)(lds + PG8_SB(b, h) + boff + n * 2048 + k * 1024); } while (0)
; #define PG8_MMA(ai, bj, At, Bt) do { __builtin_amdgcn_s_setprio(1); _Pragma("unroll") for (int m = 0; m < 4; ++m) _Pragma("unroll") for (int n = 0; n < 2; ++n) _Pragma("unroll") for (int k = 0; k < 2; ++k) \
;         acc[ai][bj][m][n] = __builtin_amdgcn_mfma_f32_16x16x32_bf16(Bt[n][k], At[m][k], acc[ai][bj][m][n], 0, 0, 0); __builtin_amdgcn_s_setprio(0); } while (0)
; #define PG8_WAIT_V(n) asm volatile("s_waitcnt vmcnt(" #n ")" ::: "memory")
; #define PG8_WAIT_L(n) asm volatile("s_waitcnt lgkmcnt(" #n ")" ::: "memory")
; #define PG8_BAR __builtin_amdgcn_s_barrier()
; #define PG8_SCHED __builtin_amdgcn_sched_barrier(0)
; template <class Epi>
; __device__ __forceinline__ void gemm_phase(LAS unsigned char* lds, const Gemm g, int G, int c, const Epi& E) {
;     ...
;         const bool has_next = S.next(ui + 1, nxt);
;         const char* nA = has_next ? (const char*)(g.A + (size_t)nxt.pb * g.sA) + (size_t)nxt.pm * 2 * hstepA : cA;
;         const char* nB = has_next ? (const char*)(g.Bt + (size_t)nxt.pb * g.sB) + (size_t)nxt.pn * 2 * hstepB : cB;
; #pragma nounroll
;         for (int t = 0; t < nt; t += 2) {
;             const bool last = (t == nt - 2);
;             const char* a1 = cA + (size_t)(t + 1) * kstep;
;             const char* a2 = last ? nA : cA + (size_t)(t + 2) * kstep; const char* b2 = last ? nB : cB + (size_t)(t + 2) * kstep;
;             const char* a3 = a2 + kstep; const char* b3 = b2 + kstep;
;             PG8_LDB(B0, 0, 0); PG8_LDB(B1, 0, 1); PG8_SCHED; PG8_LDA(At, 0, 0); PG8_STAGE(PG8_SA(1, 1), a1 + hstepA, voffA);
;             PG8_WAIT_V(8); PG8_WAIT_L(0); PG8_BAR; PG8_MMA(0, 0, At, B0); PG8_MMA(0, 1, At, B1); PG8_BAR; PG8_SCHED;
.LBB0_1451:
	s_add_u32 s33, s8, s44
	s_addc_u32 s45, s9, 0
	s_add_u32 s48, s33, 0x100
	s_addc_u32 s49, s45, 0
	s_and_b64 s[46:47], s[10:11], exec
	s_cselect_b32 s47, s41, s49
	s_cselect_b32 s46, s40, s48
	s_add_u32 s44, s6, s44
	s_addc_u32 s48, s7, 0
	s_add_u32 s44, s44, 0x100
	s_addc_u32 s48, s48, 0
	s_and_b64 s[10:11], s[10:11], exec
	s_cselect_b32 s49, s43, s48
	s_cselect_b32 s48, s42, s44
	s_add_u32 s54, s33, 0xb0080
	ds_read_b128 v[142:145], v160
	ds_read_b128 v[146:149], v160 offset:1024
	ds_read_b128 v[150:153], v160 offset:2048
	ds_read_b128 v[154:157], v160 offset:3072
	ds_read_b128 v[166:169], v161
	ds_read_b128 v[170:173], v161 offset:1024
	ds_read_b128 v[174:177], v161 offset:2048
	ds_read_b128 v[178:181], v161 offset:3072
	s_addc_u32 s55, s45, 0
	s_add_i32 s65, s82, s66
	s_add_i32 m0, s69, 0xc000
	s_add_i32 s74, s69, 0xe000
	s_add_i32 s62, s65, 0x2000
	s_add_u32 s52, s48, 0xb0000
	s_addc_u32 s53, s49, 0
	s_add_i32 s64, s83, s66
	s_add_i32 s63, s64, 0x2000
	s_add_i32 s97, 0, 0x18000
	s_add_i32 s33, 0, 0x1c000
	s_add_u32 s44, s46, 0xb0000
	s_addc_u32 s45, s47, 0
	s_add_i32 s96, s97, s66
	s_add_i32 s94, s96, 0x2000
	s_add_u32 s10, s48, 0xb0080
	s_addc_u32 s11, s49, 0
	s_add_i32 s95, s33, s66
	s_add_i32 s93, s95, 0x2000
	v_lshl_add_u64 v[214:215], s[54:55], 0, v[130:131]
	ds_read_b128 v[182:185], v162
	ds_read_b128 v[186:189], v162 offset:1024
	ds_read_b128 v[190:193], v162 offset:2048
	ds_read_b128 v[194:197], v162 offset:3072
	ds_read_b128 v[198:201], v162 offset:4096
	ds_read_b128 v[202:205], v162 offset:5120
	ds_read_b128 v[206:209], v162 offset:6144
	ds_read_b128 v[210:213], v162 offset:7168
	global_load_lds_dwordx4 v[214:215], off
	v_lshl_add_u64 v[214:215], s[54:55], 0, v[134:135]
	s_mov_b32 m0, s74
	s_nop 0
	global_load_lds_dwordx4 v[214:215], off
	s_waitcnt vmcnt(8)
	s_waitcnt lgkmcnt(0)
	s_barrier
	s_waitcnt lgkmcnt(0)
	v_mfma_f32_16x16x32_bf16 v[126:129], v[142:145], v[182:185], v[126:129]
	v_mfma_f32_16x16x32_bf16 v[122:125], v[150:153], v[182:185], v[122:125]
	v_mfma_f32_16x16x32_bf16 v[110:113], v[142:145], v[190:193], v[110:113]
	v_mfma_f32_16x16x32_bf16 v[106:109], v[150:153], v[190:193], v[106:109]
	v_mfma_f32_16x16x32_bf16 v[94:97], v[142:145], v[198:201], v[94:97]
	v_mfma_f32_16x16x32_bf16 v[90:93], v[150:153], v[198:201], v[90:93]
	v_mfma_f32_16x16x32_bf16 v[78:81], v[142:145], v[206:209], v[78:81]
	v_mfma_f32_16x16x32_bf16 v[74:77], v[150:153], v[206:209], v[74:77]
	v_mfma_f32_16x16x32_bf16 v[126:129], v[146:149], v[186:189], v[126:129]
	v_mfma_f32_16x16x32_bf16 v[122:125], v[154:157], v[186:189], v[122:125]
	v_mfma_f32_16x16x32_bf16 v[110:113], v[146:149], v[194:197], v[110:113]
	v_mfma_f32_16x16x32_bf16 v[106:109], v[154:157], v[194:197], v[106:109]
	v_mfma_f32_16x16x32_bf16 v[94:97], v[146:149], v[202:205], v[94:97]
	v_mfma_f32_16x16x32_bf16 v[90:93], v[154:157], v[202:205], v[90:93]
	v_mfma_f32_16x16x32_bf16 v[78:81], v[146:149], v[210:213], v[78:81]
	v_mfma_f32_16x16x32_bf16 v[74:77], v[154:157], v[210:213], v[74:77]
	v_mfma_f32_16x16x32_bf16 v[118:121], v[166:169], v[182:185], v[118:121]
	v_mfma_f32_16x16x32_bf16 v[114:117], v[174:177], v[182:185], v[114:117]
	v_mfma_f32_16x16x32_bf16 v[102:105], v[166:169], v[190:193], v[102:105]
	v_mfma_f32_16x16x32_bf16 v[98:101], v[174:177], v[190:193], v[98:101]
	v_mfma_f32_16x16x32_bf16 v[86:89], v[166:169], v[198:201], v[86:89]
	v_mfma_f32_16x16x32_bf16 v[82:85], v[174:177], v[198:201], v[82:85]
	v_mfma_f32_16x16x32_bf16 v[70:73], v[166:169], v[206:209], v[70:73]
	v_mfma_f32_16x16x32_bf16 v[66:69], v[174:177], v[206:209], v[66:69]
	v_mfma_f32_16x16x32_bf16 v[118:121], v[170:173], v[186:189], v[118:121]
	v_mfma_f32_16x16x32_bf16 v[114:117], v[178:181], v[186:189], v[114:117]
	v_mfma_f32_16x16x32_bf16 v[102:105], v[170:173], v[194:197], v[102:105]
	v_mfma_f32_16x16x32_bf16 v[98:101], v[178:181], v[194:197], v[98:101]
	v_mfma_f32_16x16x32_bf16 v[86:89], v[170:173], v[202:205], v[86:89]
	v_mfma_f32_16x16x32_bf16 v[82:85], v[178:181], v[202:205], v[82:85]
	v_mfma_f32_16x16x32_bf16 v[70:73], v[170:173], v[210:213], v[70:73]
	v_mfma_f32_16x16x32_bf16 v[66:69], v[178:181], v[210:213], v[66:69]
	s_barrier
	s_mov_b32 m0, s65
	v_lshl_add_u64 v[214:215], s[48:49], 0, v[132:133]
	ds_read_b128 v[182:185], v162 offset:16384
	ds_read_b128 v[186:189], v162 offset:17408
	ds_read_b128 v[190:193], v162 offset:18432
	ds_read_b128 v[194:197], v162 offset:19456
	ds_read_b128 v[198:201], v162 offset:20480
	ds_read_b128 v[202:205], v162 offset:21504
	ds_read_b128 v[206:209], v162 offset:22528
	ds_read_b128 v[210:213], v162 offset:23552
	global_load_lds_dwordx4 v[214:215], off
	v_lshl_add_u64 v[216:217], s[48:49], 0, v[136:137]
	s_mov_b32 m0, s62
	v_lshl_add_u64 v[218:219], s[52:53], 0, v[132:133]
	global_load_lds_dwordx4 v[216:217], off
	s_mov_b32 m0, s64
	v_lshl_add_u64 v[220:221], s[46:47], 0, v[134:135]
	global_load_lds_dwordx4 v[218:219], off
	v_lshl_add_u64 v[218:219], s[52:53], 0, v[136:137]
	s_mov_b32 m0, s63
	s_nop 0
	global_load_lds_dwordx4 v[218:219], off
	v_lshl_add_u64 v[218:219], s[46:47], 0, v[130:131]
	s_mov_b32 m0, s69
	s_nop 0
	global_load_lds_dwordx4 v[218:219], off
	s_mov_b32 m0, s70
	s_nop 0
	global_load_lds_dwordx4 v[220:221], off
	s_waitcnt vmcnt(8)
	s_waitcnt lgkmcnt(0)
	s_barrier
; #define PG8_STAGE(bufoff, gbase, voff) do { _Pragma("unroll") for (int _i = 0; _i < 2; ++_i) \
;         __builtin_amdgcn_global_load_lds((const unsigned*)((const char*)(gbase) + (voff)[_i]), (LAS unsigned*)(lds + (bufoff) + ldsw + _i * 8192), 16, 0, 0); } while (0)
; #define PG8_LDA(dst, b, h) do { _Pragma("unroll") for (int m = 0; m < 4; ++m) _Pragma("unroll") for (int k = 0; k < 2; ++k) dst[m][k] = *(const LAS bf16x8*)(lds + PG8_SA(b, h) + aoff + m * 2048 + k * 1024); } while (0)
; #define PG8_LDB(dst, b, h) do { _Pragma("unroll") for (int n = 0; n < 2; ++n) _Pragma("unroll") for (int k = 0; k < 2; ++k) dst[n][k] = *(const LAS bf16x8*)(lds + PG8_SB(b, h) + boff + n * 2048 + k * 1024); } while (0)
; #define PG8_MMA(ai, bj, At, Bt) do { __builtin_amdgcn_s_setprio(1); _Pragma("unroll") for (int m = 0; m < 4; ++m) _Pragma("unroll") for (int n = 0; n < 2; ++n) _Pragma("unroll") for (int k = 0; k < 2; ++k) \
;         acc[ai][bj][m][n] = __builtin_amdgcn_mfma_f32_16x16x32_bf16(Bt[n][k], At[m][k], acc[ai][bj][m][n], 0, 0, 0); __builtin_amdgcn_s_setprio(0); } while (0)
; #define PG8_WAIT_V(n) asm volatile("s_waitcnt vmcnt(" #n ")" ::: "memory")
; #define PG8_WAIT_L(n) asm volatile("s_waitcnt lgkmcnt(" #n ")" ::: "memory")
; #define PG8_BAR __builtin_amdgcn_s_barrier()
; #define PG8_SCHED __builtin_amdgcn_sched_barrier(0)
; template <class Epi>
; __device__ __forceinline__ void gemm_phase(LAS unsigned char* lds, const Gemm g, int G, int c, const Epi& E) {
;     ...
;             PG8_WAIT_V(8); PG8_WAIT_L(0); PG8_BAR; PG8_MMA(1, 0, At, B0); PG8_MMA(1, 1, At, B1); PG8_BAR; PG8_SCHED;
;             PG8_LDB(B0, 1, 0); PG8_LDB(B1, 1, 1); PG8_SCHED; PG8_LDA(At, 1, 0); PG8_STAGE(PG8_SA(0, 1), a2 + hstepA, voffA);
;             PG8_WAIT_V(8); PG8_WAIT_L(0); PG8_BAR; PG8_MMA(0, 0, At, B0); PG8_MMA(0, 1, At, B1); PG8_BAR; PG8_SCHED;
	s_waitcnt lgkmcnt(0)
	v_mfma_f32_16x16x32_bf16 v[62:65], v[142:145], v[182:185], v[62:65]
	v_mfma_f32_16x16x32_bf16 v[58:61], v[150:153], v[182:185], v[58:61]
	v_mfma_f32_16x16x32_bf16 v[46:49], v[142:145], v[190:193], v[46:49]
	v_mfma_f32_16x16x32_bf16 v[42:45], v[150:153], v[190:193], v[42:45]
	v_mfma_f32_16x16x32_bf16 v[30:33], v[142:145], v[198:201], v[30:33]
	v_mfma_f32_16x16x32_bf16 v[26:29], v[150:153], v[198:201], v[26:29]
	v_mfma_f32_16x16x32_bf16 v[14:17], v[142:145], v[206:209], v[14:17]
	v_mfma_f32_16x16x32_bf16 v[10:13], v[150:153], v[206:209], v[10:13]
	v_mfma_f32_16x16x32_bf16 v[62:65], v[146:149], v[186:189], v[62:65]
	v_mfma_f32_16x16x32_bf16 v[58:61], v[154:157], v[186:189], v[58:61]
	v_mfma_f32_16x16x32_bf16 v[46:49], v[146:149], v[194:197], v[46:49]
	v_mfma_f32_16x16x32_bf16 v[42:45], v[154:157], v[194:197], v[42:45]
	v_mfma_f32_16x16x32_bf16 v[30:33], v[146:149], v[202:205], v[30:33]
	v_mfma_f32_16x16x32_bf16 v[26:29], v[154:157], v[202:205], v[26:29]
	v_mfma_f32_16x16x32_bf16 v[14:17], v[146:149], v[210:213], v[14:17]
	v_mfma_f32_16x16x32_bf16 v[10:13], v[154:157], v[210:213], v[10:13]
	v_mfma_f32_16x16x32_bf16 v[54:57], v[166:169], v[182:185], v[54:57]
	v_mfma_f32_16x16x32_bf16 v[50:53], v[174:177], v[182:185], v[50:53]
	v_mfma_f32_16x16x32_bf16 v[38:41], v[166:169], v[190:193], v[38:41]
	v_mfma_f32_16x16x32_bf16 v[34:37], v[174:177], v[190:193], v[34:37]
	v_mfma_f32_16x16x32_bf16 v[22:25], v[166:169], v[198:201], v[22:25]
	v_mfma_f32_16x16x32_bf16 v[18:21], v[174:177], v[198:201], v[18:21]
	v_mfma_f32_16x16x32_bf16 v[6:9], v[166:169], v[206:209], v[6:9]
	v_mfma_f32_16x16x32_bf16 v[2:5], v[174:177], v[206:209], v[2:5]
	v_mfma_f32_16x16x32_bf16 v[54:57], v[170:173], v[186:189], v[54:57]
	v_mfma_f32_16x16x32_bf16 v[50:53], v[178:181], v[186:189], v[50:53]
	v_mfma_f32_16x16x32_bf16 v[38:41], v[170:173], v[194:197], v[38:41]
	v_mfma_f32_16x16x32_bf16 v[34:37], v[178:181], v[194:197], v[34:37]
	v_mfma_f32_16x16x32_bf16 v[22:25], v[170:173], v[202:205], v[22:25]
	v_mfma_f32_16x16x32_bf16 v[18:21], v[178:181], v[202:205], v[18:21]
	v_mfma_f32_16x16x32_bf16 v[6:9], v[170:173], v[210:213], v[6:9]
	v_mfma_f32_16x16x32_bf16 v[2:5], v[178:181], v[210:213], v[2:5]
	s_barrier
	v_add_u32_e32 v154, s97, v159
	v_add_u32_e32 v178, s33, v159
	ds_read_b128 v[142:145], v154
	ds_read_b128 v[146:149], v154 offset:1024
	ds_read_b128 v[150:153], v154 offset:2048
	ds_read_b128 v[154:157], v154 offset:3072
	ds_read_b128 v[166:169], v178
	ds_read_b128 v[170:173], v178 offset:1024
	ds_read_b128 v[174:177], v178 offset:2048
	ds_read_b128 v[178:181], v178 offset:3072
	s_mov_b32 m0, s71
	v_lshl_add_u64 v[222:223], s[44:45], 0, v[130:131]
	ds_read_b128 v[182:185], v162 offset:32768
	ds_read_b128 v[186:189], v162 offset:33792
	ds_read_b128 v[190:193], v162 offset:34816
	ds_read_b128 v[194:197], v162 offset:35840
	ds_read_b128 v[198:201], v162 offset:36864
	ds_read_b128 v[202:205], v162 offset:37888
	ds_read_b128 v[206:209], v162 offset:38912
	ds_read_b128 v[210:213], v162 offset:39936
	global_load_lds_dwordx4 v[222:223], off
	v_lshl_add_u64 v[222:223], s[44:45], 0, v[134:135]
	s_mov_b32 m0, s72
	s_nop 0
	global_load_lds_dwordx4 v[222:223], off
	s_waitcnt vmcnt(8)
	s_waitcnt lgkmcnt(0)
	s_barrier
	s_waitcnt lgkmcnt(0)
	v_mfma_f32_16x16x32_bf16 v[126:129], v[142:145], v[182:185], v[126:129]
	v_mfma_f32_16x16x32_bf16 v[122:125], v[150:153], v[182:185], v[122:125]
	v_mfma_f32_16x16x32_bf16 v[110:113], v[142:145], v[190:193], v[110:113]
	v_mfma_f32_16x16x32_bf16 v[106:109], v[150:153], v[190:193], v[106:109]
	v_mfma_f32_16x16x32_bf16 v[94:97], v[142:145], v[198:201], v[94:97]
	v_mfma_f32_16x16x32_bf16 v[90:93], v[150:153], v[198:201], v[90:93]
	v_mfma_f32_16x16x32_bf16 v[78:81], v[142:145], v[206:209], v[78:81]
	v_mfma_f32_16x16x32_bf16 v[74:77], v[150:153], v[206:209], v[74:77]
	v_mfma_f32_16x16x32_bf16 v[126:129], v[146:149], v[186:189], v[126:129]
	v_mfma_f32_16x16x32_bf16 v[122:125], v[154:157], v[186:189], v[122:125]
	v_mfma_f32_16x16x32_bf16 v[110:113], v[146:149], v[194:197], v[110:113]
	v_mfma_f32_16x16x32_bf16 v[106:109], v[154:157], v[194:197], v[106:109]
	v_mfma_f32_16x16x32_bf16 v[94:97], v[146:149], v[202:205], v[94:97]
	v_mfma_f32_16x16x32_bf16 v[90:93], v[154:157], v[202:205], v[90:93]
	v_mfma_f32_16x16x32_bf16 v[78:81], v[146:149], v[210:213], v[78:81]
	v_mfma_f32_16x16x32_bf16 v[74:77], v[154:157], v[210:213], v[74:77]
	v_mfma_f32_16x16x32_bf16 v[118:121], v[166:169], v[182:185], v[118:121]
	v_mfma_f32_16x16x32_bf16 v[114:117], v[174:177], v[182:185], v[114:117]
	v_mfma_f32_16x16x32_bf16 v[102:105], v[166:169], v[190:193], v[102:105]
	v_mfma_f32_16x16x32_bf16 v[98:101], v[174:177], v[190:193], v[98:101]
	v_mfma_f32_16x16x32_bf16 v[86:89], v[166:169], v[198:201], v[86:89]
	v_mfma_f32_16x16x32_bf16 v[82:85], v[174:177], v[198:201], v[82:85]
	v_mfma_f32_16x16x32_bf16 v[70:73], v[166:169], v[206:209], v[70:73]
	v_mfma_f32_16x16x32_bf16 v[66:69], v[174:177], v[206:209], v[66:69]
	v_mfma_f32_16x16x32_bf16 v[118:121], v[170:173], v[186:189], v[118:121]
	v_mfma_f32_16x16x32_bf16 v[114:117], v[178:181], v[186:189], v[114:117]
	v_mfma_f32_16x16x32_bf16 v[102:105], v[170:173], v[194:197], v[102:105]
	v_mfma_f32_16x16x32_bf16 v[98:101], v[178:181], v[194:197], v[98:101]
	v_mfma_f32_16x16x32_bf16 v[86:89], v[170:173], v[202:205], v[86:89]
	v_mfma_f32_16x16x32_bf16 v[82:85], v[178:181], v[202:205], v[82:85]
	v_mfma_f32_16x16x32_bf16 v[70:73], v[170:173], v[210:213], v[70:73]
	v_mfma_f32_16x16x32_bf16 v[66:69], v[178:181], v[210:213], v[66:69]
	s_barrier
; #define PG8_STAGE(bufoff, gbase, voff) do { _Pragma("unroll") for (int _i = 0; _i < 2; ++_i) \
;         __builtin_amdgcn_global_load_lds((const unsigned*)((const char*)(gbase) + (voff)[_i]), (LAS unsigned*)(lds + (bufoff) + ldsw + _i * 8192), 16, 0, 0); } while (0)
; #define PG8_LDA(dst, b, h) do { _Pragma("unroll") for (int m = 0; m < 4; ++m) _Pragma("unroll") for (int k = 0; k < 2; ++k) dst[m][k] = *(const LAS bf16x8*)(lds + PG8_SA(b, h) + aoff + m * 2048 + k * 1024); } while (0)
; #define PG8_MMA(ai, bj, At, Bt) do { __builtin_amdgcn_s_setprio(1); _Pragma("unroll") for (int m = 0; m < 4; ++m) _Pragma("unroll") for (int n = 0; n < 2; ++n) _Pragma("unroll") for (int k = 0; k < 2; ++k) \
;         acc[ai][bj][m][n] = __builtin_amdgcn_mfma_f32_16x16x32_bf16(Bt[n][k], At[m][k], acc[ai][bj][m][n], 0, 0, 0); __builtin_amdgcn_s_setprio(0); } while (0)
; #define PG8_WAIT_V(n) asm volatile("s_waitcnt vmcnt(" #n ")" ::: "memory")
; #define PG8_WAIT_L(n) asm volatile("s_waitcnt lgkmcnt(" #n ")" ::: "memory")
; #define PG8_BAR __builtin_amdgcn_s_barrier()
; #define PG8_SCHED __builtin_amdgcn_sched_barrier(0)
; template <class Epi>
; __device__ __forceinline__ void gemm_phase(LAS unsigned char* lds, const Gemm g, int G, int c, const Epi& E) {
;     ...
;             PG8_LDA(At, 1, 1); PG8_STAGE(PG8_SB(1, 0), b3, voffB); PG8_STAGE(PG8_SB(1, 1), b3 + hstepB, voffB); PG8_STAGE(PG8_SA(1, 0), a3, voffA);
;             PG8_WAIT_V(8); PG8_WAIT_L(0); PG8_BAR; PG8_MMA(1, 0, At, B0); PG8_MMA(1, 1, At, B1); PG8_BAR; PG8_SCHED;
;         }
;         if (wr == 0) PG8_BAR;
	s_mov_b32 m0, s96
	v_lshl_add_u64 v[214:215], v[214:215], 0, s[22:23]
	ds_read_b128 v[182:185], v162 offset:49152
	ds_read_b128 v[186:189], v162 offset:50176
	ds_read_b128 v[190:193], v162 offset:51200
	ds_read_b128 v[194:197], v162 offset:52224
	ds_read_b128 v[198:201], v162 offset:53248
	ds_read_b128 v[202:205], v162 offset:54272
	ds_read_b128 v[206:209], v162 offset:55296
	ds_read_b128 v[210:213], v162 offset:56320
	global_load_lds_dwordx4 v[214:215], off
	v_lshl_add_u64 v[214:215], v[216:217], 0, s[22:23]
	s_mov_b32 m0, s94
	s_nop 0
	global_load_lds_dwordx4 v[214:215], off
	v_lshl_add_u64 v[214:215], s[10:11], 0, v[132:133]
	s_mov_b32 m0, s95
	s_nop 0
	global_load_lds_dwordx4 v[214:215], off
	v_lshl_add_u64 v[214:215], s[10:11], 0, v[136:137]
	s_mov_b32 m0, s93
	s_nop 0
	global_load_lds_dwordx4 v[214:215], off
	v_lshl_add_u64 v[214:215], v[218:219], 0, s[22:23]
	s_mov_b32 m0, s80
	s_nop 0
	global_load_lds_dwordx4 v[214:215], off
	v_lshl_add_u64 v[214:215], v[220:221], 0, s[22:23]
	s_mov_b32 m0, s81
	s_nop 0
	global_load_lds_dwordx4 v[214:215], off
	s_waitcnt vmcnt(8)
	s_waitcnt lgkmcnt(0)
	s_barrier
	s_waitcnt lgkmcnt(0)
	v_mfma_f32_16x16x32_bf16 v[62:65], v[142:145], v[182:185], v[62:65]
	v_mfma_f32_16x16x32_bf16 v[58:61], v[150:153], v[182:185], v[58:61]
	v_mfma_f32_16x16x32_bf16 v[46:49], v[142:145], v[190:193], v[46:49]
	v_mfma_f32_16x16x32_bf16 v[42:45], v[150:153], v[190:193], v[42:45]
	v_mfma_f32_16x16x32_bf16 v[30:33], v[142:145], v[198:201], v[30:33]
	v_mfma_f32_16x16x32_bf16 v[26:29], v[150:153], v[198:201], v[26:29]
	v_mfma_f32_16x16x32_bf16 v[14:17], v[142:145], v[206:209], v[14:17]
	v_mfma_f32_16x16x32_bf16 v[10:13], v[150:153], v[206:209], v[10:13]
	v_mfma_f32_16x16x32_bf16 v[62:65], v[146:149], v[186:189], v[62:65]
	v_mfma_f32_16x16x32_bf16 v[58:61], v[154:157], v[186:189], v[58:61]
	v_mfma_f32_16x16x32_bf16 v[46:49], v[146:149], v[194:197], v[46:49]
	v_mfma_f32_16x16x32_bf16 v[42:45], v[154:157], v[194:197], v[42:45]
	v_mfma_f32_16x16x32_bf16 v[30:33], v[146:149], v[202:205], v[30:33]
	v_mfma_f32_16x16x32_bf16 v[26:29], v[154:157], v[202:205], v[26:29]
	v_mfma_f32_16x16x32_bf16 v[14:17], v[146:149], v[210:213], v[14:17]
	v_mfma_f32_16x16x32_bf16 v[10:13], v[154:157], v[210:213], v[10:13]
	v_mfma_f32_16x16x32_bf16 v[54:57], v[166:169], v[182:185], v[54:57]
	v_mfma_f32_16x16x32_bf16 v[50:53], v[174:177], v[182:185], v[50:53]
	v_mfma_f32_16x16x32_bf16 v[38:41], v[166:169], v[190:193], v[38:41]
	v_mfma_f32_16x16x32_bf16 v[34:37], v[174:177], v[190:193], v[34:37]
	v_mfma_f32_16x16x32_bf16 v[22:25], v[166:169], v[198:201], v[22:25]
	v_mfma_f32_16x16x32_bf16 v[18:21], v[174:177], v[198:201], v[18:21]
	v_mfma_f32_16x16x32_bf16 v[6:9], v[166:169], v[206:209], v[6:9]
	v_mfma_f32_16x16x32_bf16 v[2:5], v[174:177], v[206:209], v[2:5]
	v_mfma_f32_16x16x32_bf16 v[54:57], v[170:173], v[186:189], v[54:57]
	v_mfma_f32_16x16x32_bf16 v[50:53], v[178:181], v[186:189], v[50:53]
	v_mfma_f32_16x16x32_bf16 v[38:41], v[170:173], v[194:197], v[38:41]
	v_mfma_f32_16x16x32_bf16 v[34:37], v[178:181], v[194:197], v[34:37]
	v_mfma_f32_16x16x32_bf16 v[22:25], v[170:173], v[202:205], v[22:25]
	v_mfma_f32_16x16x32_bf16 v[18:21], v[178:181], v[202:205], v[18:21]
	v_mfma_f32_16x16x32_bf16 v[6:9], v[170:173], v[210:213], v[6:9]
	v_mfma_f32_16x16x32_bf16 v[2:5], v[178:181], v[210:213], v[2:5]
	s_barrier
	s_movk_i32 s44, 0x100
	s_andn2_b64 vcc, exec, s[4:5]
	s_mov_b64 s[10:11], -1
	s_mov_b64 s[4:5], 0
	s_cbranch_vccz .LBB0_1451
	s_and_b64 vcc, exec, s[24:25]
	s_cbranch_vccz .LBB0_1454
	s_barrier

; #define PG8_STAGE(bufoff, gbase, voff) do { _Pragma("unroll") for (int _i = 0; _i < 2; ++_i) \
;         __builtin_amdgcn_global_load_lds((const unsigned*)((const char*)(gbase) + (voff)[_i]), (LAS unsigned*)(lds + (bufoff) + ldsw + _i * 8192), 16, 0, 0); } while (0)
; #define PG8_LDA(dst, b, h) do { _Pragma("unroll") for (int m = 0; m < 4; ++m) _Pragma("unroll") for (int k = 0; k < 2; ++k) dst[m][k] = *(const LAS bf16x8*)(lds + PG8_SA(b, h) + aoff + m * 2048 + k * 1024); } while (0)
; #define PG8_LDB(dst, b, h) do { _Pragma("unroll") for (int n = 0; n < 2; ++n) _Pragma("unroll") for (int k = 0; k < 2; ++k) dst[n][k] = *(const LAS bf16x8*)(lds + PG8_SB(b, h) + boff + n * 2048 + k * 1024); } while (0)
; #define PG8_MMA(ai, bj, At, Bt) do { __builtin_amdgcn_s_setprio(1); _Pragma("unroll") for (int m = 0; m < 4; ++m) _Pragma("unroll") for (int n = 0; n < 2; ++n) _Pragma("unroll") for (int k = 0; k < 2; ++k) \
;         acc[ai][bj][m][n] = __builtin_amdgcn_mfma_f32_16x16x32_bf16(Bt[n][k], At[m][k], acc[ai][bj][m][n], 0, 0, 0); __builtin_amdgcn_s_setprio(0); } while (0)
; #define PG8_WAIT_V(n) asm volatile("s_waitcnt vmcnt(" #n ")" ::: "memory")
; #define PG8_WAIT_L(n) asm volatile("s_waitcnt lgkmcnt(" #n ")" ::: "memory")
; #define PG8_BAR __builtin_amdgcn_s_barrier()
; #define PG8_SCHED __builtin_amdgcn_sched_barrier(0)
; template <class Epi>
; __device__ __forceinline__ void gemm_phase(LAS unsigned char* lds, const Gemm g, int G, int c, const Epi& E) {
;     ...
;             const bool last = (t == nt - 2);
;             const char* a1 = cA + (size_t)(t + 1) * kstep;
;             const char* a2 = last ? nA : cA + (size_t)(t + 2) * kstep; const char* b2 = last ? nB : cB + (size_t)(t + 2) * kstep;
;             const char* a3 = a2 + kstep; const char* b3 = b2 + kstep;
;             PG8_LDB(B0, 0, 0); PG8_LDB(B1, 0, 1); PG8_SCHED; PG8_LDA(At, 0, 0); PG8_STAGE(PG8_SA(1, 1), a1 + hstepA, voffA);
;             PG8_WAIT_V(8); PG8_WAIT_L(0); PG8_BAR; PG8_MMA(0, 0, At, B0); PG8_MMA(0, 1, At, B1); PG8_BAR; PG8_SCHED;
;             PG8_LDA(At, 0, 1); PG8_STAGE(PG8_SB(0, 0), b2, voffB); PG8_STAGE(PG8_SB(0, 1), b2 + hstepB, voffB); PG8_STAGE(PG8_SA(0, 0), a2, voffA);
.LBB0_1537:
	s_add_u32 s33, s8, s44
	s_addc_u32 s45, s9, 0
	s_add_u32 s48, s33, 0x100
	s_addc_u32 s49, s45, 0
	s_and_b64 s[46:47], s[10:11], exec
	s_cselect_b32 s47, s41, s49
	s_cselect_b32 s46, s40, s48
	s_add_u32 s44, s6, s44
	s_addc_u32 s48, s7, 0
	s_add_u32 s44, s44, 0x100
	s_addc_u32 s48, s48, 0
	s_and_b64 s[10:11], s[10:11], exec
	s_cselect_b32 s49, s43, s48
	s_cselect_b32 s48, s42, s44
	s_add_u32 s54, s33, 0xb0080
	ds_read_b128 v[130:133], v166
	ds_read_b128 v[134:137], v166 offset:1024
	ds_read_b128 v[150:153], v166 offset:2048
	ds_read_b128 v[154:157], v166 offset:3072
	ds_read_b128 v[158:161], v167
	ds_read_b128 v[172:175], v167 offset:1024
	ds_read_b128 v[176:179], v167 offset:2048
	ds_read_b128 v[180:183], v167 offset:3072
	s_addc_u32 s55, s45, 0
	s_add_i32 s63, s87, s70
	s_add_i32 m0, s73, 0xc000
	s_add_i32 s64, s73, 0xe000
	s_add_i32 s74, s63, 0x2000
	s_add_u32 s52, s48, 0xb0000
	s_addc_u32 s53, s49, 0
	s_add_i32 s62, s88, s70
	s_add_i32 s75, s62, 0x2000
	s_add_i32 s97, 0, 0x18000
	s_add_i32 s33, 0, 0x1c000
	s_add_u32 s44, s46, 0xb0000
	s_addc_u32 s45, s47, 0
	s_add_i32 s96, s97, s70
	s_add_i32 s94, s96, 0x2000
	s_add_u32 s10, s48, 0xb0080
	s_addc_u32 s11, s49, 0
	s_add_i32 s95, s33, s70
	s_add_i32 s93, s95, 0x2000
	v_lshl_add_u64 v[162:163], s[54:55], 0, v[138:139]
	ds_read_b128 v[184:187], v168
	ds_read_b128 v[188:191], v168 offset:1024
	ds_read_b128 v[192:195], v168 offset:2048
	ds_read_b128 v[196:199], v168 offset:3072
	ds_read_b128 v[200:203], v168 offset:4096
	ds_read_b128 v[204:207], v168 offset:5120
	ds_read_b128 v[208:211], v168 offset:6144
	ds_read_b128 v[212:215], v168 offset:7168
	global_load_lds_dwordx4 v[162:163], off
	v_lshl_add_u64 v[162:163], s[54:55], 0, v[142:143]
	s_mov_b32 m0, s64
	s_nop 0
	global_load_lds_dwordx4 v[162:163], off
	s_waitcnt vmcnt(8)
	s_waitcnt lgkmcnt(0)
	s_barrier
	s_waitcnt lgkmcnt(0)
	v_mfma_f32_16x16x32_bf16 v[126:129], v[130:133], v[184:187], v[126:129]
	v_mfma_f32_16x16x32_bf16 v[122:125], v[150:153], v[184:187], v[122:125]
	v_mfma_f32_16x16x32_bf16 v[110:113], v[130:133], v[192:195], v[110:113]
	v_mfma_f32_16x16x32_bf16 v[106:109], v[150:153], v[192:195], v[106:109]
	v_mfma_f32_16x16x32_bf16 v[94:97], v[130:133], v[200:203], v[94:97]
	v_mfma_f32_16x16x32_bf16 v[90:93], v[150:153], v[200:203], v[90:93]
	v_mfma_f32_16x16x32_bf16 v[78:81], v[130:133], v[208:211], v[78:81]
	v_mfma_f32_16x16x32_bf16 v[74:77], v[150:153], v[208:211], v[74:77]
	v_mfma_f32_16x16x32_bf16 v[126:129], v[134:137], v[188:191], v[126:129]
	v_mfma_f32_16x16x32_bf16 v[122:125], v[154:157], v[188:191], v[122:125]
	v_mfma_f32_16x16x32_bf16 v[110:113], v[134:137], v[196:199], v[110:113]
	v_mfma_f32_16x16x32_bf16 v[106:109], v[154:157], v[196:199], v[106:109]
	v_mfma_f32_16x16x32_bf16 v[94:97], v[134:137], v[204:207], v[94:97]
	v_mfma_f32_16x16x32_bf16 v[90:93], v[154:157], v[204:207], v[90:93]
	v_mfma_f32_16x16x32_bf16 v[78:81], v[134:137], v[212:215], v[78:81]
	v_mfma_f32_16x16x32_bf16 v[74:77], v[154:157], v[212:215], v[74:77]
	v_mfma_f32_16x16x32_bf16 v[118:121], v[158:161], v[184:187], v[118:121]
	v_mfma_f32_16x16x32_bf16 v[114:117], v[176:179], v[184:187], v[114:117]
	v_mfma_f32_16x16x32_bf16 v[102:105], v[158:161], v[192:195], v[102:105]
	v_mfma_f32_16x16x32_bf16 v[98:101], v[176:179], v[192:195], v[98:101]
	v_mfma_f32_16x16x32_bf16 v[86:89], v[158:161], v[200:203], v[86:89]
	v_mfma_f32_16x16x32_bf16 v[82:85], v[176:179], v[200:203], v[82:85]
	v_mfma_f32_16x16x32_bf16 v[70:73], v[158:161], v[208:211], v[70:73]
	v_mfma_f32_16x16x32_bf16 v[66:69], v[176:179], v[208:211], v[66:69]
	v_mfma_f32_16x16x32_bf16 v[118:121], v[172:175], v[188:191], v[118:121]
	v_mfma_f32_16x16x32_bf16 v[114:117], v[180:183], v[188:191], v[114:117]
	v_mfma_f32_16x16x32_bf16 v[102:105], v[172:175], v[196:199], v[102:105]
	v_mfma_f32_16x16x32_bf16 v[98:101], v[180:183], v[196:199], v[98:101]
	v_mfma_f32_16x16x32_bf16 v[86:89], v[172:175], v[204:207], v[86:89]
	v_mfma_f32_16x16x32_bf16 v[82:85], v[180:183], v[204:207], v[82:85]
	v_mfma_f32_16x16x32_bf16 v[70:73], v[172:175], v[212:215], v[70:73]
	v_mfma_f32_16x16x32_bf16 v[66:69], v[180:183], v[212:215], v[66:69]
	s_barrier
	s_mov_b32 m0, s63
	v_lshl_add_u64 v[162:163], s[48:49], 0, v[140:141]
	ds_read_b128 v[184:187], v168 offset:16384
	ds_read_b128 v[188:191], v168 offset:17408
	ds_read_b128 v[192:195], v168 offset:18432
	ds_read_b128 v[196:199], v168 offset:19456
	ds_read_b128 v[200:203], v168 offset:20480
	ds_read_b128 v[204:207], v168 offset:21504
	ds_read_b128 v[208:211], v168 offset:22528
	ds_read_b128 v[212:215], v168 offset:23552
	global_load_lds_dwordx4 v[162:163], off
	v_lshl_add_u64 v[216:217], s[48:49], 0, v[144:145]
	s_mov_b32 m0, s74
	v_lshl_add_u64 v[218:219], s[52:53], 0, v[140:141]
	global_load_lds_dwordx4 v[216:217], off
	s_mov_b32 m0, s62
	v_lshl_add_u64 v[220:221], s[46:47], 0, v[142:143]
	global_load_lds_dwordx4 v[218:219], off
	v_lshl_add_u64 v[218:219], s[52:53], 0, v[144:145]
	s_mov_b32 m0, s75
	s_nop 0
	global_load_lds_dwordx4 v[218:219], off
	v_lshl_add_u64 v[218:219], s[46:47], 0, v[138:139]
	s_mov_b32 m0, s73
	s_nop 0
	global_load_lds_dwordx4 v[218:219], off
	s_mov_b32 m0, s79
	s_nop 0
	global_load_lds_dwordx4 v[220:221], off
	s_waitcnt vmcnt(8)
	s_waitcnt lgkmcnt(0)
	s_barrier
; #define PG8_STAGE(bufoff, gbase, voff) do { _Pragma("unroll") for (int _i = 0; _i < 2; ++_i) \
;         __builtin_amdgcn_global_load_lds((const unsigned*)((const char*)(gbase) + (voff)[_i]), (LAS unsigned*)(lds + (bufoff) + ldsw + _i * 8192), 16, 0, 0); } while (0)
; #define PG8_LDA(dst, b, h) do { _Pragma("unroll") for (int m = 0; m < 4; ++m) _Pragma("unroll") for (int k = 0; k < 2; ++k) dst[m][k] = *(const LAS bf16x8*)(lds + PG8_SA(b, h) + aoff + m * 2048 + k * 1024); } while (0)
; #define PG8_LDB(dst, b, h) do { _Pragma("unroll") for (int n = 0; n < 2; ++n) _Pragma("unroll") for (int k = 0; k < 2; ++k) dst[n][k] = *(const LAS bf16x8*)(lds + PG8_SB(b, h) + boff + n * 2048 + k * 1024); } while (0)
; #define PG8_MMA(ai, bj, At, Bt) do { __builtin_amdgcn_s_setprio(1); _Pragma("unroll") for (int m = 0; m < 4; ++m) _Pragma("unroll") for (int n = 0; n < 2; ++n) _Pragma("unroll") for (int k = 0; k < 2; ++k) \
;         acc[ai][bj][m][n] = __builtin_amdgcn_mfma_f32_16x16x32_bf16(Bt[n][k], At[m][k], acc[ai][bj][m][n], 0, 0, 0); __builtin_amdgcn_s_setprio(0); } while (0)
; #define PG8_WAIT_V(n) asm volatile("s_waitcnt vmcnt(" #n ")" ::: "memory")
; #define PG8_WAIT_L(n) asm volatile("s_waitcnt lgkmcnt(" #n ")" ::: "memory")
; #define PG8_BAR __builtin_amdgcn_s_barrier()
; #define PG8_SCHED __builtin_amdgcn_sched_barrier(0)
; template <class Epi>
; __device__ __forceinline__ void gemm_phase(LAS unsigned char* lds, const Gemm g, int G, int c, const Epi& E) {
;     ...
;             PG8_WAIT_V(8); PG8_WAIT_L(0); PG8_BAR; PG8_MMA(1, 0, At, B0); PG8_MMA(1, 1, At, B1); PG8_BAR; PG8_SCHED;
;             PG8_LDB(B0, 1, 0); PG8_LDB(B1, 1, 1); PG8_SCHED; PG8_LDA(At, 1, 0); PG8_STAGE(PG8_SA(0, 1), a2 + hstepA, voffA);
;             PG8_WAIT_V(8); PG8_WAIT_L(0); PG8_BAR; PG8_MMA(0, 0, At, B0); PG8_MMA(0, 1, At, B1); PG8_BAR; PG8_SCHED;
	s_waitcnt lgkmcnt(0)
	v_mfma_f32_16x16x32_bf16 v[62:65], v[130:133], v[184:187], v[62:65]
	v_mfma_f32_16x16x32_bf16 v[58:61], v[150:153], v[184:187], v[58:61]
	v_mfma_f32_16x16x32_bf16 v[46:49], v[130:133], v[192:195], v[46:49]
	v_mfma_f32_16x16x32_bf16 v[42:45], v[150:153], v[192:195], v[42:45]
	v_mfma_f32_16x16x32_bf16 v[30:33], v[130:133], v[200:203], v[30:33]
	v_mfma_f32_16x16x32_bf16 v[26:29], v[150:153], v[200:203], v[26:29]
	v_mfma_f32_16x16x32_bf16 v[14:17], v[130:133], v[208:211], v[14:17]
	v_mfma_f32_16x16x32_bf16 v[10:13], v[150:153], v[208:211], v[10:13]
	v_mfma_f32_16x16x32_bf16 v[62:65], v[134:137], v[188:191], v[62:65]
	v_mfma_f32_16x16x32_bf16 v[58:61], v[154:157], v[188:191], v[58:61]
	v_mfma_f32_16x16x32_bf16 v[46:49], v[134:137], v[196:199], v[46:49]
	v_mfma_f32_16x16x32_bf16 v[42:45], v[154:157], v[196:199], v[42:45]
	v_mfma_f32_16x16x32_bf16 v[30:33], v[134:137], v[204:207], v[30:33]
	v_mfma_f32_16x16x32_bf16 v[26:29], v[154:157], v[204:207], v[26:29]
	v_mfma_f32_16x16x32_bf16 v[14:17], v[134:137], v[212:215], v[14:17]
	v_mfma_f32_16x16x32_bf16 v[10:13], v[154:157], v[212:215], v[10:13]
	v_mfma_f32_16x16x32_bf16 v[54:57], v[158:161], v[184:187], v[54:57]
	v_mfma_f32_16x16x32_bf16 v[50:53], v[176:179], v[184:187], v[50:53]
	v_mfma_f32_16x16x32_bf16 v[38:41], v[158:161], v[192:195], v[38:41]
	v_mfma_f32_16x16x32_bf16 v[34:37], v[176:179], v[192:195], v[34:37]
	v_mfma_f32_16x16x32_bf16 v[22:25], v[158:161], v[200:203], v[22:25]
	v_mfma_f32_16x16x32_bf16 v[18:21], v[176:179], v[200:203], v[18:21]
	v_mfma_f32_16x16x32_bf16 v[6:9], v[158:161], v[208:211], v[6:9]
	v_mfma_f32_16x16x32_bf16 v[2:5], v[176:179], v[208:211], v[2:5]
	v_mfma_f32_16x16x32_bf16 v[54:57], v[172:175], v[188:191], v[54:57]
	v_mfma_f32_16x16x32_bf16 v[50:53], v[180:183], v[188:191], v[50:53]
	v_mfma_f32_16x16x32_bf16 v[38:41], v[172:175], v[196:199], v[38:41]
	v_mfma_f32_16x16x32_bf16 v[34:37], v[180:183], v[196:199], v[34:37]
	v_mfma_f32_16x16x32_bf16 v[22:25], v[172:175], v[204:207], v[22:25]
	v_mfma_f32_16x16x32_bf16 v[18:21], v[180:183], v[204:207], v[18:21]
	v_mfma_f32_16x16x32_bf16 v[6:9], v[172:175], v[212:215], v[6:9]
	v_mfma_f32_16x16x32_bf16 v[2:5], v[180:183], v[212:215], v[2:5]
	s_barrier
	v_add_u32_e32 v154, s97, v165
	v_add_u32_e32 v180, s33, v165
	ds_read_b128 v[130:133], v154
	ds_read_b128 v[134:137], v154 offset:1024
	ds_read_b128 v[150:153], v154 offset:2048
	ds_read_b128 v[154:157], v154 offset:3072
	ds_read_b128 v[158:161], v180
	ds_read_b128 v[172:175], v180 offset:1024
	ds_read_b128 v[176:179], v180 offset:2048
	ds_read_b128 v[180:183], v180 offset:3072
	s_mov_b32 m0, s80
	v_lshl_add_u64 v[222:223], s[44:45], 0, v[138:139]
	ds_read_b128 v[184:187], v168 offset:32768
	ds_read_b128 v[188:191], v168 offset:33792
	ds_read_b128 v[192:195], v168 offset:34816
	ds_read_b128 v[196:199], v168 offset:35840
	ds_read_b128 v[200:203], v168 offset:36864
	ds_read_b128 v[204:207], v168 offset:37888
	ds_read_b128 v[208:211], v168 offset:38912
	ds_read_b128 v[212:215], v168 offset:39936
	global_load_lds_dwordx4 v[222:223], off
	v_lshl_add_u64 v[222:223], s[44:45], 0, v[142:143]
	s_mov_b32 m0, s81
	s_nop 0
	global_load_lds_dwordx4 v[222:223], off
	s_waitcnt vmcnt(8)
	s_waitcnt lgkmcnt(0)
	s_barrier
	s_waitcnt lgkmcnt(0)
	v_mfma_f32_16x16x32_bf16 v[126:129], v[130:133], v[184:187], v[126:129]
	v_mfma_f32_16x16x32_bf16 v[122:125], v[150:153], v[184:187], v[122:125]
	v_mfma_f32_16x16x32_bf16 v[110:113], v[130:133], v[192:195], v[110:113]
	v_mfma_f32_16x16x32_bf16 v[106:109], v[150:153], v[192:195], v[106:109]
	v_mfma_f32_16x16x32_bf16 v[94:97], v[130:133], v[200:203], v[94:97]
	v_mfma_f32_16x16x32_bf16 v[90:93], v[150:153], v[200:203], v[90:93]
	v_mfma_f32_16x16x32_bf16 v[78:81], v[130:133], v[208:211], v[78:81]
	v_mfma_f32_16x16x32_bf16 v[74:77], v[150:153], v[208:211], v[74:77]
	v_mfma_f32_16x16x32_bf16 v[126:129], v[134:137], v[188:191], v[126:129]
	v_mfma_f32_16x16x32_bf16 v[122:125], v[154:157], v[188:191], v[122:125]
	v_mfma_f32_16x16x32_bf16 v[110:113], v[134:137], v[196:199], v[110:113]
	v_mfma_f32_16x16x32_bf16 v[106:109], v[154:157], v[196:199], v[106:109]
	v_mfma_f32_16x16x32_bf16 v[94:97], v[134:137], v[204:207], v[94:97]
	v_mfma_f32_16x16x32_bf16 v[90:93], v[154:157], v[204:207], v[90:93]
	v_mfma_f32_16x16x32_bf16 v[78:81], v[134:137], v[212:215], v[78:81]
	v_mfma_f32_16x16x32_bf16 v[74:77], v[154:157], v[212:215], v[74:77]
	v_mfma_f32_16x16x32_bf16 v[118:121], v[158:161], v[184:187], v[118:121]
	v_mfma_f32_16x16x32_bf16 v[114:117], v[176:179], v[184:187], v[114:117]
	v_mfma_f32_16x16x32_bf16 v[102:105], v[158:161], v[192:195], v[102:105]
	v_mfma_f32_16x16x32_bf16 v[98:101], v[176:179], v[192:195], v[98:101]
	v_mfma_f32_16x16x32_bf16 v[86:89], v[158:161], v[200:203], v[86:89]
	v_mfma_f32_16x16x32_bf16 v[82:85], v[176:179], v[200:203], v[82:85]
	v_mfma_f32_16x16x32_bf16 v[70:73], v[158:161], v[208:211], v[70:73]
	v_mfma_f32_16x16x32_bf16 v[66:69], v[176:179], v[208:211], v[66:69]
	v_mfma_f32_16x16x32_bf16 v[118:121], v[172:175], v[188:191], v[118:121]
	v_mfma_f32_16x16x32_bf16 v[114:117], v[180:183], v[188:191], v[114:117]
	v_mfma_f32_16x16x32_bf16 v[102:105], v[172:175], v[196:199], v[102:105]
	v_mfma_f32_16x16x32_bf16 v[98:101], v[180:183], v[196:199], v[98:101]
	v_mfma_f32_16x16x32_bf16 v[86:89], v[172:175], v[204:207], v[86:89]
	v_mfma_f32_16x16x32_bf16 v[82:85], v[180:183], v[204:207], v[82:85]
	v_mfma_f32_16x16x32_bf16 v[70:73], v[172:175], v[212:215], v[70:73]
	v_mfma_f32_16x16x32_bf16 v[66:69], v[180:183], v[212:215], v[66:69]
	s_barrier
; #define PG8_STAGE(bufoff, gbase, voff) do { _Pragma("unroll") for (int _i = 0; _i < 2; ++_i) \
;         __builtin_amdgcn_global_load_lds((const unsigned*)((const char*)(gbase) + (voff)[_i]), (LAS unsigned*)(lds + (bufoff) + ldsw + _i * 8192), 16, 0, 0); } while (0)
; #define PG8_LDA(dst, b, h) do { _Pragma("unroll") for (int m = 0; m < 4; ++m) _Pragma("unroll") for (int k = 0; k < 2; ++k) dst[m][k] = *(const LAS bf16x8*)(lds + PG8_SA(b, h) + aoff + m * 2048 + k * 1024); } while (0)
; #define PG8_MMA(ai, bj, At, Bt) do { __builtin_amdgcn_s_setprio(1); _Pragma("unroll") for (int m = 0; m < 4; ++m) _Pragma("unroll") for (int n = 0; n < 2; ++n) _Pragma("unroll") for (int k = 0; k < 2; ++k) \
;         acc[ai][bj][m][n] = __builtin_amdgcn_mfma_f32_16x16x32_bf16(Bt[n][k], At[m][k], acc[ai][bj][m][n], 0, 0, 0); __builtin_amdgcn_s_setprio(0); } while (0)
; #define PG8_WAIT_V(n) asm volatile("s_waitcnt vmcnt(" #n ")" ::: "memory")
; #define PG8_WAIT_L(n) asm volatile("s_waitcnt lgkmcnt(" #n ")" ::: "memory")
; #define PG8_BAR __builtin_amdgcn_s_barrier()
; #define PG8_SCHED __builtin_amdgcn_sched_barrier(0)
; template <class Epi>
; __device__ __forceinline__ void gemm_phase(LAS unsigned char* lds, const Gemm g, int G, int c, const Epi& E) {
;     ...
;             PG8_LDA(At, 1, 1); PG8_STAGE(PG8_SB(1, 0), b3, voffB); PG8_STAGE(PG8_SB(1, 1), b3 + hstepB, voffB); PG8_STAGE(PG8_SA(1, 0), a3, voffA);
;             PG8_WAIT_V(8); PG8_WAIT_L(0); PG8_BAR; PG8_MMA(1, 0, At, B0); PG8_MMA(1, 1, At, B1); PG8_BAR; PG8_SCHED;
;         }
;         if (wr == 0) PG8_BAR;
	s_mov_b32 m0, s96
	v_lshl_add_u64 v[162:163], v[162:163], 0, s[22:23]
	ds_read_b128 v[184:187], v168 offset:49152
	ds_read_b128 v[188:191], v168 offset:50176
	ds_read_b128 v[192:195], v168 offset:51200
	ds_read_b128 v[196:199], v168 offset:52224
	ds_read_b128 v[200:203], v168 offset:53248
	ds_read_b128 v[204:207], v168 offset:54272
	ds_read_b128 v[208:211], v168 offset:55296
	ds_read_b128 v[212:215], v168 offset:56320
	global_load_lds_dwordx4 v[162:163], off
	v_lshl_add_u64 v[162:163], v[216:217], 0, s[22:23]
	s_mov_b32 m0, s94
	s_nop 0
	global_load_lds_dwordx4 v[162:163], off
	v_lshl_add_u64 v[162:163], s[10:11], 0, v[140:141]
	s_mov_b32 m0, s95
	s_nop 0
	global_load_lds_dwordx4 v[162:163], off
	v_lshl_add_u64 v[162:163], s[10:11], 0, v[144:145]
	s_mov_b32 m0, s93
	s_nop 0
	global_load_lds_dwordx4 v[162:163], off
	v_lshl_add_u64 v[162:163], v[218:219], 0, s[22:23]
	s_mov_b32 m0, s85
	s_nop 0
	global_load_lds_dwordx4 v[162:163], off
	v_lshl_add_u64 v[162:163], v[220:221], 0, s[22:23]
	s_mov_b32 m0, s86
	s_nop 0
	global_load_lds_dwordx4 v[162:163], off
	s_waitcnt vmcnt(8)
	s_waitcnt lgkmcnt(0)
	s_barrier
	s_waitcnt lgkmcnt(0)
	v_mfma_f32_16x16x32_bf16 v[62:65], v[130:133], v[184:187], v[62:65]
	v_mfma_f32_16x16x32_bf16 v[58:61], v[150:153], v[184:187], v[58:61]
	v_mfma_f32_16x16x32_bf16 v[46:49], v[130:133], v[192:195], v[46:49]
	v_mfma_f32_16x16x32_bf16 v[42:45], v[150:153], v[192:195], v[42:45]
	v_mfma_f32_16x16x32_bf16 v[30:33], v[130:133], v[200:203], v[30:33]
	v_mfma_f32_16x16x32_bf16 v[26:29], v[150:153], v[200:203], v[26:29]
	v_mfma_f32_16x16x32_bf16 v[14:17], v[130:133], v[208:211], v[14:17]
	v_mfma_f32_16x16x32_bf16 v[10:13], v[150:153], v[208:211], v[10:13]
	v_mfma_f32_16x16x32_bf16 v[62:65], v[134:137], v[188:191], v[62:65]
	v_mfma_f32_16x16x32_bf16 v[58:61], v[154:157], v[188:191], v[58:61]
	v_mfma_f32_16x16x32_bf16 v[46:49], v[134:137], v[196:199], v[46:49]
	v_mfma_f32_16x16x32_bf16 v[42:45], v[154:157], v[196:199], v[42:45]
	v_mfma_f32_16x16x32_bf16 v[30:33], v[134:137], v[204:207], v[30:33]
	v_mfma_f32_16x16x32_bf16 v[26:29], v[154:157], v[204:207], v[26:29]
	v_mfma_f32_16x16x32_bf16 v[14:17], v[134:137], v[212:215], v[14:17]
	v_mfma_f32_16x16x32_bf16 v[10:13], v[154:157], v[212:215], v[10:13]
	v_mfma_f32_16x16x32_bf16 v[54:57], v[158:161], v[184:187], v[54:57]
	v_mfma_f32_16x16x32_bf16 v[50:53], v[176:179], v[184:187], v[50:53]
	v_mfma_f32_16x16x32_bf16 v[38:41], v[158:161], v[192:195], v[38:41]
	v_mfma_f32_16x16x32_bf16 v[34:37], v[176:179], v[192:195], v[34:37]
	v_mfma_f32_16x16x32_bf16 v[22:25], v[158:161], v[200:203], v[22:25]
	v_mfma_f32_16x16x32_bf16 v[18:21], v[176:179], v[200:203], v[18:21]
	v_mfma_f32_16x16x32_bf16 v[6:9], v[158:161], v[208:211], v[6:9]
	v_mfma_f32_16x16x32_bf16 v[2:5], v[176:179], v[208:211], v[2:5]
	v_mfma_f32_16x16x32_bf16 v[54:57], v[172:175], v[188:191], v[54:57]
	v_mfma_f32_16x16x32_bf16 v[50:53], v[180:183], v[188:191], v[50:53]
	v_mfma_f32_16x16x32_bf16 v[38:41], v[172:175], v[196:199], v[38:41]
	v_mfma_f32_16x16x32_bf16 v[34:37], v[180:183], v[196:199], v[34:37]
	v_mfma_f32_16x16x32_bf16 v[22:25], v[172:175], v[204:207], v[22:25]
	v_mfma_f32_16x16x32_bf16 v[18:21], v[180:183], v[204:207], v[18:21]
	v_mfma_f32_16x16x32_bf16 v[6:9], v[172:175], v[212:215], v[6:9]
	v_mfma_f32_16x16x32_bf16 v[2:5], v[180:183], v[212:215], v[2:5]
	s_barrier
	s_movk_i32 s44, 0x100
	s_andn2_b64 vcc, exec, s[4:5]
	s_mov_b64 s[10:11], -1
	s_mov_b64 s[4:5], 0
	s_cbranch_vccz .LBB0_1537
	s_and_b64 vcc, exec, s[24:25]
	s_cbranch_vccz .LBB0_1540
	s_barrier

; #define PG8_STAGE(bufoff, gbase, voff) do { _Pragma("unroll") for (int _i = 0; _i < 2; ++_i) \
;         __builtin_amdgcn_global_load_lds((const unsigned*)((const char*)(gbase) + (voff)[_i]), (LAS unsigned*)(lds + (bufoff) + ldsw + _i * 8192), 16, 0, 0); } while (0)
; #define PG8_LDA(dst, b, h) do { _Pragma("unroll") for (int m = 0; m < 4; ++m) _Pragma("unroll") for (int k = 0; k < 2; ++k) dst[m][k] = *(const LAS bf16x8*)(lds + PG8_SA(b, h) + aoff + m * 2048 + k * 1024); } while (0)
; #define PG8_LDB(dst, b, h) do { _Pragma("unroll") for (int n = 0; n < 2; ++n) _Pragma("unroll") for (int k = 0; k < 2; ++k) dst[n][k] = *(const LAS bf16x8*)(lds + PG8_SB(b, h) + boff + n * 2048 + k * 1024); } while (0)
; #define PG8_MMA(ai, bj, At, Bt) do { __builtin_amdgcn_s_setprio(1); _Pragma("unroll") for (int m = 0; m < 4; ++m) _Pragma("unroll") for (int n = 0; n < 2; ++n) _Pragma("unroll") for (int k = 0; k < 2; ++k) \
;         acc[ai][bj][m][n] = __builtin_amdgcn_mfma_f32_16x16x32_bf16(Bt[n][k], At[m][k], acc[ai][bj][m][n], 0, 0, 0); __builtin_amdgcn_s_setprio(0); } while (0)
; #define PG8_WAIT_V(n) asm volatile("s_waitcnt vmcnt(" #n ")" ::: "memory")
; #define PG8_WAIT_L(n) asm volatile("s_waitcnt lgkmcnt(" #n ")" ::: "memory")
; #define PG8_BAR __builtin_amdgcn_s_barrier()
; #define PG8_SCHED __builtin_amdgcn_sched_barrier(0)
; template <class Epi>
; __device__ __forceinline__ void gemm_phase(LAS unsigned char* lds, const Gemm g, int G, int c, const Epi& E) {
;     ...
;             const bool last = (t == nt - 2);
;             const char* a1 = cA + (size_t)(t + 1) * kstep;
;             const char* a2 = last ? nA : cA + (size_t)(t + 2) * kstep; const char* b2 = last ? nB : cB + (size_t)(t + 2) * kstep;
;             const char* a3 = a2 + kstep; const char* b3 = b2 + kstep;
;             PG8_LDB(B0, 0, 0); PG8_LDB(B1, 0, 1); PG8_SCHED; PG8_LDA(At, 0, 0); PG8_STAGE(PG8_SA(1, 1), a1 + hstepA, voffA);
;             PG8_WAIT_V(8); PG8_WAIT_L(0); PG8_BAR; PG8_MMA(0, 0, At, B0); PG8_MMA(0, 1, At, B1); PG8_BAR; PG8_SCHED;
;             PG8_LDA(At, 0, 1); PG8_STAGE(PG8_SB(0, 0), b2, voffB); PG8_STAGE(PG8_SB(0, 1), b2 + hstepB, voffB); PG8_STAGE(PG8_SA(0, 0), a2, voffA);
.LBB0_1653:
	s_add_u32 s33, s8, s48
	s_addc_u32 s49, s9, 0
	s_add_u32 s54, s33, 0x100
	s_addc_u32 s55, s49, 0
	s_and_b64 s[52:53], s[46:47], exec
	s_cselect_b32 s53, s41, s55
	s_cselect_b32 s52, s40, s54
	s_add_u32 s48, s6, s48
	s_addc_u32 s54, s7, 0
	s_add_u32 s48, s48, 0x100
	s_addc_u32 s54, s54, 0
	s_and_b64 s[46:47], s[46:47], exec
	s_cselect_b32 s55, s43, s54
	s_cselect_b32 s54, s42, s48
	s_add_u32 s58, s33, 0xb0080
	ds_read_b128 v[142:145], v166
	ds_read_b128 v[146:149], v166 offset:1024
	ds_read_b128 v[150:153], v166 offset:2048
	ds_read_b128 v[154:157], v166 offset:3072
	ds_read_b128 v[158:161], v167
	ds_read_b128 v[170:173], v167 offset:1024
	ds_read_b128 v[174:177], v167 offset:2048
	ds_read_b128 v[178:181], v167 offset:3072
	s_addc_u32 s59, s49, 0
	s_add_i32 s63, s80, s23
	s_add_i32 m0, s68, 0xc000
	s_add_i32 s64, s68, 0xe000
	s_add_i32 s74, s63, 0x2000
	s_add_u32 s56, s54, 0xb0000
	s_addc_u32 s57, s55, 0
	s_add_i32 s62, s81, s23
	s_add_i32 s75, s62, 0x2000
	s_add_i32 s93, 0, 0x18000
	s_add_i32 s33, 0, 0x1c000
	s_add_u32 s48, s52, 0xb0000
	s_addc_u32 s49, s53, 0
	s_add_i32 s92, s93, s23
	s_add_i32 s90, s92, 0x2000
	s_add_u32 s46, s54, 0xb0080
	s_addc_u32 s47, s55, 0
	s_add_i32 s91, s33, s23
	s_add_i32 s89, s91, 0x2000
	v_lshl_add_u64 v[162:163], s[58:59], 0, v[136:137]
	ds_read_b128 v[182:185], v168
	ds_read_b128 v[186:189], v168 offset:1024
	ds_read_b128 v[190:193], v168 offset:2048
	ds_read_b128 v[194:197], v168 offset:3072
	ds_read_b128 v[198:201], v168 offset:4096
	ds_read_b128 v[202:205], v168 offset:5120
	ds_read_b128 v[206:209], v168 offset:6144
	ds_read_b128 v[210:213], v168 offset:7168
	global_load_lds_dwordx4 v[162:163], off
	v_lshl_add_u64 v[162:163], s[58:59], 0, v[132:133]
	s_mov_b32 m0, s64
	s_nop 0
	global_load_lds_dwordx4 v[162:163], off
	s_waitcnt vmcnt(8)
	s_waitcnt lgkmcnt(0)
	s_barrier
	s_waitcnt lgkmcnt(0)
	v_mfma_f32_16x16x32_bf16 v[126:129], v[142:145], v[182:185], v[126:129]
	v_mfma_f32_16x16x32_bf16 v[122:125], v[150:153], v[182:185], v[122:125]
	v_mfma_f32_16x16x32_bf16 v[110:113], v[142:145], v[190:193], v[110:113]
	v_mfma_f32_16x16x32_bf16 v[106:109], v[150:153], v[190:193], v[106:109]
	v_mfma_f32_16x16x32_bf16 v[94:97], v[142:145], v[198:201], v[94:97]
	v_mfma_f32_16x16x32_bf16 v[90:93], v[150:153], v[198:201], v[90:93]
	v_mfma_f32_16x16x32_bf16 v[78:81], v[142:145], v[206:209], v[78:81]
	v_mfma_f32_16x16x32_bf16 v[74:77], v[150:153], v[206:209], v[74:77]
	v_mfma_f32_16x16x32_bf16 v[126:129], v[146:149], v[186:189], v[126:129]
	v_mfma_f32_16x16x32_bf16 v[122:125], v[154:157], v[186:189], v[122:125]
	v_mfma_f32_16x16x32_bf16 v[110:113], v[146:149], v[194:197], v[110:113]
	v_mfma_f32_16x16x32_bf16 v[106:109], v[154:157], v[194:197], v[106:109]
	v_mfma_f32_16x16x32_bf16 v[94:97], v[146:149], v[202:205], v[94:97]
	v_mfma_f32_16x16x32_bf16 v[90:93], v[154:157], v[202:205], v[90:93]
	v_mfma_f32_16x16x32_bf16 v[78:81], v[146:149], v[210:213], v[78:81]
	v_mfma_f32_16x16x32_bf16 v[74:77], v[154:157], v[210:213], v[74:77]
	v_mfma_f32_16x16x32_bf16 v[118:121], v[158:161], v[182:185], v[118:121]
	v_mfma_f32_16x16x32_bf16 v[114:117], v[174:177], v[182:185], v[114:117]
	v_mfma_f32_16x16x32_bf16 v[102:105], v[158:161], v[190:193], v[102:105]
	v_mfma_f32_16x16x32_bf16 v[98:101], v[174:177], v[190:193], v[98:101]
	v_mfma_f32_16x16x32_bf16 v[86:89], v[158:161], v[198:201], v[86:89]
	v_mfma_f32_16x16x32_bf16 v[82:85], v[174:177], v[198:201], v[82:85]
	v_mfma_f32_16x16x32_bf16 v[70:73], v[158:161], v[206:209], v[70:73]
	v_mfma_f32_16x16x32_bf16 v[66:69], v[174:177], v[206:209], v[66:69]
	v_mfma_f32_16x16x32_bf16 v[118:121], v[170:173], v[186:189], v[118:121]
	v_mfma_f32_16x16x32_bf16 v[114:117], v[178:181], v[186:189], v[114:117]
	v_mfma_f32_16x16x32_bf16 v[102:105], v[170:173], v[194:197], v[102:105]
	v_mfma_f32_16x16x32_bf16 v[98:101], v[178:181], v[194:197], v[98:101]
	v_mfma_f32_16x16x32_bf16 v[86:89], v[170:173], v[202:205], v[86:89]
	v_mfma_f32_16x16x32_bf16 v[82:85], v[178:181], v[202:205], v[82:85]
	v_mfma_f32_16x16x32_bf16 v[70:73], v[170:173], v[210:213], v[70:73]
	v_mfma_f32_16x16x32_bf16 v[66:69], v[178:181], v[210:213], v[66:69]
	s_barrier
	s_mov_b32 m0, s63
	v_lshl_add_u64 v[162:163], s[54:55], 0, v[134:135]
	ds_read_b128 v[182:185], v168 offset:16384
	ds_read_b128 v[186:189], v168 offset:17408
	ds_read_b128 v[190:193], v168 offset:18432
	ds_read_b128 v[194:197], v168 offset:19456
	ds_read_b128 v[198:201], v168 offset:20480
	ds_read_b128 v[202:205], v168 offset:21504
	ds_read_b128 v[206:209], v168 offset:22528
	ds_read_b128 v[210:213], v168 offset:23552
	global_load_lds_dwordx4 v[162:163], off
	v_lshl_add_u64 v[214:215], s[54:55], 0, v[130:131]
	s_mov_b32 m0, s74
	v_lshl_add_u64 v[216:217], s[56:57], 0, v[134:135]
	global_load_lds_dwordx4 v[214:215], off
	s_mov_b32 m0, s62
	v_lshl_add_u64 v[218:219], s[52:53], 0, v[132:133]
	global_load_lds_dwordx4 v[216:217], off
	v_lshl_add_u64 v[216:217], s[56:57], 0, v[130:131]
	s_mov_b32 m0, s75
	s_nop 0
	global_load_lds_dwordx4 v[216:217], off
	v_lshl_add_u64 v[216:217], s[52:53], 0, v[136:137]
	s_mov_b32 m0, s68
	s_nop 0
	global_load_lds_dwordx4 v[216:217], off
	s_mov_b32 m0, s69
	s_nop 0
	global_load_lds_dwordx4 v[218:219], off
	s_waitcnt vmcnt(8)
	s_waitcnt lgkmcnt(0)
	s_barrier
; #define PG8_STAGE(bufoff, gbase, voff) do { _Pragma("unroll") for (int _i = 0; _i < 2; ++_i) \
;         __builtin_amdgcn_global_load_lds((const unsigned*)((const char*)(gbase) + (voff)[_i]), (LAS unsigned*)(lds + (bufoff) + ldsw + _i * 8192), 16, 0, 0); } while (0)
; #define PG8_LDA(dst, b, h) do { _Pragma("unroll") for (int m = 0; m < 4; ++m) _Pragma("unroll") for (int k = 0; k < 2; ++k) dst[m][k] = *(const LAS bf16x8*)(lds + PG8_SA(b, h) + aoff + m * 2048 + k * 1024); } while (0)
; #define PG8_LDB(dst, b, h) do { _Pragma("unroll") for (int n = 0; n < 2; ++n) _Pragma("unroll") for (int k = 0; k < 2; ++k) dst[n][k] = *(const LAS bf16x8*)(lds + PG8_SB(b, h) + boff + n * 2048 + k * 1024); } while (0)
; #define PG8_MMA(ai, bj, At, Bt) do { __builtin_amdgcn_s_setprio(1); _Pragma("unroll") for (int m = 0; m < 4; ++m) _Pragma("unroll") for (int n = 0; n < 2; ++n) _Pragma("unroll") for (int k = 0; k < 2; ++k) \
;         acc[ai][bj][m][n] = __builtin_amdgcn_mfma_f32_16x16x32_bf16(Bt[n][k], At[m][k], acc[ai][bj][m][n], 0, 0, 0); __builtin_amdgcn_s_setprio(0); } while (0)
; #define PG8_WAIT_V(n) asm volatile("s_waitcnt vmcnt(" #n ")" ::: "memory")
; #define PG8_WAIT_L(n) asm volatile("s_waitcnt lgkmcnt(" #n ")" ::: "memory")
; #define PG8_BAR __builtin_amdgcn_s_barrier()
; #define PG8_SCHED __builtin_amdgcn_sched_barrier(0)
; template <class Epi>
; __device__ __forceinline__ void gemm_phase(LAS unsigned char* lds, const Gemm g, int G, int c, const Epi& E) {
;     ...
;             PG8_WAIT_V(8); PG8_WAIT_L(0); PG8_BAR; PG8_MMA(1, 0, At, B0); PG8_MMA(1, 1, At, B1); PG8_BAR; PG8_SCHED;
;             PG8_LDB(B0, 1, 0); PG8_LDB(B1, 1, 1); PG8_SCHED; PG8_LDA(At, 1, 0); PG8_STAGE(PG8_SA(0, 1), a2 + hstepA, voffA);
;             PG8_WAIT_V(8); PG8_WAIT_L(0); PG8_BAR; PG8_MMA(0, 0, At, B0); PG8_MMA(0, 1, At, B1); PG8_BAR; PG8_SCHED;
	s_waitcnt lgkmcnt(0)
	v_mfma_f32_16x16x32_bf16 v[62:65], v[142:145], v[182:185], v[62:65]
	v_mfma_f32_16x16x32_bf16 v[58:61], v[150:153], v[182:185], v[58:61]
	v_mfma_f32_16x16x32_bf16 v[46:49], v[142:145], v[190:193], v[46:49]
	v_mfma_f32_16x16x32_bf16 v[42:45], v[150:153], v[190:193], v[42:45]
	v_mfma_f32_16x16x32_bf16 v[30:33], v[142:145], v[198:201], v[30:33]
	v_mfma_f32_16x16x32_bf16 v[26:29], v[150:153], v[198:201], v[26:29]
	v_mfma_f32_16x16x32_bf16 v[14:17], v[142:145], v[206:209], v[14:17]
	v_mfma_f32_16x16x32_bf16 v[10:13], v[150:153], v[206:209], v[10:13]
	v_mfma_f32_16x16x32_bf16 v[62:65], v[146:149], v[186:189], v[62:65]
	v_mfma_f32_16x16x32_bf16 v[58:61], v[154:157], v[186:189], v[58:61]
	v_mfma_f32_16x16x32_bf16 v[46:49], v[146:149], v[194:197], v[46:49]
	v_mfma_f32_16x16x32_bf16 v[42:45], v[154:157], v[194:197], v[42:45]
	v_mfma_f32_16x16x32_bf16 v[30:33], v[146:149], v[202:205], v[30:33]
	v_mfma_f32_16x16x32_bf16 v[26:29], v[154:157], v[202:205], v[26:29]
	v_mfma_f32_16x16x32_bf16 v[14:17], v[146:149], v[210:213], v[14:17]
	v_mfma_f32_16x16x32_bf16 v[10:13], v[154:157], v[210:213], v[10:13]
	v_mfma_f32_16x16x32_bf16 v[54:57], v[158:161], v[182:185], v[54:57]
	v_mfma_f32_16x16x32_bf16 v[50:53], v[174:177], v[182:185], v[50:53]
	v_mfma_f32_16x16x32_bf16 v[38:41], v[158:161], v[190:193], v[38:41]
	v_mfma_f32_16x16x32_bf16 v[34:37], v[174:177], v[190:193], v[34:37]
	v_mfma_f32_16x16x32_bf16 v[22:25], v[158:161], v[198:201], v[22:25]
	v_mfma_f32_16x16x32_bf16 v[18:21], v[174:177], v[198:201], v[18:21]
	v_mfma_f32_16x16x32_bf16 v[6:9], v[158:161], v[206:209], v[6:9]
	v_mfma_f32_16x16x32_bf16 v[2:5], v[174:177], v[206:209], v[2:5]
	v_mfma_f32_16x16x32_bf16 v[54:57], v[170:173], v[186:189], v[54:57]
	v_mfma_f32_16x16x32_bf16 v[50:53], v[178:181], v[186:189], v[50:53]
	v_mfma_f32_16x16x32_bf16 v[38:41], v[170:173], v[194:197], v[38:41]
	v_mfma_f32_16x16x32_bf16 v[34:37], v[178:181], v[194:197], v[34:37]
	v_mfma_f32_16x16x32_bf16 v[22:25], v[170:173], v[202:205], v[22:25]
	v_mfma_f32_16x16x32_bf16 v[18:21], v[178:181], v[202:205], v[18:21]
	v_mfma_f32_16x16x32_bf16 v[6:9], v[170:173], v[210:213], v[6:9]
	v_mfma_f32_16x16x32_bf16 v[2:5], v[178:181], v[210:213], v[2:5]
	s_barrier
	v_add_u32_e32 v154, s93, v165
	v_add_u32_e32 v178, s33, v165
	ds_read_b128 v[142:145], v154
	ds_read_b128 v[146:149], v154 offset:1024
	ds_read_b128 v[150:153], v154 offset:2048
	ds_read_b128 v[154:157], v154 offset:3072
	ds_read_b128 v[158:161], v178
	ds_read_b128 v[170:173], v178 offset:1024
	ds_read_b128 v[174:177], v178 offset:2048
	ds_read_b128 v[178:181], v178 offset:3072
	s_mov_b32 m0, s70
	v_lshl_add_u64 v[220:221], s[48:49], 0, v[136:137]
	ds_read_b128 v[182:185], v168 offset:32768
	ds_read_b128 v[186:189], v168 offset:33792
	ds_read_b128 v[190:193], v168 offset:34816
	ds_read_b128 v[194:197], v168 offset:35840
	ds_read_b128 v[198:201], v168 offset:36864
	ds_read_b128 v[202:205], v168 offset:37888
	ds_read_b128 v[206:209], v168 offset:38912
	ds_read_b128 v[210:213], v168 offset:39936
	global_load_lds_dwordx4 v[220:221], off
	v_lshl_add_u64 v[220:221], s[48:49], 0, v[132:133]
	s_mov_b32 m0, s71
	s_nop 0
	global_load_lds_dwordx4 v[220:221], off
	s_waitcnt vmcnt(8)
	s_waitcnt lgkmcnt(0)
	s_barrier
	s_waitcnt lgkmcnt(0)
	v_mfma_f32_16x16x32_bf16 v[126:129], v[142:145], v[182:185], v[126:129]
	v_mfma_f32_16x16x32_bf16 v[122:125], v[150:153], v[182:185], v[122:125]
	v_mfma_f32_16x16x32_bf16 v[110:113], v[142:145], v[190:193], v[110:113]
	v_mfma_f32_16x16x32_bf16 v[106:109], v[150:153], v[190:193], v[106:109]
	v_mfma_f32_16x16x32_bf16 v[94:97], v[142:145], v[198:201], v[94:97]
	v_mfma_f32_16x16x32_bf16 v[90:93], v[150:153], v[198:201], v[90:93]
	v_mfma_f32_16x16x32_bf16 v[78:81], v[142:145], v[206:209], v[78:81]
	v_mfma_f32_16x16x32_bf16 v[74:77], v[150:153], v[206:209], v[74:77]
	v_mfma_f32_16x16x32_bf16 v[126:129], v[146:149], v[186:189], v[126:129]
	v_mfma_f32_16x16x32_bf16 v[122:125], v[154:157], v[186:189], v[122:125]
	v_mfma_f32_16x16x32_bf16 v[110:113], v[146:149], v[194:197], v[110:113]
	v_mfma_f32_16x16x32_bf16 v[106:109], v[154:157], v[194:197], v[106:109]
	v_mfma_f32_16x16x32_bf16 v[94:97], v[146:149], v[202:205], v[94:97]
	v_mfma_f32_16x16x32_bf16 v[90:93], v[154:157], v[202:205], v[90:93]
	v_mfma_f32_16x16x32_bf16 v[78:81], v[146:149], v[210:213], v[78:81]
	v_mfma_f32_16x16x32_bf16 v[74:77], v[154:157], v[210:213], v[74:77]
	v_mfma_f32_16x16x32_bf16 v[118:121], v[158:161], v[182:185], v[118:121]
	v_mfma_f32_16x16x32_bf16 v[114:117], v[174:177], v[182:185], v[114:117]
	v_mfma_f32_16x16x32_bf16 v[102:105], v[158:161], v[190:193], v[102:105]
	v_mfma_f32_16x16x32_bf16 v[98:101], v[174:177], v[190:193], v[98:101]
	v_mfma_f32_16x16x32_bf16 v[86:89], v[158:161], v[198:201], v[86:89]
	v_mfma_f32_16x16x32_bf16 v[82:85], v[174:177], v[198:201], v[82:85]
	v_mfma_f32_16x16x32_bf16 v[70:73], v[158:161], v[206:209], v[70:73]
	v_mfma_f32_16x16x32_bf16 v[66:69], v[174:177], v[206:209], v[66:69]
	v_mfma_f32_16x16x32_bf16 v[118:121], v[170:173], v[186:189], v[118:121]
	v_mfma_f32_16x16x32_bf16 v[114:117], v[178:181], v[186:189], v[114:117]
	v_mfma_f32_16x16x32_bf16 v[102:105], v[170:173], v[194:197], v[102:105]
	v_mfma_f32_16x16x32_bf16 v[98:101], v[178:181], v[194:197], v[98:101]
	v_mfma_f32_16x16x32_bf16 v[86:89], v[170:173], v[202:205], v[86:89]
	v_mfma_f32_16x16x32_bf16 v[82:85], v[178:181], v[202:205], v[82:85]
	v_mfma_f32_16x16x32_bf16 v[70:73], v[170:173], v[210:213], v[70:73]
	v_mfma_f32_16x16x32_bf16 v[66:69], v[178:181], v[210:213], v[66:69]
	s_barrier
; #define PG8_STAGE(bufoff, gbase, voff) do { _Pragma("unroll") for (int _i = 0; _i < 2; ++_i) \
;         __builtin_amdgcn_global_load_lds((const unsigned*)((const char*)(gbase) + (voff)[_i]), (LAS unsigned*)(lds + (bufoff) + ldsw + _i * 8192), 16, 0, 0); } while (0)
; #define PG8_LDA(dst, b, h) do { _Pragma("unroll") for (int m = 0; m < 4; ++m) _Pragma("unroll") for (int k = 0; k < 2; ++k) dst[m][k] = *(const LAS bf16x8*)(lds + PG8_SA(b, h) + aoff + m * 2048 + k * 1024); } while (0)
; #define PG8_MMA(ai, bj, At, Bt) do { __builtin_amdgcn_s_setprio(1); _Pragma("unroll") for (int m = 0; m < 4; ++m) _Pragma("unroll") for (int n = 0; n < 2; ++n) _Pragma("unroll") for (int k = 0; k < 2; ++k) \
;         acc[ai][bj][m][n] = __builtin_amdgcn_mfma_f32_16x16x32_bf16(Bt[n][k], At[m][k], acc[ai][bj][m][n], 0, 0, 0); __builtin_amdgcn_s_setprio(0); } while (0)
; #define PG8_WAIT_V(n) asm volatile("s_waitcnt vmcnt(" #n ")" ::: "memory")
; #define PG8_WAIT_L(n) asm volatile("s_waitcnt lgkmcnt(" #n ")" ::: "memory")
; #define PG8_BAR __builtin_amdgcn_s_barrier()
; #define PG8_SCHED __builtin_amdgcn_sched_barrier(0)
; template <class Epi>
; __device__ __forceinline__ void gemm_phase(LAS unsigned char* lds, const Gemm g, int G, int c, const Epi& E) {
;     ...
;             PG8_LDA(At, 1, 1); PG8_STAGE(PG8_SB(1, 0), b3, voffB); PG8_STAGE(PG8_SB(1, 1), b3 + hstepB, voffB); PG8_STAGE(PG8_SA(1, 0), a3, voffA);
;             PG8_WAIT_V(8); PG8_WAIT_L(0); PG8_BAR; PG8_MMA(1, 0, At, B0); PG8_MMA(1, 1, At, B1); PG8_BAR; PG8_SCHED;
;         }
;         if (wr == 0) PG8_BAR;
	s_mov_b32 m0, s92
	v_lshl_add_u64 v[162:163], v[162:163], 0, s[18:19]
	ds_read_b128 v[182:185], v168 offset:49152
	ds_read_b128 v[186:189], v168 offset:50176
	ds_read_b128 v[190:193], v168 offset:51200
	ds_read_b128 v[194:197], v168 offset:52224
	ds_read_b128 v[198:201], v168 offset:53248
	ds_read_b128 v[202:205], v168 offset:54272
	ds_read_b128 v[206:209], v168 offset:55296
	ds_read_b128 v[210:213], v168 offset:56320
	global_load_lds_dwordx4 v[162:163], off
	v_lshl_add_u64 v[162:163], v[214:215], 0, s[18:19]
	s_mov_b32 m0, s90
	s_nop 0
	global_load_lds_dwordx4 v[162:163], off
	v_lshl_add_u64 v[162:163], s[46:47], 0, v[134:135]
	s_mov_b32 m0, s91
	s_nop 0
	global_load_lds_dwordx4 v[162:163], off
	v_lshl_add_u64 v[162:163], s[46:47], 0, v[130:131]
	s_mov_b32 m0, s89
	s_nop 0
	global_load_lds_dwordx4 v[162:163], off
	v_lshl_add_u64 v[162:163], v[216:217], 0, s[18:19]
	s_mov_b32 m0, s78
	s_nop 0
	global_load_lds_dwordx4 v[162:163], off
	v_lshl_add_u64 v[162:163], v[218:219], 0, s[18:19]
	s_mov_b32 m0, s79
	s_nop 0
	global_load_lds_dwordx4 v[162:163], off
	s_waitcnt vmcnt(8)
	s_waitcnt lgkmcnt(0)
	s_barrier
	s_waitcnt lgkmcnt(0)
	v_mfma_f32_16x16x32_bf16 v[62:65], v[142:145], v[182:185], v[62:65]
	v_mfma_f32_16x16x32_bf16 v[58:61], v[150:153], v[182:185], v[58:61]
	v_mfma_f32_16x16x32_bf16 v[46:49], v[142:145], v[190:193], v[46:49]
	v_mfma_f32_16x16x32_bf16 v[42:45], v[150:153], v[190:193], v[42:45]
	v_mfma_f32_16x16x32_bf16 v[30:33], v[142:145], v[198:201], v[30:33]
	v_mfma_f32_16x16x32_bf16 v[26:29], v[150:153], v[198:201], v[26:29]
	v_mfma_f32_16x16x32_bf16 v[14:17], v[142:145], v[206:209], v[14:17]
	v_mfma_f32_16x16x32_bf16 v[10:13], v[150:153], v[206:209], v[10:13]
	v_mfma_f32_16x16x32_bf16 v[62:65], v[146:149], v[186:189], v[62:65]
	v_mfma_f32_16x16x32_bf16 v[58:61], v[154:157], v[186:189], v[58:61]
	v_mfma_f32_16x16x32_bf16 v[46:49], v[146:149], v[194:197], v[46:49]
	v_mfma_f32_16x16x32_bf16 v[42:45], v[154:157], v[194:197], v[42:45]
	v_mfma_f32_16x16x32_bf16 v[30:33], v[146:149], v[202:205], v[30:33]
	v_mfma_f32_16x16x32_bf16 v[26:29], v[154:157], v[202:205], v[26:29]
	v_mfma_f32_16x16x32_bf16 v[14:17], v[146:149], v[210:213], v[14:17]
	v_mfma_f32_16x16x32_bf16 v[10:13], v[154:157], v[210:213], v[10:13]
	v_mfma_f32_16x16x32_bf16 v[54:57], v[158:161], v[182:185], v[54:57]
	v_mfma_f32_16x16x32_bf16 v[50:53], v[174:177], v[182:185], v[50:53]
	v_mfma_f32_16x16x32_bf16 v[38:41], v[158:161], v[190:193], v[38:41]
	v_mfma_f32_16x16x32_bf16 v[34:37], v[174:177], v[190:193], v[34:37]
	v_mfma_f32_16x16x32_bf16 v[22:25], v[158:161], v[198:201], v[22:25]
	v_mfma_f32_16x16x32_bf16 v[18:21], v[174:177], v[198:201], v[18:21]
	v_mfma_f32_16x16x32_bf16 v[6:9], v[158:161], v[206:209], v[6:9]
	v_mfma_f32_16x16x32_bf16 v[2:5], v[174:177], v[206:209], v[2:5]
	v_mfma_f32_16x16x32_bf16 v[54:57], v[170:173], v[186:189], v[54:57]
	v_mfma_f32_16x16x32_bf16 v[50:53], v[178:181], v[186:189], v[50:53]
	v_mfma_f32_16x16x32_bf16 v[38:41], v[170:173], v[194:197], v[38:41]
	v_mfma_f32_16x16x32_bf16 v[34:37], v[178:181], v[194:197], v[34:37]
	v_mfma_f32_16x16x32_bf16 v[22:25], v[170:173], v[202:205], v[22:25]
	v_mfma_f32_16x16x32_bf16 v[18:21], v[178:181], v[202:205], v[18:21]
	v_mfma_f32_16x16x32_bf16 v[6:9], v[170:173], v[210:213], v[6:9]
	v_mfma_f32_16x16x32_bf16 v[2:5], v[178:181], v[210:213], v[2:5]
	s_barrier
	s_movk_i32 s48, 0x100
	s_andn2_b64 vcc, exec, s[4:5]
	s_mov_b64 s[46:47], -1
	s_mov_b64 s[4:5], 0
	s_cbranch_vccz .LBB0_1653
	s_and_b64 vcc, exec, s[20:21]
	s_cbranch_vccz .LBB0_1656
	s_barrier

; #define PG8_STAGE(bufoff, gbase, voff) do { _Pragma("unroll") for (int _i = 0; _i < 2; ++_i) \
;         __builtin_amdgcn_global_load_lds((const unsigned*)((const char*)(gbase) + (voff)[_i]), (LAS unsigned*)(lds + (bufoff) + ldsw + _i * 8192), 16, 0, 0); } while (0)
; #define PG8_LDA(dst, b, h) do { _Pragma("unroll") for (int m = 0; m < 4; ++m) _Pragma("unroll") for (int k = 0; k < 2; ++k) dst[m][k] = *(const LAS bf16x8*)(lds + PG8_SA(b, h) + aoff + m * 2048 + k * 1024); } while (0)
; #define PG8_LDB(dst, b, h) do { _Pragma("unroll") for (int n = 0; n < 2; ++n) _Pragma("unroll") for (int k = 0; k < 2; ++k) dst[n][k] = *(const LAS bf16x8*)(lds + PG8_SB(b, h) + boff + n * 2048 + k * 1024); } while (0)
; #define PG8_MMA(ai, bj, At, Bt) do { __builtin_amdgcn_s_setprio(1); _Pragma("unroll") for (int m = 0; m < 4; ++m) _Pragma("unroll") for (int n = 0; n < 2; ++n) _Pragma("unroll") for (int k = 0; k < 2; ++k) \
;         acc[ai][bj][m][n] = __builtin_amdgcn_mfma_f32_16x16x32_bf16(Bt[n][k], At[m][k], acc[ai][bj][m][n], 0, 0, 0); __builtin_amdgcn_s_setprio(0); } while (0)
; #define PG8_WAIT_V(n) asm volatile("s_waitcnt vmcnt(" #n ")" ::: "memory")
; #define PG8_WAIT_L(n) asm volatile("s_waitcnt lgkmcnt(" #n ")" ::: "memory")
; #define PG8_BAR __builtin_amdgcn_s_barrier()
; #define PG8_SCHED __builtin_amdgcn_sched_barrier(0)
; template <class Epi>
; __device__ __forceinline__ void gemm_phase(LAS unsigned char* lds, const Gemm g, int G, int c, const Epi& E) {
;     ...
;             const bool last = (t == nt - 2);
;             const char* a1 = cA + (size_t)(t + 1) * kstep;
;             const char* a2 = last ? nA : cA + (size_t)(t + 2) * kstep; const char* b2 = last ? nB : cB + (size_t)(t + 2) * kstep;
;             const char* a3 = a2 + kstep; const char* b3 = b2 + kstep;
;             PG8_LDB(B0, 0, 0); PG8_LDB(B1, 0, 1); PG8_SCHED; PG8_LDA(At, 0, 0); PG8_STAGE(PG8_SA(1, 1), a1 + hstepA, voffA);
;             PG8_WAIT_V(8); PG8_WAIT_L(0); PG8_BAR; PG8_MMA(0, 0, At, B0); PG8_MMA(0, 1, At, B1); PG8_BAR; PG8_SCHED;
;             PG8_LDA(At, 0, 1); PG8_STAGE(PG8_SB(0, 0), b2, voffB); PG8_STAGE(PG8_SB(0, 1), b2 + hstepB, voffB); PG8_STAGE(PG8_SA(0, 0), a2, voffA);
.LBB0_1825:
	ds_read_b128 v[146:149], v152
	ds_read_b128 v[156:159], v152 offset:1024
	ds_read_b128 v[160:163], v152 offset:2048
	ds_read_b128 v[164:167], v152 offset:3072
	ds_read_b128 v[168:171], v153
	ds_read_b128 v[172:175], v153 offset:1024
	ds_read_b128 v[176:179], v153 offset:2048
	ds_read_b128 v[180:183], v153 offset:3072
	s_add_u32 s33, s40, 0xfff00080
	s_addc_u32 s42, s41, -1
	s_cmp_eq_u32 s68, 60
	s_cselect_b32 s45, s15, s42
	s_cselect_b32 s44, s63, s33
	s_cselect_b32 s43, s11, s67
	s_cselect_b32 s42, s13, s66
	v_lshl_add_u64 v[216:217], s[40:41], 0, v[138:139]
	s_add_i32 m0, s17, 0xc000
	ds_read_b128 v[184:187], v154
	ds_read_b128 v[188:191], v154 offset:1024
	ds_read_b128 v[192:195], v154 offset:2048
	ds_read_b128 v[196:199], v154 offset:3072
	ds_read_b128 v[200:203], v154 offset:4096
	ds_read_b128 v[204:207], v154 offset:5120
	ds_read_b128 v[208:211], v154 offset:6144
	ds_read_b128 v[212:215], v154 offset:7168
	global_load_lds_dwordx4 v[216:217], off
	v_lshl_add_u64 v[216:217], s[40:41], 0, v[140:141]
	s_add_i32 m0, s17, 0xe000
	s_nop 0
	global_load_lds_dwordx4 v[216:217], off
	s_waitcnt vmcnt(8)
	s_waitcnt lgkmcnt(0)
	s_barrier
	s_waitcnt lgkmcnt(0)
	v_mfma_f32_16x16x32_bf16 v[126:129], v[146:149], v[184:187], v[126:129]
	v_mfma_f32_16x16x32_bf16 v[122:125], v[160:163], v[184:187], v[122:125]
	v_mfma_f32_16x16x32_bf16 v[118:121], v[146:149], v[192:195], v[118:121]
	v_mfma_f32_16x16x32_bf16 v[110:113], v[160:163], v[192:195], v[110:113]
	v_mfma_f32_16x16x32_bf16 v[102:105], v[146:149], v[200:203], v[102:105]
	v_mfma_f32_16x16x32_bf16 v[94:97], v[160:163], v[200:203], v[94:97]
	v_mfma_f32_16x16x32_bf16 v[86:89], v[146:149], v[208:211], v[86:89]
	v_mfma_f32_16x16x32_bf16 v[78:81], v[160:163], v[208:211], v[78:81]
	v_mfma_f32_16x16x32_bf16 v[126:129], v[156:159], v[188:191], v[126:129]
	v_mfma_f32_16x16x32_bf16 v[122:125], v[164:167], v[188:191], v[122:125]
	v_mfma_f32_16x16x32_bf16 v[118:121], v[156:159], v[196:199], v[118:121]
	v_mfma_f32_16x16x32_bf16 v[110:113], v[164:167], v[196:199], v[110:113]
	v_mfma_f32_16x16x32_bf16 v[102:105], v[156:159], v[204:207], v[102:105]
	v_mfma_f32_16x16x32_bf16 v[94:97], v[164:167], v[204:207], v[94:97]
	v_mfma_f32_16x16x32_bf16 v[86:89], v[156:159], v[212:215], v[86:89]
	v_mfma_f32_16x16x32_bf16 v[78:81], v[164:167], v[212:215], v[78:81]
	v_mfma_f32_16x16x32_bf16 v[114:117], v[168:171], v[184:187], v[114:117]
	v_mfma_f32_16x16x32_bf16 v[106:109], v[176:179], v[184:187], v[106:109]
	v_mfma_f32_16x16x32_bf16 v[98:101], v[168:171], v[192:195], v[98:101]
	v_mfma_f32_16x16x32_bf16 v[90:93], v[176:179], v[192:195], v[90:93]
	v_mfma_f32_16x16x32_bf16 v[82:85], v[168:171], v[200:203], v[82:85]
	v_mfma_f32_16x16x32_bf16 v[74:77], v[176:179], v[200:203], v[74:77]
	v_mfma_f32_16x16x32_bf16 v[70:73], v[168:171], v[208:211], v[70:73]
	v_mfma_f32_16x16x32_bf16 v[66:69], v[176:179], v[208:211], v[66:69]
	v_mfma_f32_16x16x32_bf16 v[114:117], v[172:175], v[188:191], v[114:117]
	v_mfma_f32_16x16x32_bf16 v[106:109], v[180:183], v[188:191], v[106:109]
	v_mfma_f32_16x16x32_bf16 v[98:101], v[172:175], v[196:199], v[98:101]
	v_mfma_f32_16x16x32_bf16 v[90:93], v[180:183], v[196:199], v[90:93]
	v_mfma_f32_16x16x32_bf16 v[82:85], v[172:175], v[204:207], v[82:85]
	v_mfma_f32_16x16x32_bf16 v[74:77], v[180:183], v[204:207], v[74:77]
	v_mfma_f32_16x16x32_bf16 v[70:73], v[172:175], v[212:215], v[70:73]
	v_mfma_f32_16x16x32_bf16 v[66:69], v[180:183], v[212:215], v[66:69]
	s_barrier
	s_add_i32 s33, s61, s52
	v_lshl_add_u64 v[216:217], s[42:43], 0, v[134:135]
	s_mov_b32 m0, s33
	ds_read_b128 v[184:187], v154 offset:16384
	ds_read_b128 v[188:191], v154 offset:17408
	ds_read_b128 v[192:195], v154 offset:18432
	ds_read_b128 v[196:199], v154 offset:19456
	ds_read_b128 v[200:203], v154 offset:20480
	ds_read_b128 v[204:207], v154 offset:21504
	ds_read_b128 v[208:211], v154 offset:22528
	ds_read_b128 v[212:215], v154 offset:23552
	global_load_lds_dwordx4 v[216:217], off
	s_add_i32 m0, s33, 0x2000
	s_add_u32 s64, s42, 0x100000
	v_lshl_add_u64 v[218:219], s[42:43], 0, v[130:131]
	s_addc_u32 s65, s43, 0
	s_add_i32 s33, s62, s52
	global_load_lds_dwordx4 v[218:219], off
	v_lshl_add_u64 v[220:221], s[64:65], 0, v[134:135]
	s_mov_b32 m0, s33
	v_lshl_add_u64 v[222:223], s[44:45], 0, v[132:133]
	global_load_lds_dwordx4 v[220:221], off
	v_lshl_add_u64 v[220:221], s[64:65], 0, v[130:131]
	s_add_i32 m0, s33, 0x2000
	s_nop 0
	global_load_lds_dwordx4 v[220:221], off
	v_lshl_add_u64 v[220:221], s[44:45], 0, v[136:137]
	s_mov_b32 m0, s17
	s_nop 0
	global_load_lds_dwordx4 v[220:221], off
	s_mov_b32 m0, s37
	s_nop 0
	global_load_lds_dwordx4 v[222:223], off
	s_waitcnt vmcnt(8)
	s_waitcnt lgkmcnt(0)
	s_barrier
; #define PG8_STAGE(bufoff, gbase, voff) do { _Pragma("unroll") for (int _i = 0; _i < 2; ++_i) \
;         __builtin_amdgcn_global_load_lds((const unsigned*)((const char*)(gbase) + (voff)[_i]), (LAS unsigned*)(lds + (bufoff) + ldsw + _i * 8192), 16, 0, 0); } while (0)
; #define PG8_LDA(dst, b, h) do { _Pragma("unroll") for (int m = 0; m < 4; ++m) _Pragma("unroll") for (int k = 0; k < 2; ++k) dst[m][k] = *(const LAS bf16x8*)(lds + PG8_SA(b, h) + aoff + m * 2048 + k * 1024); } while (0)
; #define PG8_LDB(dst, b, h) do { _Pragma("unroll") for (int n = 0; n < 2; ++n) _Pragma("unroll") for (int k = 0; k < 2; ++k) dst[n][k] = *(const LAS bf16x8*)(lds + PG8_SB(b, h) + boff + n * 2048 + k * 1024); } while (0)
; #define PG8_MMA(ai, bj, At, Bt) do { __builtin_amdgcn_s_setprio(1); _Pragma("unroll") for (int m = 0; m < 4; ++m) _Pragma("unroll") for (int n = 0; n < 2; ++n) _Pragma("unroll") for (int k = 0; k < 2; ++k) \
;         acc[ai][bj][m][n] = __builtin_amdgcn_mfma_f32_16x16x32_bf16(Bt[n][k], At[m][k], acc[ai][bj][m][n], 0, 0, 0); __builtin_amdgcn_s_setprio(0); } while (0)
; #define PG8_WAIT_V(n) asm volatile("s_waitcnt vmcnt(" #n ")" ::: "memory")
; #define PG8_WAIT_L(n) asm volatile("s_waitcnt lgkmcnt(" #n ")" ::: "memory")
; #define PG8_BAR __builtin_amdgcn_s_barrier()
; #define PG8_SCHED __builtin_amdgcn_sched_barrier(0)
; template <class Epi>
; __device__ __forceinline__ void gemm_phase(LAS unsigned char* lds, const Gemm g, int G, int c, const Epi& E) {
;     ...
;             PG8_WAIT_V(8); PG8_WAIT_L(0); PG8_BAR; PG8_MMA(1, 0, At, B0); PG8_MMA(1, 1, At, B1); PG8_BAR; PG8_SCHED;
;             PG8_LDB(B0, 1, 0); PG8_LDB(B1, 1, 1); PG8_SCHED; PG8_LDA(At, 1, 0); PG8_STAGE(PG8_SA(0, 1), a2 + hstepA, voffA);
;             PG8_WAIT_V(8); PG8_WAIT_L(0); PG8_BAR; PG8_MMA(0, 0, At, B0); PG8_MMA(0, 1, At, B1); PG8_BAR; PG8_SCHED;
	s_waitcnt lgkmcnt(0)
	v_mfma_f32_16x16x32_bf16 v[62:65], v[146:149], v[184:187], v[62:65]
	v_mfma_f32_16x16x32_bf16 v[58:61], v[160:163], v[184:187], v[58:61]
	v_mfma_f32_16x16x32_bf16 v[54:57], v[146:149], v[192:195], v[54:57]
	v_mfma_f32_16x16x32_bf16 v[46:49], v[160:163], v[192:195], v[46:49]
	v_mfma_f32_16x16x32_bf16 v[38:41], v[146:149], v[200:203], v[38:41]
	v_mfma_f32_16x16x32_bf16 v[30:33], v[160:163], v[200:203], v[30:33]
	v_mfma_f32_16x16x32_bf16 v[22:25], v[146:149], v[208:211], v[22:25]
	v_mfma_f32_16x16x32_bf16 v[14:17], v[160:163], v[208:211], v[14:17]
	v_mfma_f32_16x16x32_bf16 v[62:65], v[156:159], v[188:191], v[62:65]
	v_mfma_f32_16x16x32_bf16 v[58:61], v[164:167], v[188:191], v[58:61]
	v_mfma_f32_16x16x32_bf16 v[54:57], v[156:159], v[196:199], v[54:57]
	v_mfma_f32_16x16x32_bf16 v[46:49], v[164:167], v[196:199], v[46:49]
	v_mfma_f32_16x16x32_bf16 v[38:41], v[156:159], v[204:207], v[38:41]
	v_mfma_f32_16x16x32_bf16 v[30:33], v[164:167], v[204:207], v[30:33]
	v_mfma_f32_16x16x32_bf16 v[22:25], v[156:159], v[212:215], v[22:25]
	v_mfma_f32_16x16x32_bf16 v[14:17], v[164:167], v[212:215], v[14:17]
	v_mfma_f32_16x16x32_bf16 v[50:53], v[168:171], v[184:187], v[50:53]
	v_mfma_f32_16x16x32_bf16 v[42:45], v[176:179], v[184:187], v[42:45]
	v_mfma_f32_16x16x32_bf16 v[34:37], v[168:171], v[192:195], v[34:37]
	v_mfma_f32_16x16x32_bf16 v[26:29], v[176:179], v[192:195], v[26:29]
	v_mfma_f32_16x16x32_bf16 v[18:21], v[168:171], v[200:203], v[18:21]
	v_mfma_f32_16x16x32_bf16 v[10:13], v[176:179], v[200:203], v[10:13]
	v_mfma_f32_16x16x32_bf16 v[6:9], v[168:171], v[208:211], v[6:9]
	v_mfma_f32_16x16x32_bf16 v[2:5], v[176:179], v[208:211], v[2:5]
	v_mfma_f32_16x16x32_bf16 v[50:53], v[172:175], v[188:191], v[50:53]
	v_mfma_f32_16x16x32_bf16 v[42:45], v[180:183], v[188:191], v[42:45]
	v_mfma_f32_16x16x32_bf16 v[34:37], v[172:175], v[196:199], v[34:37]
	v_mfma_f32_16x16x32_bf16 v[26:29], v[180:183], v[196:199], v[26:29]
	v_mfma_f32_16x16x32_bf16 v[18:21], v[172:175], v[204:207], v[18:21]
	v_mfma_f32_16x16x32_bf16 v[10:13], v[180:183], v[204:207], v[10:13]
	v_mfma_f32_16x16x32_bf16 v[6:9], v[172:175], v[212:215], v[6:9]
	v_mfma_f32_16x16x32_bf16 v[2:5], v[180:183], v[212:215], v[2:5]
	s_barrier
	s_add_i32 s33, 0, 0x18000
	v_add_u32_e32 v155, s33, v151
	s_add_i32 s64, 0, 0x1c000
	ds_read_b128 v[146:149], v155
	ds_read_b128 v[156:159], v155 offset:1024
	ds_read_b128 v[160:163], v155 offset:2048
	ds_read_b128 v[164:167], v155 offset:3072
	v_add_u32_e32 v155, s64, v151
	ds_read_b128 v[168:171], v155
	ds_read_b128 v[172:175], v155 offset:1024
	ds_read_b128 v[176:179], v155 offset:2048
	ds_read_b128 v[180:183], v155 offset:3072
	s_add_u32 s44, s44, 0x100000
	s_addc_u32 s45, s45, 0
	s_mov_b32 m0, s39
	v_lshl_add_u64 v[226:227], s[44:45], 0, v[136:137]
	ds_read_b128 v[184:187], v154 offset:32768
	ds_read_b128 v[188:191], v154 offset:33792
	ds_read_b128 v[192:195], v154 offset:34816
	ds_read_b128 v[196:199], v154 offset:35840
	ds_read_b128 v[200:203], v154 offset:36864
	ds_read_b128 v[204:207], v154 offset:37888
	ds_read_b128 v[208:211], v154 offset:38912
	ds_read_b128 v[212:215], v154 offset:39936
	global_load_lds_dwordx4 v[226:227], off
	v_lshl_add_u64 v[226:227], s[44:45], 0, v[132:133]
	s_mov_b32 m0, s53
	s_nop 0
	global_load_lds_dwordx4 v[226:227], off
	s_waitcnt vmcnt(8)
	s_waitcnt lgkmcnt(0)
	s_barrier
	s_waitcnt lgkmcnt(0)
	v_mfma_f32_16x16x32_bf16 v[126:129], v[146:149], v[184:187], v[126:129]
	v_mfma_f32_16x16x32_bf16 v[122:125], v[160:163], v[184:187], v[122:125]
	v_mfma_f32_16x16x32_bf16 v[118:121], v[146:149], v[192:195], v[118:121]
	v_mfma_f32_16x16x32_bf16 v[110:113], v[160:163], v[192:195], v[110:113]
	v_mfma_f32_16x16x32_bf16 v[102:105], v[146:149], v[200:203], v[102:105]
	v_mfma_f32_16x16x32_bf16 v[94:97], v[160:163], v[200:203], v[94:97]
	v_mfma_f32_16x16x32_bf16 v[86:89], v[146:149], v[208:211], v[86:89]
	v_mfma_f32_16x16x32_bf16 v[78:81], v[160:163], v[208:211], v[78:81]
	v_mfma_f32_16x16x32_bf16 v[126:129], v[156:159], v[188:191], v[126:129]
	v_mfma_f32_16x16x32_bf16 v[122:125], v[164:167], v[188:191], v[122:125]
	v_mfma_f32_16x16x32_bf16 v[118:121], v[156:159], v[196:199], v[118:121]
	v_mfma_f32_16x16x32_bf16 v[110:113], v[164:167], v[196:199], v[110:113]
	v_mfma_f32_16x16x32_bf16 v[102:105], v[156:159], v[204:207], v[102:105]
	v_mfma_f32_16x16x32_bf16 v[94:97], v[164:167], v[204:207], v[94:97]
	v_mfma_f32_16x16x32_bf16 v[86:89], v[156:159], v[212:215], v[86:89]
	v_mfma_f32_16x16x32_bf16 v[78:81], v[164:167], v[212:215], v[78:81]
	v_mfma_f32_16x16x32_bf16 v[114:117], v[168:171], v[184:187], v[114:117]
	v_mfma_f32_16x16x32_bf16 v[106:109], v[176:179], v[184:187], v[106:109]
	v_mfma_f32_16x16x32_bf16 v[98:101], v[168:171], v[192:195], v[98:101]
	v_mfma_f32_16x16x32_bf16 v[90:93], v[176:179], v[192:195], v[90:93]
	v_mfma_f32_16x16x32_bf16 v[82:85], v[168:171], v[200:203], v[82:85]
	v_mfma_f32_16x16x32_bf16 v[74:77], v[176:179], v[200:203], v[74:77]
	v_mfma_f32_16x16x32_bf16 v[70:73], v[168:171], v[208:211], v[70:73]
	v_mfma_f32_16x16x32_bf16 v[66:69], v[176:179], v[208:211], v[66:69]
	v_mfma_f32_16x16x32_bf16 v[114:117], v[172:175], v[188:191], v[114:117]
	v_mfma_f32_16x16x32_bf16 v[106:109], v[180:183], v[188:191], v[106:109]
	v_mfma_f32_16x16x32_bf16 v[98:101], v[172:175], v[196:199], v[98:101]
	v_mfma_f32_16x16x32_bf16 v[90:93], v[180:183], v[196:199], v[90:93]
	v_mfma_f32_16x16x32_bf16 v[82:85], v[172:175], v[204:207], v[82:85]
	v_mfma_f32_16x16x32_bf16 v[74:77], v[180:183], v[204:207], v[74:77]
	v_mfma_f32_16x16x32_bf16 v[70:73], v[172:175], v[212:215], v[70:73]
	v_mfma_f32_16x16x32_bf16 v[66:69], v[180:183], v[212:215], v[66:69]
	s_barrier
; #define PG8_STAGE(bufoff, gbase, voff) do { _Pragma("unroll") for (int _i = 0; _i < 2; ++_i) \
;         __builtin_amdgcn_global_load_lds((const unsigned*)((const char*)(gbase) + (voff)[_i]), (LAS unsigned*)(lds + (bufoff) + ldsw + _i * 8192), 16, 0, 0); } while (0)
; #define PG8_LDA(dst, b, h) do { _Pragma("unroll") for (int m = 0; m < 4; ++m) _Pragma("unroll") for (int k = 0; k < 2; ++k) dst[m][k] = *(const LAS bf16x8*)(lds + PG8_SA(b, h) + aoff + m * 2048 + k * 1024); } while (0)
; #define PG8_MMA(ai, bj, At, Bt) do { __builtin_amdgcn_s_setprio(1); _Pragma("unroll") for (int m = 0; m < 4; ++m) _Pragma("unroll") for (int n = 0; n < 2; ++n) _Pragma("unroll") for (int k = 0; k < 2; ++k) \
;         acc[ai][bj][m][n] = __builtin_amdgcn_mfma_f32_16x16x32_bf16(Bt[n][k], At[m][k], acc[ai][bj][m][n], 0, 0, 0); __builtin_amdgcn_s_setprio(0); } while (0)
; #define PG8_WAIT_V(n) asm volatile("s_waitcnt vmcnt(" #n ")" ::: "memory")
; #define PG8_WAIT_L(n) asm volatile("s_waitcnt lgkmcnt(" #n ")" ::: "memory")
; #define PG8_BAR __builtin_amdgcn_s_barrier()
; #define PG8_SCHED __builtin_amdgcn_sched_barrier(0)
; template <class Epi>
; __device__ __forceinline__ void gemm_phase(LAS unsigned char* lds, const Gemm g, int G, int c, const Epi& E) {
;     ...
;             PG8_LDA(At, 1, 1); PG8_STAGE(PG8_SB(1, 0), b3, voffB); PG8_STAGE(PG8_SB(1, 1), b3 + hstepB, voffB); PG8_STAGE(PG8_SA(1, 0), a3, voffA);
;             PG8_WAIT_V(8); PG8_WAIT_L(0); PG8_BAR; PG8_MMA(1, 0, At, B0); PG8_MMA(1, 1, At, B1); PG8_BAR; PG8_SCHED;
;         }
;         if (wr == 0) PG8_BAR;
	s_add_i32 s33, s33, s52
	v_lshl_add_u64 v[216:217], v[216:217], 0, s[6:7]
	s_mov_b32 m0, s33
	ds_read_b128 v[184:187], v154 offset:49152
	ds_read_b128 v[188:191], v154 offset:50176
	ds_read_b128 v[192:195], v154 offset:51200
	ds_read_b128 v[196:199], v154 offset:52224
	ds_read_b128 v[200:203], v154 offset:53248
	ds_read_b128 v[204:207], v154 offset:54272
	ds_read_b128 v[208:211], v154 offset:55296
	ds_read_b128 v[212:215], v154 offset:56320
	global_load_lds_dwordx4 v[216:217], off
	s_add_i32 m0, s33, 0x2000
	s_add_u32 s42, s42, 0x100080
	v_lshl_add_u64 v[216:217], v[218:219], 0, s[6:7]
	s_addc_u32 s43, s43, 0
	s_add_i32 s33, s64, s52
	global_load_lds_dwordx4 v[216:217], off
	v_lshl_add_u64 v[216:217], s[42:43], 0, v[134:135]
	s_mov_b32 m0, s33
	s_nop 0
	global_load_lds_dwordx4 v[216:217], off
	v_lshl_add_u64 v[216:217], s[42:43], 0, v[130:131]
	s_add_i32 m0, s33, 0x2000
	s_nop 0
	global_load_lds_dwordx4 v[216:217], off
	v_lshl_add_u64 v[216:217], v[220:221], 0, s[6:7]
	s_mov_b32 m0, s59
	s_nop 0
	global_load_lds_dwordx4 v[216:217], off
	v_lshl_add_u64 v[216:217], v[222:223], 0, s[6:7]
	s_mov_b32 m0, s60
	s_nop 0
	global_load_lds_dwordx4 v[216:217], off
	s_waitcnt vmcnt(8)
	s_waitcnt lgkmcnt(0)
	s_barrier
	s_waitcnt lgkmcnt(0)
	v_mfma_f32_16x16x32_bf16 v[62:65], v[146:149], v[184:187], v[62:65]
	v_mfma_f32_16x16x32_bf16 v[58:61], v[160:163], v[184:187], v[58:61]
	v_mfma_f32_16x16x32_bf16 v[54:57], v[146:149], v[192:195], v[54:57]
	v_mfma_f32_16x16x32_bf16 v[46:49], v[160:163], v[192:195], v[46:49]
	v_mfma_f32_16x16x32_bf16 v[38:41], v[146:149], v[200:203], v[38:41]
	v_mfma_f32_16x16x32_bf16 v[30:33], v[160:163], v[200:203], v[30:33]
	v_mfma_f32_16x16x32_bf16 v[22:25], v[146:149], v[208:211], v[22:25]
	v_mfma_f32_16x16x32_bf16 v[14:17], v[160:163], v[208:211], v[14:17]
	v_mfma_f32_16x16x32_bf16 v[62:65], v[156:159], v[188:191], v[62:65]
	v_mfma_f32_16x16x32_bf16 v[58:61], v[164:167], v[188:191], v[58:61]
	v_mfma_f32_16x16x32_bf16 v[54:57], v[156:159], v[196:199], v[54:57]
	v_mfma_f32_16x16x32_bf16 v[46:49], v[164:167], v[196:199], v[46:49]
	v_mfma_f32_16x16x32_bf16 v[38:41], v[156:159], v[204:207], v[38:41]
	v_mfma_f32_16x16x32_bf16 v[30:33], v[164:167], v[204:207], v[30:33]
	v_mfma_f32_16x16x32_bf16 v[22:25], v[156:159], v[212:215], v[22:25]
	v_mfma_f32_16x16x32_bf16 v[14:17], v[164:167], v[212:215], v[14:17]
	v_mfma_f32_16x16x32_bf16 v[50:53], v[168:171], v[184:187], v[50:53]
	v_mfma_f32_16x16x32_bf16 v[42:45], v[176:179], v[184:187], v[42:45]
	v_mfma_f32_16x16x32_bf16 v[34:37], v[168:171], v[192:195], v[34:37]
	v_mfma_f32_16x16x32_bf16 v[26:29], v[176:179], v[192:195], v[26:29]
	v_mfma_f32_16x16x32_bf16 v[18:21], v[168:171], v[200:203], v[18:21]
	v_mfma_f32_16x16x32_bf16 v[10:13], v[176:179], v[200:203], v[10:13]
	v_mfma_f32_16x16x32_bf16 v[6:9], v[168:171], v[208:211], v[6:9]
	v_mfma_f32_16x16x32_bf16 v[2:5], v[176:179], v[208:211], v[2:5]
	v_mfma_f32_16x16x32_bf16 v[50:53], v[172:175], v[188:191], v[50:53]
	v_mfma_f32_16x16x32_bf16 v[42:45], v[180:183], v[188:191], v[42:45]
	v_mfma_f32_16x16x32_bf16 v[34:37], v[172:175], v[196:199], v[34:37]
	v_mfma_f32_16x16x32_bf16 v[26:29], v[180:183], v[196:199], v[26:29]
	v_mfma_f32_16x16x32_bf16 v[18:21], v[172:175], v[204:207], v[18:21]
	v_mfma_f32_16x16x32_bf16 v[10:13], v[180:183], v[204:207], v[10:13]
	v_mfma_f32_16x16x32_bf16 v[6:9], v[172:175], v[212:215], v[6:9]
	v_mfma_f32_16x16x32_bf16 v[2:5], v[180:183], v[212:215], v[2:5]
	s_barrier
	s_add_i32 s68, s68, 2
	s_add_u32 s40, s40, 0x100
	s_addc_u32 s41, s41, 0
	s_add_u32 s66, s66, 0x100
	s_addc_u32 s67, s67, 0
	s_cmp_gt_u32 s68, 61
	s_cbranch_scc0 .LBB0_1825
	s_and_b64 vcc, exec, s[8:9]
	s_cbranch_vccz .LBB0_1828
	s_barrier

; #define PG8_STAGE(bufoff, gbase, voff) do { _Pragma("unroll") for (int _i = 0; _i < 2; ++_i) \
;         __builtin_amdgcn_global_load_lds((const unsigned*)((const char*)(gbase) + (voff)[_i]), (LAS unsigned*)(lds + (bufoff) + ldsw + _i * 8192), 16, 0, 0); } while (0)
; #define PG8_LDA(dst, b, h) do { _Pragma("unroll") for (int m = 0; m < 4; ++m) _Pragma("unroll") for (int k = 0; k < 2; ++k) dst[m][k] = *(const LAS bf16x8*)(lds + PG8_SA(b, h) + aoff + m * 2048 + k * 1024); } while (0)
; #define PG8_LDB(dst, b, h) do { _Pragma("unroll") for (int n = 0; n < 2; ++n) _Pragma("unroll") for (int k = 0; k < 2; ++k) dst[n][k] = *(const LAS bf16x8*)(lds + PG8_SB(b, h) + boff + n * 2048 + k * 1024); } while (0)
; #define PG8_MMA(ai, bj, At, Bt) do { __builtin_amdgcn_s_setprio(1); _Pragma("unroll") for (int m = 0; m < 4; ++m) _Pragma("unroll") for (int n = 0; n < 2; ++n) _Pragma("unroll") for (int k = 0; k < 2; ++k) \
;         acc[ai][bj][m][n] = __builtin_amdgcn_mfma_f32_16x16x32_bf16(Bt[n][k], At[m][k], acc[ai][bj][m][n], 0, 0, 0); __builtin_amdgcn_s_setprio(0); } while (0)
; #define PG8_WAIT_V(n) asm volatile("s_waitcnt vmcnt(" #n ")" ::: "memory")
; #define PG8_WAIT_L(n) asm volatile("s_waitcnt lgkmcnt(" #n ")" ::: "memory")
; #define PG8_BAR __builtin_amdgcn_s_barrier()
; #define PG8_SCHED __builtin_amdgcn_sched_barrier(0)
; template <class Epi>
; __device__ __forceinline__ void gemm_phase(LAS unsigned char* lds, const Gemm g, int G, int c, const Epi& E) {
;     ...
;             const bool last = (t == nt - 2);
;             const char* a1 = cA + (size_t)(t + 1) * kstep;
;             const char* a2 = last ? nA : cA + (size_t)(t + 2) * kstep; const char* b2 = last ? nB : cB + (size_t)(t + 2) * kstep;
;             const char* a3 = a2 + kstep; const char* b3 = b2 + kstep;
;             PG8_LDB(B0, 0, 0); PG8_LDB(B1, 0, 1); PG8_SCHED; PG8_LDA(At, 0, 0); PG8_STAGE(PG8_SA(1, 1), a1 + hstepA, voffA);
;             PG8_WAIT_V(8); PG8_WAIT_L(0); PG8_BAR; PG8_MMA(0, 0, At, B0); PG8_MMA(0, 1, At, B1); PG8_BAR; PG8_SCHED;
;             PG8_LDA(At, 0, 1); PG8_STAGE(PG8_SB(0, 0), b2, voffB); PG8_STAGE(PG8_SB(0, 1), b2 + hstepB, voffB); PG8_STAGE(PG8_SA(0, 0), a2, voffA);
.LBB0_1931:
	ds_read_b128 v[122:125], v168
	ds_read_b128 v[126:129], v168 offset:1024
	ds_read_b128 v[130:133], v168 offset:2048
	ds_read_b128 v[134:137], v168 offset:3072
	ds_read_b128 v[162:165], v169
	ds_read_b128 v[172:175], v169 offset:1024
	ds_read_b128 v[176:179], v169 offset:2048
	ds_read_b128 v[180:183], v169 offset:3072
	s_add_u32 s33, s4, 0xfffc0080
	s_addc_u32 s36, s5, -1
	s_cmp_eq_u32 s62, 12
	s_cselect_b32 s39, s19, s36
	s_cselect_b32 s38, s18, s33
	s_cselect_b32 s37, s15, s61
	s_cselect_b32 s36, s17, s60
	v_lshl_add_u64 v[216:217], s[4:5], 0, v[154:155]
	s_add_i32 m0, s23, 0xc000
	ds_read_b128 v[184:187], v170
	ds_read_b128 v[188:191], v170 offset:1024
	ds_read_b128 v[192:195], v170 offset:2048
	ds_read_b128 v[196:199], v170 offset:3072
	ds_read_b128 v[200:203], v170 offset:4096
	ds_read_b128 v[204:207], v170 offset:5120
	ds_read_b128 v[208:211], v170 offset:6144
	ds_read_b128 v[212:215], v170 offset:7168
	global_load_lds_dwordx4 v[216:217], off
	v_lshl_add_u64 v[216:217], s[4:5], 0, v[156:157]
	s_add_i32 m0, s23, 0xe000
	s_nop 0
	global_load_lds_dwordx4 v[216:217], off
	s_waitcnt vmcnt(8)
	s_waitcnt lgkmcnt(0)
	s_barrier
	s_waitcnt lgkmcnt(0)
	v_mfma_f32_16x16x32_bf16 v[142:145], v[122:125], v[184:187], v[142:145]
	v_mfma_f32_16x16x32_bf16 v[138:141], v[130:133], v[184:187], v[138:141]
	v_mfma_f32_16x16x32_bf16 v[118:121], v[122:125], v[192:195], v[118:121]
	v_mfma_f32_16x16x32_bf16 v[106:109], v[130:133], v[192:195], v[106:109]
	v_mfma_f32_16x16x32_bf16 v[102:105], v[122:125], v[200:203], v[102:105]
	v_mfma_f32_16x16x32_bf16 v[90:93], v[130:133], v[200:203], v[90:93]
	v_mfma_f32_16x16x32_bf16 v[86:89], v[122:125], v[208:211], v[86:89]
	v_mfma_f32_16x16x32_bf16 v[74:77], v[130:133], v[208:211], v[74:77]
	v_mfma_f32_16x16x32_bf16 v[142:145], v[126:129], v[188:191], v[142:145]
	v_mfma_f32_16x16x32_bf16 v[138:141], v[134:137], v[188:191], v[138:141]
	v_mfma_f32_16x16x32_bf16 v[118:121], v[126:129], v[196:199], v[118:121]
	v_mfma_f32_16x16x32_bf16 v[106:109], v[134:137], v[196:199], v[106:109]
	v_mfma_f32_16x16x32_bf16 v[102:105], v[126:129], v[204:207], v[102:105]
	v_mfma_f32_16x16x32_bf16 v[90:93], v[134:137], v[204:207], v[90:93]
	v_mfma_f32_16x16x32_bf16 v[86:89], v[126:129], v[212:215], v[86:89]
	v_mfma_f32_16x16x32_bf16 v[74:77], v[134:137], v[212:215], v[74:77]
	v_mfma_f32_16x16x32_bf16 v[114:117], v[162:165], v[184:187], v[114:117]
	v_mfma_f32_16x16x32_bf16 v[110:113], v[176:179], v[184:187], v[110:113]
	v_mfma_f32_16x16x32_bf16 v[98:101], v[162:165], v[192:195], v[98:101]
	v_mfma_f32_16x16x32_bf16 v[94:97], v[176:179], v[192:195], v[94:97]
	v_mfma_f32_16x16x32_bf16 v[82:85], v[162:165], v[200:203], v[82:85]
	v_mfma_f32_16x16x32_bf16 v[78:81], v[176:179], v[200:203], v[78:81]
	v_mfma_f32_16x16x32_bf16 v[70:73], v[162:165], v[208:211], v[70:73]
	v_mfma_f32_16x16x32_bf16 v[66:69], v[176:179], v[208:211], v[66:69]
	v_mfma_f32_16x16x32_bf16 v[114:117], v[172:175], v[188:191], v[114:117]
	v_mfma_f32_16x16x32_bf16 v[110:113], v[180:183], v[188:191], v[110:113]
	v_mfma_f32_16x16x32_bf16 v[98:101], v[172:175], v[196:199], v[98:101]
	v_mfma_f32_16x16x32_bf16 v[94:97], v[180:183], v[196:199], v[94:97]
	v_mfma_f32_16x16x32_bf16 v[82:85], v[172:175], v[204:207], v[82:85]
	v_mfma_f32_16x16x32_bf16 v[78:81], v[180:183], v[204:207], v[78:81]
	v_mfma_f32_16x16x32_bf16 v[70:73], v[172:175], v[212:215], v[70:73]
	v_mfma_f32_16x16x32_bf16 v[66:69], v[180:183], v[212:215], v[66:69]
	s_barrier
	s_add_i32 s33, s56, s42
	v_lshl_add_u64 v[216:217], s[36:37], 0, v[150:151]
	s_mov_b32 m0, s33
	ds_read_b128 v[184:187], v170 offset:16384
	ds_read_b128 v[188:191], v170 offset:17408
	ds_read_b128 v[192:195], v170 offset:18432
	ds_read_b128 v[196:199], v170 offset:19456
	ds_read_b128 v[200:203], v170 offset:20480
	ds_read_b128 v[204:207], v170 offset:21504
	ds_read_b128 v[208:211], v170 offset:22528
	ds_read_b128 v[212:215], v170 offset:23552
	global_load_lds_dwordx4 v[216:217], off
	s_add_i32 m0, s33, 0x2000
	s_add_u32 s64, s36, 0x40000
	v_lshl_add_u64 v[218:219], s[36:37], 0, v[146:147]
	s_addc_u32 s65, s37, 0
	s_add_i32 s33, s57, s42
	global_load_lds_dwordx4 v[218:219], off
	v_lshl_add_u64 v[220:221], s[64:65], 0, v[150:151]
	s_mov_b32 m0, s33
	v_lshl_add_u64 v[222:223], s[38:39], 0, v[148:149]
	global_load_lds_dwordx4 v[220:221], off
	v_lshl_add_u64 v[220:221], s[64:65], 0, v[146:147]
	s_add_i32 m0, s33, 0x2000
	s_nop 0
	global_load_lds_dwordx4 v[220:221], off
	v_lshl_add_u64 v[220:221], s[38:39], 0, v[152:153]
	s_mov_b32 m0, s23
	s_nop 0
	global_load_lds_dwordx4 v[220:221], off
	s_mov_b32 m0, s25
	s_nop 0
	global_load_lds_dwordx4 v[222:223], off
	s_waitcnt vmcnt(8)
	s_waitcnt lgkmcnt(0)
	s_barrier
; #define PG8_STAGE(bufoff, gbase, voff) do { _Pragma("unroll") for (int _i = 0; _i < 2; ++_i) \
;         __builtin_amdgcn_global_load_lds((const unsigned*)((const char*)(gbase) + (voff)[_i]), (LAS unsigned*)(lds + (bufoff) + ldsw + _i * 8192), 16, 0, 0); } while (0)
; #define PG8_LDA(dst, b, h) do { _Pragma("unroll") for (int m = 0; m < 4; ++m) _Pragma("unroll") for (int k = 0; k < 2; ++k) dst[m][k] = *(const LAS bf16x8*)(lds + PG8_SA(b, h) + aoff + m * 2048 + k * 1024); } while (0)
; #define PG8_LDB(dst, b, h) do { _Pragma("unroll") for (int n = 0; n < 2; ++n) _Pragma("unroll") for (int k = 0; k < 2; ++k) dst[n][k] = *(const LAS bf16x8*)(lds + PG8_SB(b, h) + boff + n * 2048 + k * 1024); } while (0)
; #define PG8_MMA(ai, bj, At, Bt) do { __builtin_amdgcn_s_setprio(1); _Pragma("unroll") for (int m = 0; m < 4; ++m) _Pragma("unroll") for (int n = 0; n < 2; ++n) _Pragma("unroll") for (int k = 0; k < 2; ++k) \
;         acc[ai][bj][m][n] = __builtin_amdgcn_mfma_f32_16x16x32_bf16(Bt[n][k], At[m][k], acc[ai][bj][m][n], 0, 0, 0); __builtin_amdgcn_s_setprio(0); } while (0)
; #define PG8_WAIT_V(n) asm volatile("s_waitcnt vmcnt(" #n ")" ::: "memory")
; #define PG8_WAIT_L(n) asm volatile("s_waitcnt lgkmcnt(" #n ")" ::: "memory")
; #define PG8_BAR __builtin_amdgcn_s_barrier()
; #define PG8_SCHED __builtin_amdgcn_sched_barrier(0)
; template <class Epi>
; __device__ __forceinline__ void gemm_phase(LAS unsigned char* lds, const Gemm g, int G, int c, const Epi& E) {
;     ...
;             PG8_WAIT_V(8); PG8_WAIT_L(0); PG8_BAR; PG8_MMA(1, 0, At, B0); PG8_MMA(1, 1, At, B1); PG8_BAR; PG8_SCHED;
;             PG8_LDB(B0, 1, 0); PG8_LDB(B1, 1, 1); PG8_SCHED; PG8_LDA(At, 1, 0); PG8_STAGE(PG8_SA(0, 1), a2 + hstepA, voffA);
;             PG8_WAIT_V(8); PG8_WAIT_L(0); PG8_BAR; PG8_MMA(0, 0, At, B0); PG8_MMA(0, 1, At, B1); PG8_BAR; PG8_SCHED;
	s_waitcnt lgkmcnt(0)
	v_mfma_f32_16x16x32_bf16 v[62:65], v[122:125], v[184:187], v[62:65]
	v_mfma_f32_16x16x32_bf16 v[58:61], v[130:133], v[184:187], v[58:61]
	v_mfma_f32_16x16x32_bf16 v[54:57], v[122:125], v[192:195], v[54:57]
	v_mfma_f32_16x16x32_bf16 v[42:45], v[130:133], v[192:195], v[42:45]
	v_mfma_f32_16x16x32_bf16 v[38:41], v[122:125], v[200:203], v[38:41]
	v_mfma_f32_16x16x32_bf16 v[26:29], v[130:133], v[200:203], v[26:29]
	v_mfma_f32_16x16x32_bf16 v[22:25], v[122:125], v[208:211], v[22:25]
	v_mfma_f32_16x16x32_bf16 v[10:13], v[130:133], v[208:211], v[10:13]
	v_mfma_f32_16x16x32_bf16 v[62:65], v[126:129], v[188:191], v[62:65]
	v_mfma_f32_16x16x32_bf16 v[58:61], v[134:137], v[188:191], v[58:61]
	v_mfma_f32_16x16x32_bf16 v[54:57], v[126:129], v[196:199], v[54:57]
	v_mfma_f32_16x16x32_bf16 v[42:45], v[134:137], v[196:199], v[42:45]
	v_mfma_f32_16x16x32_bf16 v[38:41], v[126:129], v[204:207], v[38:41]
	v_mfma_f32_16x16x32_bf16 v[26:29], v[134:137], v[204:207], v[26:29]
	v_mfma_f32_16x16x32_bf16 v[22:25], v[126:129], v[212:215], v[22:25]
	v_mfma_f32_16x16x32_bf16 v[10:13], v[134:137], v[212:215], v[10:13]
	v_mfma_f32_16x16x32_bf16 v[50:53], v[162:165], v[184:187], v[50:53]
	v_mfma_f32_16x16x32_bf16 v[46:49], v[176:179], v[184:187], v[46:49]
	v_mfma_f32_16x16x32_bf16 v[34:37], v[162:165], v[192:195], v[34:37]
	v_mfma_f32_16x16x32_bf16 v[30:33], v[176:179], v[192:195], v[30:33]
	v_mfma_f32_16x16x32_bf16 v[18:21], v[162:165], v[200:203], v[18:21]
	v_mfma_f32_16x16x32_bf16 v[14:17], v[176:179], v[200:203], v[14:17]
	v_mfma_f32_16x16x32_bf16 v[6:9], v[162:165], v[208:211], v[6:9]
	v_mfma_f32_16x16x32_bf16 v[2:5], v[176:179], v[208:211], v[2:5]
	v_mfma_f32_16x16x32_bf16 v[50:53], v[172:175], v[188:191], v[50:53]
	v_mfma_f32_16x16x32_bf16 v[46:49], v[180:183], v[188:191], v[46:49]
	v_mfma_f32_16x16x32_bf16 v[34:37], v[172:175], v[196:199], v[34:37]
	v_mfma_f32_16x16x32_bf16 v[30:33], v[180:183], v[196:199], v[30:33]
	v_mfma_f32_16x16x32_bf16 v[18:21], v[172:175], v[204:207], v[18:21]
	v_mfma_f32_16x16x32_bf16 v[14:17], v[180:183], v[204:207], v[14:17]
	v_mfma_f32_16x16x32_bf16 v[6:9], v[172:175], v[212:215], v[6:9]
	v_mfma_f32_16x16x32_bf16 v[2:5], v[180:183], v[212:215], v[2:5]
	s_barrier
	s_add_i32 s33, 0, 0x18000
	s_add_i32 s63, 0, 0x1c000
	v_add_u32_e32 v134, s33, v167
	v_add_u32_e32 v171, s63, v167
	ds_read_b128 v[122:125], v134
	ds_read_b128 v[126:129], v134 offset:1024
	ds_read_b128 v[130:133], v134 offset:2048
	ds_read_b128 v[134:137], v134 offset:3072
	ds_read_b128 v[162:165], v171
	ds_read_b128 v[172:175], v171 offset:1024
	ds_read_b128 v[176:179], v171 offset:2048
	ds_read_b128 v[180:183], v171 offset:3072
	s_add_u32 s38, s38, 0x40000
	s_addc_u32 s39, s39, 0
	s_mov_b32 m0, s44
	v_lshl_add_u64 v[224:225], s[38:39], 0, v[152:153]
	ds_read_b128 v[184:187], v170 offset:32768
	ds_read_b128 v[188:191], v170 offset:33792
	ds_read_b128 v[192:195], v170 offset:34816
	ds_read_b128 v[196:199], v170 offset:35840
	ds_read_b128 v[200:203], v170 offset:36864
	ds_read_b128 v[204:207], v170 offset:37888
	ds_read_b128 v[208:211], v170 offset:38912
	ds_read_b128 v[212:215], v170 offset:39936
	global_load_lds_dwordx4 v[224:225], off
	v_lshl_add_u64 v[224:225], s[38:39], 0, v[148:149]
	s_mov_b32 m0, s45
	s_nop 0
	global_load_lds_dwordx4 v[224:225], off
	s_waitcnt vmcnt(8)
	s_waitcnt lgkmcnt(0)
	s_barrier
	s_waitcnt lgkmcnt(0)
	v_mfma_f32_16x16x32_bf16 v[142:145], v[122:125], v[184:187], v[142:145]
	v_mfma_f32_16x16x32_bf16 v[138:141], v[130:133], v[184:187], v[138:141]
	v_mfma_f32_16x16x32_bf16 v[118:121], v[122:125], v[192:195], v[118:121]
	v_mfma_f32_16x16x32_bf16 v[106:109], v[130:133], v[192:195], v[106:109]
	v_mfma_f32_16x16x32_bf16 v[102:105], v[122:125], v[200:203], v[102:105]
	v_mfma_f32_16x16x32_bf16 v[90:93], v[130:133], v[200:203], v[90:93]
	v_mfma_f32_16x16x32_bf16 v[86:89], v[122:125], v[208:211], v[86:89]
	v_mfma_f32_16x16x32_bf16 v[74:77], v[130:133], v[208:211], v[74:77]
	v_mfma_f32_16x16x32_bf16 v[142:145], v[126:129], v[188:191], v[142:145]
	v_mfma_f32_16x16x32_bf16 v[138:141], v[134:137], v[188:191], v[138:141]
	v_mfma_f32_16x16x32_bf16 v[118:121], v[126:129], v[196:199], v[118:121]
	v_mfma_f32_16x16x32_bf16 v[106:109], v[134:137], v[196:199], v[106:109]
	v_mfma_f32_16x16x32_bf16 v[102:105], v[126:129], v[204:207], v[102:105]
	v_mfma_f32_16x16x32_bf16 v[90:93], v[134:137], v[204:207], v[90:93]
	v_mfma_f32_16x16x32_bf16 v[86:89], v[126:129], v[212:215], v[86:89]
	v_mfma_f32_16x16x32_bf16 v[74:77], v[134:137], v[212:215], v[74:77]
	v_mfma_f32_16x16x32_bf16 v[114:117], v[162:165], v[184:187], v[114:117]
	v_mfma_f32_16x16x32_bf16 v[110:113], v[176:179], v[184:187], v[110:113]
	v_mfma_f32_16x16x32_bf16 v[98:101], v[162:165], v[192:195], v[98:101]
	v_mfma_f32_16x16x32_bf16 v[94:97], v[176:179], v[192:195], v[94:97]
	v_mfma_f32_16x16x32_bf16 v[82:85], v[162:165], v[200:203], v[82:85]
	v_mfma_f32_16x16x32_bf16 v[78:81], v[176:179], v[200:203], v[78:81]
	v_mfma_f32_16x16x32_bf16 v[70:73], v[162:165], v[208:211], v[70:73]
	v_mfma_f32_16x16x32_bf16 v[66:69], v[176:179], v[208:211], v[66:69]
	v_mfma_f32_16x16x32_bf16 v[114:117], v[172:175], v[188:191], v[114:117]
	v_mfma_f32_16x16x32_bf16 v[110:113], v[180:183], v[188:191], v[110:113]
	v_mfma_f32_16x16x32_bf16 v[98:101], v[172:175], v[196:199], v[98:101]
	v_mfma_f32_16x16x32_bf16 v[94:97], v[180:183], v[196:199], v[94:97]
	v_mfma_f32_16x16x32_bf16 v[82:85], v[172:175], v[204:207], v[82:85]
	v_mfma_f32_16x16x32_bf16 v[78:81], v[180:183], v[204:207], v[78:81]
	v_mfma_f32_16x16x32_bf16 v[70:73], v[172:175], v[212:215], v[70:73]
	v_mfma_f32_16x16x32_bf16 v[66:69], v[180:183], v[212:215], v[66:69]
	s_barrier
; #define PG8_STAGE(bufoff, gbase, voff) do { _Pragma("unroll") for (int _i = 0; _i < 2; ++_i) \
;         __builtin_amdgcn_global_load_lds((const unsigned*)((const char*)(gbase) + (voff)[_i]), (LAS unsigned*)(lds + (bufoff) + ldsw + _i * 8192), 16, 0, 0); } while (0)
; #define PG8_LDA(dst, b, h) do { _Pragma("unroll") for (int m = 0; m < 4; ++m) _Pragma("unroll") for (int k = 0; k < 2; ++k) dst[m][k] = *(const LAS bf16x8*)(lds + PG8_SA(b, h) + aoff + m * 2048 + k * 1024); } while (0)
; #define PG8_MMA(ai, bj, At, Bt) do { __builtin_amdgcn_s_setprio(1); _Pragma("unroll") for (int m = 0; m < 4; ++m) _Pragma("unroll") for (int n = 0; n < 2; ++n) _Pragma("unroll") for (int k = 0; k < 2; ++k) \
;         acc[ai][bj][m][n] = __builtin_amdgcn_mfma_f32_16x16x32_bf16(Bt[n][k], At[m][k], acc[ai][bj][m][n], 0, 0, 0); __builtin_amdgcn_s_setprio(0); } while (0)
; #define PG8_WAIT_V(n) asm volatile("s_waitcnt vmcnt(" #n ")" ::: "memory")
; #define PG8_WAIT_L(n) asm volatile("s_waitcnt lgkmcnt(" #n ")" ::: "memory")
; #define PG8_BAR __builtin_amdgcn_s_barrier()
; #define PG8_SCHED __builtin_amdgcn_sched_barrier(0)
; template <class Epi>
; __device__ __forceinline__ void gemm_phase(LAS unsigned char* lds, const Gemm g, int G, int c, const Epi& E) {
;     ...
;             PG8_LDA(At, 1, 1); PG8_STAGE(PG8_SB(1, 0), b3, voffB); PG8_STAGE(PG8_SB(1, 1), b3 + hstepB, voffB); PG8_STAGE(PG8_SA(1, 0), a3, voffA);
;             PG8_WAIT_V(8); PG8_WAIT_L(0); PG8_BAR; PG8_MMA(1, 0, At, B0); PG8_MMA(1, 1, At, B1); PG8_BAR; PG8_SCHED;
;         }
;         if (wr == 0) PG8_BAR;
	s_add_i32 s33, s33, s42
	v_lshl_add_u64 v[216:217], v[216:217], 0, s[10:11]
	s_mov_b32 m0, s33
	ds_read_b128 v[184:187], v170 offset:49152
	ds_read_b128 v[188:191], v170 offset:50176
	ds_read_b128 v[192:195], v170 offset:51200
	ds_read_b128 v[196:199], v170 offset:52224
	ds_read_b128 v[200:203], v170 offset:53248
	ds_read_b128 v[204:207], v170 offset:54272
	ds_read_b128 v[208:211], v170 offset:55296
	ds_read_b128 v[212:215], v170 offset:56320
	global_load_lds_dwordx4 v[216:217], off
	s_add_i32 m0, s33, 0x2000
	s_add_u32 s36, s36, 0x40080
	v_lshl_add_u64 v[216:217], v[218:219], 0, s[10:11]
	s_addc_u32 s37, s37, 0
	s_add_i32 s33, s63, s42
	global_load_lds_dwordx4 v[216:217], off
	v_lshl_add_u64 v[216:217], s[36:37], 0, v[150:151]
	s_mov_b32 m0, s33
	s_nop 0
	global_load_lds_dwordx4 v[216:217], off
	v_lshl_add_u64 v[216:217], s[36:37], 0, v[146:147]
	s_add_i32 m0, s33, 0x2000
	s_nop 0
	global_load_lds_dwordx4 v[216:217], off
	v_lshl_add_u64 v[216:217], v[220:221], 0, s[10:11]
	s_mov_b32 m0, s53
	s_nop 0
	global_load_lds_dwordx4 v[216:217], off
	v_lshl_add_u64 v[216:217], v[222:223], 0, s[10:11]
	s_mov_b32 m0, s54
	s_nop 0
	global_load_lds_dwordx4 v[216:217], off
	s_waitcnt vmcnt(8)
	s_waitcnt lgkmcnt(0)
	s_barrier
	s_waitcnt lgkmcnt(0)
	v_mfma_f32_16x16x32_bf16 v[62:65], v[122:125], v[184:187], v[62:65]
	v_mfma_f32_16x16x32_bf16 v[58:61], v[130:133], v[184:187], v[58:61]
	v_mfma_f32_16x16x32_bf16 v[54:57], v[122:125], v[192:195], v[54:57]
	v_mfma_f32_16x16x32_bf16 v[42:45], v[130:133], v[192:195], v[42:45]
	v_mfma_f32_16x16x32_bf16 v[38:41], v[122:125], v[200:203], v[38:41]
	v_mfma_f32_16x16x32_bf16 v[26:29], v[130:133], v[200:203], v[26:29]
	v_mfma_f32_16x16x32_bf16 v[22:25], v[122:125], v[208:211], v[22:25]
	v_mfma_f32_16x16x32_bf16 v[10:13], v[130:133], v[208:211], v[10:13]
	v_mfma_f32_16x16x32_bf16 v[62:65], v[126:129], v[188:191], v[62:65]
	v_mfma_f32_16x16x32_bf16 v[58:61], v[134:137], v[188:191], v[58:61]
	v_mfma_f32_16x16x32_bf16 v[54:57], v[126:129], v[196:199], v[54:57]
	v_mfma_f32_16x16x32_bf16 v[42:45], v[134:137], v[196:199], v[42:45]
	v_mfma_f32_16x16x32_bf16 v[38:41], v[126:129], v[204:207], v[38:41]
	v_mfma_f32_16x16x32_bf16 v[26:29], v[134:137], v[204:207], v[26:29]
	v_mfma_f32_16x16x32_bf16 v[22:25], v[126:129], v[212:215], v[22:25]
	v_mfma_f32_16x16x32_bf16 v[10:13], v[134:137], v[212:215], v[10:13]
	v_mfma_f32_16x16x32_bf16 v[50:53], v[162:165], v[184:187], v[50:53]
	v_mfma_f32_16x16x32_bf16 v[46:49], v[176:179], v[184:187], v[46:49]
	v_mfma_f32_16x16x32_bf16 v[34:37], v[162:165], v[192:195], v[34:37]
	v_mfma_f32_16x16x32_bf16 v[30:33], v[176:179], v[192:195], v[30:33]
	v_mfma_f32_16x16x32_bf16 v[18:21], v[162:165], v[200:203], v[18:21]
	v_mfma_f32_16x16x32_bf16 v[14:17], v[176:179], v[200:203], v[14:17]
	v_mfma_f32_16x16x32_bf16 v[6:9], v[162:165], v[208:211], v[6:9]
	v_mfma_f32_16x16x32_bf16 v[2:5], v[176:179], v[208:211], v[2:5]
	v_mfma_f32_16x16x32_bf16 v[50:53], v[172:175], v[188:191], v[50:53]
	v_mfma_f32_16x16x32_bf16 v[46:49], v[180:183], v[188:191], v[46:49]
	v_mfma_f32_16x16x32_bf16 v[34:37], v[172:175], v[196:199], v[34:37]
	v_mfma_f32_16x16x32_bf16 v[30:33], v[180:183], v[196:199], v[30:33]
	v_mfma_f32_16x16x32_bf16 v[18:21], v[172:175], v[204:207], v[18:21]
	v_mfma_f32_16x16x32_bf16 v[14:17], v[180:183], v[204:207], v[14:17]
	v_mfma_f32_16x16x32_bf16 v[6:9], v[172:175], v[212:215], v[6:9]
	v_mfma_f32_16x16x32_bf16 v[2:5], v[180:183], v[212:215], v[2:5]
	s_barrier
	s_add_i32 s62, s62, 2
	s_add_u32 s4, s4, 0x100
	s_addc_u32 s5, s5, 0
	s_add_u32 s60, s60, 0x100
	s_addc_u32 s61, s61, 0
	s_cmp_gt_u32 s62, 13
	s_cbranch_scc0 .LBB0_1931
	s_and_b64 vcc, exec, s[12:13]
	s_cbranch_vccz .LBB0_1934
	s_barrier

; #define PG8_STAGE(bufoff, gbase, voff) do { _Pragma("unroll") for (int _i = 0; _i < 2; ++_i) \
;         __builtin_amdgcn_global_load_lds((const unsigned*)((const char*)(gbase) + (voff)[_i]), (LAS unsigned*)(lds + (bufoff) + ldsw + _i * 8192), 16, 0, 0); } while (0)
; #define PG8_LDA(dst, b, h) do { _Pragma("unroll") for (int m = 0; m < 4; ++m) _Pragma("unroll") for (int k = 0; k < 2; ++k) dst[m][k] = *(const LAS bf16x8*)(lds + PG8_SA(b, h) + aoff + m * 2048 + k * 1024); } while (0)
; #define PG8_LDB(dst, b, h) do { _Pragma("unroll") for (int n = 0; n < 2; ++n) _Pragma("unroll") for (int k = 0; k < 2; ++k) dst[n][k] = *(const LAS bf16x8*)(lds + PG8_SB(b, h) + boff + n * 2048 + k * 1024); } while (0)
; #define PG8_MMA(ai, bj, At, Bt) do { __builtin_amdgcn_s_setprio(1); _Pragma("unroll") for (int m = 0; m < 4; ++m) _Pragma("unroll") for (int n = 0; n < 2; ++n) _Pragma("unroll") for (int k = 0; k < 2; ++k) \
;         acc[ai][bj][m][n] = __builtin_amdgcn_mfma_f32_16x16x32_bf16(Bt[n][k], At[m][k], acc[ai][bj][m][n], 0, 0, 0); __builtin_amdgcn_s_setprio(0); } while (0)
; #define PG8_WAIT_V(n) asm volatile("s_waitcnt vmcnt(" #n ")" ::: "memory")
; #define PG8_WAIT_L(n) asm volatile("s_waitcnt lgkmcnt(" #n ")" ::: "memory")
; #define PG8_BAR __builtin_amdgcn_s_barrier()
; #define PG8_SCHED __builtin_amdgcn_sched_barrier(0)
; template <class Epi>
; __device__ __forceinline__ void gemm_phase(LAS unsigned char* lds, const Gemm g, int G, int c, const Epi& E) {
;     ...
;             const bool last = (t == nt - 2);
;             const char* a1 = cA + (size_t)(t + 1) * kstep;
;             const char* a2 = last ? nA : cA + (size_t)(t + 2) * kstep; const char* b2 = last ? nB : cB + (size_t)(t + 2) * kstep;
;             const char* a3 = a2 + kstep; const char* b3 = b2 + kstep;
;             PG8_LDB(B0, 0, 0); PG8_LDB(B1, 0, 1); PG8_SCHED; PG8_LDA(At, 0, 0); PG8_STAGE(PG8_SA(1, 1), a1 + hstepA, voffA);
;             PG8_WAIT_V(8); PG8_WAIT_L(0); PG8_BAR; PG8_MMA(0, 0, At, B0); PG8_MMA(0, 1, At, B1); PG8_BAR; PG8_SCHED;
;             PG8_LDA(At, 0, 1); PG8_STAGE(PG8_SB(0, 0), b2, voffB); PG8_STAGE(PG8_SB(0, 1), b2 + hstepB, voffB); PG8_STAGE(PG8_SA(0, 0), a2, voffA);
.LBB0_2084:
	ds_read_b128 v[152:155], v148
	ds_read_b128 v[156:159], v148 offset:1024
	ds_read_b128 v[160:163], v148 offset:2048
	ds_read_b128 v[164:167], v148 offset:3072
	ds_read_b128 v[168:171], v149
	ds_read_b128 v[172:175], v149 offset:1024
	ds_read_b128 v[176:179], v149 offset:2048
	ds_read_b128 v[180:183], v149 offset:3072
	s_add_u32 s33, s4, 0xfffc0080
	s_addc_u32 s38, s5, -1
	s_cmp_eq_u32 s68, 12
	s_cselect_b32 s41, s21, s38
	s_cselect_b32 s40, s20, s33
	s_cselect_b32 s39, s17, s67
	s_cselect_b32 s38, s19, s66
	v_lshl_add_u64 v[216:217], s[4:5], 0, v[138:139]
	s_add_i32 m0, s25, 0xc000
	ds_read_b128 v[184:187], v150
	ds_read_b128 v[188:191], v150 offset:1024
	ds_read_b128 v[192:195], v150 offset:2048
	ds_read_b128 v[196:199], v150 offset:3072
	ds_read_b128 v[200:203], v150 offset:4096
	ds_read_b128 v[204:207], v150 offset:5120
	ds_read_b128 v[208:211], v150 offset:6144
	ds_read_b128 v[212:215], v150 offset:7168
	global_load_lds_dwordx4 v[216:217], off
	v_lshl_add_u64 v[216:217], s[4:5], 0, v[140:141]
	s_add_i32 m0, s25, 0xe000
	s_nop 0
	global_load_lds_dwordx4 v[216:217], off
	s_waitcnt vmcnt(8)
	s_waitcnt lgkmcnt(0)
	s_barrier
	s_waitcnt lgkmcnt(0)
	v_mfma_f32_16x16x32_bf16 v[126:129], v[152:155], v[184:187], v[126:129]
	v_mfma_f32_16x16x32_bf16 v[122:125], v[160:163], v[184:187], v[122:125]
	v_mfma_f32_16x16x32_bf16 v[110:113], v[152:155], v[192:195], v[110:113]
	v_mfma_f32_16x16x32_bf16 v[106:109], v[160:163], v[192:195], v[106:109]
	v_mfma_f32_16x16x32_bf16 v[94:97], v[152:155], v[200:203], v[94:97]
	v_mfma_f32_16x16x32_bf16 v[90:93], v[160:163], v[200:203], v[90:93]
	v_mfma_f32_16x16x32_bf16 v[78:81], v[152:155], v[208:211], v[78:81]
	v_mfma_f32_16x16x32_bf16 v[74:77], v[160:163], v[208:211], v[74:77]
	v_mfma_f32_16x16x32_bf16 v[126:129], v[156:159], v[188:191], v[126:129]
	v_mfma_f32_16x16x32_bf16 v[122:125], v[164:167], v[188:191], v[122:125]
	v_mfma_f32_16x16x32_bf16 v[110:113], v[156:159], v[196:199], v[110:113]
	v_mfma_f32_16x16x32_bf16 v[106:109], v[164:167], v[196:199], v[106:109]
	v_mfma_f32_16x16x32_bf16 v[94:97], v[156:159], v[204:207], v[94:97]
	v_mfma_f32_16x16x32_bf16 v[90:93], v[164:167], v[204:207], v[90:93]
	v_mfma_f32_16x16x32_bf16 v[78:81], v[156:159], v[212:215], v[78:81]
	v_mfma_f32_16x16x32_bf16 v[74:77], v[164:167], v[212:215], v[74:77]
	v_mfma_f32_16x16x32_bf16 v[118:121], v[168:171], v[184:187], v[118:121]
	v_mfma_f32_16x16x32_bf16 v[114:117], v[176:179], v[184:187], v[114:117]
	v_mfma_f32_16x16x32_bf16 v[102:105], v[168:171], v[192:195], v[102:105]
	v_mfma_f32_16x16x32_bf16 v[98:101], v[176:179], v[192:195], v[98:101]
	v_mfma_f32_16x16x32_bf16 v[86:89], v[168:171], v[200:203], v[86:89]
	v_mfma_f32_16x16x32_bf16 v[82:85], v[176:179], v[200:203], v[82:85]
	v_mfma_f32_16x16x32_bf16 v[70:73], v[168:171], v[208:211], v[70:73]
	v_mfma_f32_16x16x32_bf16 v[66:69], v[176:179], v[208:211], v[66:69]
	v_mfma_f32_16x16x32_bf16 v[118:121], v[172:175], v[188:191], v[118:121]
	v_mfma_f32_16x16x32_bf16 v[114:117], v[180:183], v[188:191], v[114:117]
	v_mfma_f32_16x16x32_bf16 v[102:105], v[172:175], v[196:199], v[102:105]
	v_mfma_f32_16x16x32_bf16 v[98:101], v[180:183], v[196:199], v[98:101]
	v_mfma_f32_16x16x32_bf16 v[86:89], v[172:175], v[204:207], v[86:89]
	v_mfma_f32_16x16x32_bf16 v[82:85], v[180:183], v[204:207], v[82:85]
	v_mfma_f32_16x16x32_bf16 v[70:73], v[172:175], v[212:215], v[70:73]
	v_mfma_f32_16x16x32_bf16 v[66:69], v[180:183], v[212:215], v[66:69]
	s_barrier
	s_add_i32 s33, s56, s46
	v_lshl_add_u64 v[216:217], s[38:39], 0, v[134:135]
	s_mov_b32 m0, s33
	ds_read_b128 v[184:187], v150 offset:16384
	ds_read_b128 v[188:191], v150 offset:17408
	ds_read_b128 v[192:195], v150 offset:18432
	ds_read_b128 v[196:199], v150 offset:19456
	ds_read_b128 v[200:203], v150 offset:20480
	ds_read_b128 v[204:207], v150 offset:21504
	ds_read_b128 v[208:211], v150 offset:22528
	ds_read_b128 v[212:215], v150 offset:23552
	global_load_lds_dwordx4 v[216:217], off
	s_add_i32 m0, s33, 0x2000
	s_add_u32 s70, s38, 0x40000
	v_lshl_add_u64 v[218:219], s[38:39], 0, v[130:131]
	s_addc_u32 s71, s39, 0
	s_add_i32 s33, s57, s46
	global_load_lds_dwordx4 v[218:219], off
	v_lshl_add_u64 v[220:221], s[70:71], 0, v[134:135]
	s_mov_b32 m0, s33
	v_lshl_add_u64 v[222:223], s[40:41], 0, v[132:133]
	global_load_lds_dwordx4 v[220:221], off
	v_lshl_add_u64 v[220:221], s[70:71], 0, v[130:131]
	s_add_i32 m0, s33, 0x2000
	s_nop 0
	global_load_lds_dwordx4 v[220:221], off
	v_lshl_add_u64 v[220:221], s[40:41], 0, v[136:137]
	s_mov_b32 m0, s25
	s_nop 0
	global_load_lds_dwordx4 v[220:221], off
	s_mov_b32 m0, s37
	s_nop 0
	global_load_lds_dwordx4 v[222:223], off
	s_waitcnt vmcnt(8)
	s_waitcnt lgkmcnt(0)
	s_barrier
; #define PG8_STAGE(bufoff, gbase, voff) do { _Pragma("unroll") for (int _i = 0; _i < 2; ++_i) \
;         __builtin_amdgcn_global_load_lds((const unsigned*)((const char*)(gbase) + (voff)[_i]), (LAS unsigned*)(lds + (bufoff) + ldsw + _i * 8192), 16, 0, 0); } while (0)
; #define PG8_LDA(dst, b, h) do { _Pragma("unroll") for (int m = 0; m < 4; ++m) _Pragma("unroll") for (int k = 0; k < 2; ++k) dst[m][k] = *(const LAS bf16x8*)(lds + PG8_SA(b, h) + aoff + m * 2048 + k * 1024); } while (0)
; #define PG8_LDB(dst, b, h) do { _Pragma("unroll") for (int n = 0; n < 2; ++n) _Pragma("unroll") for (int k = 0; k < 2; ++k) dst[n][k] = *(const LAS bf16x8*)(lds + PG8_SB(b, h) + boff + n * 2048 + k * 1024); } while (0)
; #define PG8_MMA(ai, bj, At, Bt) do { __builtin_amdgcn_s_setprio(1); _Pragma("unroll") for (int m = 0; m < 4; ++m) _Pragma("unroll") for (int n = 0; n < 2; ++n) _Pragma("unroll") for (int k = 0; k < 2; ++k) \
;         acc[ai][bj][m][n] = __builtin_amdgcn_mfma_f32_16x16x32_bf16(Bt[n][k], At[m][k], acc[ai][bj][m][n], 0, 0, 0); __builtin_amdgcn_s_setprio(0); } while (0)
; #define PG8_WAIT_V(n) asm volatile("s_waitcnt vmcnt(" #n ")" ::: "memory")
; #define PG8_WAIT_L(n) asm volatile("s_waitcnt lgkmcnt(" #n ")" ::: "memory")
; #define PG8_BAR __builtin_amdgcn_s_barrier()
; #define PG8_SCHED __builtin_amdgcn_sched_barrier(0)
; template <class Epi>
; __device__ __forceinline__ void gemm_phase(LAS unsigned char* lds, const Gemm g, int G, int c, const Epi& E) {
;     ...
;             PG8_WAIT_V(8); PG8_WAIT_L(0); PG8_BAR; PG8_MMA(1, 0, At, B0); PG8_MMA(1, 1, At, B1); PG8_BAR; PG8_SCHED;
;             PG8_LDB(B0, 1, 0); PG8_LDB(B1, 1, 1); PG8_SCHED; PG8_LDA(At, 1, 0); PG8_STAGE(PG8_SA(0, 1), a2 + hstepA, voffA);
;             PG8_WAIT_V(8); PG8_WAIT_L(0); PG8_BAR; PG8_MMA(0, 0, At, B0); PG8_MMA(0, 1, At, B1); PG8_BAR; PG8_SCHED;
	s_waitcnt lgkmcnt(0)
	v_mfma_f32_16x16x32_bf16 v[62:65], v[152:155], v[184:187], v[62:65]
	v_mfma_f32_16x16x32_bf16 v[58:61], v[160:163], v[184:187], v[58:61]
	v_mfma_f32_16x16x32_bf16 v[46:49], v[152:155], v[192:195], v[46:49]
	v_mfma_f32_16x16x32_bf16 v[42:45], v[160:163], v[192:195], v[42:45]
	v_mfma_f32_16x16x32_bf16 v[30:33], v[152:155], v[200:203], v[30:33]
	v_mfma_f32_16x16x32_bf16 v[26:29], v[160:163], v[200:203], v[26:29]
	v_mfma_f32_16x16x32_bf16 v[14:17], v[152:155], v[208:211], v[14:17]
	v_mfma_f32_16x16x32_bf16 v[10:13], v[160:163], v[208:211], v[10:13]
	v_mfma_f32_16x16x32_bf16 v[62:65], v[156:159], v[188:191], v[62:65]
	v_mfma_f32_16x16x32_bf16 v[58:61], v[164:167], v[188:191], v[58:61]
	v_mfma_f32_16x16x32_bf16 v[46:49], v[156:159], v[196:199], v[46:49]
	v_mfma_f32_16x16x32_bf16 v[42:45], v[164:167], v[196:199], v[42:45]
	v_mfma_f32_16x16x32_bf16 v[30:33], v[156:159], v[204:207], v[30:33]
	v_mfma_f32_16x16x32_bf16 v[26:29], v[164:167], v[204:207], v[26:29]
	v_mfma_f32_16x16x32_bf16 v[14:17], v[156:159], v[212:215], v[14:17]
	v_mfma_f32_16x16x32_bf16 v[10:13], v[164:167], v[212:215], v[10:13]
	v_mfma_f32_16x16x32_bf16 v[54:57], v[168:171], v[184:187], v[54:57]
	v_mfma_f32_16x16x32_bf16 v[50:53], v[176:179], v[184:187], v[50:53]
	v_mfma_f32_16x16x32_bf16 v[38:41], v[168:171], v[192:195], v[38:41]
	v_mfma_f32_16x16x32_bf16 v[34:37], v[176:179], v[192:195], v[34:37]
	v_mfma_f32_16x16x32_bf16 v[22:25], v[168:171], v[200:203], v[22:25]
	v_mfma_f32_16x16x32_bf16 v[18:21], v[176:179], v[200:203], v[18:21]
	v_mfma_f32_16x16x32_bf16 v[6:9], v[168:171], v[208:211], v[6:9]
	v_mfma_f32_16x16x32_bf16 v[2:5], v[176:179], v[208:211], v[2:5]
	v_mfma_f32_16x16x32_bf16 v[54:57], v[172:175], v[188:191], v[54:57]
	v_mfma_f32_16x16x32_bf16 v[50:53], v[180:183], v[188:191], v[50:53]
	v_mfma_f32_16x16x32_bf16 v[38:41], v[172:175], v[196:199], v[38:41]
	v_mfma_f32_16x16x32_bf16 v[34:37], v[180:183], v[196:199], v[34:37]
	v_mfma_f32_16x16x32_bf16 v[22:25], v[172:175], v[204:207], v[22:25]
	v_mfma_f32_16x16x32_bf16 v[18:21], v[180:183], v[204:207], v[18:21]
	v_mfma_f32_16x16x32_bf16 v[6:9], v[172:175], v[212:215], v[6:9]
	v_mfma_f32_16x16x32_bf16 v[2:5], v[180:183], v[212:215], v[2:5]
	s_barrier
	s_add_i32 s33, 0, 0x18000
	s_add_i32 s69, 0, 0x1c000
	v_add_u32_e32 v164, s33, v147
	v_add_u32_e32 v180, s69, v147
	ds_read_b128 v[152:155], v164
	ds_read_b128 v[156:159], v164 offset:1024
	ds_read_b128 v[160:163], v164 offset:2048
	ds_read_b128 v[164:167], v164 offset:3072
	ds_read_b128 v[168:171], v180
	ds_read_b128 v[172:175], v180 offset:1024
	ds_read_b128 v[176:179], v180 offset:2048
	ds_read_b128 v[180:183], v180 offset:3072
	s_add_u32 s40, s40, 0x40000
	s_addc_u32 s41, s41, 0
	s_mov_b32 m0, s47
	v_lshl_add_u64 v[224:225], s[40:41], 0, v[136:137]
	ds_read_b128 v[184:187], v150 offset:32768
	ds_read_b128 v[188:191], v150 offset:33792
	ds_read_b128 v[192:195], v150 offset:34816
	ds_read_b128 v[196:199], v150 offset:35840
	ds_read_b128 v[200:203], v150 offset:36864
	ds_read_b128 v[204:207], v150 offset:37888
	ds_read_b128 v[208:211], v150 offset:38912
	ds_read_b128 v[212:215], v150 offset:39936
	global_load_lds_dwordx4 v[224:225], off
	v_lshl_add_u64 v[224:225], s[40:41], 0, v[132:133]
	s_mov_b32 m0, s48
	s_nop 0
	global_load_lds_dwordx4 v[224:225], off
	s_waitcnt vmcnt(8)
	s_waitcnt lgkmcnt(0)
	s_barrier
	s_waitcnt lgkmcnt(0)
	v_mfma_f32_16x16x32_bf16 v[126:129], v[152:155], v[184:187], v[126:129]
	v_mfma_f32_16x16x32_bf16 v[122:125], v[160:163], v[184:187], v[122:125]
	v_mfma_f32_16x16x32_bf16 v[110:113], v[152:155], v[192:195], v[110:113]
	v_mfma_f32_16x16x32_bf16 v[106:109], v[160:163], v[192:195], v[106:109]
	v_mfma_f32_16x16x32_bf16 v[94:97], v[152:155], v[200:203], v[94:97]
	v_mfma_f32_16x16x32_bf16 v[90:93], v[160:163], v[200:203], v[90:93]
	v_mfma_f32_16x16x32_bf16 v[78:81], v[152:155], v[208:211], v[78:81]
	v_mfma_f32_16x16x32_bf16 v[74:77], v[160:163], v[208:211], v[74:77]
	v_mfma_f32_16x16x32_bf16 v[126:129], v[156:159], v[188:191], v[126:129]
	v_mfma_f32_16x16x32_bf16 v[122:125], v[164:167], v[188:191], v[122:125]
	v_mfma_f32_16x16x32_bf16 v[110:113], v[156:159], v[196:199], v[110:113]
	v_mfma_f32_16x16x32_bf16 v[106:109], v[164:167], v[196:199], v[106:109]
	v_mfma_f32_16x16x32_bf16 v[94:97], v[156:159], v[204:207], v[94:97]
	v_mfma_f32_16x16x32_bf16 v[90:93], v[164:167], v[204:207], v[90:93]
	v_mfma_f32_16x16x32_bf16 v[78:81], v[156:159], v[212:215], v[78:81]
	v_mfma_f32_16x16x32_bf16 v[74:77], v[164:167], v[212:215], v[74:77]
	v_mfma_f32_16x16x32_bf16 v[118:121], v[168:171], v[184:187], v[118:121]
	v_mfma_f32_16x16x32_bf16 v[114:117], v[176:179], v[184:187], v[114:117]
	v_mfma_f32_16x16x32_bf16 v[102:105], v[168:171], v[192:195], v[102:105]
	v_mfma_f32_16x16x32_bf16 v[98:101], v[176:179], v[192:195], v[98:101]
	v_mfma_f32_16x16x32_bf16 v[86:89], v[168:171], v[200:203], v[86:89]
	v_mfma_f32_16x16x32_bf16 v[82:85], v[176:179], v[200:203], v[82:85]
	v_mfma_f32_16x16x32_bf16 v[70:73], v[168:171], v[208:211], v[70:73]
	v_mfma_f32_16x16x32_bf16 v[66:69], v[176:179], v[208:211], v[66:69]
	v_mfma_f32_16x16x32_bf16 v[118:121], v[172:175], v[188:191], v[118:121]
	v_mfma_f32_16x16x32_bf16 v[114:117], v[180:183], v[188:191], v[114:117]
	v_mfma_f32_16x16x32_bf16 v[102:105], v[172:175], v[196:199], v[102:105]
	v_mfma_f32_16x16x32_bf16 v[98:101], v[180:183], v[196:199], v[98:101]
	v_mfma_f32_16x16x32_bf16 v[86:89], v[172:175], v[204:207], v[86:89]
	v_mfma_f32_16x16x32_bf16 v[82:85], v[180:183], v[204:207], v[82:85]
	v_mfma_f32_16x16x32_bf16 v[70:73], v[172:175], v[212:215], v[70:73]
	v_mfma_f32_16x16x32_bf16 v[66:69], v[180:183], v[212:215], v[66:69]
	s_barrier
; #define PG8_STAGE(bufoff, gbase, voff) do { _Pragma("unroll") for (int _i = 0; _i < 2; ++_i) \
;         __builtin_amdgcn_global_load_lds((const unsigned*)((const char*)(gbase) + (voff)[_i]), (LAS unsigned*)(lds + (bufoff) + ldsw + _i * 8192), 16, 0, 0); } while (0)
; #define PG8_LDA(dst, b, h) do { _Pragma("unroll") for (int m = 0; m < 4; ++m) _Pragma("unroll") for (int k = 0; k < 2; ++k) dst[m][k] = *(const LAS bf16x8*)(lds + PG8_SA(b, h) + aoff + m * 2048 + k * 1024); } while (0)
; #define PG8_MMA(ai, bj, At, Bt) do { __builtin_amdgcn_s_setprio(1); _Pragma("unroll") for (int m = 0; m < 4; ++m) _Pragma("unroll") for (int n = 0; n < 2; ++n) _Pragma("unroll") for (int k = 0; k < 2; ++k) \
;         acc[ai][bj][m][n] = __builtin_amdgcn_mfma_f32_16x16x32_bf16(Bt[n][k], At[m][k], acc[ai][bj][m][n], 0, 0, 0); __builtin_amdgcn_s_setprio(0); } while (0)
; #define PG8_WAIT_V(n) asm volatile("s_waitcnt vmcnt(" #n ")" ::: "memory")
; #define PG8_WAIT_L(n) asm volatile("s_waitcnt lgkmcnt(" #n ")" ::: "memory")
; #define PG8_BAR __builtin_amdgcn_s_barrier()
; #define PG8_SCHED __builtin_amdgcn_sched_barrier(0)
; template <class Epi>
; __device__ __forceinline__ void gemm_phase(LAS unsigned char* lds, const Gemm g, int G, int c, const Epi& E) {
;     ...
;             PG8_LDA(At, 1, 1); PG8_STAGE(PG8_SB(1, 0), b3, voffB); PG8_STAGE(PG8_SB(1, 1), b3 + hstepB, voffB); PG8_STAGE(PG8_SA(1, 0), a3, voffA);
;             PG8_WAIT_V(8); PG8_WAIT_L(0); PG8_BAR; PG8_MMA(1, 0, At, B0); PG8_MMA(1, 1, At, B1); PG8_BAR; PG8_SCHED;
;         }
;         if (wr == 0) PG8_BAR;
	s_add_i32 s33, s33, s46
	v_lshl_add_u64 v[216:217], v[216:217], 0, s[12:13]
	s_mov_b32 m0, s33
	ds_read_b128 v[184:187], v150 offset:49152
	ds_read_b128 v[188:191], v150 offset:50176
	ds_read_b128 v[192:195], v150 offset:51200
	ds_read_b128 v[196:199], v150 offset:52224
	ds_read_b128 v[200:203], v150 offset:53248
	ds_read_b128 v[204:207], v150 offset:54272
	ds_read_b128 v[208:211], v150 offset:55296
	ds_read_b128 v[212:215], v150 offset:56320
	global_load_lds_dwordx4 v[216:217], off
	s_add_i32 m0, s33, 0x2000
	s_add_u32 s38, s38, 0x40080
	v_lshl_add_u64 v[216:217], v[218:219], 0, s[12:13]
	s_addc_u32 s39, s39, 0
	s_add_i32 s33, s69, s46
	global_load_lds_dwordx4 v[216:217], off
	v_lshl_add_u64 v[216:217], s[38:39], 0, v[134:135]
	s_mov_b32 m0, s33
	s_nop 0
	global_load_lds_dwordx4 v[216:217], off
	v_lshl_add_u64 v[216:217], s[38:39], 0, v[130:131]
	s_add_i32 m0, s33, 0x2000
	s_nop 0
	global_load_lds_dwordx4 v[216:217], off
	v_lshl_add_u64 v[216:217], v[220:221], 0, s[12:13]
	s_mov_b32 m0, s53
	s_nop 0
	global_load_lds_dwordx4 v[216:217], off
	v_lshl_add_u64 v[216:217], v[222:223], 0, s[12:13]
	s_mov_b32 m0, s54
	s_nop 0
	global_load_lds_dwordx4 v[216:217], off
	s_waitcnt vmcnt(8)
	s_waitcnt lgkmcnt(0)
	s_barrier
	s_waitcnt lgkmcnt(0)
	v_mfma_f32_16x16x32_bf16 v[62:65], v[152:155], v[184:187], v[62:65]
	v_mfma_f32_16x16x32_bf16 v[58:61], v[160:163], v[184:187], v[58:61]
	v_mfma_f32_16x16x32_bf16 v[46:49], v[152:155], v[192:195], v[46:49]
	v_mfma_f32_16x16x32_bf16 v[42:45], v[160:163], v[192:195], v[42:45]
	v_mfma_f32_16x16x32_bf16 v[30:33], v[152:155], v[200:203], v[30:33]
	v_mfma_f32_16x16x32_bf16 v[26:29], v[160:163], v[200:203], v[26:29]
	v_mfma_f32_16x16x32_bf16 v[14:17], v[152:155], v[208:211], v[14:17]
	v_mfma_f32_16x16x32_bf16 v[10:13], v[160:163], v[208:211], v[10:13]
	v_mfma_f32_16x16x32_bf16 v[62:65], v[156:159], v[188:191], v[62:65]
	v_mfma_f32_16x16x32_bf16 v[58:61], v[164:167], v[188:191], v[58:61]
	v_mfma_f32_16x16x32_bf16 v[46:49], v[156:159], v[196:199], v[46:49]
	v_mfma_f32_16x16x32_bf16 v[42:45], v[164:167], v[196:199], v[42:45]
	v_mfma_f32_16x16x32_bf16 v[30:33], v[156:159], v[204:207], v[30:33]
	v_mfma_f32_16x16x32_bf16 v[26:29], v[164:167], v[204:207], v[26:29]
	v_mfma_f32_16x16x32_bf16 v[14:17], v[156:159], v[212:215], v[14:17]
	v_mfma_f32_16x16x32_bf16 v[10:13], v[164:167], v[212:215], v[10:13]
	v_mfma_f32_16x16x32_bf16 v[54:57], v[168:171], v[184:187], v[54:57]
	v_mfma_f32_16x16x32_bf16 v[50:53], v[176:179], v[184:187], v[50:53]
	v_mfma_f32_16x16x32_bf16 v[38:41], v[168:171], v[192:195], v[38:41]
	v_mfma_f32_16x16x32_bf16 v[34:37], v[176:179], v[192:195], v[34:37]
	v_mfma_f32_16x16x32_bf16 v[22:25], v[168:171], v[200:203], v[22:25]
	v_mfma_f32_16x16x32_bf16 v[18:21], v[176:179], v[200:203], v[18:21]
	v_mfma_f32_16x16x32_bf16 v[6:9], v[168:171], v[208:211], v[6:9]
	v_mfma_f32_16x16x32_bf16 v[2:5], v[176:179], v[208:211], v[2:5]
	v_mfma_f32_16x16x32_bf16 v[54:57], v[172:175], v[188:191], v[54:57]
	v_mfma_f32_16x16x32_bf16 v[50:53], v[180:183], v[188:191], v[50:53]
	v_mfma_f32_16x16x32_bf16 v[38:41], v[172:175], v[196:199], v[38:41]
	v_mfma_f32_16x16x32_bf16 v[34:37], v[180:183], v[196:199], v[34:37]
	v_mfma_f32_16x16x32_bf16 v[22:25], v[172:175], v[204:207], v[22:25]
	v_mfma_f32_16x16x32_bf16 v[18:21], v[180:183], v[204:207], v[18:21]
	v_mfma_f32_16x16x32_bf16 v[6:9], v[172:175], v[212:215], v[6:9]
	v_mfma_f32_16x16x32_bf16 v[2:5], v[180:183], v[212:215], v[2:5]
	s_barrier
	s_add_i32 s68, s68, 2
	s_add_u32 s4, s4, 0x100
	s_addc_u32 s5, s5, 0
	s_add_u32 s66, s66, 0x100
	s_addc_u32 s67, s67, 0
	s_cmp_gt_u32 s68, 13
	s_cbranch_scc0 .LBB0_2084
	s_and_b64 vcc, exec, s[14:15]
	s_cbranch_vccz .LBB0_2087
	s_barrier

; #define PG8_STAGE(bufoff, gbase, voff) do { _Pragma("unroll") for (int _i = 0; _i < 2; ++_i) \
;         __builtin_amdgcn_global_load_lds((const unsigned*)((const char*)(gbase) + (voff)[_i]), (LAS unsigned*)(lds + (bufoff) + ldsw + _i * 8192), 16, 0, 0); } while (0)
; #define PG8_LDA(dst, b, h) do { _Pragma("unroll") for (int m = 0; m < 4; ++m) _Pragma("unroll") for (int k = 0; k < 2; ++k) dst[m][k] = *(const LAS bf16x8*)(lds + PG8_SA(b, h) + aoff + m * 2048 + k * 1024); } while (0)
; #define PG8_LDB(dst, b, h) do { _Pragma("unroll") for (int n = 0; n < 2; ++n) _Pragma("unroll") for (int k = 0; k < 2; ++k) dst[n][k] = *(const LAS bf16x8*)(lds + PG8_SB(b, h) + boff + n * 2048 + k * 1024); } while (0)
; #define PG8_MMA(ai, bj, At, Bt) do { __builtin_amdgcn_s_setprio(1); _Pragma("unroll") for (int m = 0; m < 4; ++m) _Pragma("unroll") for (int n = 0; n < 2; ++n) _Pragma("unroll") for (int k = 0; k < 2; ++k) \
;         acc[ai][bj][m][n] = __builtin_amdgcn_mfma_f32_16x16x32_bf16(Bt[n][k], At[m][k], acc[ai][bj][m][n], 0, 0, 0); __builtin_amdgcn_s_setprio(0); } while (0)
; #define PG8_WAIT_V(n) asm volatile("s_waitcnt vmcnt(" #n ")" ::: "memory")
; #define PG8_WAIT_L(n) asm volatile("s_waitcnt lgkmcnt(" #n ")" ::: "memory")
; #define PG8_BAR __builtin_amdgcn_s_barrier()
; #define PG8_SCHED __builtin_amdgcn_sched_barrier(0)
; template <class Epi>
; __device__ __forceinline__ void gemm_phase(LAS unsigned char* lds, const Gemm g, int G, int c, const Epi& E) {
;     ...
;             const bool last = (t == nt - 2);
;             const char* a1 = cA + (size_t)(t + 1) * kstep;
;             const char* a2 = last ? nA : cA + (size_t)(t + 2) * kstep; const char* b2 = last ? nB : cB + (size_t)(t + 2) * kstep;
;             const char* a3 = a2 + kstep; const char* b3 = b2 + kstep;
;             PG8_LDB(B0, 0, 0); PG8_LDB(B1, 0, 1); PG8_SCHED; PG8_LDA(At, 0, 0); PG8_STAGE(PG8_SA(1, 1), a1 + hstepA, voffA);
;             PG8_WAIT_V(8); PG8_WAIT_L(0); PG8_BAR; PG8_MMA(0, 0, At, B0); PG8_MMA(0, 1, At, B1); PG8_BAR; PG8_SCHED;
;             PG8_LDA(At, 0, 1); PG8_STAGE(PG8_SB(0, 0), b2, voffB); PG8_STAGE(PG8_SB(0, 1), b2 + hstepB, voffB); PG8_STAGE(PG8_SA(0, 0), a2, voffA);
.LBB0_2169:
	ds_read_b128 v[106:109], v168
	ds_read_b128 v[110:113], v168 offset:1024
	ds_read_b128 v[114:117], v168 offset:2048
	ds_read_b128 v[118:121], v168 offset:3072
	ds_read_b128 v[162:165], v169
	ds_read_b128 v[172:175], v169 offset:1024
	ds_read_b128 v[176:179], v169 offset:2048
	ds_read_b128 v[180:183], v169 offset:3072
	s_add_u32 s20, s18, 0x100
	s_addc_u32 s21, s19, 0
	s_cmp_eq_u32 s62, 40
	s_cselect_b32 s25, s5, s21
	s_cselect_b32 s24, s4, s20
	s_cselect_b32 s23, s17, s61
	s_cselect_b32 s22, s16, s60
	v_lshl_add_u64 v[216:217], s[18:19], 0, v[154:155]
	s_add_i32 m0, s40, 0xc000
	ds_read_b128 v[184:187], v170
	ds_read_b128 v[188:191], v170 offset:1024
	ds_read_b128 v[192:195], v170 offset:2048
	ds_read_b128 v[196:199], v170 offset:3072
	ds_read_b128 v[200:203], v170 offset:4096
	ds_read_b128 v[204:207], v170 offset:5120
	ds_read_b128 v[208:211], v170 offset:6144
	ds_read_b128 v[212:215], v170 offset:7168
	global_load_lds_dwordx4 v[216:217], off
	v_lshl_add_u64 v[216:217], s[18:19], 0, v[156:157]
	s_add_i32 m0, s40, 0xe000
	s_nop 0
	global_load_lds_dwordx4 v[216:217], off
	s_waitcnt vmcnt(8)
	s_waitcnt lgkmcnt(0)
	s_barrier
	s_waitcnt lgkmcnt(0)
	v_mfma_f32_16x16x32_bf16 v[142:145], v[106:109], v[184:187], v[142:145]
	v_mfma_f32_16x16x32_bf16 v[138:141], v[114:117], v[184:187], v[138:141]
	v_mfma_f32_16x16x32_bf16 v[126:129], v[106:109], v[192:195], v[126:129]
	v_mfma_f32_16x16x32_bf16 v[122:125], v[114:117], v[192:195], v[122:125]
	v_mfma_f32_16x16x32_bf16 v[94:97], v[106:109], v[200:203], v[94:97]
	v_mfma_f32_16x16x32_bf16 v[90:93], v[114:117], v[200:203], v[90:93]
	v_mfma_f32_16x16x32_bf16 v[78:81], v[106:109], v[208:211], v[78:81]
	v_mfma_f32_16x16x32_bf16 v[74:77], v[114:117], v[208:211], v[74:77]
	v_mfma_f32_16x16x32_bf16 v[142:145], v[110:113], v[188:191], v[142:145]
	v_mfma_f32_16x16x32_bf16 v[138:141], v[118:121], v[188:191], v[138:141]
	v_mfma_f32_16x16x32_bf16 v[126:129], v[110:113], v[196:199], v[126:129]
	v_mfma_f32_16x16x32_bf16 v[122:125], v[118:121], v[196:199], v[122:125]
	v_mfma_f32_16x16x32_bf16 v[94:97], v[110:113], v[204:207], v[94:97]
	v_mfma_f32_16x16x32_bf16 v[90:93], v[118:121], v[204:207], v[90:93]
	v_mfma_f32_16x16x32_bf16 v[78:81], v[110:113], v[212:215], v[78:81]
	v_mfma_f32_16x16x32_bf16 v[74:77], v[118:121], v[212:215], v[74:77]
	v_mfma_f32_16x16x32_bf16 v[134:137], v[162:165], v[184:187], v[134:137]
	v_mfma_f32_16x16x32_bf16 v[130:133], v[176:179], v[184:187], v[130:133]
	v_mfma_f32_16x16x32_bf16 v[102:105], v[162:165], v[192:195], v[102:105]
	v_mfma_f32_16x16x32_bf16 v[98:101], v[176:179], v[192:195], v[98:101]
	v_mfma_f32_16x16x32_bf16 v[86:89], v[162:165], v[200:203], v[86:89]
	v_mfma_f32_16x16x32_bf16 v[82:85], v[176:179], v[200:203], v[82:85]
	v_mfma_f32_16x16x32_bf16 v[70:73], v[162:165], v[208:211], v[70:73]
	v_mfma_f32_16x16x32_bf16 v[66:69], v[176:179], v[208:211], v[66:69]
	v_mfma_f32_16x16x32_bf16 v[134:137], v[172:175], v[188:191], v[134:137]
	v_mfma_f32_16x16x32_bf16 v[130:133], v[180:183], v[188:191], v[130:133]
	v_mfma_f32_16x16x32_bf16 v[102:105], v[172:175], v[196:199], v[102:105]
	v_mfma_f32_16x16x32_bf16 v[98:101], v[180:183], v[196:199], v[98:101]
	v_mfma_f32_16x16x32_bf16 v[86:89], v[172:175], v[204:207], v[86:89]
	v_mfma_f32_16x16x32_bf16 v[82:85], v[180:183], v[204:207], v[82:85]
	v_mfma_f32_16x16x32_bf16 v[70:73], v[172:175], v[212:215], v[70:73]
	v_mfma_f32_16x16x32_bf16 v[66:69], v[180:183], v[212:215], v[66:69]
	s_barrier
	s_add_i32 s18, s52, s38
	v_lshl_add_u64 v[216:217], s[22:23], 0, v[150:151]
	s_mov_b32 m0, s18
	ds_read_b128 v[184:187], v170 offset:16384
	ds_read_b128 v[188:191], v170 offset:17408
	ds_read_b128 v[192:195], v170 offset:18432
	ds_read_b128 v[196:199], v170 offset:19456
	ds_read_b128 v[200:203], v170 offset:20480
	ds_read_b128 v[204:207], v170 offset:21504
	ds_read_b128 v[208:211], v170 offset:22528
	ds_read_b128 v[212:215], v170 offset:23552
	global_load_lds_dwordx4 v[216:217], off
	s_add_i32 m0, s18, 0x2000
	s_add_u32 s18, s22, 0xb0000
	v_lshl_add_u64 v[218:219], s[22:23], 0, v[146:147]
	s_addc_u32 s19, s23, 0
	s_add_i32 s33, s53, s38
	global_load_lds_dwordx4 v[218:219], off
	v_lshl_add_u64 v[220:221], s[18:19], 0, v[150:151]
	s_mov_b32 m0, s33
	v_lshl_add_u64 v[222:223], s[24:25], 0, v[148:149]
	global_load_lds_dwordx4 v[220:221], off
	v_lshl_add_u64 v[220:221], s[18:19], 0, v[146:147]
	s_add_i32 m0, s33, 0x2000
	s_nop 0
	global_load_lds_dwordx4 v[220:221], off
	v_lshl_add_u64 v[220:221], s[24:25], 0, v[152:153]
	s_mov_b32 m0, s40
	s_nop 0
	global_load_lds_dwordx4 v[220:221], off
	s_mov_b32 m0, s41
	s_nop 0
	global_load_lds_dwordx4 v[222:223], off
	s_waitcnt vmcnt(8)
	s_waitcnt lgkmcnt(0)
	s_barrier
; #define PG8_STAGE(bufoff, gbase, voff) do { _Pragma("unroll") for (int _i = 0; _i < 2; ++_i) \
;         __builtin_amdgcn_global_load_lds((const unsigned*)((const char*)(gbase) + (voff)[_i]), (LAS unsigned*)(lds + (bufoff) + ldsw + _i * 8192), 16, 0, 0); } while (0)
; #define PG8_LDA(dst, b, h) do { _Pragma("unroll") for (int m = 0; m < 4; ++m) _Pragma("unroll") for (int k = 0; k < 2; ++k) dst[m][k] = *(const LAS bf16x8*)(lds + PG8_SA(b, h) + aoff + m * 2048 + k * 1024); } while (0)
; #define PG8_LDB(dst, b, h) do { _Pragma("unroll") for (int n = 0; n < 2; ++n) _Pragma("unroll") for (int k = 0; k < 2; ++k) dst[n][k] = *(const LAS bf16x8*)(lds + PG8_SB(b, h) + boff + n * 2048 + k * 1024); } while (0)
; #define PG8_MMA(ai, bj, At, Bt) do { __builtin_amdgcn_s_setprio(1); _Pragma("unroll") for (int m = 0; m < 4; ++m) _Pragma("unroll") for (int n = 0; n < 2; ++n) _Pragma("unroll") for (int k = 0; k < 2; ++k) \
;         acc[ai][bj][m][n] = __builtin_amdgcn_mfma_f32_16x16x32_bf16(Bt[n][k], At[m][k], acc[ai][bj][m][n], 0, 0, 0); __builtin_amdgcn_s_setprio(0); } while (0)
; #define PG8_WAIT_V(n) asm volatile("s_waitcnt vmcnt(" #n ")" ::: "memory")
; #define PG8_WAIT_L(n) asm volatile("s_waitcnt lgkmcnt(" #n ")" ::: "memory")
; #define PG8_BAR __builtin_amdgcn_s_barrier()
; #define PG8_SCHED __builtin_amdgcn_sched_barrier(0)
; template <class Epi>
; __device__ __forceinline__ void gemm_phase(LAS unsigned char* lds, const Gemm g, int G, int c, const Epi& E) {
;     ...
;             PG8_WAIT_V(8); PG8_WAIT_L(0); PG8_BAR; PG8_MMA(1, 0, At, B0); PG8_MMA(1, 1, At, B1); PG8_BAR; PG8_SCHED;
;             PG8_LDB(B0, 1, 0); PG8_LDB(B1, 1, 1); PG8_SCHED; PG8_LDA(At, 1, 0); PG8_STAGE(PG8_SA(0, 1), a2 + hstepA, voffA);
;             PG8_WAIT_V(8); PG8_WAIT_L(0); PG8_BAR; PG8_MMA(0, 0, At, B0); PG8_MMA(0, 1, At, B1); PG8_BAR; PG8_SCHED;
	s_waitcnt lgkmcnt(0)
	v_mfma_f32_16x16x32_bf16 v[62:65], v[106:109], v[184:187], v[62:65]
	v_mfma_f32_16x16x32_bf16 v[58:61], v[114:117], v[184:187], v[58:61]
	v_mfma_f32_16x16x32_bf16 v[46:49], v[106:109], v[192:195], v[46:49]
	v_mfma_f32_16x16x32_bf16 v[42:45], v[114:117], v[192:195], v[42:45]
	v_mfma_f32_16x16x32_bf16 v[30:33], v[106:109], v[200:203], v[30:33]
	v_mfma_f32_16x16x32_bf16 v[26:29], v[114:117], v[200:203], v[26:29]
	v_mfma_f32_16x16x32_bf16 v[14:17], v[106:109], v[208:211], v[14:17]
	v_mfma_f32_16x16x32_bf16 v[10:13], v[114:117], v[208:211], v[10:13]
	v_mfma_f32_16x16x32_bf16 v[62:65], v[110:113], v[188:191], v[62:65]
	v_mfma_f32_16x16x32_bf16 v[58:61], v[118:121], v[188:191], v[58:61]
	v_mfma_f32_16x16x32_bf16 v[46:49], v[110:113], v[196:199], v[46:49]
	v_mfma_f32_16x16x32_bf16 v[42:45], v[118:121], v[196:199], v[42:45]
	v_mfma_f32_16x16x32_bf16 v[30:33], v[110:113], v[204:207], v[30:33]
	v_mfma_f32_16x16x32_bf16 v[26:29], v[118:121], v[204:207], v[26:29]
	v_mfma_f32_16x16x32_bf16 v[14:17], v[110:113], v[212:215], v[14:17]
	v_mfma_f32_16x16x32_bf16 v[10:13], v[118:121], v[212:215], v[10:13]
	v_mfma_f32_16x16x32_bf16 v[54:57], v[162:165], v[184:187], v[54:57]
	v_mfma_f32_16x16x32_bf16 v[50:53], v[176:179], v[184:187], v[50:53]
	v_mfma_f32_16x16x32_bf16 v[38:41], v[162:165], v[192:195], v[38:41]
	v_mfma_f32_16x16x32_bf16 v[34:37], v[176:179], v[192:195], v[34:37]
	v_mfma_f32_16x16x32_bf16 v[22:25], v[162:165], v[200:203], v[22:25]
	v_mfma_f32_16x16x32_bf16 v[18:21], v[176:179], v[200:203], v[18:21]
	v_mfma_f32_16x16x32_bf16 v[6:9], v[162:165], v[208:211], v[6:9]
	v_mfma_f32_16x16x32_bf16 v[2:5], v[176:179], v[208:211], v[2:5]
	v_mfma_f32_16x16x32_bf16 v[54:57], v[172:175], v[188:191], v[54:57]
	v_mfma_f32_16x16x32_bf16 v[50:53], v[180:183], v[188:191], v[50:53]
	v_mfma_f32_16x16x32_bf16 v[38:41], v[172:175], v[196:199], v[38:41]
	v_mfma_f32_16x16x32_bf16 v[34:37], v[180:183], v[196:199], v[34:37]
	v_mfma_f32_16x16x32_bf16 v[22:25], v[172:175], v[204:207], v[22:25]
	v_mfma_f32_16x16x32_bf16 v[18:21], v[180:183], v[204:207], v[18:21]
	v_mfma_f32_16x16x32_bf16 v[6:9], v[172:175], v[212:215], v[6:9]
	v_mfma_f32_16x16x32_bf16 v[2:5], v[180:183], v[212:215], v[2:5]
	s_barrier
	s_add_i32 s33, 0, 0x18000
	s_add_i32 s63, 0, 0x1c000
	v_add_u32_e32 v118, s33, v167
	v_add_u32_e32 v171, s63, v167
	ds_read_b128 v[106:109], v118
	ds_read_b128 v[110:113], v118 offset:1024
	ds_read_b128 v[114:117], v118 offset:2048
	ds_read_b128 v[118:121], v118 offset:3072
	ds_read_b128 v[162:165], v171
	ds_read_b128 v[172:175], v171 offset:1024
	ds_read_b128 v[176:179], v171 offset:2048
	ds_read_b128 v[180:183], v171 offset:3072
	s_add_u32 s18, s24, 0xb0000
	s_addc_u32 s19, s25, 0
	s_mov_b32 m0, s42
	v_lshl_add_u64 v[224:225], s[18:19], 0, v[152:153]
	ds_read_b128 v[184:187], v170 offset:32768
	ds_read_b128 v[188:191], v170 offset:33792
	ds_read_b128 v[192:195], v170 offset:34816
	ds_read_b128 v[196:199], v170 offset:35840
	ds_read_b128 v[200:203], v170 offset:36864
	ds_read_b128 v[204:207], v170 offset:37888
	ds_read_b128 v[208:211], v170 offset:38912
	ds_read_b128 v[212:215], v170 offset:39936
	global_load_lds_dwordx4 v[224:225], off
	v_lshl_add_u64 v[224:225], s[18:19], 0, v[148:149]
	s_mov_b32 m0, s43
	s_nop 0
	global_load_lds_dwordx4 v[224:225], off
	s_waitcnt vmcnt(8)
	s_waitcnt lgkmcnt(0)
	s_barrier
	s_waitcnt lgkmcnt(0)
	v_mfma_f32_16x16x32_bf16 v[142:145], v[106:109], v[184:187], v[142:145]
	v_mfma_f32_16x16x32_bf16 v[138:141], v[114:117], v[184:187], v[138:141]
	v_mfma_f32_16x16x32_bf16 v[126:129], v[106:109], v[192:195], v[126:129]
	v_mfma_f32_16x16x32_bf16 v[122:125], v[114:117], v[192:195], v[122:125]
	v_mfma_f32_16x16x32_bf16 v[94:97], v[106:109], v[200:203], v[94:97]
	v_mfma_f32_16x16x32_bf16 v[90:93], v[114:117], v[200:203], v[90:93]
	v_mfma_f32_16x16x32_bf16 v[78:81], v[106:109], v[208:211], v[78:81]
	v_mfma_f32_16x16x32_bf16 v[74:77], v[114:117], v[208:211], v[74:77]
	v_mfma_f32_16x16x32_bf16 v[142:145], v[110:113], v[188:191], v[142:145]
	v_mfma_f32_16x16x32_bf16 v[138:141], v[118:121], v[188:191], v[138:141]
	v_mfma_f32_16x16x32_bf16 v[126:129], v[110:113], v[196:199], v[126:129]
	v_mfma_f32_16x16x32_bf16 v[122:125], v[118:121], v[196:199], v[122:125]
	v_mfma_f32_16x16x32_bf16 v[94:97], v[110:113], v[204:207], v[94:97]
	v_mfma_f32_16x16x32_bf16 v[90:93], v[118:121], v[204:207], v[90:93]
	v_mfma_f32_16x16x32_bf16 v[78:81], v[110:113], v[212:215], v[78:81]
	v_mfma_f32_16x16x32_bf16 v[74:77], v[118:121], v[212:215], v[74:77]
	v_mfma_f32_16x16x32_bf16 v[134:137], v[162:165], v[184:187], v[134:137]
	v_mfma_f32_16x16x32_bf16 v[130:133], v[176:179], v[184:187], v[130:133]
	v_mfma_f32_16x16x32_bf16 v[102:105], v[162:165], v[192:195], v[102:105]
	v_mfma_f32_16x16x32_bf16 v[98:101], v[176:179], v[192:195], v[98:101]
	v_mfma_f32_16x16x32_bf16 v[86:89], v[162:165], v[200:203], v[86:89]
	v_mfma_f32_16x16x32_bf16 v[82:85], v[176:179], v[200:203], v[82:85]
	v_mfma_f32_16x16x32_bf16 v[70:73], v[162:165], v[208:211], v[70:73]
	v_mfma_f32_16x16x32_bf16 v[66:69], v[176:179], v[208:211], v[66:69]
	v_mfma_f32_16x16x32_bf16 v[134:137], v[172:175], v[188:191], v[134:137]
	v_mfma_f32_16x16x32_bf16 v[130:133], v[180:183], v[188:191], v[130:133]
	v_mfma_f32_16x16x32_bf16 v[102:105], v[172:175], v[196:199], v[102:105]
	v_mfma_f32_16x16x32_bf16 v[98:101], v[180:183], v[196:199], v[98:101]
	v_mfma_f32_16x16x32_bf16 v[86:89], v[172:175], v[204:207], v[86:89]
	v_mfma_f32_16x16x32_bf16 v[82:85], v[180:183], v[204:207], v[82:85]
	v_mfma_f32_16x16x32_bf16 v[70:73], v[172:175], v[212:215], v[70:73]
	v_mfma_f32_16x16x32_bf16 v[66:69], v[180:183], v[212:215], v[66:69]
	s_barrier
; #define PG8_STAGE(bufoff, gbase, voff) do { _Pragma("unroll") for (int _i = 0; _i < 2; ++_i) \
;         __builtin_amdgcn_global_load_lds((const unsigned*)((const char*)(gbase) + (voff)[_i]), (LAS unsigned*)(lds + (bufoff) + ldsw + _i * 8192), 16, 0, 0); } while (0)
; #define PG8_LDA(dst, b, h) do { _Pragma("unroll") for (int m = 0; m < 4; ++m) _Pragma("unroll") for (int k = 0; k < 2; ++k) dst[m][k] = *(const LAS bf16x8*)(lds + PG8_SA(b, h) + aoff + m * 2048 + k * 1024); } while (0)
; #define PG8_MMA(ai, bj, At, Bt) do { __builtin_amdgcn_s_setprio(1); _Pragma("unroll") for (int m = 0; m < 4; ++m) _Pragma("unroll") for (int n = 0; n < 2; ++n) _Pragma("unroll") for (int k = 0; k < 2; ++k) \
;         acc[ai][bj][m][n] = __builtin_amdgcn_mfma_f32_16x16x32_bf16(Bt[n][k], At[m][k], acc[ai][bj][m][n], 0, 0, 0); __builtin_amdgcn_s_setprio(0); } while (0)
; #define PG8_WAIT_V(n) asm volatile("s_waitcnt vmcnt(" #n ")" ::: "memory")
; #define PG8_WAIT_L(n) asm volatile("s_waitcnt lgkmcnt(" #n ")" ::: "memory")
; #define PG8_BAR __builtin_amdgcn_s_barrier()
; #define PG8_SCHED __builtin_amdgcn_sched_barrier(0)
; template <class Epi>
; __device__ __forceinline__ void gemm_phase(LAS unsigned char* lds, const Gemm g, int G, int c, const Epi& E) {
;     ...
;             PG8_LDA(At, 1, 1); PG8_STAGE(PG8_SB(1, 0), b3, voffB); PG8_STAGE(PG8_SB(1, 1), b3 + hstepB, voffB); PG8_STAGE(PG8_SA(1, 0), a3, voffA);
;             PG8_WAIT_V(8); PG8_WAIT_L(0); PG8_BAR; PG8_MMA(1, 0, At, B0); PG8_MMA(1, 1, At, B1); PG8_BAR; PG8_SCHED;
;         }
;         if (wr == 0) PG8_BAR;
	s_add_i32 s18, s33, s38
	v_lshl_add_u64 v[216:217], v[216:217], 0, s[12:13]
	s_mov_b32 m0, s18
	ds_read_b128 v[184:187], v170 offset:49152
	ds_read_b128 v[188:191], v170 offset:50176
	ds_read_b128 v[192:195], v170 offset:51200
	ds_read_b128 v[196:199], v170 offset:52224
	ds_read_b128 v[200:203], v170 offset:53248
	ds_read_b128 v[204:207], v170 offset:54272
	ds_read_b128 v[208:211], v170 offset:55296
	ds_read_b128 v[212:215], v170 offset:56320
	global_load_lds_dwordx4 v[216:217], off
	s_add_i32 m0, s18, 0x2000
	s_add_u32 s18, s22, 0xb0080
	v_lshl_add_u64 v[216:217], v[218:219], 0, s[12:13]
	s_addc_u32 s19, s23, 0
	s_add_i32 s22, s63, s38
	global_load_lds_dwordx4 v[216:217], off
	v_lshl_add_u64 v[216:217], s[18:19], 0, v[150:151]
	s_mov_b32 m0, s22
	s_nop 0
	global_load_lds_dwordx4 v[216:217], off
	v_lshl_add_u64 v[216:217], s[18:19], 0, v[146:147]
	s_add_i32 m0, s22, 0x2000
	s_nop 0
	global_load_lds_dwordx4 v[216:217], off
	v_lshl_add_u64 v[216:217], v[220:221], 0, s[12:13]
	s_mov_b32 m0, s49
	s_nop 0
	global_load_lds_dwordx4 v[216:217], off
	v_lshl_add_u64 v[216:217], v[222:223], 0, s[12:13]
	s_mov_b32 m0, s50
	s_nop 0
	global_load_lds_dwordx4 v[216:217], off
	s_waitcnt vmcnt(8)
	s_waitcnt lgkmcnt(0)
	s_barrier
	s_waitcnt lgkmcnt(0)
	v_mfma_f32_16x16x32_bf16 v[62:65], v[106:109], v[184:187], v[62:65]
	v_mfma_f32_16x16x32_bf16 v[58:61], v[114:117], v[184:187], v[58:61]
	v_mfma_f32_16x16x32_bf16 v[46:49], v[106:109], v[192:195], v[46:49]
	v_mfma_f32_16x16x32_bf16 v[42:45], v[114:117], v[192:195], v[42:45]
	v_mfma_f32_16x16x32_bf16 v[30:33], v[106:109], v[200:203], v[30:33]
	v_mfma_f32_16x16x32_bf16 v[26:29], v[114:117], v[200:203], v[26:29]
	v_mfma_f32_16x16x32_bf16 v[14:17], v[106:109], v[208:211], v[14:17]
	v_mfma_f32_16x16x32_bf16 v[10:13], v[114:117], v[208:211], v[10:13]
	v_mfma_f32_16x16x32_bf16 v[62:65], v[110:113], v[188:191], v[62:65]
	v_mfma_f32_16x16x32_bf16 v[58:61], v[118:121], v[188:191], v[58:61]
	v_mfma_f32_16x16x32_bf16 v[46:49], v[110:113], v[196:199], v[46:49]
	v_mfma_f32_16x16x32_bf16 v[42:45], v[118:121], v[196:199], v[42:45]
	v_mfma_f32_16x16x32_bf16 v[30:33], v[110:113], v[204:207], v[30:33]
	v_mfma_f32_16x16x32_bf16 v[26:29], v[118:121], v[204:207], v[26:29]
	v_mfma_f32_16x16x32_bf16 v[14:17], v[110:113], v[212:215], v[14:17]
	v_mfma_f32_16x16x32_bf16 v[10:13], v[118:121], v[212:215], v[10:13]
	v_mfma_f32_16x16x32_bf16 v[54:57], v[162:165], v[184:187], v[54:57]
	v_mfma_f32_16x16x32_bf16 v[50:53], v[176:179], v[184:187], v[50:53]
	v_mfma_f32_16x16x32_bf16 v[38:41], v[162:165], v[192:195], v[38:41]
	v_mfma_f32_16x16x32_bf16 v[34:37], v[176:179], v[192:195], v[34:37]
	v_mfma_f32_16x16x32_bf16 v[22:25], v[162:165], v[200:203], v[22:25]
	v_mfma_f32_16x16x32_bf16 v[18:21], v[176:179], v[200:203], v[18:21]
	v_mfma_f32_16x16x32_bf16 v[6:9], v[162:165], v[208:211], v[6:9]
	v_mfma_f32_16x16x32_bf16 v[2:5], v[176:179], v[208:211], v[2:5]
	v_mfma_f32_16x16x32_bf16 v[54:57], v[172:175], v[188:191], v[54:57]
	v_mfma_f32_16x16x32_bf16 v[50:53], v[180:183], v[188:191], v[50:53]
	v_mfma_f32_16x16x32_bf16 v[38:41], v[172:175], v[196:199], v[38:41]
	v_mfma_f32_16x16x32_bf16 v[34:37], v[180:183], v[196:199], v[34:37]
	v_mfma_f32_16x16x32_bf16 v[22:25], v[172:175], v[204:207], v[22:25]
	v_mfma_f32_16x16x32_bf16 v[18:21], v[180:183], v[204:207], v[18:21]
	v_mfma_f32_16x16x32_bf16 v[6:9], v[172:175], v[212:215], v[6:9]
	v_mfma_f32_16x16x32_bf16 v[2:5], v[180:183], v[212:215], v[2:5]
	s_barrier
	s_add_i32 s62, s62, 2
	s_add_u32 s60, s60, 0x100
	s_addc_u32 s61, s61, 0
	s_cmp_gt_u32 s62, 41
	s_mov_b64 s[18:19], s[20:21]
	s_cbranch_scc0 .LBB0_2169
	s_and_b64 vcc, exec, s[14:15]
	s_cbranch_vccz .LBB0_2172
	s_barrier
